# PEER U sweep: gelu evaluated once per four experts-per-group (batched across lanes), scalar table bases with 32-bit offsets
# speedup vs baseline: 1.1060x; 1.0125x over previous
; __device__ __forceinline__ void run_step(const Params& p, int step, unsigned char* smem) {
;     ...
;     const int s = step - N_PRO, l = s / (NGRP * N_SLOT), g = (s / N_SLOT) % NGRP, slot = s % N_SLOT;
;     float* X = p.out + (size_t)g * GT * 1024;
;     bf16_t* H = (bf16_t*)(ws + O_H); bf16_t* PROJ = (bf16_t*)(ws + O_PROJ); bf16_t* ZT = (bf16_t*)(ws + O_ZT); bf16_t* YT = (bf16_t*)(ws + O_YT);
;     bf16_t* GA = (bf16_t*)(ws + O_GA); bf16_t* Y = (bf16_t*)(ws + O_Y); float* MT = (float*)(ws + O_MT); bf16_t* MBb = (bf16_t*)(ws + O_MB);
;     int* IDX = (int*)(ws + O_IDX); float* GATE = (float*)(ws + O_GATE); float* SC = (float*)(ws + O_SC);
;     switch (slot) {
;     case 0: {
;         const float* xin = X; float* xc = nullptr;
;         if (l == 0) { xin = (g == 0) ? p.in[0] : p.in[1] + (size_t)(g - 1) * GT * 1024; xc = X; }
;         ph_rmsnorm(xin, xc, p.in[2] + l * 1024, H, GT);
;     } break;
;     case 1: { EpiProj E{PROJ}; run_gemm(smem, H, (const bf16_t*)(ws + O_WIN) + (size_t)l * 8192 * 1024, GT, 8192, 1024, E); } break;
;     case 2:
;         ph_gmlp(PROJ, GA, (const bf16_t*)(ws + O_GWS) + (size_t)l * 12 * 128 * 128, p.in[4] + l * 1536, p.in[5] + l * 1536, p.in[7] + l * 12 * 128, smem);
;         ph_shortconv(PROJ, ZT, p.in[8] + (size_t)l * 3 * 3072, p.in[9] + l * 3072, g == 0 ? 2048 : 4096, smem);
;         break;
;     case 3:
;         if (g == 0) ph_hyena<2048>(ZT, YT, (const bf16_t*)(ws + O_FILT + (size_t)l * FILT_LAYER), p.in[20] + l * 2048, smem);
;         else ph_hyena<4096>(ZT, YT, (const bf16_t*)(ws + O_FILT + (size_t)l * FILT_LAYER + FILT_L0), p.in[20] + l * 2048, smem);
;         break;
;     case 4: {
;         ph_transpose_y(YT, Y, smem);
;         EpiMa E{MT, PROJ}; run_gemm(smem, GA, (const bf16_t*)(ws + O_WAO) + (size_t)l * 1024 * 1536, GT, 1024, 1536, E);
;     } break;
;     case 5: { EpiMb E{MT, PROJ, MBb}; run_gemm(smem, Y, (const bf16_t*)(ws + O_WBO) + (size_t)l * 1024 * 1024, GT, 1024, 1024, E); } break;
;     case 6: { EpiRes E{X, H}; run_gemm(smem, MBb, (const bf16_t*)(ws + O_WO) + (size_t)l * 1024 * 1024, GT, 1024, 1024, E); } break;
;     case 7: { EpiSc E{SC}; run_gemm(smem, H, (const bf16_t*)(ws + O_WP) + (size_t)l * 2048 * 1024, GT, 2048, 1024, E); } break;
;     case 8: ph_peer(SC, H, p.in[24] + l * 1024, ws + O_U + (size_t)l * 16384 * 768, ws + O_V + (size_t)l * 16384 * 768, X, l == 1 ? p.in[29] : nullptr); break;
.LBB0_213:
	v_readlane_b32 s0, v254, 54
	s_add_i32 s0, s0, -3
	s_mul_hi_i32 s1, s0, 0xb60b60b7
	s_add_i32 s1, s1, s0
	s_lshr_b32 s2, s1, 31
	s_ashr_i32 s1, s1, 5
	s_add_i32 s86, s1, s2
	s_mul_hi_i32 s1, s0, 0x38e38e39
	s_lshr_b32 s2, s1, 31
	s_ashr_i32 s1, s1, 1
	s_add_i32 s1, s1, s2
	s_mul_hi_i32 s2, s1, 0x66666667
	s_lshr_b32 s6, s2, 31
	s_ashr_i32 s2, s2, 1
	s_add_i32 s2, s2, s6
	s_mul_i32 s2, s2, 5
	s_sub_i32 s90, s1, s2
	s_mul_i32 s1, s1, 9
	s_ashr_i32 s91, s90, 31
	s_sub_i32 s84, s0, s1
	s_lshl_b64 s[0:1], s[90:91], 26
	s_add_u32 s88, s20, s0
	s_addc_u32 s89, s21, s1
	s_mov_b64 s[0:1], -1
	s_mov_b64 s[78:79], 0
	s_cmp_lt_i32 s84, 4
	s_mov_b64 s[92:93], 0
	s_cbranch_scc1 .LBB0_335
	s_cmp_gt_i32 s84, 5
	s_cbranch_scc0 .LBB0_281
	s_cmp_gt_i32 s84, 6
	s_cbranch_scc0 .LBB0_258
	s_cmp_gt_i32 s84, 7
	s_mov_b64 s[6:7], -1
	s_cbranch_scc0 .LBB0_236
	s_cmp_eq_u32 s84, 8
	s_cbranch_scc0 .LBB0_235
	s_waitcnt vmcnt(3)
	v_mov_b32_e32 v0, v131
	v_readlane_b32 s0, v251, 28
	v_ashrrev_i32_e32 v1, 6, v0
	v_mov_b32_e32 v0, v131
	v_add_u32_e32 v72, s0, v1
	s_movk_i32 s0, 0x4000
	v_cmp_gt_i32_e32 vcc, s0, v72
	s_and_saveexec_b64 s[38:39], vcc
	s_cbranch_execz .LBB0_234
	v_readlane_b32 s0, v254, 54
	s_sub_i32 s0, s0, 48
	s_cmp_lt_u32 s0, 45
	s_mul_i32 s14, s86, 0xc00000
	v_readlane_b32 s6, v251, 16
	s_cselect_b32 s1, s19, 0
	s_cselect_b32 s0, s18, 0
	s_mul_hi_i32 s2, s86, 0xc00000
	v_readlane_b32 s7, v251, 17
	s_add_u32 s6, s6, s14
	s_addc_u32 s7, s7, s2
	v_readlane_b32 s16, v254, 48
	v_readlane_b32 s17, v254, 49
	s_add_u32 s24, s16, s14
	s_addc_u32 s25, s17, s2
	s_lshl_b32 s14, s86, 10
	s_ashr_i32 s15, s14, 31
	s_lshl_b64 s[14:15], s[14:15], 2
	s_add_u32 s26, s8, s14
	v_and_b32_e32 v1, 15, v0
	s_addc_u32 s27, s9, s15
	v_lshlrev_b32_e32 v128, 8, v1
	global_load_dwordx4 v[64:67], v128, s[26:27]
	global_load_dwordx4 v[68:71], v128, s[26:27] offset:16
	v_and_b32_e32 v74, 63, v0
	v_lshlrev_b32_e32 v2, 1, v74
	v_bfe_u32 v3, v0, 2, 4
	s_waitcnt vmcnt(2)
	v_and_b32_e32 v146, 64, v174
	v_and_b32_e32 v6, 31, v0
	v_mul_u32_u24_e32 v4, 48, v1
	v_mov_b32_e32 v5, v129
	v_xor_b32_e32 v76, 0x7f, v2
	v_xor_b32_e32 v75, 0x7e, v2
	v_or_b32_e32 v2, v146, v3
	v_lshl_add_u64 v[80:81], s[24:25], 0, v[4:5]
	v_mul_u32_u24_e32 v4, 24, v6
	v_bfe_u32 v91, v0, 4, 2
	v_lshlrev_b32_e32 v8, 2, v0
	v_lshlrev_b32_e32 v147, 2, v2
	v_or_b32_e32 v2, v146, v1
	v_lshl_add_u64 v[82:83], s[6:7], 0, v[4:5]
	v_lshlrev_b32_e32 v4, 7, v6
	v_lshlrev_b32_e32 v0, 1, v0
	v_lshlrev_b32_e32 v149, 2, v2
	v_lshlrev_b32_e32 v2, 6, v1
	v_lshl_add_u64 v[6:7], s[88:89], 0, v[4:5]
	v_and_b32_e32 v0, 64, v0
	v_mov_b32_e32 v1, v129
	v_lshl_add_u64 v[4:5], s[0:1], 0, v[4:5]
	v_lshl_add_u64 v[84:85], v[6:7], 0, v[0:1]
	v_lshl_add_u64 v[86:87], v[4:5], 0, v[0:1]
	v_lshlrev_b32_e32 v0, 4, v3
	v_and_b32_e32 v1, 12, v8
	v_xor_b32_e32 v0, 0xff, v0
	v_or_b32_e32 v3, v146, v1
	v_lshlrev_b32_e32 v150, 2, v3
	v_xad_u32 v88, v1, -1, v0
	v_sub_u32_e32 v77, v0, v1
	v_or_b32_e32 v3, 2, v1
	v_or_b32_e32 v1, 3, v1
	v_sub_u32_e32 v89, v0, v3
	v_sub_u32_e32 v90, v0, v1
	v_xor_b32_e32 v0, 32, v174
	v_add_u32_e32 v1, 64, v146
	v_cmp_lt_i32_e32 vcc, v0, v1
	v_lshl_add_u64 v[78:79], s[26:27], 0, v[128:129]
	s_cmp_lg_u64 s[0:1], 0
	v_cndmask_b32_e32 v0, v174, v0, vcc
	v_lshlrev_b32_e32 v128, 3, v74
	v_lshlrev_b32_e32 v148, 2, v146
	v_cmp_gt_u32_e64 s[42:43], 16, v74
	v_cmp_gt_u32_e64 s[44:45], 32, v74
	s_mov_b64 s[26:27], 0
	s_cselect_b64 s[92:93], -1, 0
	v_or_b32_e32 v151, 4, v150
	v_or_b32_e32 v152, 8, v150
	v_or_b32_e32 v153, 12, v150
	v_cmp_eq_u32_e64 s[46:47], 0, v74
	v_cmp_eq_u32_e64 s[48:49], 1, v74
	v_cmp_eq_u32_e64 s[50:51], 2, v74
	v_cmp_eq_u32_e64 s[52:53], 3, v74
	v_cmp_eq_u32_e64 s[54:55], 4, v74
	v_cmp_eq_u32_e64 s[56:57], 5, v74
	v_cmp_eq_u32_e64 s[58:59], 6, v74
	v_cmp_eq_u32_e64 s[60:61], 7, v74
	v_cmp_eq_u32_e64 s[62:63], 8, v74
	v_cmp_eq_u32_e64 s[64:65], 9, v74
	v_cmp_eq_u32_e64 s[66:67], 10, v74
	v_cmp_eq_u32_e64 s[68:69], 11, v74
	v_cmp_eq_u32_e64 s[70:71], 12, v74
	v_cmp_eq_u32_e64 s[72:73], 13, v74
	v_cmp_eq_u32_e64 s[74:75], 14, v74
	v_cmp_eq_u32_e64 s[76:77], 15, v74
	v_lshlrev_b32_e32 v154, 2, v0
	v_or_b32_e32 v155, v146, v91
	v_lshl_add_u64 v[92:93], s[82:83], 0, v[128:129]
	v_lshlrev_b32_e32 v128, 4, v74
	v_lshlrev_b32_e32 v94, 1, v2
	v_and_b32_e32 v216, 3, v74
	v_lshlrev_b32_e32 v155, 4, v216
	v_cmp_eq_u32_e64 s[50:51], 0, v216
	v_cmp_eq_u32_e64 s[52:53], 1, v216
	v_cmp_eq_u32_e64 s[54:55], 2, v216
	v_cmp_eq_u32_e64 s[56:57], 3, v216
	v_readfirstlane_b32 s46, v80
	v_readfirstlane_b32 s47, v81
	v_readfirstlane_b32 s48, v82
	v_readfirstlane_b32 s49, v83
	v_and_b32_e32 v92, 15, v74
	v_mul_u32_u24_e32 v92, 48, v92
	v_and_b32_e32 v93, 31, v74
	v_mul_u32_u24_e32 v93, 24, v93
	v_readfirstlane_b32 s0, v72
	s_mov_b32 s30, 0xffffff80
	s_mov_b32 s31, 0xffffff00
	s_mov_b32 s36, 0x1000000
	s_lshl_b32 s1, s0, 13
	s_add_u32 s28, s82, s1
	s_addc_u32 s29, s83, 0
	v_lshrrev_b32_e32 v216, 3, v74
	v_and_b32_e32 v217, 7, v74
	v_lshlrev_b32_e32 v216, 10, v216
	v_lshl_or_b32 v216, v217, 4, v216
	v_lshrrev_b32_e32 v144, 6, v131
	v_mul_u32_u24_e32 v145, 0x2400, v144
	v_lshrrev_b32_e32 v157, 3, v74
	v_mul_u32_u24_e32 v157, 0x90, v157
	v_lshl_add_u32 v157, v217, 4, v157
	v_add_u32_e32 v144, v145, v157
	v_mul_u32_u24_e32 v157, 0x90, v74
	v_add_u32_e32 v145, v145, v157
	v_lshrrev_b32_e32 v156, 6, v131
	v_mul_u32_u24_e32 v156, 0x1c00, v156
	v_mul_u32_u24_e32 v157, 0x70, v74
	v_add_u32_e32 v156, v156, v157
	v_add_u32_e32 v156, 0x12000, v156
	v_mov_b32_e32 v217, v216
	global_load_dwordx4 v[180:183], v217, s[28:29] offset:0
	v_add_u32_e32 v157, s36, v217
	global_load_dwordx4 v[184:187], v157, s[28:29] offset:0
	v_add_u32_e32 v217, s36, v157
	global_load_dwordx4 v[188:191], v217, s[28:29] offset:0
	v_add_u32_e32 v157, s36, v217
	global_load_dwordx4 v[192:195], v157, s[28:29] offset:0
	v_add_u32_e32 v217, s36, v157
	global_load_dwordx4 v[196:199], v217, s[28:29] offset:0
	v_add_u32_e32 v157, s36, v217
	global_load_dwordx4 v[200:203], v157, s[28:29] offset:0
	v_add_u32_e32 v217, s36, v157
	global_load_dwordx4 v[204:207], v217, s[28:29] offset:0
	v_add_u32_e32 v157, s36, v217
	global_load_dwordx4 v[208:211], v157, s[28:29] offset:0
	v_mov_b32_e32 v217, v216
	global_load_dwordx4 v[52:55], v217, s[28:29] offset:128
	v_add_u32_e32 v157, s36, v217
	global_load_dwordx4 v[56:59], v157, s[28:29] offset:128
	v_add_u32_e32 v217, s36, v157
	global_load_dwordx4 v[60:63], v217, s[28:29] offset:128
	v_add_u32_e32 v157, s36, v217
	global_load_dwordx4 v[112:115], v157, s[28:29] offset:128
	v_add_u32_e32 v217, s36, v157
	global_load_dwordx4 v[116:119], v217, s[28:29] offset:128
	v_add_u32_e32 v157, s36, v217
	global_load_dwordx4 v[120:123], v157, s[28:29] offset:128
	v_add_u32_e32 v217, s36, v157
	global_load_dwordx4 v[124:127], v217, s[28:29] offset:128
	v_add_u32_e32 v157, s36, v217
	global_load_dwordx4 v[158:161], v157, s[28:29] offset:128
	s_waitcnt vmcnt(8)
; __device__ __forceinline__ unsigned f2key(float f) { const unsigned u = __float_as_uint(f); return (u & 0x80000000u) ? ~u : (u | 0x80000000u); }
; __device__ void ph_peer(const float* __restrict__ SC, const bf16_t* __restrict__ H  , const float* __restrict__ gffn, const unsigned char* __restrict__ U, const unsigned char* __restrict__ V, float* X, const float* __restrict__ fgain) {
;     ...
;             for (int u = 0; u < 2; ++u) { const float* sc = SC + (size_t)tok * 2048 + (h + u) * 256;
;                 const float2 a0 = ((const float2*)sc)[lane], a1 = ((const float2*)(sc + 128))[lane];
;                 k00[u] = (f2key(a0.x) & ~127u) | (unsigned)(127 - 2 * lane); k01[u] = (f2key(a0.y) & ~127u) | (unsigned)(126 - 2 * lane);
;                 k10[u] = (f2key(a1.x) & ~127u) | (unsigned)(127 - 2 * lane); k11[u] = (f2key(a1.y) & ~127u) | (unsigned)(126 - 2 * lane);
	ds_write_b128 v144, v[180:183] offset:0
	ds_write_b128 v144, v[184:187] offset:1152
	ds_write_b128 v144, v[188:191] offset:2304
	ds_write_b128 v144, v[192:195] offset:3456
	ds_write_b128 v144, v[196:199] offset:4608
	ds_write_b128 v144, v[200:203] offset:5760
	ds_write_b128 v144, v[204:207] offset:6912
	ds_write_b128 v144, v[208:211] offset:8064
	ds_read_b128 v[0:3], v145 offset:0
	ds_read_b128 v[4:7], v145 offset:16
	ds_read_b128 v[8:11], v145 offset:32
	ds_read_b128 v[12:15], v145 offset:48
	ds_read_b128 v[16:19], v145 offset:64
	ds_read_b128 v[20:23], v145 offset:80
	ds_read_b128 v[24:27], v145 offset:96
	ds_read_b128 v[28:31], v145 offset:112
	s_waitcnt lgkmcnt(0)
	v_ashrrev_i32_e32 v212, 31, v0
	v_or_b32_e32 v212, 0x80000000, v212
	v_xor_b32_e32 v0, v0, v212
	v_and_b32_e32 v0, s30, v0
	v_or_b32_e32 v0, 0x7f, v0
	v_ashrrev_i32_e32 v212, 31, v1
	v_or_b32_e32 v212, 0x80000000, v212
	v_xor_b32_e32 v1, v1, v212
	v_and_b32_e32 v1, s30, v1
	v_or_b32_e32 v1, 0x7e, v1
	v_ashrrev_i32_e32 v212, 31, v2
	v_or_b32_e32 v212, 0x80000000, v212
	v_xor_b32_e32 v2, v2, v212
	v_and_b32_e32 v2, s30, v2
	v_or_b32_e32 v2, 0x7d, v2
	v_ashrrev_i32_e32 v212, 31, v3
	v_or_b32_e32 v212, 0x80000000, v212
	v_xor_b32_e32 v3, v3, v212
	v_and_b32_e32 v3, s30, v3
	v_or_b32_e32 v3, 0x7c, v3
	v_ashrrev_i32_e32 v212, 31, v4
	v_or_b32_e32 v212, 0x80000000, v212
	v_xor_b32_e32 v4, v4, v212
	v_and_b32_e32 v4, s30, v4
	v_or_b32_e32 v4, 0x7b, v4
	v_ashrrev_i32_e32 v212, 31, v5
	v_or_b32_e32 v212, 0x80000000, v212
	v_xor_b32_e32 v5, v5, v212
	v_and_b32_e32 v5, s30, v5
	v_or_b32_e32 v5, 0x7a, v5
	v_ashrrev_i32_e32 v212, 31, v6
	v_or_b32_e32 v212, 0x80000000, v212
	v_xor_b32_e32 v6, v6, v212
	v_and_b32_e32 v6, s30, v6
	v_or_b32_e32 v6, 0x79, v6
	v_ashrrev_i32_e32 v212, 31, v7
	v_or_b32_e32 v212, 0x80000000, v212
	v_xor_b32_e32 v7, v7, v212
	v_and_b32_e32 v7, s30, v7
	v_or_b32_e32 v7, 0x78, v7
	v_ashrrev_i32_e32 v212, 31, v8
	v_or_b32_e32 v212, 0x80000000, v212
	v_xor_b32_e32 v8, v8, v212
	v_and_b32_e32 v8, s30, v8
	v_or_b32_e32 v8, 0x77, v8
	v_ashrrev_i32_e32 v212, 31, v9
	v_or_b32_e32 v212, 0x80000000, v212
	v_xor_b32_e32 v9, v9, v212
	v_and_b32_e32 v9, s30, v9
	v_or_b32_e32 v9, 0x76, v9
	v_ashrrev_i32_e32 v212, 31, v10
	v_or_b32_e32 v212, 0x80000000, v212
	v_xor_b32_e32 v10, v10, v212
	v_and_b32_e32 v10, s30, v10
	v_or_b32_e32 v10, 0x75, v10
	v_ashrrev_i32_e32 v212, 31, v11
	v_or_b32_e32 v212, 0x80000000, v212
	v_xor_b32_e32 v11, v11, v212
	v_and_b32_e32 v11, s30, v11
	v_or_b32_e32 v11, 0x74, v11
	v_ashrrev_i32_e32 v212, 31, v12
	v_or_b32_e32 v212, 0x80000000, v212
	v_xor_b32_e32 v12, v12, v212
	v_and_b32_e32 v12, s30, v12
	v_or_b32_e32 v12, 0x73, v12
	v_ashrrev_i32_e32 v212, 31, v13
	v_or_b32_e32 v212, 0x80000000, v212
	v_xor_b32_e32 v13, v13, v212
	v_and_b32_e32 v13, s30, v13
	v_or_b32_e32 v13, 0x72, v13
	v_ashrrev_i32_e32 v212, 31, v14
	v_or_b32_e32 v212, 0x80000000, v212
	v_xor_b32_e32 v14, v14, v212
	v_and_b32_e32 v14, s30, v14
	v_or_b32_e32 v14, 0x71, v14
	v_ashrrev_i32_e32 v212, 31, v15
	v_or_b32_e32 v212, 0x80000000, v212
	v_xor_b32_e32 v15, v15, v212
	v_and_b32_e32 v15, s30, v15
	v_or_b32_e32 v15, 0x70, v15
	v_ashrrev_i32_e32 v212, 31, v16
	v_or_b32_e32 v212, 0x80000000, v212
	v_xor_b32_e32 v16, v16, v212
	v_and_b32_e32 v16, s30, v16
	v_or_b32_e32 v16, 0x6f, v16
	v_ashrrev_i32_e32 v212, 31, v17
	v_or_b32_e32 v212, 0x80000000, v212
	v_xor_b32_e32 v17, v17, v212
	v_and_b32_e32 v17, s30, v17
	v_or_b32_e32 v17, 0x6e, v17
	v_ashrrev_i32_e32 v212, 31, v18
	v_or_b32_e32 v212, 0x80000000, v212
	v_xor_b32_e32 v18, v18, v212
	v_and_b32_e32 v18, s30, v18
	v_or_b32_e32 v18, 0x6d, v18
	v_ashrrev_i32_e32 v212, 31, v19
	v_or_b32_e32 v212, 0x80000000, v212
	v_xor_b32_e32 v19, v19, v212
	v_and_b32_e32 v19, s30, v19
	v_or_b32_e32 v19, 0x6c, v19
	v_ashrrev_i32_e32 v212, 31, v20
	v_or_b32_e32 v212, 0x80000000, v212
	v_xor_b32_e32 v20, v20, v212
	v_and_b32_e32 v20, s30, v20
	v_or_b32_e32 v20, 0x6b, v20
	v_ashrrev_i32_e32 v212, 31, v21
	v_or_b32_e32 v212, 0x80000000, v212
	v_xor_b32_e32 v21, v21, v212
	v_and_b32_e32 v21, s30, v21
	v_or_b32_e32 v21, 0x6a, v21
	v_ashrrev_i32_e32 v212, 31, v22
	v_or_b32_e32 v212, 0x80000000, v212
	v_xor_b32_e32 v22, v22, v212
	v_and_b32_e32 v22, s30, v22
	v_or_b32_e32 v22, 0x69, v22
	v_ashrrev_i32_e32 v212, 31, v23
	v_or_b32_e32 v212, 0x80000000, v212
	v_xor_b32_e32 v23, v23, v212
	v_and_b32_e32 v23, s30, v23
	v_or_b32_e32 v23, 0x68, v23
	v_ashrrev_i32_e32 v212, 31, v24
	v_or_b32_e32 v212, 0x80000000, v212
	v_xor_b32_e32 v24, v24, v212
	v_and_b32_e32 v24, s30, v24
	v_or_b32_e32 v24, 0x67, v24
	v_ashrrev_i32_e32 v212, 31, v25
	v_or_b32_e32 v212, 0x80000000, v212
	v_xor_b32_e32 v25, v25, v212
	v_and_b32_e32 v25, s30, v25
	v_or_b32_e32 v25, 0x66, v25
	v_ashrrev_i32_e32 v212, 31, v26
	v_or_b32_e32 v212, 0x80000000, v212
	v_xor_b32_e32 v26, v26, v212
	v_and_b32_e32 v26, s30, v26
	v_or_b32_e32 v26, 0x65, v26
	v_ashrrev_i32_e32 v212, 31, v27
	v_or_b32_e32 v212, 0x80000000, v212
	v_xor_b32_e32 v27, v27, v212
	v_and_b32_e32 v27, s30, v27
	v_or_b32_e32 v27, 0x64, v27
	v_ashrrev_i32_e32 v212, 31, v28
	v_or_b32_e32 v212, 0x80000000, v212
	v_xor_b32_e32 v28, v28, v212
	v_and_b32_e32 v28, s30, v28
	v_or_b32_e32 v28, 0x63, v28
	v_ashrrev_i32_e32 v212, 31, v29
	v_or_b32_e32 v212, 0x80000000, v212
	v_xor_b32_e32 v29, v29, v212
	v_and_b32_e32 v29, s30, v29
	v_or_b32_e32 v29, 0x62, v29
	v_ashrrev_i32_e32 v212, 31, v30
	v_or_b32_e32 v212, 0x80000000, v212
	v_xor_b32_e32 v30, v30, v212
	v_and_b32_e32 v30, s30, v30
	v_or_b32_e32 v30, 0x61, v30
	v_ashrrev_i32_e32 v212, 31, v31
	v_or_b32_e32 v212, 0x80000000, v212
	v_xor_b32_e32 v31, v31, v212
	v_and_b32_e32 v31, s30, v31
; __device__ void ph_peer(const float* __restrict__ SC, const bf16_t* __restrict__ H  , const float* __restrict__ gffn, const unsigned char* __restrict__ U, const unsigned char* __restrict__ V, float* X, const float* __restrict__ fgain) {
;     ...
;             for (int it = 0; it < 16; ++it) {
; #pragma unroll
;                 for (int u = 0; u < 2; ++u) {
;                     const unsigned m0 = wave_max_u32(k00[u] > k01[u] ? k00[u] : k01[u]);
;                     const unsigned m1 = wave_max_u32(k10[u] > k11[u] ? k10[u] : k11[u]);
;                     if (lane == it) { top0[u] = m0; top1[u] = m1; }
;                     if (k00[u] == m0) k00[u] = 0u; if (k01[u] == m0) k01[u] = 0u;
;                     if (k10[u] == m1) k10[u] = 0u; if (k11[u] == m1) k11[u] = 0u; }
;             }
	v_or_b32_e32 v31, 0x60, v31
	v_max_u32_e32 v215, v0, v1
	v_min_u32_e32 v1, v0, v1
	v_max_u32_e32 v214, v16, v17
	v_min_u32_e32 v17, v16, v17
	v_max_u32_e32 v213, v2, v3
	v_min_u32_e32 v3, v2, v3
	v_max_u32_e32 v0, v18, v19
	v_min_u32_e32 v19, v18, v19
	v_max_u32_e32 v16, v4, v5
	v_min_u32_e32 v5, v4, v5
	v_max_u32_e32 v2, v20, v21
	v_min_u32_e32 v21, v20, v21
	v_max_u32_e32 v18, v6, v7
	v_min_u32_e32 v7, v6, v7
	v_max_u32_e32 v4, v22, v23
	v_min_u32_e32 v23, v22, v23
	v_max_u32_e32 v20, v8, v9
	v_min_u32_e32 v9, v8, v9
	v_max_u32_e32 v6, v24, v25
	v_min_u32_e32 v25, v24, v25
	v_max_u32_e32 v22, v10, v11
	v_min_u32_e32 v11, v10, v11
	v_max_u32_e32 v8, v26, v27
	v_min_u32_e32 v27, v26, v27
	v_max_u32_e32 v24, v12, v13
	v_min_u32_e32 v13, v12, v13
	v_max_u32_e32 v10, v28, v29
	v_min_u32_e32 v29, v28, v29
	v_max_u32_e32 v26, v14, v15
	v_min_u32_e32 v15, v14, v15
	v_max_u32_e32 v12, v30, v31
	v_min_u32_e32 v31, v30, v31
	v_max_u32_e32 v28, v215, v213
	v_min_u32_e32 v213, v215, v213
	v_max_u32_e32 v14, v214, v0
	v_min_u32_e32 v0, v214, v0
	v_max_u32_e32 v30, v1, v3
	v_min_u32_e32 v3, v1, v3
	v_max_u32_e32 v215, v17, v19
	v_min_u32_e32 v19, v17, v19
	v_max_u32_e32 v214, v16, v18
	v_min_u32_e32 v18, v16, v18
	v_max_u32_e32 v1, v2, v4
	v_min_u32_e32 v4, v2, v4
	v_max_u32_e32 v17, v5, v7
	v_min_u32_e32 v7, v5, v7
	v_max_u32_e32 v16, v21, v23
	v_min_u32_e32 v23, v21, v23
	v_max_u32_e32 v2, v20, v22
	v_min_u32_e32 v22, v20, v22
	v_max_u32_e32 v5, v6, v8
	v_min_u32_e32 v8, v6, v8
	v_max_u32_e32 v21, v9, v11
	v_min_u32_e32 v11, v9, v11
	v_max_u32_e32 v20, v25, v27
	v_min_u32_e32 v27, v25, v27
	v_max_u32_e32 v6, v24, v26
	v_min_u32_e32 v26, v24, v26
	v_max_u32_e32 v9, v10, v12
	v_min_u32_e32 v12, v10, v12
	v_max_u32_e32 v25, v13, v15
	v_min_u32_e32 v15, v13, v15
	v_max_u32_e32 v24, v29, v31
	v_min_u32_e32 v31, v29, v31
	v_max_u32_e32 v10, v30, v213
	v_min_u32_e32 v213, v30, v213
	v_max_u32_e32 v13, v215, v0
	v_min_u32_e32 v0, v215, v0
	v_max_u32_e32 v29, v17, v18
	v_min_u32_e32 v18, v17, v18
	v_max_u32_e32 v30, v16, v4
	v_min_u32_e32 v4, v16, v4
	v_max_u32_e32 v215, v21, v22
	v_min_u32_e32 v22, v21, v22
	v_max_u32_e32 v17, v20, v8
	v_min_u32_e32 v8, v20, v8
	v_max_u32_e32 v16, v25, v26
	v_min_u32_e32 v26, v25, v26
	v_max_u32_e32 v21, v24, v12
	v_min_u32_e32 v12, v24, v12
	v_max_u32_e32 v20, v28, v214
	v_min_u32_e32 v214, v28, v214
	v_max_u32_e32 v25, v14, v1
	v_min_u32_e32 v1, v14, v1
	v_max_u32_e32 v24, v10, v29
	v_min_u32_e32 v29, v10, v29
	v_max_u32_e32 v28, v13, v30
	v_min_u32_e32 v30, v13, v30
	v_max_u32_e32 v14, v213, v18
	v_min_u32_e32 v18, v213, v18
	v_max_u32_e32 v10, v0, v4
	v_min_u32_e32 v4, v0, v4
	v_max_u32_e32 v13, v3, v7
	v_min_u32_e32 v7, v3, v7
	v_max_u32_e32 v213, v19, v23
	v_min_u32_e32 v23, v19, v23
	v_max_u32_e32 v0, v2, v6
	v_min_u32_e32 v6, v2, v6
	v_max_u32_e32 v3, v5, v9
	v_min_u32_e32 v9, v5, v9
	v_max_u32_e32 v19, v215, v16
	v_min_u32_e32 v16, v215, v16
	v_max_u32_e32 v2, v17, v21
	v_min_u32_e32 v21, v17, v21
	v_max_u32_e32 v5, v22, v26
	v_min_u32_e32 v26, v22, v26
	v_max_u32_e32 v215, v8, v12
	v_min_u32_e32 v12, v8, v12
	v_max_u32_e32 v17, v11, v15
	v_min_u32_e32 v15, v11, v15
	v_max_u32_e32 v22, v27, v31
	v_min_u32_e32 v31, v27, v31
	v_max_u32_e32 v8, v14, v214
	v_min_u32_e32 v214, v14, v214
	v_max_u32_e32 v11, v10, v1
	v_min_u32_e32 v1, v10, v1
	v_max_u32_e32 v27, v13, v29
	v_min_u32_e32 v29, v13, v29
	v_max_u32_e32 v14, v213, v30
	v_min_u32_e32 v30, v213, v30
	v_max_u32_e32 v10, v5, v6
	v_min_u32_e32 v6, v5, v6
	v_max_u32_e32 v13, v215, v9
	v_min_u32_e32 v9, v215, v9
	v_max_u32_e32 v213, v17, v16
	v_min_u32_e32 v16, v17, v16
	v_max_u32_e32 v5, v22, v21
	v_min_u32_e32 v21, v22, v21
	v_max_u32_e32 v215, v24, v8
	v_min_u32_e32 v8, v24, v8
	v_max_u32_e32 v17, v28, v11
	v_min_u32_e32 v11, v28, v11
	v_max_u32_e32 v22, v27, v214
	v_min_u32_e32 v214, v27, v214
	v_max_u32_e32 v24, v14, v1
	v_min_u32_e32 v1, v14, v1
	v_max_u32_e32 v28, v29, v18
	v_min_u32_e32 v18, v29, v18
	v_max_u32_e32 v27, v30, v4
	v_min_u32_e32 v4, v30, v4
	v_max_u32_e32 v14, v19, v10
	v_min_u32_e32 v10, v19, v10
	v_max_u32_e32 v29, v2, v13
	v_min_u32_e32 v13, v2, v13
	v_max_u32_e32 v30, v213, v6
	v_min_u32_e32 v6, v213, v6
	v_max_u32_e32 v19, v5, v9
	v_min_u32_e32 v9, v5, v9
	v_max_u32_e32 v2, v16, v26
	v_min_u32_e32 v26, v16, v26
	v_max_u32_e32 v213, v21, v12
	v_min_u32_e32 v12, v21, v12
	v_max_u32_e32 v5, v20, v0
	v_min_u32_e32 v0, v20, v0
	v_max_u32_e32 v16, v25, v3
	v_min_u32_e32 v3, v25, v3
	v_max_u32_e32 v21, v215, v14
	v_min_u32_e32 v14, v215, v14
	v_max_u32_e32 v20, v17, v29
	v_min_u32_e32 v29, v17, v29
	v_max_u32_e32 v25, v8, v10
	v_min_u32_e32 v10, v8, v10
	v_max_u32_e32 v215, v11, v13
	v_min_u32_e32 v13, v11, v13
	v_max_u32_e32 v17, v22, v30
	v_min_u32_e32 v30, v22, v30
	v_max_u32_e32 v8, v24, v19
	v_min_u32_e32 v19, v24, v19
	v_max_u32_e32 v11, v214, v6
	v_min_u32_e32 v6, v214, v6
	v_max_u32_e32 v22, v1, v9
	v_min_u32_e32 v9, v1, v9
	v_max_u32_e32 v24, v28, v2
	v_min_u32_e32 v2, v28, v2
	v_max_u32_e32 v214, v27, v213
	v_min_u32_e32 v213, v27, v213
	v_max_u32_e32 v1, v18, v26
	v_min_u32_e32 v26, v18, v26
	v_max_u32_e32 v28, v4, v12
	v_min_u32_e32 v12, v4, v12
	v_max_u32_e32 v27, v7, v15
	v_min_u32_e32 v15, v7, v15
	v_max_u32_e32 v18, v23, v31
	v_min_u32_e32 v31, v23, v31
	v_max_u32_e32 v4, v11, v0
	v_min_u32_e32 v0, v11, v0
	v_max_u32_e32 v7, v22, v3
	v_min_u32_e32 v3, v22, v3
	v_max_u32_e32 v23, v24, v14
	v_min_u32_e32 v14, v24, v14
	v_max_u32_e32 v11, v214, v29
	v_min_u32_e32 v29, v214, v29
	v_max_u32_e32 v22, v1, v10
	v_min_u32_e32 v10, v1, v10
	v_max_u32_e32 v24, v28, v13
	v_min_u32_e32 v13, v28, v13
	v_max_u32_e32 v214, v27, v30
; __device__ void ph_peer(const float* __restrict__ SC, const bf16_t* __restrict__ H  , const float* __restrict__ gffn, const unsigned char* __restrict__ U, const unsigned char* __restrict__ V, float* X, const float* __restrict__ fgain) {
;     ...
;             for (int u = 0; u < 2; ++u) { const float* sc = SC + (size_t)tok * 2048 + (h + u) * 256;
;                 const float2 a0 = ((const float2*)sc)[lane], a1 = ((const float2*)(sc + 128))[lane];
;     ...
;             for (int it = 0; it < 16; ++it) {
; #pragma unroll
;                 for (int u = 0; u < 2; ++u) {
;                     const unsigned m0 = wave_max_u32(k00[u] > k01[u] ? k00[u] : k01[u]);
;                     const unsigned m1 = wave_max_u32(k10[u] > k11[u] ? k10[u] : k11[u]);
;                     if (lane == it) { top0[u] = m0; top1[u] = m1; }
;                     if (k00[u] == m0) k00[u] = 0u; if (k01[u] == m0) k01[u] = 0u;
;                     if (k10[u] == m1) k10[u] = 0u; if (k11[u] == m1) k11[u] = 0u; }
;             }
	v_min_u32_e32 v30, v27, v30
	v_max_u32_e32 v1, v18, v19
	v_min_u32_e32 v19, v18, v19
	v_max_u32_e32 v28, v25, v4
	v_min_u32_e32 v4, v25, v4
	v_max_u32_e32 v27, v215, v7
	v_min_u32_e32 v7, v215, v7
	v_max_u32_e32 v18, v17, v23
	v_min_u32_e32 v23, v17, v23
	v_max_u32_e32 v25, v8, v11
	v_min_u32_e32 v11, v8, v11
	v_max_u32_e32 v215, v22, v0
	v_min_u32_e32 v0, v22, v0
	v_max_u32_e32 v17, v24, v3
	v_min_u32_e32 v3, v24, v3
	v_max_u32_e32 v8, v214, v14
	v_min_u32_e32 v14, v214, v14
	v_max_u32_e32 v22, v1, v29
	v_min_u32_e32 v29, v1, v29
	v_max_u32_e32 v24, v10, v6
	v_min_u32_e32 v6, v10, v6
	v_max_u32_e32 v214, v13, v9
	v_min_u32_e32 v9, v13, v9
	v_max_u32_e32 v1, v30, v2
	v_min_u32_e32 v2, v30, v2
	v_max_u32_e32 v10, v19, v213
	v_min_u32_e32 v213, v19, v213
	v_max_u32_e32 v13, v21, v28
	v_min_u32_e32 v28, v21, v28
	v_max_u32_e32 v30, v20, v27
	v_min_u32_e32 v27, v20, v27
	v_max_u32_e32 v19, v18, v4
	v_min_u32_e32 v4, v18, v4
	v_max_u32_e32 v21, v25, v7
	v_min_u32_e32 v7, v25, v7
	v_max_u32_e32 v20, v23, v215
	v_min_u32_e32 v215, v23, v215
	v_max_u32_e32 v18, v11, v17
	v_min_u32_e32 v17, v11, v17
	v_max_u32_e32 v25, v8, v0
	v_min_u32_e32 v0, v8, v0
	v_max_u32_e32 v23, v22, v3
	v_min_u32_e32 v3, v22, v3
	v_max_u32_e32 v11, v14, v24
	v_min_u32_e32 v24, v14, v24
	v_max_u32_e32 v8, v29, v214
	v_min_u32_e32 v214, v29, v214
	v_max_u32_e32 v22, v1, v6
	v_min_u32_e32 v6, v1, v6
	v_max_u32_e32 v14, v10, v9
	v_min_u32_e32 v9, v10, v9
	v_max_u32_e32 v29, v2, v26
	v_min_u32_e32 v26, v2, v26
	v_max_u32_e32 v1, v213, v12
	v_min_u32_e32 v12, v213, v12
	v_mov_b32_e32 v51, v5
	v_mov_b32_e32 v50, v13
	v_mov_b32_e32 v49, v28
	v_mov_b32_e32 v48, v19
	v_mov_b32_e32 v47, v4
	v_mov_b32_e32 v46, v20
	v_mov_b32_e32 v45, v215
	v_mov_b32_e32 v44, v25
	v_mov_b32_e32 v43, v0
	v_mov_b32_e32 v42, v11
	v_mov_b32_e32 v41, v24
	v_mov_b32_e32 v40, v22
	v_mov_b32_e32 v39, v6
	v_mov_b32_e32 v38, v29
	v_mov_b32_e32 v37, v26
	v_mov_b32_e32 v36, v15
	v_max_u32_e32 v35, v51, v31
	v_max_u32_e32 v34, v50, v12
	v_max_u32_e32 v33, v49, v1
	v_max_u32_e32 v32, v48, v9
	v_max_u32_e32 v51, v47, v14
	v_max_u32_e32 v50, v46, v214
	v_max_u32_e32 v49, v45, v8
	v_max_u32_e32 v48, v44, v3
	v_max_u32_e32 v47, v43, v23
	v_max_u32_e32 v46, v42, v17
	v_max_u32_e32 v45, v41, v18
	v_max_u32_e32 v44, v40, v7
	v_max_u32_e32 v43, v39, v21
	v_max_u32_e32 v42, v38, v27
	v_max_u32_e32 v41, v37, v30
	v_max_u32_e32 v40, v36, v16
	v_max_u32_e32 v39, v35, v47
	v_min_u32_e32 v47, v35, v47
	v_max_u32_e32 v38, v34, v46
	v_min_u32_e32 v46, v34, v46
	v_max_u32_e32 v37, v33, v45
	v_min_u32_e32 v45, v33, v45
	v_max_u32_e32 v36, v32, v44
	v_min_u32_e32 v44, v32, v44
	v_max_u32_e32 v35, v51, v43
	v_min_u32_e32 v43, v51, v43
	v_max_u32_e32 v34, v50, v42
	v_min_u32_e32 v42, v50, v42
	v_max_u32_e32 v33, v49, v41
	v_min_u32_e32 v41, v49, v41
	v_max_u32_e32 v32, v48, v40
	v_min_u32_e32 v40, v48, v40
	v_max_u32_e32 v51, v39, v35
	v_min_u32_e32 v35, v39, v35
	v_max_u32_e32 v50, v38, v34
	v_min_u32_e32 v34, v38, v34
	v_max_u32_e32 v49, v37, v33
	v_min_u32_e32 v33, v37, v33
	v_max_u32_e32 v48, v36, v32
	v_min_u32_e32 v32, v36, v32
	v_max_u32_e32 v39, v47, v43
	v_min_u32_e32 v43, v47, v43
	v_max_u32_e32 v38, v46, v42
	v_min_u32_e32 v42, v46, v42
	v_max_u32_e32 v37, v45, v41
	v_min_u32_e32 v41, v45, v41
	v_max_u32_e32 v36, v44, v40
	v_min_u32_e32 v40, v44, v40
	v_max_u32_e32 v47, v51, v49
	v_min_u32_e32 v49, v51, v49
	v_max_u32_e32 v46, v50, v48
	v_min_u32_e32 v48, v50, v48
	v_max_u32_e32 v45, v35, v33
	v_min_u32_e32 v33, v35, v33
	v_max_u32_e32 v44, v34, v32
	v_min_u32_e32 v32, v34, v32
	v_max_u32_e32 v51, v39, v37
	v_min_u32_e32 v37, v39, v37
	v_max_u32_e32 v50, v38, v36
	v_min_u32_e32 v36, v38, v36
	v_max_u32_e32 v35, v43, v41
	v_min_u32_e32 v41, v43, v41
	v_max_u32_e32 v34, v42, v40
	v_min_u32_e32 v40, v42, v40
	v_max_u32_e32 v39, v47, v46
	v_min_u32_e32 v46, v47, v46
	v_max_u32_e32 v38, v49, v48
	v_min_u32_e32 v48, v49, v48
	v_max_u32_e32 v43, v45, v44
	v_min_u32_e32 v44, v45, v44
	v_max_u32_e32 v42, v33, v32
	v_min_u32_e32 v32, v33, v32
	v_max_u32_e32 v47, v51, v50
	v_min_u32_e32 v50, v51, v50
	v_max_u32_e32 v49, v37, v36
	v_min_u32_e32 v36, v37, v36
	v_max_u32_e32 v45, v35, v34
	v_min_u32_e32 v34, v35, v34
	v_max_u32_e32 v33, v41, v40
	v_min_u32_e32 v40, v41, v40
	v_mov_b32_e32 v217, v216
	global_load_dwordx4 v[180:183], v217, s[28:29] offset:256
	v_add_u32_e32 v157, s36, v217
	global_load_dwordx4 v[184:187], v157, s[28:29] offset:256
	v_add_u32_e32 v217, s36, v157
	global_load_dwordx4 v[188:191], v217, s[28:29] offset:256
	v_add_u32_e32 v157, s36, v217
	global_load_dwordx4 v[192:195], v157, s[28:29] offset:256
	v_add_u32_e32 v217, s36, v157
	global_load_dwordx4 v[196:199], v217, s[28:29] offset:256
	v_add_u32_e32 v157, s36, v217
	global_load_dwordx4 v[200:203], v157, s[28:29] offset:256
	v_add_u32_e32 v217, s36, v157
	global_load_dwordx4 v[204:207], v217, s[28:29] offset:256
	v_add_u32_e32 v157, s36, v217
	global_load_dwordx4 v[208:211], v157, s[28:29] offset:256
	s_waitcnt vmcnt(8)
	ds_write_b128 v144, v[52:55] offset:0
	ds_write_b128 v144, v[56:59] offset:1152
	ds_write_b128 v144, v[60:63] offset:2304
	ds_write_b128 v144, v[112:115] offset:3456
	ds_write_b128 v144, v[116:119] offset:4608
	ds_write_b128 v144, v[120:123] offset:5760
	ds_write_b128 v144, v[124:127] offset:6912
	ds_write_b128 v144, v[158:161] offset:8064
	ds_read_b128 v[0:3], v145 offset:0
	ds_read_b128 v[4:7], v145 offset:16
	ds_read_b128 v[8:11], v145 offset:32
	ds_read_b128 v[12:15], v145 offset:48
	ds_read_b128 v[16:19], v145 offset:64
	ds_read_b128 v[20:23], v145 offset:80
	ds_read_b128 v[24:27], v145 offset:96
	ds_read_b128 v[28:31], v145 offset:112
	s_waitcnt lgkmcnt(0)
; __device__ __forceinline__ unsigned f2key(float f) { const unsigned u = __float_as_uint(f); return (u & 0x80000000u) ? ~u : (u | 0x80000000u); }
; __device__ void ph_peer(const float* __restrict__ SC, const bf16_t* __restrict__ H  , const float* __restrict__ gffn, const unsigned char* __restrict__ U, const unsigned char* __restrict__ V, float* X, const float* __restrict__ fgain) {
;     ...
;             for (int u = 0; u < 2; ++u) { const float* sc = SC + (size_t)tok * 2048 + (h + u) * 256;
;                 const float2 a0 = ((const float2*)sc)[lane], a1 = ((const float2*)(sc + 128))[lane];
;                 k00[u] = (f2key(a0.x) & ~127u) | (unsigned)(127 - 2 * lane); k01[u] = (f2key(a0.y) & ~127u) | (unsigned)(126 - 2 * lane);
;                 k10[u] = (f2key(a1.x) & ~127u) | (unsigned)(127 - 2 * lane); k11[u] = (f2key(a1.y) & ~127u) | (unsigned)(126 - 2 * lane);
;     ...
;             for (int it = 0; it < 16; ++it) {
; #pragma unroll
;                 for (int u = 0; u < 2; ++u) {
;                     const unsigned m0 = wave_max_u32(k00[u] > k01[u] ? k00[u] : k01[u]);
;                     const unsigned m1 = wave_max_u32(k10[u] > k11[u] ? k10[u] : k11[u]);
;                     if (lane == it) { top0[u] = m0; top1[u] = m1; }
;                     if (k00[u] == m0) k00[u] = 0u; if (k01[u] == m0) k01[u] = 0u;
;                     if (k10[u] == m1) k10[u] = 0u; if (k11[u] == m1) k11[u] = 0u; }
;             }
	v_ashrrev_i32_e32 v212, 31, v0
	v_or_b32_e32 v212, 0x80000000, v212
	v_xor_b32_e32 v0, v0, v212
	v_and_b32_e32 v0, s30, v0
	v_or_b32_e32 v0, 0x5f, v0
	v_ashrrev_i32_e32 v212, 31, v1
	v_or_b32_e32 v212, 0x80000000, v212
	v_xor_b32_e32 v1, v1, v212
	v_and_b32_e32 v1, s30, v1
	v_or_b32_e32 v1, 0x5e, v1
	v_ashrrev_i32_e32 v212, 31, v2
	v_or_b32_e32 v212, 0x80000000, v212
	v_xor_b32_e32 v2, v2, v212
	v_and_b32_e32 v2, s30, v2
	v_or_b32_e32 v2, 0x5d, v2
	v_ashrrev_i32_e32 v212, 31, v3
	v_or_b32_e32 v212, 0x80000000, v212
	v_xor_b32_e32 v3, v3, v212
	v_and_b32_e32 v3, s30, v3
	v_or_b32_e32 v3, 0x5c, v3
	v_ashrrev_i32_e32 v212, 31, v4
	v_or_b32_e32 v212, 0x80000000, v212
	v_xor_b32_e32 v4, v4, v212
	v_and_b32_e32 v4, s30, v4
	v_or_b32_e32 v4, 0x5b, v4
	v_ashrrev_i32_e32 v212, 31, v5
	v_or_b32_e32 v212, 0x80000000, v212
	v_xor_b32_e32 v5, v5, v212
	v_and_b32_e32 v5, s30, v5
	v_or_b32_e32 v5, 0x5a, v5
	v_ashrrev_i32_e32 v212, 31, v6
	v_or_b32_e32 v212, 0x80000000, v212
	v_xor_b32_e32 v6, v6, v212
	v_and_b32_e32 v6, s30, v6
	v_or_b32_e32 v6, 0x59, v6
	v_ashrrev_i32_e32 v212, 31, v7
	v_or_b32_e32 v212, 0x80000000, v212
	v_xor_b32_e32 v7, v7, v212
	v_and_b32_e32 v7, s30, v7
	v_or_b32_e32 v7, 0x58, v7
	v_ashrrev_i32_e32 v212, 31, v8
	v_or_b32_e32 v212, 0x80000000, v212
	v_xor_b32_e32 v8, v8, v212
	v_and_b32_e32 v8, s30, v8
	v_or_b32_e32 v8, 0x57, v8
	v_ashrrev_i32_e32 v212, 31, v9
	v_or_b32_e32 v212, 0x80000000, v212
	v_xor_b32_e32 v9, v9, v212
	v_and_b32_e32 v9, s30, v9
	v_or_b32_e32 v9, 0x56, v9
	v_ashrrev_i32_e32 v212, 31, v10
	v_or_b32_e32 v212, 0x80000000, v212
	v_xor_b32_e32 v10, v10, v212
	v_and_b32_e32 v10, s30, v10
	v_or_b32_e32 v10, 0x55, v10
	v_ashrrev_i32_e32 v212, 31, v11
	v_or_b32_e32 v212, 0x80000000, v212
	v_xor_b32_e32 v11, v11, v212
	v_and_b32_e32 v11, s30, v11
	v_or_b32_e32 v11, 0x54, v11
	v_ashrrev_i32_e32 v212, 31, v12
	v_or_b32_e32 v212, 0x80000000, v212
	v_xor_b32_e32 v12, v12, v212
	v_and_b32_e32 v12, s30, v12
	v_or_b32_e32 v12, 0x53, v12
	v_ashrrev_i32_e32 v212, 31, v13
	v_or_b32_e32 v212, 0x80000000, v212
	v_xor_b32_e32 v13, v13, v212
	v_and_b32_e32 v13, s30, v13
	v_or_b32_e32 v13, 0x52, v13
	v_ashrrev_i32_e32 v212, 31, v14
	v_or_b32_e32 v212, 0x80000000, v212
	v_xor_b32_e32 v14, v14, v212
	v_and_b32_e32 v14, s30, v14
	v_or_b32_e32 v14, 0x51, v14
	v_ashrrev_i32_e32 v212, 31, v15
	v_or_b32_e32 v212, 0x80000000, v212
	v_xor_b32_e32 v15, v15, v212
	v_and_b32_e32 v15, s30, v15
	v_or_b32_e32 v15, 0x50, v15
	v_ashrrev_i32_e32 v212, 31, v16
	v_or_b32_e32 v212, 0x80000000, v212
	v_xor_b32_e32 v16, v16, v212
	v_and_b32_e32 v16, s30, v16
	v_or_b32_e32 v16, 0x4f, v16
	v_ashrrev_i32_e32 v212, 31, v17
	v_or_b32_e32 v212, 0x80000000, v212
	v_xor_b32_e32 v17, v17, v212
	v_and_b32_e32 v17, s30, v17
	v_or_b32_e32 v17, 0x4e, v17
	v_ashrrev_i32_e32 v212, 31, v18
	v_or_b32_e32 v212, 0x80000000, v212
	v_xor_b32_e32 v18, v18, v212
	v_and_b32_e32 v18, s30, v18
	v_or_b32_e32 v18, 0x4d, v18
	v_ashrrev_i32_e32 v212, 31, v19
	v_or_b32_e32 v212, 0x80000000, v212
	v_xor_b32_e32 v19, v19, v212
	v_and_b32_e32 v19, s30, v19
	v_or_b32_e32 v19, 0x4c, v19
	v_ashrrev_i32_e32 v212, 31, v20
	v_or_b32_e32 v212, 0x80000000, v212
	v_xor_b32_e32 v20, v20, v212
	v_and_b32_e32 v20, s30, v20
	v_or_b32_e32 v20, 0x4b, v20
	v_ashrrev_i32_e32 v212, 31, v21
	v_or_b32_e32 v212, 0x80000000, v212
	v_xor_b32_e32 v21, v21, v212
	v_and_b32_e32 v21, s30, v21
	v_or_b32_e32 v21, 0x4a, v21
	v_ashrrev_i32_e32 v212, 31, v22
	v_or_b32_e32 v212, 0x80000000, v212
	v_xor_b32_e32 v22, v22, v212
	v_and_b32_e32 v22, s30, v22
	v_or_b32_e32 v22, 0x49, v22
	v_ashrrev_i32_e32 v212, 31, v23
	v_or_b32_e32 v212, 0x80000000, v212
	v_xor_b32_e32 v23, v23, v212
	v_and_b32_e32 v23, s30, v23
	v_or_b32_e32 v23, 0x48, v23
	v_ashrrev_i32_e32 v212, 31, v24
	v_or_b32_e32 v212, 0x80000000, v212
	v_xor_b32_e32 v24, v24, v212
	v_and_b32_e32 v24, s30, v24
	v_or_b32_e32 v24, 0x47, v24
	v_ashrrev_i32_e32 v212, 31, v25
	v_or_b32_e32 v212, 0x80000000, v212
	v_xor_b32_e32 v25, v25, v212
	v_and_b32_e32 v25, s30, v25
	v_or_b32_e32 v25, 0x46, v25
	v_ashrrev_i32_e32 v212, 31, v26
	v_or_b32_e32 v212, 0x80000000, v212
	v_xor_b32_e32 v26, v26, v212
	v_and_b32_e32 v26, s30, v26
	v_or_b32_e32 v26, 0x45, v26
	v_ashrrev_i32_e32 v212, 31, v27
	v_or_b32_e32 v212, 0x80000000, v212
	v_xor_b32_e32 v27, v27, v212
	v_and_b32_e32 v27, s30, v27
	v_or_b32_e32 v27, 0x44, v27
	v_ashrrev_i32_e32 v212, 31, v28
	v_or_b32_e32 v212, 0x80000000, v212
	v_xor_b32_e32 v28, v28, v212
	v_and_b32_e32 v28, s30, v28
	v_or_b32_e32 v28, 0x43, v28
	v_ashrrev_i32_e32 v212, 31, v29
	v_or_b32_e32 v212, 0x80000000, v212
	v_xor_b32_e32 v29, v29, v212
	v_and_b32_e32 v29, s30, v29
	v_or_b32_e32 v29, 0x42, v29
	v_ashrrev_i32_e32 v212, 31, v30
	v_or_b32_e32 v212, 0x80000000, v212
	v_xor_b32_e32 v30, v30, v212
	v_and_b32_e32 v30, s30, v30
	v_or_b32_e32 v30, 0x41, v30
	v_ashrrev_i32_e32 v212, 31, v31
	v_or_b32_e32 v212, 0x80000000, v212
	v_xor_b32_e32 v31, v31, v212
	v_and_or_b32 v31, v31, s30, 64
	v_max_u32_e32 v215, v0, v1
	v_min_u32_e32 v1, v0, v1
	v_max_u32_e32 v214, v16, v17
	v_min_u32_e32 v17, v16, v17
	v_max_u32_e32 v213, v2, v3
	v_min_u32_e32 v3, v2, v3
	v_max_u32_e32 v0, v18, v19
	v_min_u32_e32 v19, v18, v19
	v_max_u32_e32 v16, v4, v5
	v_min_u32_e32 v5, v4, v5
	v_max_u32_e32 v2, v20, v21
	v_min_u32_e32 v21, v20, v21
	v_max_u32_e32 v18, v6, v7
	v_min_u32_e32 v7, v6, v7
	v_max_u32_e32 v4, v22, v23
	v_min_u32_e32 v23, v22, v23
	v_max_u32_e32 v20, v8, v9
	v_min_u32_e32 v9, v8, v9
	v_max_u32_e32 v6, v24, v25
	v_min_u32_e32 v25, v24, v25
	v_max_u32_e32 v22, v10, v11
	v_min_u32_e32 v11, v10, v11
	v_max_u32_e32 v8, v26, v27
	v_min_u32_e32 v27, v26, v27
; __device__ void ph_peer(const float* __restrict__ SC, const bf16_t* __restrict__ H  , const float* __restrict__ gffn, const unsigned char* __restrict__ U, const unsigned char* __restrict__ V, float* X, const float* __restrict__ fgain) {
;     ...
;             for (int it = 0; it < 16; ++it) {
; #pragma unroll
;                 for (int u = 0; u < 2; ++u) {
;                     const unsigned m0 = wave_max_u32(k00[u] > k01[u] ? k00[u] : k01[u]);
;                     const unsigned m1 = wave_max_u32(k10[u] > k11[u] ? k10[u] : k11[u]);
;                     if (lane == it) { top0[u] = m0; top1[u] = m1; }
;                     if (k00[u] == m0) k00[u] = 0u; if (k01[u] == m0) k01[u] = 0u;
;                     if (k10[u] == m1) k10[u] = 0u; if (k11[u] == m1) k11[u] = 0u; }
;             }
	v_max_u32_e32 v24, v12, v13
	v_min_u32_e32 v13, v12, v13
	v_max_u32_e32 v10, v28, v29
	v_min_u32_e32 v29, v28, v29
	v_max_u32_e32 v26, v14, v15
	v_min_u32_e32 v15, v14, v15
	v_max_u32_e32 v12, v30, v31
	v_min_u32_e32 v31, v30, v31
	v_max_u32_e32 v28, v215, v213
	v_min_u32_e32 v213, v215, v213
	v_max_u32_e32 v14, v214, v0
	v_min_u32_e32 v0, v214, v0
	v_max_u32_e32 v30, v1, v3
	v_min_u32_e32 v3, v1, v3
	v_max_u32_e32 v215, v17, v19
	v_min_u32_e32 v19, v17, v19
	v_max_u32_e32 v214, v16, v18
	v_min_u32_e32 v18, v16, v18
	v_max_u32_e32 v1, v2, v4
	v_min_u32_e32 v4, v2, v4
	v_max_u32_e32 v17, v5, v7
	v_min_u32_e32 v7, v5, v7
	v_max_u32_e32 v16, v21, v23
	v_min_u32_e32 v23, v21, v23
	v_max_u32_e32 v2, v20, v22
	v_min_u32_e32 v22, v20, v22
	v_max_u32_e32 v5, v6, v8
	v_min_u32_e32 v8, v6, v8
	v_max_u32_e32 v21, v9, v11
	v_min_u32_e32 v11, v9, v11
	v_max_u32_e32 v20, v25, v27
	v_min_u32_e32 v27, v25, v27
	v_max_u32_e32 v6, v24, v26
	v_min_u32_e32 v26, v24, v26
	v_max_u32_e32 v9, v10, v12
	v_min_u32_e32 v12, v10, v12
	v_max_u32_e32 v25, v13, v15
	v_min_u32_e32 v15, v13, v15
	v_max_u32_e32 v24, v29, v31
	v_min_u32_e32 v31, v29, v31
	v_max_u32_e32 v10, v30, v213
	v_min_u32_e32 v213, v30, v213
	v_max_u32_e32 v13, v215, v0
	v_min_u32_e32 v0, v215, v0
	v_max_u32_e32 v29, v17, v18
	v_min_u32_e32 v18, v17, v18
	v_max_u32_e32 v30, v16, v4
	v_min_u32_e32 v4, v16, v4
	v_max_u32_e32 v215, v21, v22
	v_min_u32_e32 v22, v21, v22
	v_max_u32_e32 v17, v20, v8
	v_min_u32_e32 v8, v20, v8
	v_max_u32_e32 v16, v25, v26
	v_min_u32_e32 v26, v25, v26
	v_max_u32_e32 v21, v24, v12
	v_min_u32_e32 v12, v24, v12
	v_max_u32_e32 v20, v28, v214
	v_min_u32_e32 v214, v28, v214
	v_max_u32_e32 v25, v14, v1
	v_min_u32_e32 v1, v14, v1
	v_max_u32_e32 v24, v10, v29
	v_min_u32_e32 v29, v10, v29
	v_max_u32_e32 v28, v13, v30
	v_min_u32_e32 v30, v13, v30
	v_max_u32_e32 v14, v213, v18
	v_min_u32_e32 v18, v213, v18
	v_max_u32_e32 v10, v0, v4
	v_min_u32_e32 v4, v0, v4
	v_max_u32_e32 v13, v3, v7
	v_min_u32_e32 v7, v3, v7
	v_max_u32_e32 v213, v19, v23
	v_min_u32_e32 v23, v19, v23
	v_max_u32_e32 v0, v2, v6
	v_min_u32_e32 v6, v2, v6
	v_max_u32_e32 v3, v5, v9
	v_min_u32_e32 v9, v5, v9
	v_max_u32_e32 v19, v215, v16
	v_min_u32_e32 v16, v215, v16
	v_max_u32_e32 v2, v17, v21
	v_min_u32_e32 v21, v17, v21
	v_max_u32_e32 v5, v22, v26
	v_min_u32_e32 v26, v22, v26
	v_max_u32_e32 v215, v8, v12
	v_min_u32_e32 v12, v8, v12
	v_max_u32_e32 v17, v11, v15
	v_min_u32_e32 v15, v11, v15
	v_max_u32_e32 v22, v27, v31
	v_min_u32_e32 v31, v27, v31
	v_max_u32_e32 v8, v14, v214
	v_min_u32_e32 v214, v14, v214
	v_max_u32_e32 v11, v10, v1
	v_min_u32_e32 v1, v10, v1
	v_max_u32_e32 v27, v13, v29
	v_min_u32_e32 v29, v13, v29
	v_max_u32_e32 v14, v213, v30
	v_min_u32_e32 v30, v213, v30
	v_max_u32_e32 v10, v5, v6
	v_min_u32_e32 v6, v5, v6
	v_max_u32_e32 v13, v215, v9
	v_min_u32_e32 v9, v215, v9
	v_max_u32_e32 v213, v17, v16
	v_min_u32_e32 v16, v17, v16
	v_max_u32_e32 v5, v22, v21
	v_min_u32_e32 v21, v22, v21
	v_max_u32_e32 v215, v24, v8
	v_min_u32_e32 v8, v24, v8
	v_max_u32_e32 v17, v28, v11
	v_min_u32_e32 v11, v28, v11
	v_max_u32_e32 v22, v27, v214
	v_min_u32_e32 v214, v27, v214
	v_max_u32_e32 v24, v14, v1
	v_min_u32_e32 v1, v14, v1
	v_max_u32_e32 v28, v29, v18
	v_min_u32_e32 v18, v29, v18
	v_max_u32_e32 v27, v30, v4
	v_min_u32_e32 v4, v30, v4
	v_max_u32_e32 v14, v19, v10
	v_min_u32_e32 v10, v19, v10
	v_max_u32_e32 v29, v2, v13
	v_min_u32_e32 v13, v2, v13
	v_max_u32_e32 v30, v213, v6
	v_min_u32_e32 v6, v213, v6
	v_max_u32_e32 v19, v5, v9
	v_min_u32_e32 v9, v5, v9
	v_max_u32_e32 v2, v16, v26
	v_min_u32_e32 v26, v16, v26
	v_max_u32_e32 v213, v21, v12
	v_min_u32_e32 v12, v21, v12
	v_max_u32_e32 v5, v20, v0
	v_min_u32_e32 v0, v20, v0
	v_max_u32_e32 v16, v25, v3
	v_min_u32_e32 v3, v25, v3
	v_max_u32_e32 v21, v215, v14
	v_min_u32_e32 v14, v215, v14
	v_max_u32_e32 v20, v17, v29
	v_min_u32_e32 v29, v17, v29
	v_max_u32_e32 v25, v8, v10
	v_min_u32_e32 v10, v8, v10
	v_max_u32_e32 v215, v11, v13
	v_min_u32_e32 v13, v11, v13
	v_max_u32_e32 v17, v22, v30
	v_min_u32_e32 v30, v22, v30
	v_max_u32_e32 v8, v24, v19
	v_min_u32_e32 v19, v24, v19
	v_max_u32_e32 v11, v214, v6
	v_min_u32_e32 v6, v214, v6
	v_max_u32_e32 v22, v1, v9
	v_min_u32_e32 v9, v1, v9
	v_max_u32_e32 v24, v28, v2
	v_min_u32_e32 v2, v28, v2
	v_max_u32_e32 v214, v27, v213
	v_min_u32_e32 v213, v27, v213
	v_max_u32_e32 v1, v18, v26
	v_min_u32_e32 v26, v18, v26
	v_max_u32_e32 v28, v4, v12
	v_min_u32_e32 v12, v4, v12
	v_max_u32_e32 v27, v7, v15
	v_min_u32_e32 v15, v7, v15
	v_max_u32_e32 v18, v23, v31
	v_min_u32_e32 v31, v23, v31
	v_max_u32_e32 v4, v11, v0
	v_min_u32_e32 v0, v11, v0
	v_max_u32_e32 v7, v22, v3
	v_min_u32_e32 v3, v22, v3
	v_max_u32_e32 v23, v24, v14
	v_min_u32_e32 v14, v24, v14
	v_max_u32_e32 v11, v214, v29
	v_min_u32_e32 v29, v214, v29
	v_max_u32_e32 v22, v1, v10
	v_min_u32_e32 v10, v1, v10
	v_max_u32_e32 v24, v28, v13
	v_min_u32_e32 v13, v28, v13
	v_max_u32_e32 v214, v27, v30
	v_min_u32_e32 v30, v27, v30
	v_max_u32_e32 v1, v18, v19
	v_min_u32_e32 v19, v18, v19
	v_max_u32_e32 v28, v25, v4
	v_min_u32_e32 v4, v25, v4
	v_max_u32_e32 v27, v215, v7
	v_min_u32_e32 v7, v215, v7
	v_max_u32_e32 v18, v17, v23
	v_min_u32_e32 v23, v17, v23
	v_max_u32_e32 v25, v8, v11
	v_min_u32_e32 v11, v8, v11
	v_max_u32_e32 v215, v22, v0
	v_min_u32_e32 v0, v22, v0
	v_max_u32_e32 v17, v24, v3
	v_min_u32_e32 v3, v24, v3
	v_max_u32_e32 v8, v214, v14
	v_min_u32_e32 v14, v214, v14
	v_max_u32_e32 v22, v1, v29
	v_min_u32_e32 v29, v1, v29
	v_max_u32_e32 v24, v10, v6
	v_min_u32_e32 v6, v10, v6
	v_max_u32_e32 v214, v13, v9
	v_min_u32_e32 v9, v13, v9
	v_max_u32_e32 v1, v30, v2
	v_min_u32_e32 v2, v30, v2
; __device__ void ph_peer(const float* __restrict__ SC, const bf16_t* __restrict__ H  , const float* __restrict__ gffn, const unsigned char* __restrict__ U, const unsigned char* __restrict__ V, float* X, const float* __restrict__ fgain) {
;     ...
;             for (int it = 0; it < 16; ++it) {
; #pragma unroll
;                 for (int u = 0; u < 2; ++u) {
;                     const unsigned m0 = wave_max_u32(k00[u] > k01[u] ? k00[u] : k01[u]);
;                     const unsigned m1 = wave_max_u32(k10[u] > k11[u] ? k10[u] : k11[u]);
;                     if (lane == it) { top0[u] = m0; top1[u] = m1; }
;                     if (k00[u] == m0) k00[u] = 0u; if (k01[u] == m0) k01[u] = 0u;
;                     if (k10[u] == m1) k10[u] = 0u; if (k11[u] == m1) k11[u] = 0u; }
;             }
	v_max_u32_e32 v10, v19, v213
	v_min_u32_e32 v213, v19, v213
	v_max_u32_e32 v13, v21, v28
	v_min_u32_e32 v28, v21, v28
	v_max_u32_e32 v30, v20, v27
	v_min_u32_e32 v27, v20, v27
	v_max_u32_e32 v19, v18, v4
	v_min_u32_e32 v4, v18, v4
	v_max_u32_e32 v21, v25, v7
	v_min_u32_e32 v7, v25, v7
	v_max_u32_e32 v20, v23, v215
	v_min_u32_e32 v215, v23, v215
	v_max_u32_e32 v18, v11, v17
	v_min_u32_e32 v17, v11, v17
	v_max_u32_e32 v25, v8, v0
	v_min_u32_e32 v0, v8, v0
	v_max_u32_e32 v23, v22, v3
	v_min_u32_e32 v3, v22, v3
	v_max_u32_e32 v11, v14, v24
	v_min_u32_e32 v24, v14, v24
	v_max_u32_e32 v8, v29, v214
	v_min_u32_e32 v214, v29, v214
	v_max_u32_e32 v22, v1, v6
	v_min_u32_e32 v6, v1, v6
	v_max_u32_e32 v14, v10, v9
	v_min_u32_e32 v9, v10, v9
	v_max_u32_e32 v29, v2, v26
	v_min_u32_e32 v26, v2, v26
	v_max_u32_e32 v1, v213, v12
	v_min_u32_e32 v12, v213, v12
	v_max_u32_e32 v51, v39, v15
	v_max_u32_e32 v37, v46, v26
	v_max_u32_e32 v35, v38, v29
	v_max_u32_e32 v41, v48, v6
	v_max_u32_e32 v39, v43, v22
	v_max_u32_e32 v46, v44, v24
	v_max_u32_e32 v38, v42, v11
	v_max_u32_e32 v48, v32, v0
	v_max_u32_e32 v43, v47, v25
	v_max_u32_e32 v44, v50, v215
	v_max_u32_e32 v42, v49, v20
	v_max_u32_e32 v32, v36, v4
	v_max_u32_e32 v47, v45, v19
	v_max_u32_e32 v50, v34, v28
	v_max_u32_e32 v49, v33, v13
	v_max_u32_e32 v36, v40, v5
	v_max_u32_e32 v45, v51, v43
	v_min_u32_e32 v43, v51, v43
	v_max_u32_e32 v34, v37, v44
	v_min_u32_e32 v44, v37, v44
	v_max_u32_e32 v33, v35, v42
	v_min_u32_e32 v42, v35, v42
	v_max_u32_e32 v40, v41, v32
	v_min_u32_e32 v32, v41, v32
	v_max_u32_e32 v51, v39, v47
	v_min_u32_e32 v47, v39, v47
	v_max_u32_e32 v37, v46, v50
	v_min_u32_e32 v50, v46, v50
	v_max_u32_e32 v35, v38, v49
	v_min_u32_e32 v49, v38, v49
	v_max_u32_e32 v41, v48, v36
	v_min_u32_e32 v36, v48, v36
	v_max_u32_e32 v39, v45, v51
	v_min_u32_e32 v51, v45, v51
	v_max_u32_e32 v46, v34, v37
	v_min_u32_e32 v37, v34, v37
	v_max_u32_e32 v38, v33, v35
	v_min_u32_e32 v35, v33, v35
	v_max_u32_e32 v48, v40, v41
	v_min_u32_e32 v41, v40, v41
	v_max_u32_e32 v45, v43, v47
	v_min_u32_e32 v47, v43, v47
	v_max_u32_e32 v34, v44, v50
	v_min_u32_e32 v50, v44, v50
	v_max_u32_e32 v33, v42, v49
	v_min_u32_e32 v49, v42, v49
	v_max_u32_e32 v40, v32, v36
	v_min_u32_e32 v36, v32, v36
	v_max_u32_e32 v43, v39, v38
	v_min_u32_e32 v38, v39, v38
	v_max_u32_e32 v44, v46, v48
	v_min_u32_e32 v48, v46, v48
	v_max_u32_e32 v42, v51, v35
	v_min_u32_e32 v35, v51, v35
	v_max_u32_e32 v32, v37, v41
	v_min_u32_e32 v41, v37, v41
	v_max_u32_e32 v39, v45, v33
	v_min_u32_e32 v33, v45, v33
	v_max_u32_e32 v46, v34, v40
	v_min_u32_e32 v40, v34, v40
	v_max_u32_e32 v51, v47, v49
	v_min_u32_e32 v49, v47, v49
	v_max_u32_e32 v37, v50, v36
	v_min_u32_e32 v36, v50, v36
	v_max_u32_e32 v45, v43, v44
	v_min_u32_e32 v44, v43, v44
	v_max_u32_e32 v34, v38, v48
	v_min_u32_e32 v48, v38, v48
	v_max_u32_e32 v47, v42, v32
	v_min_u32_e32 v32, v42, v32
	v_max_u32_e32 v50, v35, v41
	v_min_u32_e32 v41, v35, v41
	v_max_u32_e32 v43, v39, v46
	v_min_u32_e32 v46, v39, v46
	v_max_u32_e32 v38, v33, v40
	v_min_u32_e32 v40, v33, v40
	v_max_u32_e32 v42, v51, v37
	v_min_u32_e32 v37, v51, v37
	v_max_u32_e32 v35, v49, v36
	v_min_u32_e32 v36, v49, v36
	v_max_u32_e32 v39, v45, v31
	v_max_u32_e32 v33, v44, v12
	v_max_u32_e32 v51, v34, v1
	v_max_u32_e32 v49, v48, v9
	v_max_u32_e32 v45, v47, v14
	v_max_u32_e32 v44, v32, v214
	v_max_u32_e32 v34, v50, v8
	v_max_u32_e32 v48, v41, v3
	v_max_u32_e32 v47, v43, v23
	v_max_u32_e32 v32, v46, v17
	v_max_u32_e32 v50, v38, v18
	v_max_u32_e32 v41, v40, v7
	v_max_u32_e32 v43, v42, v21
	v_max_u32_e32 v46, v37, v27
	v_max_u32_e32 v38, v35, v30
	v_max_u32_e32 v40, v36, v16
	v_max_u32_e32 v42, v39, v47
	v_min_u32_e32 v47, v39, v47
	v_max_u32_e32 v37, v33, v32
	v_min_u32_e32 v32, v33, v32
	v_max_u32_e32 v35, v51, v50
	v_min_u32_e32 v50, v51, v50
	v_max_u32_e32 v36, v49, v41
	v_min_u32_e32 v41, v49, v41
	v_max_u32_e32 v39, v45, v43
	v_min_u32_e32 v43, v45, v43
	v_max_u32_e32 v33, v44, v46
	v_min_u32_e32 v46, v44, v46
	v_max_u32_e32 v51, v34, v38
	v_min_u32_e32 v38, v34, v38
	v_max_u32_e32 v49, v48, v40
	v_min_u32_e32 v40, v48, v40
	v_max_u32_e32 v45, v42, v39
	v_min_u32_e32 v39, v42, v39
	v_max_u32_e32 v44, v37, v33
	v_min_u32_e32 v33, v37, v33
	v_max_u32_e32 v34, v35, v51
	v_min_u32_e32 v51, v35, v51
	v_max_u32_e32 v48, v36, v49
	v_min_u32_e32 v49, v36, v49
	v_max_u32_e32 v42, v47, v43
	v_min_u32_e32 v43, v47, v43
	v_max_u32_e32 v37, v32, v46
	v_min_u32_e32 v46, v32, v46
	v_max_u32_e32 v35, v50, v38
	v_min_u32_e32 v38, v50, v38
	v_max_u32_e32 v36, v41, v40
	v_min_u32_e32 v40, v41, v40
	v_max_u32_e32 v47, v45, v34
	v_min_u32_e32 v34, v45, v34
	v_max_u32_e32 v32, v44, v48
	v_min_u32_e32 v48, v44, v48
	v_max_u32_e32 v50, v39, v51
	v_min_u32_e32 v51, v39, v51
	v_max_u32_e32 v41, v33, v49
	v_min_u32_e32 v49, v33, v49
	v_max_u32_e32 v45, v42, v35
	v_min_u32_e32 v35, v42, v35
	v_max_u32_e32 v44, v37, v36
	v_min_u32_e32 v36, v37, v36
	v_max_u32_e32 v39, v43, v38
	v_min_u32_e32 v38, v43, v38
	v_max_u32_e32 v33, v46, v40
	v_min_u32_e32 v40, v46, v40
	v_max_u32_e32 v42, v47, v32
	v_min_u32_e32 v32, v47, v32
	v_max_u32_e32 v37, v34, v48
	v_min_u32_e32 v48, v34, v48
	v_max_u32_e32 v43, v50, v41
	v_min_u32_e32 v41, v50, v41
	v_max_u32_e32 v46, v51, v49
	v_min_u32_e32 v49, v51, v49
	v_max_u32_e32 v47, v45, v44
	v_min_u32_e32 v44, v45, v44
	v_max_u32_e32 v34, v35, v36
	v_min_u32_e32 v36, v35, v36
	v_max_u32_e32 v50, v39, v33
	v_min_u32_e32 v33, v39, v33
	v_max_u32_e32 v51, v38, v40
	v_min_u32_e32 v40, v38, v40
	v_mov_b32_e32 v217, v216
	global_load_dwordx4 v[52:55], v217, s[28:29] offset:384
	v_add_u32_e32 v157, s36, v217
	global_load_dwordx4 v[56:59], v157, s[28:29] offset:384
	v_add_u32_e32 v217, s36, v157
	global_load_dwordx4 v[60:63], v217, s[28:29] offset:384
	v_add_u32_e32 v157, s36, v217
	global_load_dwordx4 v[112:115], v157, s[28:29] offset:384
	v_add_u32_e32 v217, s36, v157
	global_load_dwordx4 v[116:119], v217, s[28:29] offset:384
	v_add_u32_e32 v157, s36, v217
	global_load_dwordx4 v[120:123], v157, s[28:29] offset:384
	v_add_u32_e32 v217, s36, v157
	global_load_dwordx4 v[124:127], v217, s[28:29] offset:384
	v_add_u32_e32 v157, s36, v217
	global_load_dwordx4 v[158:161], v157, s[28:29] offset:384
	s_waitcnt vmcnt(8)
; __device__ __forceinline__ unsigned f2key(float f) { const unsigned u = __float_as_uint(f); return (u & 0x80000000u) ? ~u : (u | 0x80000000u); }
; __device__ void ph_peer(const float* __restrict__ SC, const bf16_t* __restrict__ H  , const float* __restrict__ gffn, const unsigned char* __restrict__ U, const unsigned char* __restrict__ V, float* X, const float* __restrict__ fgain) {
;     ...
;             for (int u = 0; u < 2; ++u) { const float* sc = SC + (size_t)tok * 2048 + (h + u) * 256;
;                 const float2 a0 = ((const float2*)sc)[lane], a1 = ((const float2*)(sc + 128))[lane];
;                 k00[u] = (f2key(a0.x) & ~127u) | (unsigned)(127 - 2 * lane); k01[u] = (f2key(a0.y) & ~127u) | (unsigned)(126 - 2 * lane);
;                 k10[u] = (f2key(a1.x) & ~127u) | (unsigned)(127 - 2 * lane); k11[u] = (f2key(a1.y) & ~127u) | (unsigned)(126 - 2 * lane);
;     ...
;             for (int it = 0; it < 16; ++it) {
; #pragma unroll
;                 for (int u = 0; u < 2; ++u) {
;                     const unsigned m0 = wave_max_u32(k00[u] > k01[u] ? k00[u] : k01[u]);
;                     const unsigned m1 = wave_max_u32(k10[u] > k11[u] ? k10[u] : k11[u]);
;                     if (lane == it) { top0[u] = m0; top1[u] = m1; }
;                     if (k00[u] == m0) k00[u] = 0u; if (k01[u] == m0) k01[u] = 0u;
;                     if (k10[u] == m1) k10[u] = 0u; if (k11[u] == m1) k11[u] = 0u; }
;             }
	ds_write_b128 v144, v[180:183] offset:0
	ds_write_b128 v144, v[184:187] offset:1152
	ds_write_b128 v144, v[188:191] offset:2304
	ds_write_b128 v144, v[192:195] offset:3456
	ds_write_b128 v144, v[196:199] offset:4608
	ds_write_b128 v144, v[200:203] offset:5760
	ds_write_b128 v144, v[204:207] offset:6912
	ds_write_b128 v144, v[208:211] offset:8064
	ds_read_b128 v[0:3], v145 offset:0
	ds_read_b128 v[4:7], v145 offset:16
	ds_read_b128 v[8:11], v145 offset:32
	ds_read_b128 v[12:15], v145 offset:48
	ds_read_b128 v[16:19], v145 offset:64
	ds_read_b128 v[20:23], v145 offset:80
	ds_read_b128 v[24:27], v145 offset:96
	ds_read_b128 v[28:31], v145 offset:112
	s_waitcnt lgkmcnt(0)
	v_ashrrev_i32_e32 v212, 31, v0
	v_or_b32_e32 v212, 0x80000000, v212
	v_xor_b32_e32 v0, v0, v212
	v_and_or_b32 v0, v0, s30, 63
	v_ashrrev_i32_e32 v212, 31, v1
	v_or_b32_e32 v212, 0x80000000, v212
	v_xor_b32_e32 v1, v1, v212
	v_and_or_b32 v1, v1, s30, 62
	v_ashrrev_i32_e32 v212, 31, v2
	v_or_b32_e32 v212, 0x80000000, v212
	v_xor_b32_e32 v2, v2, v212
	v_and_or_b32 v2, v2, s30, 61
	v_ashrrev_i32_e32 v212, 31, v3
	v_or_b32_e32 v212, 0x80000000, v212
	v_xor_b32_e32 v3, v3, v212
	v_and_or_b32 v3, v3, s30, 60
	v_ashrrev_i32_e32 v212, 31, v4
	v_or_b32_e32 v212, 0x80000000, v212
	v_xor_b32_e32 v4, v4, v212
	v_and_or_b32 v4, v4, s30, 59
	v_ashrrev_i32_e32 v212, 31, v5
	v_or_b32_e32 v212, 0x80000000, v212
	v_xor_b32_e32 v5, v5, v212
	v_and_or_b32 v5, v5, s30, 58
	v_ashrrev_i32_e32 v212, 31, v6
	v_or_b32_e32 v212, 0x80000000, v212
	v_xor_b32_e32 v6, v6, v212
	v_and_or_b32 v6, v6, s30, 57
	v_ashrrev_i32_e32 v212, 31, v7
	v_or_b32_e32 v212, 0x80000000, v212
	v_xor_b32_e32 v7, v7, v212
	v_and_or_b32 v7, v7, s30, 56
	v_ashrrev_i32_e32 v212, 31, v8
	v_or_b32_e32 v212, 0x80000000, v212
	v_xor_b32_e32 v8, v8, v212
	v_and_or_b32 v8, v8, s30, 55
	v_ashrrev_i32_e32 v212, 31, v9
	v_or_b32_e32 v212, 0x80000000, v212
	v_xor_b32_e32 v9, v9, v212
	v_and_or_b32 v9, v9, s30, 54
	v_ashrrev_i32_e32 v212, 31, v10
	v_or_b32_e32 v212, 0x80000000, v212
	v_xor_b32_e32 v10, v10, v212
	v_and_or_b32 v10, v10, s30, 53
	v_ashrrev_i32_e32 v212, 31, v11
	v_or_b32_e32 v212, 0x80000000, v212
	v_xor_b32_e32 v11, v11, v212
	v_and_or_b32 v11, v11, s30, 52
	v_ashrrev_i32_e32 v212, 31, v12
	v_or_b32_e32 v212, 0x80000000, v212
	v_xor_b32_e32 v12, v12, v212
	v_and_or_b32 v12, v12, s30, 51
	v_ashrrev_i32_e32 v212, 31, v13
	v_or_b32_e32 v212, 0x80000000, v212
	v_xor_b32_e32 v13, v13, v212
	v_and_or_b32 v13, v13, s30, 50
	v_ashrrev_i32_e32 v212, 31, v14
	v_or_b32_e32 v212, 0x80000000, v212
	v_xor_b32_e32 v14, v14, v212
	v_and_or_b32 v14, v14, s30, 49
	v_ashrrev_i32_e32 v212, 31, v15
	v_or_b32_e32 v212, 0x80000000, v212
	v_xor_b32_e32 v15, v15, v212
	v_and_or_b32 v15, v15, s30, 48
	v_ashrrev_i32_e32 v212, 31, v16
	v_or_b32_e32 v212, 0x80000000, v212
	v_xor_b32_e32 v16, v16, v212
	v_and_or_b32 v16, v16, s30, 47
	v_ashrrev_i32_e32 v212, 31, v17
	v_or_b32_e32 v212, 0x80000000, v212
	v_xor_b32_e32 v17, v17, v212
	v_and_or_b32 v17, v17, s30, 46
	v_ashrrev_i32_e32 v212, 31, v18
	v_or_b32_e32 v212, 0x80000000, v212
	v_xor_b32_e32 v18, v18, v212
	v_and_or_b32 v18, v18, s30, 45
	v_ashrrev_i32_e32 v212, 31, v19
	v_or_b32_e32 v212, 0x80000000, v212
	v_xor_b32_e32 v19, v19, v212
	v_and_or_b32 v19, v19, s30, 44
	v_ashrrev_i32_e32 v212, 31, v20
	v_or_b32_e32 v212, 0x80000000, v212
	v_xor_b32_e32 v20, v20, v212
	v_and_or_b32 v20, v20, s30, 43
	v_ashrrev_i32_e32 v212, 31, v21
	v_or_b32_e32 v212, 0x80000000, v212
	v_xor_b32_e32 v21, v21, v212
	v_and_or_b32 v21, v21, s30, 42
	v_ashrrev_i32_e32 v212, 31, v22
	v_or_b32_e32 v212, 0x80000000, v212
	v_xor_b32_e32 v22, v22, v212
	v_and_or_b32 v22, v22, s30, 41
	v_ashrrev_i32_e32 v212, 31, v23
	v_or_b32_e32 v212, 0x80000000, v212
	v_xor_b32_e32 v23, v23, v212
	v_and_or_b32 v23, v23, s30, 40
	v_ashrrev_i32_e32 v212, 31, v24
	v_or_b32_e32 v212, 0x80000000, v212
	v_xor_b32_e32 v24, v24, v212
	v_and_or_b32 v24, v24, s30, 39
	v_ashrrev_i32_e32 v212, 31, v25
	v_or_b32_e32 v212, 0x80000000, v212
	v_xor_b32_e32 v25, v25, v212
	v_and_or_b32 v25, v25, s30, 38
	v_ashrrev_i32_e32 v212, 31, v26
	v_or_b32_e32 v212, 0x80000000, v212
	v_xor_b32_e32 v26, v26, v212
	v_and_or_b32 v26, v26, s30, 37
	v_ashrrev_i32_e32 v212, 31, v27
	v_or_b32_e32 v212, 0x80000000, v212
	v_xor_b32_e32 v27, v27, v212
	v_and_or_b32 v27, v27, s30, 36
	v_ashrrev_i32_e32 v212, 31, v28
	v_or_b32_e32 v212, 0x80000000, v212
	v_xor_b32_e32 v28, v28, v212
	v_and_or_b32 v28, v28, s30, 35
	v_ashrrev_i32_e32 v212, 31, v29
	v_or_b32_e32 v212, 0x80000000, v212
	v_xor_b32_e32 v29, v29, v212
	v_and_or_b32 v29, v29, s30, 34
	v_ashrrev_i32_e32 v212, 31, v30
	v_or_b32_e32 v212, 0x80000000, v212
	v_xor_b32_e32 v30, v30, v212
	v_and_or_b32 v30, v30, s30, 33
	v_ashrrev_i32_e32 v212, 31, v31
	v_or_b32_e32 v212, 0x80000000, v212
	v_xor_b32_e32 v31, v31, v212
	v_and_or_b32 v31, v31, s30, 32
	v_max_u32_e32 v215, v0, v1
	v_min_u32_e32 v1, v0, v1
	v_max_u32_e32 v214, v16, v17
	v_min_u32_e32 v17, v16, v17
	v_max_u32_e32 v213, v2, v3
	v_min_u32_e32 v3, v2, v3
	v_max_u32_e32 v0, v18, v19
	v_min_u32_e32 v19, v18, v19
	v_max_u32_e32 v16, v4, v5
	v_min_u32_e32 v5, v4, v5
	v_max_u32_e32 v2, v20, v21
	v_min_u32_e32 v21, v20, v21
	v_max_u32_e32 v18, v6, v7
	v_min_u32_e32 v7, v6, v7
	v_max_u32_e32 v4, v22, v23
	v_min_u32_e32 v23, v22, v23
	v_max_u32_e32 v20, v8, v9
	v_min_u32_e32 v9, v8, v9
	v_max_u32_e32 v6, v24, v25
	v_min_u32_e32 v25, v24, v25
	v_max_u32_e32 v22, v10, v11
	v_min_u32_e32 v11, v10, v11
	v_max_u32_e32 v8, v26, v27
	v_min_u32_e32 v27, v26, v27
	v_max_u32_e32 v24, v12, v13
	v_min_u32_e32 v13, v12, v13
	v_max_u32_e32 v10, v28, v29
	v_min_u32_e32 v29, v28, v29
; __device__ void ph_peer(const float* __restrict__ SC, const bf16_t* __restrict__ H  , const float* __restrict__ gffn, const unsigned char* __restrict__ U, const unsigned char* __restrict__ V, float* X, const float* __restrict__ fgain) {
;     ...
;             for (int it = 0; it < 16; ++it) {
; #pragma unroll
;                 for (int u = 0; u < 2; ++u) {
;                     const unsigned m0 = wave_max_u32(k00[u] > k01[u] ? k00[u] : k01[u]);
;                     const unsigned m1 = wave_max_u32(k10[u] > k11[u] ? k10[u] : k11[u]);
;                     if (lane == it) { top0[u] = m0; top1[u] = m1; }
;                     if (k00[u] == m0) k00[u] = 0u; if (k01[u] == m0) k01[u] = 0u;
;                     if (k10[u] == m1) k10[u] = 0u; if (k11[u] == m1) k11[u] = 0u; }
;             }
	v_max_u32_e32 v26, v14, v15
	v_min_u32_e32 v15, v14, v15
	v_max_u32_e32 v12, v30, v31
	v_min_u32_e32 v31, v30, v31
	v_max_u32_e32 v28, v215, v213
	v_min_u32_e32 v213, v215, v213
	v_max_u32_e32 v14, v214, v0
	v_min_u32_e32 v0, v214, v0
	v_max_u32_e32 v30, v1, v3
	v_min_u32_e32 v3, v1, v3
	v_max_u32_e32 v215, v17, v19
	v_min_u32_e32 v19, v17, v19
	v_max_u32_e32 v214, v16, v18
	v_min_u32_e32 v18, v16, v18
	v_max_u32_e32 v1, v2, v4
	v_min_u32_e32 v4, v2, v4
	v_max_u32_e32 v17, v5, v7
	v_min_u32_e32 v7, v5, v7
	v_max_u32_e32 v16, v21, v23
	v_min_u32_e32 v23, v21, v23
	v_max_u32_e32 v2, v20, v22
	v_min_u32_e32 v22, v20, v22
	v_max_u32_e32 v5, v6, v8
	v_min_u32_e32 v8, v6, v8
	v_max_u32_e32 v21, v9, v11
	v_min_u32_e32 v11, v9, v11
	v_max_u32_e32 v20, v25, v27
	v_min_u32_e32 v27, v25, v27
	v_max_u32_e32 v6, v24, v26
	v_min_u32_e32 v26, v24, v26
	v_max_u32_e32 v9, v10, v12
	v_min_u32_e32 v12, v10, v12
	v_max_u32_e32 v25, v13, v15
	v_min_u32_e32 v15, v13, v15
	v_max_u32_e32 v24, v29, v31
	v_min_u32_e32 v31, v29, v31
	v_max_u32_e32 v10, v30, v213
	v_min_u32_e32 v213, v30, v213
	v_max_u32_e32 v13, v215, v0
	v_min_u32_e32 v0, v215, v0
	v_max_u32_e32 v29, v17, v18
	v_min_u32_e32 v18, v17, v18
	v_max_u32_e32 v30, v16, v4
	v_min_u32_e32 v4, v16, v4
	v_max_u32_e32 v215, v21, v22
	v_min_u32_e32 v22, v21, v22
	v_max_u32_e32 v17, v20, v8
	v_min_u32_e32 v8, v20, v8
	v_max_u32_e32 v16, v25, v26
	v_min_u32_e32 v26, v25, v26
	v_max_u32_e32 v21, v24, v12
	v_min_u32_e32 v12, v24, v12
	v_max_u32_e32 v20, v28, v214
	v_min_u32_e32 v214, v28, v214
	v_max_u32_e32 v25, v14, v1
	v_min_u32_e32 v1, v14, v1
	v_max_u32_e32 v24, v10, v29
	v_min_u32_e32 v29, v10, v29
	v_max_u32_e32 v28, v13, v30
	v_min_u32_e32 v30, v13, v30
	v_max_u32_e32 v14, v213, v18
	v_min_u32_e32 v18, v213, v18
	v_max_u32_e32 v10, v0, v4
	v_min_u32_e32 v4, v0, v4
	v_max_u32_e32 v13, v3, v7
	v_min_u32_e32 v7, v3, v7
	v_max_u32_e32 v213, v19, v23
	v_min_u32_e32 v23, v19, v23
	v_max_u32_e32 v0, v2, v6
	v_min_u32_e32 v6, v2, v6
	v_max_u32_e32 v3, v5, v9
	v_min_u32_e32 v9, v5, v9
	v_max_u32_e32 v19, v215, v16
	v_min_u32_e32 v16, v215, v16
	v_max_u32_e32 v2, v17, v21
	v_min_u32_e32 v21, v17, v21
	v_max_u32_e32 v5, v22, v26
	v_min_u32_e32 v26, v22, v26
	v_max_u32_e32 v215, v8, v12
	v_min_u32_e32 v12, v8, v12
	v_max_u32_e32 v17, v11, v15
	v_min_u32_e32 v15, v11, v15
	v_max_u32_e32 v22, v27, v31
	v_min_u32_e32 v31, v27, v31
	v_max_u32_e32 v8, v14, v214
	v_min_u32_e32 v214, v14, v214
	v_max_u32_e32 v11, v10, v1
	v_min_u32_e32 v1, v10, v1
	v_max_u32_e32 v27, v13, v29
	v_min_u32_e32 v29, v13, v29
	v_max_u32_e32 v14, v213, v30
	v_min_u32_e32 v30, v213, v30
	v_max_u32_e32 v10, v5, v6
	v_min_u32_e32 v6, v5, v6
	v_max_u32_e32 v13, v215, v9
	v_min_u32_e32 v9, v215, v9
	v_max_u32_e32 v213, v17, v16
	v_min_u32_e32 v16, v17, v16
	v_max_u32_e32 v5, v22, v21
	v_min_u32_e32 v21, v22, v21
	v_max_u32_e32 v215, v24, v8
	v_min_u32_e32 v8, v24, v8
	v_max_u32_e32 v17, v28, v11
	v_min_u32_e32 v11, v28, v11
	v_max_u32_e32 v22, v27, v214
	v_min_u32_e32 v214, v27, v214
	v_max_u32_e32 v24, v14, v1
	v_min_u32_e32 v1, v14, v1
	v_max_u32_e32 v28, v29, v18
	v_min_u32_e32 v18, v29, v18
	v_max_u32_e32 v27, v30, v4
	v_min_u32_e32 v4, v30, v4
	v_max_u32_e32 v14, v19, v10
	v_min_u32_e32 v10, v19, v10
	v_max_u32_e32 v29, v2, v13
	v_min_u32_e32 v13, v2, v13
	v_max_u32_e32 v30, v213, v6
	v_min_u32_e32 v6, v213, v6
	v_max_u32_e32 v19, v5, v9
	v_min_u32_e32 v9, v5, v9
	v_max_u32_e32 v2, v16, v26
	v_min_u32_e32 v26, v16, v26
	v_max_u32_e32 v213, v21, v12
	v_min_u32_e32 v12, v21, v12
	v_max_u32_e32 v5, v20, v0
	v_min_u32_e32 v0, v20, v0
	v_max_u32_e32 v16, v25, v3
	v_min_u32_e32 v3, v25, v3
	v_max_u32_e32 v21, v215, v14
	v_min_u32_e32 v14, v215, v14
	v_max_u32_e32 v20, v17, v29
	v_min_u32_e32 v29, v17, v29
	v_max_u32_e32 v25, v8, v10
	v_min_u32_e32 v10, v8, v10
	v_max_u32_e32 v215, v11, v13
	v_min_u32_e32 v13, v11, v13
	v_max_u32_e32 v17, v22, v30
	v_min_u32_e32 v30, v22, v30
	v_max_u32_e32 v8, v24, v19
	v_min_u32_e32 v19, v24, v19
	v_max_u32_e32 v11, v214, v6
	v_min_u32_e32 v6, v214, v6
	v_max_u32_e32 v22, v1, v9
	v_min_u32_e32 v9, v1, v9
	v_max_u32_e32 v24, v28, v2
	v_min_u32_e32 v2, v28, v2
	v_max_u32_e32 v214, v27, v213
	v_min_u32_e32 v213, v27, v213
	v_max_u32_e32 v1, v18, v26
	v_min_u32_e32 v26, v18, v26
	v_max_u32_e32 v28, v4, v12
	v_min_u32_e32 v12, v4, v12
	v_max_u32_e32 v27, v7, v15
	v_min_u32_e32 v15, v7, v15
	v_max_u32_e32 v18, v23, v31
	v_min_u32_e32 v31, v23, v31
	v_max_u32_e32 v4, v11, v0
	v_min_u32_e32 v0, v11, v0
	v_max_u32_e32 v7, v22, v3
	v_min_u32_e32 v3, v22, v3
	v_max_u32_e32 v23, v24, v14
	v_min_u32_e32 v14, v24, v14
	v_max_u32_e32 v11, v214, v29
	v_min_u32_e32 v29, v214, v29
	v_max_u32_e32 v22, v1, v10
	v_min_u32_e32 v10, v1, v10
	v_max_u32_e32 v24, v28, v13
	v_min_u32_e32 v13, v28, v13
	v_max_u32_e32 v214, v27, v30
	v_min_u32_e32 v30, v27, v30
	v_max_u32_e32 v1, v18, v19
	v_min_u32_e32 v19, v18, v19
	v_max_u32_e32 v28, v25, v4
	v_min_u32_e32 v4, v25, v4
	v_max_u32_e32 v27, v215, v7
	v_min_u32_e32 v7, v215, v7
	v_max_u32_e32 v18, v17, v23
	v_min_u32_e32 v23, v17, v23
	v_max_u32_e32 v25, v8, v11
	v_min_u32_e32 v11, v8, v11
	v_max_u32_e32 v215, v22, v0
	v_min_u32_e32 v0, v22, v0
	v_max_u32_e32 v17, v24, v3
	v_min_u32_e32 v3, v24, v3
	v_max_u32_e32 v8, v214, v14
	v_min_u32_e32 v14, v214, v14
	v_max_u32_e32 v22, v1, v29
	v_min_u32_e32 v29, v1, v29
	v_max_u32_e32 v24, v10, v6
	v_min_u32_e32 v6, v10, v6
	v_max_u32_e32 v214, v13, v9
	v_min_u32_e32 v9, v13, v9
	v_max_u32_e32 v1, v30, v2
	v_min_u32_e32 v2, v30, v2
	v_max_u32_e32 v10, v19, v213
	v_min_u32_e32 v213, v19, v213
	v_max_u32_e32 v13, v21, v28
	v_min_u32_e32 v28, v21, v28
; __device__ void ph_peer(const float* __restrict__ SC, const bf16_t* __restrict__ H  , const float* __restrict__ gffn, const unsigned char* __restrict__ U, const unsigned char* __restrict__ V, float* X, const float* __restrict__ fgain) {
;     ...
;             for (int it = 0; it < 16; ++it) {
; #pragma unroll
;                 for (int u = 0; u < 2; ++u) {
;                     const unsigned m0 = wave_max_u32(k00[u] > k01[u] ? k00[u] : k01[u]);
;                     const unsigned m1 = wave_max_u32(k10[u] > k11[u] ? k10[u] : k11[u]);
;                     if (lane == it) { top0[u] = m0; top1[u] = m1; }
;                     if (k00[u] == m0) k00[u] = 0u; if (k01[u] == m0) k01[u] = 0u;
;                     if (k10[u] == m1) k10[u] = 0u; if (k11[u] == m1) k11[u] = 0u; }
;             }
	v_max_u32_e32 v30, v20, v27
	v_min_u32_e32 v27, v20, v27
	v_max_u32_e32 v19, v18, v4
	v_min_u32_e32 v4, v18, v4
	v_max_u32_e32 v21, v25, v7
	v_min_u32_e32 v7, v25, v7
	v_max_u32_e32 v20, v23, v215
	v_min_u32_e32 v215, v23, v215
	v_max_u32_e32 v18, v11, v17
	v_min_u32_e32 v17, v11, v17
	v_max_u32_e32 v25, v8, v0
	v_min_u32_e32 v0, v8, v0
	v_max_u32_e32 v23, v22, v3
	v_min_u32_e32 v3, v22, v3
	v_max_u32_e32 v11, v14, v24
	v_min_u32_e32 v24, v14, v24
	v_max_u32_e32 v8, v29, v214
	v_min_u32_e32 v214, v29, v214
	v_max_u32_e32 v22, v1, v6
	v_min_u32_e32 v6, v1, v6
	v_max_u32_e32 v14, v10, v9
	v_min_u32_e32 v9, v10, v9
	v_max_u32_e32 v29, v2, v26
	v_min_u32_e32 v26, v2, v26
	v_max_u32_e32 v1, v213, v12
	v_min_u32_e32 v12, v213, v12
	v_max_u32_e32 v45, v42, v15
	v_max_u32_e32 v35, v32, v26
	v_max_u32_e32 v39, v37, v29
	v_max_u32_e32 v38, v48, v6
	v_max_u32_e32 v42, v43, v22
	v_max_u32_e32 v32, v41, v24
	v_max_u32_e32 v37, v46, v11
	v_max_u32_e32 v48, v49, v0
	v_max_u32_e32 v43, v47, v25
	v_max_u32_e32 v41, v44, v215
	v_max_u32_e32 v46, v34, v20
	v_max_u32_e32 v49, v36, v4
	v_max_u32_e32 v47, v50, v19
	v_max_u32_e32 v44, v33, v28
	v_max_u32_e32 v34, v51, v13
	v_max_u32_e32 v36, v40, v5
	v_max_u32_e32 v50, v45, v43
	v_min_u32_e32 v43, v45, v43
	v_max_u32_e32 v33, v35, v41
	v_min_u32_e32 v41, v35, v41
	v_max_u32_e32 v51, v39, v46
	v_min_u32_e32 v46, v39, v46
	v_max_u32_e32 v40, v38, v49
	v_min_u32_e32 v49, v38, v49
	v_max_u32_e32 v45, v42, v47
	v_min_u32_e32 v47, v42, v47
	v_max_u32_e32 v35, v32, v44
	v_min_u32_e32 v44, v32, v44
	v_max_u32_e32 v39, v37, v34
	v_min_u32_e32 v34, v37, v34
	v_max_u32_e32 v38, v48, v36
	v_min_u32_e32 v36, v48, v36
	v_max_u32_e32 v42, v50, v45
	v_min_u32_e32 v45, v50, v45
	v_max_u32_e32 v32, v33, v35
	v_min_u32_e32 v35, v33, v35
	v_max_u32_e32 v37, v51, v39
	v_min_u32_e32 v39, v51, v39
	v_max_u32_e32 v48, v40, v38
	v_min_u32_e32 v38, v40, v38
	v_max_u32_e32 v50, v43, v47
	v_min_u32_e32 v47, v43, v47
	v_max_u32_e32 v33, v41, v44
	v_min_u32_e32 v44, v41, v44
	v_max_u32_e32 v51, v46, v34
	v_min_u32_e32 v34, v46, v34
	v_max_u32_e32 v40, v49, v36
	v_min_u32_e32 v36, v49, v36
	v_max_u32_e32 v43, v42, v37
	v_min_u32_e32 v37, v42, v37
	v_max_u32_e32 v41, v32, v48
	v_min_u32_e32 v48, v32, v48
	v_max_u32_e32 v46, v45, v39
	v_min_u32_e32 v39, v45, v39
	v_max_u32_e32 v49, v35, v38
	v_min_u32_e32 v38, v35, v38
	v_max_u32_e32 v42, v50, v51
	v_min_u32_e32 v51, v50, v51
	v_max_u32_e32 v32, v33, v40
	v_min_u32_e32 v40, v33, v40
	v_max_u32_e32 v45, v47, v34
	v_min_u32_e32 v34, v47, v34
	v_max_u32_e32 v35, v44, v36
	v_min_u32_e32 v36, v44, v36
	v_max_u32_e32 v50, v43, v41
	v_min_u32_e32 v41, v43, v41
	v_max_u32_e32 v33, v37, v48
	v_min_u32_e32 v48, v37, v48
	v_max_u32_e32 v47, v46, v49
	v_min_u32_e32 v49, v46, v49
	v_max_u32_e32 v44, v39, v38
	v_min_u32_e32 v38, v39, v38
	v_max_u32_e32 v43, v42, v32
	v_min_u32_e32 v32, v42, v32
	v_max_u32_e32 v37, v51, v40
	v_min_u32_e32 v40, v51, v40
	v_max_u32_e32 v46, v45, v35
	v_min_u32_e32 v35, v45, v35
	v_max_u32_e32 v39, v34, v36
	v_min_u32_e32 v36, v34, v36
	v_max_u32_e32 v42, v50, v31
	v_max_u32_e32 v51, v41, v12
	v_max_u32_e32 v45, v33, v1
	v_max_u32_e32 v34, v48, v9
	v_max_u32_e32 v50, v47, v14
	v_max_u32_e32 v41, v49, v214
	v_max_u32_e32 v33, v44, v8
	v_max_u32_e32 v48, v38, v3
	v_max_u32_e32 v47, v43, v23
	v_max_u32_e32 v49, v32, v17
	v_max_u32_e32 v44, v37, v18
	v_max_u32_e32 v38, v40, v7
	v_max_u32_e32 v43, v46, v21
	v_max_u32_e32 v32, v35, v27
	v_max_u32_e32 v37, v39, v30
	v_max_u32_e32 v40, v36, v16
	v_max_u32_e32 v46, v42, v47
	v_min_u32_e32 v47, v42, v47
	v_max_u32_e32 v35, v51, v49
	v_min_u32_e32 v49, v51, v49
	v_max_u32_e32 v39, v45, v44
	v_min_u32_e32 v44, v45, v44
	v_max_u32_e32 v36, v34, v38
	v_min_u32_e32 v38, v34, v38
	v_max_u32_e32 v42, v50, v43
	v_min_u32_e32 v43, v50, v43
	v_max_u32_e32 v51, v41, v32
	v_min_u32_e32 v32, v41, v32
	v_max_u32_e32 v45, v33, v37
	v_min_u32_e32 v37, v33, v37
	v_max_u32_e32 v34, v48, v40
	v_min_u32_e32 v40, v48, v40
	v_max_u32_e32 v50, v46, v42
	v_min_u32_e32 v42, v46, v42
	v_max_u32_e32 v41, v35, v51
	v_min_u32_e32 v51, v35, v51
	v_max_u32_e32 v33, v39, v45
	v_min_u32_e32 v45, v39, v45
	v_max_u32_e32 v48, v36, v34
	v_min_u32_e32 v34, v36, v34
	v_max_u32_e32 v46, v47, v43
	v_min_u32_e32 v43, v47, v43
	v_max_u32_e32 v35, v49, v32
	v_min_u32_e32 v32, v49, v32
	v_max_u32_e32 v39, v44, v37
	v_min_u32_e32 v37, v44, v37
	v_max_u32_e32 v36, v38, v40
	v_min_u32_e32 v40, v38, v40
	v_max_u32_e32 v47, v50, v33
	v_min_u32_e32 v33, v50, v33
	v_max_u32_e32 v49, v41, v48
	v_min_u32_e32 v48, v41, v48
	v_max_u32_e32 v44, v42, v45
	v_min_u32_e32 v45, v42, v45
	v_max_u32_e32 v38, v51, v34
	v_min_u32_e32 v34, v51, v34
	v_max_u32_e32 v50, v46, v39
	v_min_u32_e32 v39, v46, v39
	v_max_u32_e32 v41, v35, v36
	v_min_u32_e32 v36, v35, v36
	v_max_u32_e32 v42, v43, v37
	v_min_u32_e32 v37, v43, v37
	v_max_u32_e32 v51, v32, v40
	v_min_u32_e32 v40, v32, v40
	v_max_u32_e32 v46, v47, v49
	v_min_u32_e32 v49, v47, v49
	v_max_u32_e32 v35, v33, v48
	v_min_u32_e32 v48, v33, v48
	v_max_u32_e32 v43, v44, v38
	v_min_u32_e32 v38, v44, v38
	v_max_u32_e32 v32, v45, v34
	v_min_u32_e32 v34, v45, v34
	v_max_u32_e32 v47, v50, v41
	v_min_u32_e32 v41, v50, v41
	v_max_u32_e32 v33, v39, v36
	v_min_u32_e32 v36, v39, v36
	v_max_u32_e32 v44, v42, v51
	v_min_u32_e32 v51, v42, v51
	v_max_u32_e32 v45, v37, v40
	v_min_u32_e32 v40, v37, v40
	v_mov_b32_e32 v217, v216
	global_load_dwordx4 v[180:183], v217, s[28:29] offset:512
	v_add_u32_e32 v157, s36, v217
	global_load_dwordx4 v[184:187], v157, s[28:29] offset:512
	v_add_u32_e32 v217, s36, v157
	global_load_dwordx4 v[188:191], v217, s[28:29] offset:512
	v_add_u32_e32 v157, s36, v217
	global_load_dwordx4 v[192:195], v157, s[28:29] offset:512
	v_add_u32_e32 v217, s36, v157
	global_load_dwordx4 v[196:199], v217, s[28:29] offset:512
	v_add_u32_e32 v157, s36, v217
	global_load_dwordx4 v[200:203], v157, s[28:29] offset:512
	v_add_u32_e32 v217, s36, v157
	global_load_dwordx4 v[204:207], v217, s[28:29] offset:512
	v_add_u32_e32 v157, s36, v217
	global_load_dwordx4 v[208:211], v157, s[28:29] offset:512
	s_waitcnt vmcnt(8)
; __device__ __forceinline__ unsigned f2key(float f) { const unsigned u = __float_as_uint(f); return (u & 0x80000000u) ? ~u : (u | 0x80000000u); }
; __device__ void ph_peer(const float* __restrict__ SC, const bf16_t* __restrict__ H  , const float* __restrict__ gffn, const unsigned char* __restrict__ U, const unsigned char* __restrict__ V, float* X, const float* __restrict__ fgain) {
;     ...
;             for (int u = 0; u < 2; ++u) { const float* sc = SC + (size_t)tok * 2048 + (h + u) * 256;
;                 const float2 a0 = ((const float2*)sc)[lane], a1 = ((const float2*)(sc + 128))[lane];
;                 k00[u] = (f2key(a0.x) & ~127u) | (unsigned)(127 - 2 * lane); k01[u] = (f2key(a0.y) & ~127u) | (unsigned)(126 - 2 * lane);
;                 k10[u] = (f2key(a1.x) & ~127u) | (unsigned)(127 - 2 * lane); k11[u] = (f2key(a1.y) & ~127u) | (unsigned)(126 - 2 * lane);
;     ...
;             for (int it = 0; it < 16; ++it) {
; #pragma unroll
;                 for (int u = 0; u < 2; ++u) {
;                     const unsigned m0 = wave_max_u32(k00[u] > k01[u] ? k00[u] : k01[u]);
;                     const unsigned m1 = wave_max_u32(k10[u] > k11[u] ? k10[u] : k11[u]);
;                     if (lane == it) { top0[u] = m0; top1[u] = m1; }
;                     if (k00[u] == m0) k00[u] = 0u; if (k01[u] == m0) k01[u] = 0u;
;                     if (k10[u] == m1) k10[u] = 0u; if (k11[u] == m1) k11[u] = 0u; }
;             }
	ds_write_b128 v144, v[52:55] offset:0
	ds_write_b128 v144, v[56:59] offset:1152
	ds_write_b128 v144, v[60:63] offset:2304
	ds_write_b128 v144, v[112:115] offset:3456
	ds_write_b128 v144, v[116:119] offset:4608
	ds_write_b128 v144, v[120:123] offset:5760
	ds_write_b128 v144, v[124:127] offset:6912
	ds_write_b128 v144, v[158:161] offset:8064
	ds_read_b128 v[0:3], v145 offset:0
	ds_read_b128 v[4:7], v145 offset:16
	ds_read_b128 v[8:11], v145 offset:32
	ds_read_b128 v[12:15], v145 offset:48
	ds_read_b128 v[16:19], v145 offset:64
	ds_read_b128 v[20:23], v145 offset:80
	ds_read_b128 v[24:27], v145 offset:96
	ds_read_b128 v[28:31], v145 offset:112
	s_waitcnt lgkmcnt(0)
	v_ashrrev_i32_e32 v212, 31, v0
	v_or_b32_e32 v212, 0x80000000, v212
	v_xor_b32_e32 v0, v0, v212
	v_and_or_b32 v0, v0, s30, 31
	v_ashrrev_i32_e32 v212, 31, v1
	v_or_b32_e32 v212, 0x80000000, v212
	v_xor_b32_e32 v1, v1, v212
	v_and_or_b32 v1, v1, s30, 30
	v_ashrrev_i32_e32 v212, 31, v2
	v_or_b32_e32 v212, 0x80000000, v212
	v_xor_b32_e32 v2, v2, v212
	v_and_or_b32 v2, v2, s30, 29
	v_ashrrev_i32_e32 v212, 31, v3
	v_or_b32_e32 v212, 0x80000000, v212
	v_xor_b32_e32 v3, v3, v212
	v_and_or_b32 v3, v3, s30, 28
	v_ashrrev_i32_e32 v212, 31, v4
	v_or_b32_e32 v212, 0x80000000, v212
	v_xor_b32_e32 v4, v4, v212
	v_and_or_b32 v4, v4, s30, 27
	v_ashrrev_i32_e32 v212, 31, v5
	v_or_b32_e32 v212, 0x80000000, v212
	v_xor_b32_e32 v5, v5, v212
	v_and_or_b32 v5, v5, s30, 26
	v_ashrrev_i32_e32 v212, 31, v6
	v_or_b32_e32 v212, 0x80000000, v212
	v_xor_b32_e32 v6, v6, v212
	v_and_or_b32 v6, v6, s30, 25
	v_ashrrev_i32_e32 v212, 31, v7
	v_or_b32_e32 v212, 0x80000000, v212
	v_xor_b32_e32 v7, v7, v212
	v_and_or_b32 v7, v7, s30, 24
	v_ashrrev_i32_e32 v212, 31, v8
	v_or_b32_e32 v212, 0x80000000, v212
	v_xor_b32_e32 v8, v8, v212
	v_and_or_b32 v8, v8, s30, 23
	v_ashrrev_i32_e32 v212, 31, v9
	v_or_b32_e32 v212, 0x80000000, v212
	v_xor_b32_e32 v9, v9, v212
	v_and_or_b32 v9, v9, s30, 22
	v_ashrrev_i32_e32 v212, 31, v10
	v_or_b32_e32 v212, 0x80000000, v212
	v_xor_b32_e32 v10, v10, v212
	v_and_or_b32 v10, v10, s30, 21
	v_ashrrev_i32_e32 v212, 31, v11
	v_or_b32_e32 v212, 0x80000000, v212
	v_xor_b32_e32 v11, v11, v212
	v_and_or_b32 v11, v11, s30, 20
	v_ashrrev_i32_e32 v212, 31, v12
	v_or_b32_e32 v212, 0x80000000, v212
	v_xor_b32_e32 v12, v12, v212
	v_and_or_b32 v12, v12, s30, 19
	v_ashrrev_i32_e32 v212, 31, v13
	v_or_b32_e32 v212, 0x80000000, v212
	v_xor_b32_e32 v13, v13, v212
	v_and_or_b32 v13, v13, s30, 18
	v_ashrrev_i32_e32 v212, 31, v14
	v_or_b32_e32 v212, 0x80000000, v212
	v_xor_b32_e32 v14, v14, v212
	v_and_or_b32 v14, v14, s30, 17
	v_ashrrev_i32_e32 v212, 31, v15
	v_or_b32_e32 v212, 0x80000000, v212
	v_xor_b32_e32 v15, v15, v212
	v_and_or_b32 v15, v15, s30, 16
	v_ashrrev_i32_e32 v212, 31, v16
	v_or_b32_e32 v212, 0x80000000, v212
	v_xor_b32_e32 v16, v16, v212
	v_and_or_b32 v16, v16, s30, 15
	v_ashrrev_i32_e32 v212, 31, v17
	v_or_b32_e32 v212, 0x80000000, v212
	v_xor_b32_e32 v17, v17, v212
	v_and_or_b32 v17, v17, s30, 14
	v_ashrrev_i32_e32 v212, 31, v18
	v_or_b32_e32 v212, 0x80000000, v212
	v_xor_b32_e32 v18, v18, v212
	v_and_or_b32 v18, v18, s30, 13
	v_ashrrev_i32_e32 v212, 31, v19
	v_or_b32_e32 v212, 0x80000000, v212
	v_xor_b32_e32 v19, v19, v212
	v_and_or_b32 v19, v19, s30, 12
	v_ashrrev_i32_e32 v212, 31, v20
	v_or_b32_e32 v212, 0x80000000, v212
	v_xor_b32_e32 v20, v20, v212
	v_and_or_b32 v20, v20, s30, 11
	v_ashrrev_i32_e32 v212, 31, v21
	v_or_b32_e32 v212, 0x80000000, v212
	v_xor_b32_e32 v21, v21, v212
	v_and_or_b32 v21, v21, s30, 10
	v_ashrrev_i32_e32 v212, 31, v22
	v_or_b32_e32 v212, 0x80000000, v212
	v_xor_b32_e32 v22, v22, v212
	v_and_or_b32 v22, v22, s30, 9
	v_ashrrev_i32_e32 v212, 31, v23
	v_or_b32_e32 v212, 0x80000000, v212
	v_xor_b32_e32 v23, v23, v212
	v_and_or_b32 v23, v23, s30, 8
	v_ashrrev_i32_e32 v212, 31, v24
	v_or_b32_e32 v212, 0x80000000, v212
	v_xor_b32_e32 v24, v24, v212
	v_and_or_b32 v24, v24, s30, 7
	v_ashrrev_i32_e32 v212, 31, v25
	v_or_b32_e32 v212, 0x80000000, v212
	v_xor_b32_e32 v25, v25, v212
	v_and_or_b32 v25, v25, s30, 6
	v_ashrrev_i32_e32 v212, 31, v26
	v_or_b32_e32 v212, 0x80000000, v212
	v_xor_b32_e32 v26, v26, v212
	v_and_or_b32 v26, v26, s30, 5
	v_ashrrev_i32_e32 v212, 31, v27
	v_or_b32_e32 v212, 0x80000000, v212
	v_xor_b32_e32 v27, v27, v212
	v_and_or_b32 v27, v27, s30, 4
	v_ashrrev_i32_e32 v212, 31, v28
	v_or_b32_e32 v212, 0x80000000, v212
	v_xor_b32_e32 v28, v28, v212
	v_and_or_b32 v28, v28, s30, 3
	v_ashrrev_i32_e32 v212, 31, v29
	v_or_b32_e32 v212, 0x80000000, v212
	v_xor_b32_e32 v29, v29, v212
	v_and_or_b32 v29, v29, s30, 2
	v_ashrrev_i32_e32 v212, 31, v30
	v_or_b32_e32 v212, 0x80000000, v212
	v_xor_b32_e32 v30, v30, v212
	v_and_or_b32 v30, v30, s30, 1
	v_ashrrev_i32_e32 v212, 31, v31
	v_or_b32_e32 v212, 0x80000000, v212
	v_xor_b32_e32 v31, v31, v212
	v_and_or_b32 v31, v31, s30, 0
	v_max_u32_e32 v215, v0, v1
	v_min_u32_e32 v1, v0, v1
	v_max_u32_e32 v214, v16, v17
	v_min_u32_e32 v17, v16, v17
	v_max_u32_e32 v213, v2, v3
	v_min_u32_e32 v3, v2, v3
	v_max_u32_e32 v0, v18, v19
	v_min_u32_e32 v19, v18, v19
	v_max_u32_e32 v16, v4, v5
	v_min_u32_e32 v5, v4, v5
	v_max_u32_e32 v2, v20, v21
	v_min_u32_e32 v21, v20, v21
	v_max_u32_e32 v18, v6, v7
	v_min_u32_e32 v7, v6, v7
	v_max_u32_e32 v4, v22, v23
	v_min_u32_e32 v23, v22, v23
	v_max_u32_e32 v20, v8, v9
	v_min_u32_e32 v9, v8, v9
	v_max_u32_e32 v6, v24, v25
	v_min_u32_e32 v25, v24, v25
	v_max_u32_e32 v22, v10, v11
	v_min_u32_e32 v11, v10, v11
	v_max_u32_e32 v8, v26, v27
	v_min_u32_e32 v27, v26, v27
	v_max_u32_e32 v24, v12, v13
	v_min_u32_e32 v13, v12, v13
	v_max_u32_e32 v10, v28, v29
	v_min_u32_e32 v29, v28, v29
	v_max_u32_e32 v26, v14, v15
; __device__ void ph_peer(const float* __restrict__ SC, const bf16_t* __restrict__ H  , const float* __restrict__ gffn, const unsigned char* __restrict__ U, const unsigned char* __restrict__ V, float* X, const float* __restrict__ fgain) {
;     ...
;             for (int it = 0; it < 16; ++it) {
; #pragma unroll
;                 for (int u = 0; u < 2; ++u) {
;                     const unsigned m0 = wave_max_u32(k00[u] > k01[u] ? k00[u] : k01[u]);
;                     const unsigned m1 = wave_max_u32(k10[u] > k11[u] ? k10[u] : k11[u]);
;                     if (lane == it) { top0[u] = m0; top1[u] = m1; }
;                     if (k00[u] == m0) k00[u] = 0u; if (k01[u] == m0) k01[u] = 0u;
;                     if (k10[u] == m1) k10[u] = 0u; if (k11[u] == m1) k11[u] = 0u; }
;             }
	v_min_u32_e32 v15, v14, v15
	v_max_u32_e32 v12, v30, v31
	v_min_u32_e32 v31, v30, v31
	v_max_u32_e32 v28, v215, v213
	v_min_u32_e32 v213, v215, v213
	v_max_u32_e32 v14, v214, v0
	v_min_u32_e32 v0, v214, v0
	v_max_u32_e32 v30, v1, v3
	v_min_u32_e32 v3, v1, v3
	v_max_u32_e32 v215, v17, v19
	v_min_u32_e32 v19, v17, v19
	v_max_u32_e32 v214, v16, v18
	v_min_u32_e32 v18, v16, v18
	v_max_u32_e32 v1, v2, v4
	v_min_u32_e32 v4, v2, v4
	v_max_u32_e32 v17, v5, v7
	v_min_u32_e32 v7, v5, v7
	v_max_u32_e32 v16, v21, v23
	v_min_u32_e32 v23, v21, v23
	v_max_u32_e32 v2, v20, v22
	v_min_u32_e32 v22, v20, v22
	v_max_u32_e32 v5, v6, v8
	v_min_u32_e32 v8, v6, v8
	v_max_u32_e32 v21, v9, v11
	v_min_u32_e32 v11, v9, v11
	v_max_u32_e32 v20, v25, v27
	v_min_u32_e32 v27, v25, v27
	v_max_u32_e32 v6, v24, v26
	v_min_u32_e32 v26, v24, v26
	v_max_u32_e32 v9, v10, v12
	v_min_u32_e32 v12, v10, v12
	v_max_u32_e32 v25, v13, v15
	v_min_u32_e32 v15, v13, v15
	v_max_u32_e32 v24, v29, v31
	v_min_u32_e32 v31, v29, v31
	v_max_u32_e32 v10, v30, v213
	v_min_u32_e32 v213, v30, v213
	v_max_u32_e32 v13, v215, v0
	v_min_u32_e32 v0, v215, v0
	v_max_u32_e32 v29, v17, v18
	v_min_u32_e32 v18, v17, v18
	v_max_u32_e32 v30, v16, v4
	v_min_u32_e32 v4, v16, v4
	v_max_u32_e32 v215, v21, v22
	v_min_u32_e32 v22, v21, v22
	v_max_u32_e32 v17, v20, v8
	v_min_u32_e32 v8, v20, v8
	v_max_u32_e32 v16, v25, v26
	v_min_u32_e32 v26, v25, v26
	v_max_u32_e32 v21, v24, v12
	v_min_u32_e32 v12, v24, v12
	v_max_u32_e32 v20, v28, v214
	v_min_u32_e32 v214, v28, v214
	v_max_u32_e32 v25, v14, v1
	v_min_u32_e32 v1, v14, v1
	v_max_u32_e32 v24, v10, v29
	v_min_u32_e32 v29, v10, v29
	v_max_u32_e32 v28, v13, v30
	v_min_u32_e32 v30, v13, v30
	v_max_u32_e32 v14, v213, v18
	v_min_u32_e32 v18, v213, v18
	v_max_u32_e32 v10, v0, v4
	v_min_u32_e32 v4, v0, v4
	v_max_u32_e32 v13, v3, v7
	v_min_u32_e32 v7, v3, v7
	v_max_u32_e32 v213, v19, v23
	v_min_u32_e32 v23, v19, v23
	v_max_u32_e32 v0, v2, v6
	v_min_u32_e32 v6, v2, v6
	v_max_u32_e32 v3, v5, v9
	v_min_u32_e32 v9, v5, v9
	v_max_u32_e32 v19, v215, v16
	v_min_u32_e32 v16, v215, v16
	v_max_u32_e32 v2, v17, v21
	v_min_u32_e32 v21, v17, v21
	v_max_u32_e32 v5, v22, v26
	v_min_u32_e32 v26, v22, v26
	v_max_u32_e32 v215, v8, v12
	v_min_u32_e32 v12, v8, v12
	v_max_u32_e32 v17, v11, v15
	v_min_u32_e32 v15, v11, v15
	v_max_u32_e32 v22, v27, v31
	v_min_u32_e32 v31, v27, v31
	v_max_u32_e32 v8, v14, v214
	v_min_u32_e32 v214, v14, v214
	v_max_u32_e32 v11, v10, v1
	v_min_u32_e32 v1, v10, v1
	v_max_u32_e32 v27, v13, v29
	v_min_u32_e32 v29, v13, v29
	v_max_u32_e32 v14, v213, v30
	v_min_u32_e32 v30, v213, v30
	v_max_u32_e32 v10, v5, v6
	v_min_u32_e32 v6, v5, v6
	v_max_u32_e32 v13, v215, v9
	v_min_u32_e32 v9, v215, v9
	v_max_u32_e32 v213, v17, v16
	v_min_u32_e32 v16, v17, v16
	v_max_u32_e32 v5, v22, v21
	v_min_u32_e32 v21, v22, v21
	v_max_u32_e32 v215, v24, v8
	v_min_u32_e32 v8, v24, v8
	v_max_u32_e32 v17, v28, v11
	v_min_u32_e32 v11, v28, v11
	v_max_u32_e32 v22, v27, v214
	v_min_u32_e32 v214, v27, v214
	v_max_u32_e32 v24, v14, v1
	v_min_u32_e32 v1, v14, v1
	v_max_u32_e32 v28, v29, v18
	v_min_u32_e32 v18, v29, v18
	v_max_u32_e32 v27, v30, v4
	v_min_u32_e32 v4, v30, v4
	v_max_u32_e32 v14, v19, v10
	v_min_u32_e32 v10, v19, v10
	v_max_u32_e32 v29, v2, v13
	v_min_u32_e32 v13, v2, v13
	v_max_u32_e32 v30, v213, v6
	v_min_u32_e32 v6, v213, v6
	v_max_u32_e32 v19, v5, v9
	v_min_u32_e32 v9, v5, v9
	v_max_u32_e32 v2, v16, v26
	v_min_u32_e32 v26, v16, v26
	v_max_u32_e32 v213, v21, v12
	v_min_u32_e32 v12, v21, v12
	v_max_u32_e32 v5, v20, v0
	v_min_u32_e32 v0, v20, v0
	v_max_u32_e32 v16, v25, v3
	v_min_u32_e32 v3, v25, v3
	v_max_u32_e32 v21, v215, v14
	v_min_u32_e32 v14, v215, v14
	v_max_u32_e32 v20, v17, v29
	v_min_u32_e32 v29, v17, v29
	v_max_u32_e32 v25, v8, v10
	v_min_u32_e32 v10, v8, v10
	v_max_u32_e32 v215, v11, v13
	v_min_u32_e32 v13, v11, v13
	v_max_u32_e32 v17, v22, v30
	v_min_u32_e32 v30, v22, v30
	v_max_u32_e32 v8, v24, v19
	v_min_u32_e32 v19, v24, v19
	v_max_u32_e32 v11, v214, v6
	v_min_u32_e32 v6, v214, v6
	v_max_u32_e32 v22, v1, v9
	v_min_u32_e32 v9, v1, v9
	v_max_u32_e32 v24, v28, v2
	v_min_u32_e32 v2, v28, v2
	v_max_u32_e32 v214, v27, v213
	v_min_u32_e32 v213, v27, v213
	v_max_u32_e32 v1, v18, v26
	v_min_u32_e32 v26, v18, v26
	v_max_u32_e32 v28, v4, v12
	v_min_u32_e32 v12, v4, v12
	v_max_u32_e32 v27, v7, v15
	v_min_u32_e32 v15, v7, v15
	v_max_u32_e32 v18, v23, v31
	v_min_u32_e32 v31, v23, v31
	v_max_u32_e32 v4, v11, v0
	v_min_u32_e32 v0, v11, v0
	v_max_u32_e32 v7, v22, v3
	v_min_u32_e32 v3, v22, v3
	v_max_u32_e32 v23, v24, v14
	v_min_u32_e32 v14, v24, v14
	v_max_u32_e32 v11, v214, v29
	v_min_u32_e32 v29, v214, v29
	v_max_u32_e32 v22, v1, v10
	v_min_u32_e32 v10, v1, v10
	v_max_u32_e32 v24, v28, v13
	v_min_u32_e32 v13, v28, v13
	v_max_u32_e32 v214, v27, v30
	v_min_u32_e32 v30, v27, v30
	v_max_u32_e32 v1, v18, v19
	v_min_u32_e32 v19, v18, v19
	v_max_u32_e32 v28, v25, v4
	v_min_u32_e32 v4, v25, v4
	v_max_u32_e32 v27, v215, v7
	v_min_u32_e32 v7, v215, v7
	v_max_u32_e32 v18, v17, v23
	v_min_u32_e32 v23, v17, v23
	v_max_u32_e32 v25, v8, v11
	v_min_u32_e32 v11, v8, v11
	v_max_u32_e32 v215, v22, v0
	v_min_u32_e32 v0, v22, v0
	v_max_u32_e32 v17, v24, v3
	v_min_u32_e32 v3, v24, v3
	v_max_u32_e32 v8, v214, v14
	v_min_u32_e32 v14, v214, v14
	v_max_u32_e32 v22, v1, v29
	v_min_u32_e32 v29, v1, v29
	v_max_u32_e32 v24, v10, v6
	v_min_u32_e32 v6, v10, v6
	v_max_u32_e32 v214, v13, v9
	v_min_u32_e32 v9, v13, v9
	v_max_u32_e32 v1, v30, v2
	v_min_u32_e32 v2, v30, v2
	v_max_u32_e32 v10, v19, v213
	v_min_u32_e32 v213, v19, v213
	v_max_u32_e32 v13, v21, v28
	v_min_u32_e32 v28, v21, v28
	v_max_u32_e32 v30, v20, v27
; __device__ __forceinline__ float key2f(unsigned k) { return __uint_as_float((k & 0x80000000u) ? (k & 0x7fffffffu) : ~k); }
; __device__ void ph_peer(const float* __restrict__ SC, const bf16_t* __restrict__ H  , const float* __restrict__ gffn, const unsigned char* __restrict__ U, const unsigned char* __restrict__ V, float* X, const float* __restrict__ fgain) {
;     ...
;             for (int it = 0; it < 16; ++it) {
; #pragma unroll
;                 for (int u = 0; u < 2; ++u) {
;                     const unsigned m0 = wave_max_u32(k00[u] > k01[u] ? k00[u] : k01[u]);
;                     const unsigned m1 = wave_max_u32(k10[u] > k11[u] ? k10[u] : k11[u]);
;                     if (lane == it) { top0[u] = m0; top1[u] = m1; }
;                     if (k00[u] == m0) k00[u] = 0u; if (k01[u] == m0) k01[u] = 0u;
;                     if (k10[u] == m1) k10[u] = 0u; if (k11[u] == m1) k11[u] = 0u; }
;             }
;     ...
;                 const float s0 = key2f(top0[u] & ~127u), s1 = key2f(top1[u] & ~127u);
;                 n0[u] = 127 - (int)(top0[u] & 127u); n1[u] = 127 - (int)(top1[u] & 127u);
	v_min_u32_e32 v27, v20, v27
	v_max_u32_e32 v19, v18, v4
	v_min_u32_e32 v4, v18, v4
	v_max_u32_e32 v21, v25, v7
	v_min_u32_e32 v7, v25, v7
	v_max_u32_e32 v20, v23, v215
	v_min_u32_e32 v215, v23, v215
	v_max_u32_e32 v18, v11, v17
	v_min_u32_e32 v17, v11, v17
	v_max_u32_e32 v25, v8, v0
	v_min_u32_e32 v0, v8, v0
	v_max_u32_e32 v23, v22, v3
	v_min_u32_e32 v3, v22, v3
	v_max_u32_e32 v11, v14, v24
	v_min_u32_e32 v24, v14, v24
	v_max_u32_e32 v8, v29, v214
	v_min_u32_e32 v214, v29, v214
	v_max_u32_e32 v22, v1, v6
	v_min_u32_e32 v6, v1, v6
	v_max_u32_e32 v14, v10, v9
	v_min_u32_e32 v9, v10, v9
	v_max_u32_e32 v29, v2, v26
	v_min_u32_e32 v26, v2, v26
	v_max_u32_e32 v1, v213, v12
	v_min_u32_e32 v12, v213, v12
	v_max_u32_e32 v50, v46, v15
	v_max_u32_e32 v39, v49, v26
	v_max_u32_e32 v42, v35, v29
	v_max_u32_e32 v37, v48, v6
	v_max_u32_e32 v46, v43, v22
	v_max_u32_e32 v49, v38, v24
	v_max_u32_e32 v35, v32, v11
	v_max_u32_e32 v48, v34, v0
	v_max_u32_e32 v43, v47, v25
	v_max_u32_e32 v38, v41, v215
	v_max_u32_e32 v32, v33, v20
	v_max_u32_e32 v34, v36, v4
	v_max_u32_e32 v47, v44, v19
	v_max_u32_e32 v41, v51, v28
	v_max_u32_e32 v33, v45, v13
	v_max_u32_e32 v36, v40, v5
	v_max_u32_e32 v44, v50, v43
	v_min_u32_e32 v43, v50, v43
	v_max_u32_e32 v51, v39, v38
	v_min_u32_e32 v38, v39, v38
	v_max_u32_e32 v45, v42, v32
	v_min_u32_e32 v32, v42, v32
	v_max_u32_e32 v40, v37, v34
	v_min_u32_e32 v34, v37, v34
	v_max_u32_e32 v50, v46, v47
	v_min_u32_e32 v47, v46, v47
	v_max_u32_e32 v39, v49, v41
	v_min_u32_e32 v41, v49, v41
	v_max_u32_e32 v42, v35, v33
	v_min_u32_e32 v33, v35, v33
	v_max_u32_e32 v37, v48, v36
	v_min_u32_e32 v36, v48, v36
	v_max_u32_e32 v46, v44, v50
	v_min_u32_e32 v50, v44, v50
	v_max_u32_e32 v49, v51, v39
	v_min_u32_e32 v39, v51, v39
	v_max_u32_e32 v35, v45, v42
	v_min_u32_e32 v42, v45, v42
	v_max_u32_e32 v48, v40, v37
	v_min_u32_e32 v37, v40, v37
	v_max_u32_e32 v44, v43, v47
	v_min_u32_e32 v47, v43, v47
	v_max_u32_e32 v51, v38, v41
	v_min_u32_e32 v41, v38, v41
	v_max_u32_e32 v45, v32, v33
	v_min_u32_e32 v33, v32, v33
	v_max_u32_e32 v40, v34, v36
	v_min_u32_e32 v36, v34, v36
	v_max_u32_e32 v43, v46, v35
	v_min_u32_e32 v35, v46, v35
	v_max_u32_e32 v38, v49, v48
	v_min_u32_e32 v48, v49, v48
	v_max_u32_e32 v32, v50, v42
	v_min_u32_e32 v42, v50, v42
	v_max_u32_e32 v34, v39, v37
	v_min_u32_e32 v37, v39, v37
	v_max_u32_e32 v46, v44, v45
	v_min_u32_e32 v45, v44, v45
	v_max_u32_e32 v49, v51, v40
	v_min_u32_e32 v40, v51, v40
	v_max_u32_e32 v50, v47, v33
	v_min_u32_e32 v33, v47, v33
	v_max_u32_e32 v39, v41, v36
	v_min_u32_e32 v36, v41, v36
	v_max_u32_e32 v44, v43, v38
	v_min_u32_e32 v38, v43, v38
	v_max_u32_e32 v51, v35, v48
	v_min_u32_e32 v48, v35, v48
	v_max_u32_e32 v47, v32, v34
	v_min_u32_e32 v34, v32, v34
	v_max_u32_e32 v41, v42, v37
	v_min_u32_e32 v37, v42, v37
	v_max_u32_e32 v43, v46, v49
	v_min_u32_e32 v49, v46, v49
	v_max_u32_e32 v35, v45, v40
	v_min_u32_e32 v40, v45, v40
	v_max_u32_e32 v32, v50, v39
	v_min_u32_e32 v39, v50, v39
	v_max_u32_e32 v42, v33, v36
	v_min_u32_e32 v36, v33, v36
	v_max_u32_e32 v46, v44, v31
	v_max_u32_e32 v45, v38, v12
	v_max_u32_e32 v50, v51, v1
	v_max_u32_e32 v33, v48, v9
	v_max_u32_e32 v44, v47, v14
	v_max_u32_e32 v38, v34, v214
	v_max_u32_e32 v51, v41, v8
	v_max_u32_e32 v48, v37, v3
	v_max_u32_e32 v47, v43, v23
	v_max_u32_e32 v34, v49, v17
	v_max_u32_e32 v41, v35, v18
	v_max_u32_e32 v37, v40, v7
	v_max_u32_e32 v43, v32, v21
	v_max_u32_e32 v49, v39, v27
	v_max_u32_e32 v35, v42, v30
	v_max_u32_e32 v40, v36, v16
	v_max_u32_e32 v32, v46, v47
	v_min_u32_e32 v47, v46, v47
	v_max_u32_e32 v39, v45, v34
	v_min_u32_e32 v34, v45, v34
	v_max_u32_e32 v42, v50, v41
	v_min_u32_e32 v41, v50, v41
	v_max_u32_e32 v36, v33, v37
	v_min_u32_e32 v37, v33, v37
	v_max_u32_e32 v46, v44, v43
	v_min_u32_e32 v43, v44, v43
	v_max_u32_e32 v45, v38, v49
	v_min_u32_e32 v49, v38, v49
	v_max_u32_e32 v50, v51, v35
	v_min_u32_e32 v35, v51, v35
	v_max_u32_e32 v33, v48, v40
	v_min_u32_e32 v40, v48, v40
	v_max_u32_e32 v44, v32, v46
	v_min_u32_e32 v46, v32, v46
	v_max_u32_e32 v38, v39, v45
	v_min_u32_e32 v45, v39, v45
	v_max_u32_e32 v51, v42, v50
	v_min_u32_e32 v50, v42, v50
	v_max_u32_e32 v48, v36, v33
	v_min_u32_e32 v33, v36, v33
	v_max_u32_e32 v32, v47, v43
	v_min_u32_e32 v43, v47, v43
	v_max_u32_e32 v39, v34, v49
	v_min_u32_e32 v49, v34, v49
	v_max_u32_e32 v42, v41, v35
	v_min_u32_e32 v35, v41, v35
	v_max_u32_e32 v36, v37, v40
	v_min_u32_e32 v40, v37, v40
	v_max_u32_e32 v47, v44, v51
	v_min_u32_e32 v51, v44, v51
	v_max_u32_e32 v34, v38, v48
	v_min_u32_e32 v48, v38, v48
	v_max_u32_e32 v41, v46, v50
	v_min_u32_e32 v50, v46, v50
	v_max_u32_e32 v37, v45, v33
	v_min_u32_e32 v33, v45, v33
	v_max_u32_e32 v44, v32, v42
	v_min_u32_e32 v42, v32, v42
	v_max_u32_e32 v38, v39, v36
	v_min_u32_e32 v36, v39, v36
	v_max_u32_e32 v46, v43, v35
	v_min_u32_e32 v35, v43, v35
	v_max_u32_e32 v45, v49, v40
	v_min_u32_e32 v40, v49, v40
	v_max_u32_e32 v32, v47, v34
	v_min_u32_e32 v34, v47, v34
	v_max_u32_e32 v39, v51, v48
	v_min_u32_e32 v48, v51, v48
	v_max_u32_e32 v43, v41, v37
	v_min_u32_e32 v37, v41, v37
	v_max_u32_e32 v49, v50, v33
	v_min_u32_e32 v33, v50, v33
	v_max_u32_e32 v47, v44, v38
	v_min_u32_e32 v38, v44, v38
	v_max_u32_e32 v51, v42, v36
	v_min_u32_e32 v36, v42, v36
	v_max_u32_e32 v41, v46, v45
	v_min_u32_e32 v45, v46, v45
	v_max_u32_e32 v50, v35, v40
	v_min_u32_e32 v40, v35, v40
	ds_write_b8 v156, v32 offset:0
	ds_write_b8 v156, v34 offset:1
	ds_write_b8 v156, v39 offset:2
	ds_write_b8 v156, v48 offset:3
	ds_write_b8 v156, v43 offset:4
	ds_write_b8 v156, v37 offset:5
	ds_write_b8 v156, v49 offset:6
	ds_write_b8 v156, v33 offset:7
	ds_write_b8 v156, v47 offset:8
; __device__ __forceinline__ unsigned f2key(float f) { const unsigned u = __float_as_uint(f); return (u & 0x80000000u) ? ~u : (u | 0x80000000u); }
; __device__ __forceinline__ float key2f(unsigned k) { return __uint_as_float((k & 0x80000000u) ? (k & 0x7fffffffu) : ~k); }
; __device__ void ph_peer(const float* __restrict__ SC, const bf16_t* __restrict__ H  , const float* __restrict__ gffn, const unsigned char* __restrict__ U, const unsigned char* __restrict__ V, float* X, const float* __restrict__ fgain) {
;     ...
;             for (int u = 0; u < 2; ++u) { const float* sc = SC + (size_t)tok * 2048 + (h + u) * 256;
;                 const float2 a0 = ((const float2*)sc)[lane], a1 = ((const float2*)(sc + 128))[lane];
;                 k00[u] = (f2key(a0.x) & ~127u) | (unsigned)(127 - 2 * lane); k01[u] = (f2key(a0.y) & ~127u) | (unsigned)(126 - 2 * lane);
;                 k10[u] = (f2key(a1.x) & ~127u) | (unsigned)(127 - 2 * lane); k11[u] = (f2key(a1.y) & ~127u) | (unsigned)(126 - 2 * lane);
;     ...
;                 const float s0 = key2f(top0[u] & ~127u), s1 = key2f(top1[u] & ~127u);
;                 n0[u] = 127 - (int)(top0[u] & 127u); n1[u] = 127 - (int)(top1[u] & 127u);
	ds_write_b8 v156, v38 offset:9
	ds_write_b8 v156, v51 offset:10
	ds_write_b8 v156, v36 offset:11
	ds_write_b8 v156, v41 offset:12
	ds_write_b8 v156, v45 offset:13
	ds_write_b8 v156, v50 offset:14
	ds_write_b8 v156, v40 offset:15
	v_and_b32_e32 v96, s30, v32
	v_ashrrev_i32_e32 v212, 31, v96
	v_lshrrev_b32_e32 v212, 1, v212
	v_xnor_b32_e32 v96, v96, v212
	v_and_b32_e32 v97, s30, v34
	v_ashrrev_i32_e32 v212, 31, v97
	v_lshrrev_b32_e32 v212, 1, v212
	v_xnor_b32_e32 v97, v97, v212
	v_and_b32_e32 v98, s30, v39
	v_ashrrev_i32_e32 v212, 31, v98
	v_lshrrev_b32_e32 v212, 1, v212
	v_xnor_b32_e32 v98, v98, v212
	v_and_b32_e32 v99, s30, v48
	v_ashrrev_i32_e32 v212, 31, v99
	v_lshrrev_b32_e32 v212, 1, v212
	v_xnor_b32_e32 v99, v99, v212
	v_and_b32_e32 v100, s30, v43
	v_ashrrev_i32_e32 v212, 31, v100
	v_lshrrev_b32_e32 v212, 1, v212
	v_xnor_b32_e32 v100, v100, v212
	v_and_b32_e32 v101, s30, v37
	v_ashrrev_i32_e32 v212, 31, v101
	v_lshrrev_b32_e32 v212, 1, v212
	v_xnor_b32_e32 v101, v101, v212
	v_and_b32_e32 v102, s30, v49
	v_ashrrev_i32_e32 v212, 31, v102
	v_lshrrev_b32_e32 v212, 1, v212
	v_xnor_b32_e32 v102, v102, v212
	v_and_b32_e32 v103, s30, v33
	v_ashrrev_i32_e32 v212, 31, v103
	v_lshrrev_b32_e32 v212, 1, v212
	v_xnor_b32_e32 v103, v103, v212
	v_and_b32_e32 v104, s30, v47
	v_ashrrev_i32_e32 v212, 31, v104
	v_lshrrev_b32_e32 v212, 1, v212
	v_xnor_b32_e32 v104, v104, v212
	v_and_b32_e32 v105, s30, v38
	v_ashrrev_i32_e32 v212, 31, v105
	v_lshrrev_b32_e32 v212, 1, v212
	v_xnor_b32_e32 v105, v105, v212
	v_and_b32_e32 v106, s30, v51
	v_ashrrev_i32_e32 v212, 31, v106
	v_lshrrev_b32_e32 v212, 1, v212
	v_xnor_b32_e32 v106, v106, v212
	v_and_b32_e32 v107, s30, v36
	v_ashrrev_i32_e32 v212, 31, v107
	v_lshrrev_b32_e32 v212, 1, v212
	v_xnor_b32_e32 v107, v107, v212
	v_and_b32_e32 v108, s30, v41
	v_ashrrev_i32_e32 v212, 31, v108
	v_lshrrev_b32_e32 v212, 1, v212
	v_xnor_b32_e32 v108, v108, v212
	v_and_b32_e32 v109, s30, v45
	v_ashrrev_i32_e32 v212, 31, v109
	v_lshrrev_b32_e32 v212, 1, v212
	v_xnor_b32_e32 v109, v109, v212
	v_and_b32_e32 v110, s30, v50
	v_ashrrev_i32_e32 v212, 31, v110
	v_lshrrev_b32_e32 v212, 1, v212
	v_xnor_b32_e32 v110, v110, v212
	v_and_b32_e32 v111, s30, v40
	v_ashrrev_i32_e32 v212, 31, v111
	v_lshrrev_b32_e32 v212, 1, v212
	v_xnor_b32_e32 v111, v111, v212
	v_mov_b32_e32 v217, v216
	global_load_dwordx4 v[52:55], v217, s[28:29] offset:640
	v_add_u32_e32 v157, s36, v217
	global_load_dwordx4 v[56:59], v157, s[28:29] offset:640
	v_add_u32_e32 v217, s36, v157
	global_load_dwordx4 v[60:63], v217, s[28:29] offset:640
	v_add_u32_e32 v157, s36, v217
	global_load_dwordx4 v[112:115], v157, s[28:29] offset:640
	v_add_u32_e32 v217, s36, v157
	global_load_dwordx4 v[116:119], v217, s[28:29] offset:640
	v_add_u32_e32 v157, s36, v217
	global_load_dwordx4 v[120:123], v157, s[28:29] offset:640
	v_add_u32_e32 v217, s36, v157
	global_load_dwordx4 v[124:127], v217, s[28:29] offset:640
	v_add_u32_e32 v157, s36, v217
	global_load_dwordx4 v[158:161], v157, s[28:29] offset:640
	s_waitcnt vmcnt(8)
	ds_write_b128 v144, v[180:183] offset:0
	ds_write_b128 v144, v[184:187] offset:1152
	ds_write_b128 v144, v[188:191] offset:2304
	ds_write_b128 v144, v[192:195] offset:3456
	ds_write_b128 v144, v[196:199] offset:4608
	ds_write_b128 v144, v[200:203] offset:5760
	ds_write_b128 v144, v[204:207] offset:6912
	ds_write_b128 v144, v[208:211] offset:8064
	ds_read_b128 v[0:3], v145 offset:0
	ds_read_b128 v[4:7], v145 offset:16
	ds_read_b128 v[8:11], v145 offset:32
	ds_read_b128 v[12:15], v145 offset:48
	ds_read_b128 v[16:19], v145 offset:64
	ds_read_b128 v[20:23], v145 offset:80
	ds_read_b128 v[24:27], v145 offset:96
	ds_read_b128 v[28:31], v145 offset:112
	s_waitcnt lgkmcnt(0)
	v_ashrrev_i32_e32 v212, 31, v0
	v_or_b32_e32 v212, 0x80000000, v212
	v_xor_b32_e32 v0, v0, v212
	v_and_b32_e32 v0, s30, v0
	v_or_b32_e32 v0, 0x7f, v0
	v_ashrrev_i32_e32 v212, 31, v1
	v_or_b32_e32 v212, 0x80000000, v212
	v_xor_b32_e32 v1, v1, v212
	v_and_b32_e32 v1, s30, v1
	v_or_b32_e32 v1, 0x7e, v1
	v_ashrrev_i32_e32 v212, 31, v2
	v_or_b32_e32 v212, 0x80000000, v212
	v_xor_b32_e32 v2, v2, v212
	v_and_b32_e32 v2, s30, v2
	v_or_b32_e32 v2, 0x7d, v2
	v_ashrrev_i32_e32 v212, 31, v3
	v_or_b32_e32 v212, 0x80000000, v212
	v_xor_b32_e32 v3, v3, v212
	v_and_b32_e32 v3, s30, v3
	v_or_b32_e32 v3, 0x7c, v3
	v_ashrrev_i32_e32 v212, 31, v4
	v_or_b32_e32 v212, 0x80000000, v212
	v_xor_b32_e32 v4, v4, v212
	v_and_b32_e32 v4, s30, v4
	v_or_b32_e32 v4, 0x7b, v4
	v_ashrrev_i32_e32 v212, 31, v5
	v_or_b32_e32 v212, 0x80000000, v212
	v_xor_b32_e32 v5, v5, v212
	v_and_b32_e32 v5, s30, v5
	v_or_b32_e32 v5, 0x7a, v5
	v_ashrrev_i32_e32 v212, 31, v6
	v_or_b32_e32 v212, 0x80000000, v212
	v_xor_b32_e32 v6, v6, v212
	v_and_b32_e32 v6, s30, v6
	v_or_b32_e32 v6, 0x79, v6
	v_ashrrev_i32_e32 v212, 31, v7
	v_or_b32_e32 v212, 0x80000000, v212
	v_xor_b32_e32 v7, v7, v212
	v_and_b32_e32 v7, s30, v7
	v_or_b32_e32 v7, 0x78, v7
	v_ashrrev_i32_e32 v212, 31, v8
	v_or_b32_e32 v212, 0x80000000, v212
	v_xor_b32_e32 v8, v8, v212
	v_and_b32_e32 v8, s30, v8
	v_or_b32_e32 v8, 0x77, v8
	v_ashrrev_i32_e32 v212, 31, v9
	v_or_b32_e32 v212, 0x80000000, v212
	v_xor_b32_e32 v9, v9, v212
	v_and_b32_e32 v9, s30, v9
	v_or_b32_e32 v9, 0x76, v9
	v_ashrrev_i32_e32 v212, 31, v10
	v_or_b32_e32 v212, 0x80000000, v212
	v_xor_b32_e32 v10, v10, v212
	v_and_b32_e32 v10, s30, v10
	v_or_b32_e32 v10, 0x75, v10
	v_ashrrev_i32_e32 v212, 31, v11
	v_or_b32_e32 v212, 0x80000000, v212
	v_xor_b32_e32 v11, v11, v212
	v_and_b32_e32 v11, s30, v11
	v_or_b32_e32 v11, 0x74, v11
	v_ashrrev_i32_e32 v212, 31, v12
	v_or_b32_e32 v212, 0x80000000, v212
	v_xor_b32_e32 v12, v12, v212
; __device__ __forceinline__ unsigned f2key(float f) { const unsigned u = __float_as_uint(f); return (u & 0x80000000u) ? ~u : (u | 0x80000000u); }
; __device__ void ph_peer(const float* __restrict__ SC, const bf16_t* __restrict__ H  , const float* __restrict__ gffn, const unsigned char* __restrict__ U, const unsigned char* __restrict__ V, float* X, const float* __restrict__ fgain) {
;     ...
;             for (int u = 0; u < 2; ++u) { const float* sc = SC + (size_t)tok * 2048 + (h + u) * 256;
;                 const float2 a0 = ((const float2*)sc)[lane], a1 = ((const float2*)(sc + 128))[lane];
;                 k00[u] = (f2key(a0.x) & ~127u) | (unsigned)(127 - 2 * lane); k01[u] = (f2key(a0.y) & ~127u) | (unsigned)(126 - 2 * lane);
;                 k10[u] = (f2key(a1.x) & ~127u) | (unsigned)(127 - 2 * lane); k11[u] = (f2key(a1.y) & ~127u) | (unsigned)(126 - 2 * lane);
;     ...
;             for (int it = 0; it < 16; ++it) {
; #pragma unroll
;                 for (int u = 0; u < 2; ++u) {
;                     const unsigned m0 = wave_max_u32(k00[u] > k01[u] ? k00[u] : k01[u]);
;                     const unsigned m1 = wave_max_u32(k10[u] > k11[u] ? k10[u] : k11[u]);
;                     if (lane == it) { top0[u] = m0; top1[u] = m1; }
;                     if (k00[u] == m0) k00[u] = 0u; if (k01[u] == m0) k01[u] = 0u;
;                     if (k10[u] == m1) k10[u] = 0u; if (k11[u] == m1) k11[u] = 0u; }
;             }
	v_and_b32_e32 v12, s30, v12
	v_or_b32_e32 v12, 0x73, v12
	v_ashrrev_i32_e32 v212, 31, v13
	v_or_b32_e32 v212, 0x80000000, v212
	v_xor_b32_e32 v13, v13, v212
	v_and_b32_e32 v13, s30, v13
	v_or_b32_e32 v13, 0x72, v13
	v_ashrrev_i32_e32 v212, 31, v14
	v_or_b32_e32 v212, 0x80000000, v212
	v_xor_b32_e32 v14, v14, v212
	v_and_b32_e32 v14, s30, v14
	v_or_b32_e32 v14, 0x71, v14
	v_ashrrev_i32_e32 v212, 31, v15
	v_or_b32_e32 v212, 0x80000000, v212
	v_xor_b32_e32 v15, v15, v212
	v_and_b32_e32 v15, s30, v15
	v_or_b32_e32 v15, 0x70, v15
	v_ashrrev_i32_e32 v212, 31, v16
	v_or_b32_e32 v212, 0x80000000, v212
	v_xor_b32_e32 v16, v16, v212
	v_and_b32_e32 v16, s30, v16
	v_or_b32_e32 v16, 0x6f, v16
	v_ashrrev_i32_e32 v212, 31, v17
	v_or_b32_e32 v212, 0x80000000, v212
	v_xor_b32_e32 v17, v17, v212
	v_and_b32_e32 v17, s30, v17
	v_or_b32_e32 v17, 0x6e, v17
	v_ashrrev_i32_e32 v212, 31, v18
	v_or_b32_e32 v212, 0x80000000, v212
	v_xor_b32_e32 v18, v18, v212
	v_and_b32_e32 v18, s30, v18
	v_or_b32_e32 v18, 0x6d, v18
	v_ashrrev_i32_e32 v212, 31, v19
	v_or_b32_e32 v212, 0x80000000, v212
	v_xor_b32_e32 v19, v19, v212
	v_and_b32_e32 v19, s30, v19
	v_or_b32_e32 v19, 0x6c, v19
	v_ashrrev_i32_e32 v212, 31, v20
	v_or_b32_e32 v212, 0x80000000, v212
	v_xor_b32_e32 v20, v20, v212
	v_and_b32_e32 v20, s30, v20
	v_or_b32_e32 v20, 0x6b, v20
	v_ashrrev_i32_e32 v212, 31, v21
	v_or_b32_e32 v212, 0x80000000, v212
	v_xor_b32_e32 v21, v21, v212
	v_and_b32_e32 v21, s30, v21
	v_or_b32_e32 v21, 0x6a, v21
	v_ashrrev_i32_e32 v212, 31, v22
	v_or_b32_e32 v212, 0x80000000, v212
	v_xor_b32_e32 v22, v22, v212
	v_and_b32_e32 v22, s30, v22
	v_or_b32_e32 v22, 0x69, v22
	v_ashrrev_i32_e32 v212, 31, v23
	v_or_b32_e32 v212, 0x80000000, v212
	v_xor_b32_e32 v23, v23, v212
	v_and_b32_e32 v23, s30, v23
	v_or_b32_e32 v23, 0x68, v23
	v_ashrrev_i32_e32 v212, 31, v24
	v_or_b32_e32 v212, 0x80000000, v212
	v_xor_b32_e32 v24, v24, v212
	v_and_b32_e32 v24, s30, v24
	v_or_b32_e32 v24, 0x67, v24
	v_ashrrev_i32_e32 v212, 31, v25
	v_or_b32_e32 v212, 0x80000000, v212
	v_xor_b32_e32 v25, v25, v212
	v_and_b32_e32 v25, s30, v25
	v_or_b32_e32 v25, 0x66, v25
	v_ashrrev_i32_e32 v212, 31, v26
	v_or_b32_e32 v212, 0x80000000, v212
	v_xor_b32_e32 v26, v26, v212
	v_and_b32_e32 v26, s30, v26
	v_or_b32_e32 v26, 0x65, v26
	v_ashrrev_i32_e32 v212, 31, v27
	v_or_b32_e32 v212, 0x80000000, v212
	v_xor_b32_e32 v27, v27, v212
	v_and_b32_e32 v27, s30, v27
	v_or_b32_e32 v27, 0x64, v27
	v_ashrrev_i32_e32 v212, 31, v28
	v_or_b32_e32 v212, 0x80000000, v212
	v_xor_b32_e32 v28, v28, v212
	v_and_b32_e32 v28, s30, v28
	v_or_b32_e32 v28, 0x63, v28
	v_ashrrev_i32_e32 v212, 31, v29
	v_or_b32_e32 v212, 0x80000000, v212
	v_xor_b32_e32 v29, v29, v212
	v_and_b32_e32 v29, s30, v29
	v_or_b32_e32 v29, 0x62, v29
	v_ashrrev_i32_e32 v212, 31, v30
	v_or_b32_e32 v212, 0x80000000, v212
	v_xor_b32_e32 v30, v30, v212
	v_and_b32_e32 v30, s30, v30
	v_or_b32_e32 v30, 0x61, v30
	v_ashrrev_i32_e32 v212, 31, v31
	v_or_b32_e32 v212, 0x80000000, v212
	v_xor_b32_e32 v31, v31, v212
	v_and_b32_e32 v31, s30, v31
	v_or_b32_e32 v31, 0x60, v31
	v_max_u32_e32 v215, v0, v1
	v_min_u32_e32 v1, v0, v1
	v_max_u32_e32 v214, v16, v17
	v_min_u32_e32 v17, v16, v17
	v_max_u32_e32 v213, v2, v3
	v_min_u32_e32 v3, v2, v3
	v_max_u32_e32 v0, v18, v19
	v_min_u32_e32 v19, v18, v19
	v_max_u32_e32 v16, v4, v5
	v_min_u32_e32 v5, v4, v5
	v_max_u32_e32 v2, v20, v21
	v_min_u32_e32 v21, v20, v21
	v_max_u32_e32 v18, v6, v7
	v_min_u32_e32 v7, v6, v7
	v_max_u32_e32 v4, v22, v23
	v_min_u32_e32 v23, v22, v23
	v_max_u32_e32 v20, v8, v9
	v_min_u32_e32 v9, v8, v9
	v_max_u32_e32 v6, v24, v25
	v_min_u32_e32 v25, v24, v25
	v_max_u32_e32 v22, v10, v11
	v_min_u32_e32 v11, v10, v11
	v_max_u32_e32 v8, v26, v27
	v_min_u32_e32 v27, v26, v27
	v_max_u32_e32 v24, v12, v13
	v_min_u32_e32 v13, v12, v13
	v_max_u32_e32 v10, v28, v29
	v_min_u32_e32 v29, v28, v29
	v_max_u32_e32 v26, v14, v15
	v_min_u32_e32 v15, v14, v15
	v_max_u32_e32 v12, v30, v31
	v_min_u32_e32 v31, v30, v31
	v_max_u32_e32 v28, v215, v213
	v_min_u32_e32 v213, v215, v213
	v_max_u32_e32 v14, v214, v0
	v_min_u32_e32 v0, v214, v0
	v_max_u32_e32 v30, v1, v3
	v_min_u32_e32 v3, v1, v3
	v_max_u32_e32 v215, v17, v19
	v_min_u32_e32 v19, v17, v19
	v_max_u32_e32 v214, v16, v18
	v_min_u32_e32 v18, v16, v18
	v_max_u32_e32 v1, v2, v4
	v_min_u32_e32 v4, v2, v4
	v_max_u32_e32 v17, v5, v7
	v_min_u32_e32 v7, v5, v7
	v_max_u32_e32 v16, v21, v23
	v_min_u32_e32 v23, v21, v23
	v_max_u32_e32 v2, v20, v22
	v_min_u32_e32 v22, v20, v22
	v_max_u32_e32 v5, v6, v8
	v_min_u32_e32 v8, v6, v8
	v_max_u32_e32 v21, v9, v11
	v_min_u32_e32 v11, v9, v11
	v_max_u32_e32 v20, v25, v27
	v_min_u32_e32 v27, v25, v27
	v_max_u32_e32 v6, v24, v26
	v_min_u32_e32 v26, v24, v26
	v_max_u32_e32 v9, v10, v12
	v_min_u32_e32 v12, v10, v12
	v_max_u32_e32 v25, v13, v15
	v_min_u32_e32 v15, v13, v15
	v_max_u32_e32 v24, v29, v31
	v_min_u32_e32 v31, v29, v31
	v_max_u32_e32 v10, v30, v213
	v_min_u32_e32 v213, v30, v213
	v_max_u32_e32 v13, v215, v0
	v_min_u32_e32 v0, v215, v0
	v_max_u32_e32 v29, v17, v18
	v_min_u32_e32 v18, v17, v18
	v_max_u32_e32 v30, v16, v4
	v_min_u32_e32 v4, v16, v4
	v_max_u32_e32 v215, v21, v22
	v_min_u32_e32 v22, v21, v22
	v_max_u32_e32 v17, v20, v8
	v_min_u32_e32 v8, v20, v8
	v_max_u32_e32 v16, v25, v26
	v_min_u32_e32 v26, v25, v26
	v_max_u32_e32 v21, v24, v12
	v_min_u32_e32 v12, v24, v12
	v_max_u32_e32 v20, v28, v214
	v_min_u32_e32 v214, v28, v214
	v_max_u32_e32 v25, v14, v1
	v_min_u32_e32 v1, v14, v1
	v_max_u32_e32 v24, v10, v29
	v_min_u32_e32 v29, v10, v29
	v_max_u32_e32 v28, v13, v30
	v_min_u32_e32 v30, v13, v30
	v_max_u32_e32 v14, v213, v18
	v_min_u32_e32 v18, v213, v18
	v_max_u32_e32 v10, v0, v4
; __device__ void ph_peer(const float* __restrict__ SC, const bf16_t* __restrict__ H  , const float* __restrict__ gffn, const unsigned char* __restrict__ U, const unsigned char* __restrict__ V, float* X, const float* __restrict__ fgain) {
;     ...
;             for (int it = 0; it < 16; ++it) {
; #pragma unroll
;                 for (int u = 0; u < 2; ++u) {
;                     const unsigned m0 = wave_max_u32(k00[u] > k01[u] ? k00[u] : k01[u]);
;                     const unsigned m1 = wave_max_u32(k10[u] > k11[u] ? k10[u] : k11[u]);
;                     if (lane == it) { top0[u] = m0; top1[u] = m1; }
;                     if (k00[u] == m0) k00[u] = 0u; if (k01[u] == m0) k01[u] = 0u;
;                     if (k10[u] == m1) k10[u] = 0u; if (k11[u] == m1) k11[u] = 0u; }
;             }
	v_min_u32_e32 v4, v0, v4
	v_max_u32_e32 v13, v3, v7
	v_min_u32_e32 v7, v3, v7
	v_max_u32_e32 v213, v19, v23
	v_min_u32_e32 v23, v19, v23
	v_max_u32_e32 v0, v2, v6
	v_min_u32_e32 v6, v2, v6
	v_max_u32_e32 v3, v5, v9
	v_min_u32_e32 v9, v5, v9
	v_max_u32_e32 v19, v215, v16
	v_min_u32_e32 v16, v215, v16
	v_max_u32_e32 v2, v17, v21
	v_min_u32_e32 v21, v17, v21
	v_max_u32_e32 v5, v22, v26
	v_min_u32_e32 v26, v22, v26
	v_max_u32_e32 v215, v8, v12
	v_min_u32_e32 v12, v8, v12
	v_max_u32_e32 v17, v11, v15
	v_min_u32_e32 v15, v11, v15
	v_max_u32_e32 v22, v27, v31
	v_min_u32_e32 v31, v27, v31
	v_max_u32_e32 v8, v14, v214
	v_min_u32_e32 v214, v14, v214
	v_max_u32_e32 v11, v10, v1
	v_min_u32_e32 v1, v10, v1
	v_max_u32_e32 v27, v13, v29
	v_min_u32_e32 v29, v13, v29
	v_max_u32_e32 v14, v213, v30
	v_min_u32_e32 v30, v213, v30
	v_max_u32_e32 v10, v5, v6
	v_min_u32_e32 v6, v5, v6
	v_max_u32_e32 v13, v215, v9
	v_min_u32_e32 v9, v215, v9
	v_max_u32_e32 v213, v17, v16
	v_min_u32_e32 v16, v17, v16
	v_max_u32_e32 v5, v22, v21
	v_min_u32_e32 v21, v22, v21
	v_max_u32_e32 v215, v24, v8
	v_min_u32_e32 v8, v24, v8
	v_max_u32_e32 v17, v28, v11
	v_min_u32_e32 v11, v28, v11
	v_max_u32_e32 v22, v27, v214
	v_min_u32_e32 v214, v27, v214
	v_max_u32_e32 v24, v14, v1
	v_min_u32_e32 v1, v14, v1
	v_max_u32_e32 v28, v29, v18
	v_min_u32_e32 v18, v29, v18
	v_max_u32_e32 v27, v30, v4
	v_min_u32_e32 v4, v30, v4
	v_max_u32_e32 v14, v19, v10
	v_min_u32_e32 v10, v19, v10
	v_max_u32_e32 v29, v2, v13
	v_min_u32_e32 v13, v2, v13
	v_max_u32_e32 v30, v213, v6
	v_min_u32_e32 v6, v213, v6
	v_max_u32_e32 v19, v5, v9
	v_min_u32_e32 v9, v5, v9
	v_max_u32_e32 v2, v16, v26
	v_min_u32_e32 v26, v16, v26
	v_max_u32_e32 v213, v21, v12
	v_min_u32_e32 v12, v21, v12
	v_max_u32_e32 v5, v20, v0
	v_min_u32_e32 v0, v20, v0
	v_max_u32_e32 v16, v25, v3
	v_min_u32_e32 v3, v25, v3
	v_max_u32_e32 v21, v215, v14
	v_min_u32_e32 v14, v215, v14
	v_max_u32_e32 v20, v17, v29
	v_min_u32_e32 v29, v17, v29
	v_max_u32_e32 v25, v8, v10
	v_min_u32_e32 v10, v8, v10
	v_max_u32_e32 v215, v11, v13
	v_min_u32_e32 v13, v11, v13
	v_max_u32_e32 v17, v22, v30
	v_min_u32_e32 v30, v22, v30
	v_max_u32_e32 v8, v24, v19
	v_min_u32_e32 v19, v24, v19
	v_max_u32_e32 v11, v214, v6
	v_min_u32_e32 v6, v214, v6
	v_max_u32_e32 v22, v1, v9
	v_min_u32_e32 v9, v1, v9
	v_max_u32_e32 v24, v28, v2
	v_min_u32_e32 v2, v28, v2
	v_max_u32_e32 v214, v27, v213
	v_min_u32_e32 v213, v27, v213
	v_max_u32_e32 v1, v18, v26
	v_min_u32_e32 v26, v18, v26
	v_max_u32_e32 v28, v4, v12
	v_min_u32_e32 v12, v4, v12
	v_max_u32_e32 v27, v7, v15
	v_min_u32_e32 v15, v7, v15
	v_max_u32_e32 v18, v23, v31
	v_min_u32_e32 v31, v23, v31
	v_max_u32_e32 v4, v11, v0
	v_min_u32_e32 v0, v11, v0
	v_max_u32_e32 v7, v22, v3
	v_min_u32_e32 v3, v22, v3
	v_max_u32_e32 v23, v24, v14
	v_min_u32_e32 v14, v24, v14
	v_max_u32_e32 v11, v214, v29
	v_min_u32_e32 v29, v214, v29
	v_max_u32_e32 v22, v1, v10
	v_min_u32_e32 v10, v1, v10
	v_max_u32_e32 v24, v28, v13
	v_min_u32_e32 v13, v28, v13
	v_max_u32_e32 v214, v27, v30
	v_min_u32_e32 v30, v27, v30
	v_max_u32_e32 v1, v18, v19
	v_min_u32_e32 v19, v18, v19
	v_max_u32_e32 v28, v25, v4
	v_min_u32_e32 v4, v25, v4
	v_max_u32_e32 v27, v215, v7
	v_min_u32_e32 v7, v215, v7
	v_max_u32_e32 v18, v17, v23
	v_min_u32_e32 v23, v17, v23
	v_max_u32_e32 v25, v8, v11
	v_min_u32_e32 v11, v8, v11
	v_max_u32_e32 v215, v22, v0
	v_min_u32_e32 v0, v22, v0
	v_max_u32_e32 v17, v24, v3
	v_min_u32_e32 v3, v24, v3
	v_max_u32_e32 v8, v214, v14
	v_min_u32_e32 v14, v214, v14
	v_max_u32_e32 v22, v1, v29
	v_min_u32_e32 v29, v1, v29
	v_max_u32_e32 v24, v10, v6
	v_min_u32_e32 v6, v10, v6
	v_max_u32_e32 v214, v13, v9
	v_min_u32_e32 v9, v13, v9
	v_max_u32_e32 v1, v30, v2
	v_min_u32_e32 v2, v30, v2
	v_max_u32_e32 v10, v19, v213
	v_min_u32_e32 v213, v19, v213
	v_max_u32_e32 v13, v21, v28
	v_min_u32_e32 v28, v21, v28
	v_max_u32_e32 v30, v20, v27
	v_min_u32_e32 v27, v20, v27
	v_max_u32_e32 v19, v18, v4
	v_min_u32_e32 v4, v18, v4
	v_max_u32_e32 v21, v25, v7
	v_min_u32_e32 v7, v25, v7
	v_max_u32_e32 v20, v23, v215
	v_min_u32_e32 v215, v23, v215
	v_max_u32_e32 v18, v11, v17
	v_min_u32_e32 v17, v11, v17
	v_max_u32_e32 v25, v8, v0
	v_min_u32_e32 v0, v8, v0
	v_max_u32_e32 v23, v22, v3
	v_min_u32_e32 v3, v22, v3
	v_max_u32_e32 v11, v14, v24
	v_min_u32_e32 v24, v14, v24
	v_max_u32_e32 v8, v29, v214
	v_min_u32_e32 v214, v29, v214
	v_max_u32_e32 v22, v1, v6
	v_min_u32_e32 v6, v1, v6
	v_max_u32_e32 v14, v10, v9
	v_min_u32_e32 v9, v10, v9
	v_max_u32_e32 v29, v2, v26
	v_min_u32_e32 v26, v2, v26
	v_max_u32_e32 v1, v213, v12
	v_min_u32_e32 v12, v213, v12
	v_mov_b32_e32 v51, v5
	v_mov_b32_e32 v50, v13
	v_mov_b32_e32 v49, v28
	v_mov_b32_e32 v48, v19
	v_mov_b32_e32 v47, v4
	v_mov_b32_e32 v46, v20
	v_mov_b32_e32 v45, v215
	v_mov_b32_e32 v44, v25
	v_mov_b32_e32 v43, v0
	v_mov_b32_e32 v42, v11
	v_mov_b32_e32 v41, v24
	v_mov_b32_e32 v40, v22
	v_mov_b32_e32 v39, v6
	v_mov_b32_e32 v38, v29
	v_mov_b32_e32 v37, v26
	v_mov_b32_e32 v36, v15
	v_max_u32_e32 v35, v51, v31
	v_max_u32_e32 v34, v50, v12
	v_max_u32_e32 v33, v49, v1
	v_max_u32_e32 v32, v48, v9
	v_max_u32_e32 v51, v47, v14
	v_max_u32_e32 v50, v46, v214
	v_max_u32_e32 v49, v45, v8
	v_max_u32_e32 v48, v44, v3
	v_max_u32_e32 v47, v43, v23
	v_max_u32_e32 v46, v42, v17
	v_max_u32_e32 v45, v41, v18
	v_max_u32_e32 v44, v40, v7
	v_max_u32_e32 v43, v39, v21
	v_max_u32_e32 v42, v38, v27
	v_max_u32_e32 v41, v37, v30
	v_max_u32_e32 v40, v36, v16
	v_max_u32_e32 v39, v35, v47
	v_min_u32_e32 v47, v35, v47
	v_max_u32_e32 v38, v34, v46
	v_min_u32_e32 v46, v34, v46
	v_max_u32_e32 v37, v33, v45
	v_min_u32_e32 v45, v33, v45
	v_max_u32_e32 v36, v32, v44
	v_min_u32_e32 v44, v32, v44
; __device__ __forceinline__ unsigned f2key(float f) { const unsigned u = __float_as_uint(f); return (u & 0x80000000u) ? ~u : (u | 0x80000000u); }
; __device__ void ph_peer(const float* __restrict__ SC, const bf16_t* __restrict__ H  , const float* __restrict__ gffn, const unsigned char* __restrict__ U, const unsigned char* __restrict__ V, float* X, const float* __restrict__ fgain) {
;     ...
;             for (int u = 0; u < 2; ++u) { const float* sc = SC + (size_t)tok * 2048 + (h + u) * 256;
;                 const float2 a0 = ((const float2*)sc)[lane], a1 = ((const float2*)(sc + 128))[lane];
;                 k00[u] = (f2key(a0.x) & ~127u) | (unsigned)(127 - 2 * lane); k01[u] = (f2key(a0.y) & ~127u) | (unsigned)(126 - 2 * lane);
;                 k10[u] = (f2key(a1.x) & ~127u) | (unsigned)(127 - 2 * lane); k11[u] = (f2key(a1.y) & ~127u) | (unsigned)(126 - 2 * lane);
;     ...
;             for (int it = 0; it < 16; ++it) {
; #pragma unroll
;                 for (int u = 0; u < 2; ++u) {
;                     const unsigned m0 = wave_max_u32(k00[u] > k01[u] ? k00[u] : k01[u]);
;                     const unsigned m1 = wave_max_u32(k10[u] > k11[u] ? k10[u] : k11[u]);
;                     if (lane == it) { top0[u] = m0; top1[u] = m1; }
;                     if (k00[u] == m0) k00[u] = 0u; if (k01[u] == m0) k01[u] = 0u;
;                     if (k10[u] == m1) k10[u] = 0u; if (k11[u] == m1) k11[u] = 0u; }
;             }
	v_max_u32_e32 v35, v51, v43
	v_min_u32_e32 v43, v51, v43
	v_max_u32_e32 v34, v50, v42
	v_min_u32_e32 v42, v50, v42
	v_max_u32_e32 v33, v49, v41
	v_min_u32_e32 v41, v49, v41
	v_max_u32_e32 v32, v48, v40
	v_min_u32_e32 v40, v48, v40
	v_max_u32_e32 v51, v39, v35
	v_min_u32_e32 v35, v39, v35
	v_max_u32_e32 v50, v38, v34
	v_min_u32_e32 v34, v38, v34
	v_max_u32_e32 v49, v37, v33
	v_min_u32_e32 v33, v37, v33
	v_max_u32_e32 v48, v36, v32
	v_min_u32_e32 v32, v36, v32
	v_max_u32_e32 v39, v47, v43
	v_min_u32_e32 v43, v47, v43
	v_max_u32_e32 v38, v46, v42
	v_min_u32_e32 v42, v46, v42
	v_max_u32_e32 v37, v45, v41
	v_min_u32_e32 v41, v45, v41
	v_max_u32_e32 v36, v44, v40
	v_min_u32_e32 v40, v44, v40
	v_max_u32_e32 v47, v51, v49
	v_min_u32_e32 v49, v51, v49
	v_max_u32_e32 v46, v50, v48
	v_min_u32_e32 v48, v50, v48
	v_max_u32_e32 v45, v35, v33
	v_min_u32_e32 v33, v35, v33
	v_max_u32_e32 v44, v34, v32
	v_min_u32_e32 v32, v34, v32
	v_max_u32_e32 v51, v39, v37
	v_min_u32_e32 v37, v39, v37
	v_max_u32_e32 v50, v38, v36
	v_min_u32_e32 v36, v38, v36
	v_max_u32_e32 v35, v43, v41
	v_min_u32_e32 v41, v43, v41
	v_max_u32_e32 v34, v42, v40
	v_min_u32_e32 v40, v42, v40
	v_max_u32_e32 v39, v47, v46
	v_min_u32_e32 v46, v47, v46
	v_max_u32_e32 v38, v49, v48
	v_min_u32_e32 v48, v49, v48
	v_max_u32_e32 v43, v45, v44
	v_min_u32_e32 v44, v45, v44
	v_max_u32_e32 v42, v33, v32
	v_min_u32_e32 v32, v33, v32
	v_max_u32_e32 v47, v51, v50
	v_min_u32_e32 v50, v51, v50
	v_max_u32_e32 v49, v37, v36
	v_min_u32_e32 v36, v37, v36
	v_max_u32_e32 v45, v35, v34
	v_min_u32_e32 v34, v35, v34
	v_max_u32_e32 v33, v41, v40
	v_min_u32_e32 v40, v41, v40
	v_mov_b32_e32 v217, v216
	global_load_dwordx4 v[180:183], v217, s[28:29] offset:768
	v_add_u32_e32 v157, s36, v217
	global_load_dwordx4 v[184:187], v157, s[28:29] offset:768
	v_add_u32_e32 v217, s36, v157
	global_load_dwordx4 v[188:191], v217, s[28:29] offset:768
	v_add_u32_e32 v157, s36, v217
	global_load_dwordx4 v[192:195], v157, s[28:29] offset:768
	v_add_u32_e32 v217, s36, v157
	global_load_dwordx4 v[196:199], v217, s[28:29] offset:768
	v_add_u32_e32 v157, s36, v217
	global_load_dwordx4 v[200:203], v157, s[28:29] offset:768
	v_add_u32_e32 v217, s36, v157
	global_load_dwordx4 v[204:207], v217, s[28:29] offset:768
	v_add_u32_e32 v157, s36, v217
	global_load_dwordx4 v[208:211], v157, s[28:29] offset:768
	s_waitcnt vmcnt(8)
	ds_write_b128 v144, v[52:55] offset:0
	ds_write_b128 v144, v[56:59] offset:1152
	ds_write_b128 v144, v[60:63] offset:2304
	ds_write_b128 v144, v[112:115] offset:3456
	ds_write_b128 v144, v[116:119] offset:4608
	ds_write_b128 v144, v[120:123] offset:5760
	ds_write_b128 v144, v[124:127] offset:6912
	ds_write_b128 v144, v[158:161] offset:8064
	ds_read_b128 v[0:3], v145 offset:0
	ds_read_b128 v[4:7], v145 offset:16
	ds_read_b128 v[8:11], v145 offset:32
	ds_read_b128 v[12:15], v145 offset:48
	ds_read_b128 v[16:19], v145 offset:64
	ds_read_b128 v[20:23], v145 offset:80
	ds_read_b128 v[24:27], v145 offset:96
	ds_read_b128 v[28:31], v145 offset:112
	s_waitcnt lgkmcnt(0)
	v_ashrrev_i32_e32 v212, 31, v0
	v_or_b32_e32 v212, 0x80000000, v212
	v_xor_b32_e32 v0, v0, v212
	v_and_b32_e32 v0, s30, v0
	v_or_b32_e32 v0, 0x5f, v0
	v_ashrrev_i32_e32 v212, 31, v1
	v_or_b32_e32 v212, 0x80000000, v212
	v_xor_b32_e32 v1, v1, v212
	v_and_b32_e32 v1, s30, v1
	v_or_b32_e32 v1, 0x5e, v1
	v_ashrrev_i32_e32 v212, 31, v2
	v_or_b32_e32 v212, 0x80000000, v212
	v_xor_b32_e32 v2, v2, v212
	v_and_b32_e32 v2, s30, v2
	v_or_b32_e32 v2, 0x5d, v2
	v_ashrrev_i32_e32 v212, 31, v3
	v_or_b32_e32 v212, 0x80000000, v212
	v_xor_b32_e32 v3, v3, v212
	v_and_b32_e32 v3, s30, v3
	v_or_b32_e32 v3, 0x5c, v3
	v_ashrrev_i32_e32 v212, 31, v4
	v_or_b32_e32 v212, 0x80000000, v212
	v_xor_b32_e32 v4, v4, v212
	v_and_b32_e32 v4, s30, v4
	v_or_b32_e32 v4, 0x5b, v4
	v_ashrrev_i32_e32 v212, 31, v5
	v_or_b32_e32 v212, 0x80000000, v212
	v_xor_b32_e32 v5, v5, v212
	v_and_b32_e32 v5, s30, v5
	v_or_b32_e32 v5, 0x5a, v5
	v_ashrrev_i32_e32 v212, 31, v6
	v_or_b32_e32 v212, 0x80000000, v212
	v_xor_b32_e32 v6, v6, v212
	v_and_b32_e32 v6, s30, v6
	v_or_b32_e32 v6, 0x59, v6
	v_ashrrev_i32_e32 v212, 31, v7
	v_or_b32_e32 v212, 0x80000000, v212
	v_xor_b32_e32 v7, v7, v212
	v_and_b32_e32 v7, s30, v7
	v_or_b32_e32 v7, 0x58, v7
	v_ashrrev_i32_e32 v212, 31, v8
	v_or_b32_e32 v212, 0x80000000, v212
	v_xor_b32_e32 v8, v8, v212
	v_and_b32_e32 v8, s30, v8
	v_or_b32_e32 v8, 0x57, v8
	v_ashrrev_i32_e32 v212, 31, v9
	v_or_b32_e32 v212, 0x80000000, v212
	v_xor_b32_e32 v9, v9, v212
	v_and_b32_e32 v9, s30, v9
	v_or_b32_e32 v9, 0x56, v9
	v_ashrrev_i32_e32 v212, 31, v10
	v_or_b32_e32 v212, 0x80000000, v212
	v_xor_b32_e32 v10, v10, v212
	v_and_b32_e32 v10, s30, v10
	v_or_b32_e32 v10, 0x55, v10
	v_ashrrev_i32_e32 v212, 31, v11
	v_or_b32_e32 v212, 0x80000000, v212
	v_xor_b32_e32 v11, v11, v212
	v_and_b32_e32 v11, s30, v11
	v_or_b32_e32 v11, 0x54, v11
	v_ashrrev_i32_e32 v212, 31, v12
	v_or_b32_e32 v212, 0x80000000, v212
	v_xor_b32_e32 v12, v12, v212
	v_and_b32_e32 v12, s30, v12
	v_or_b32_e32 v12, 0x53, v12
	v_ashrrev_i32_e32 v212, 31, v13
	v_or_b32_e32 v212, 0x80000000, v212
	v_xor_b32_e32 v13, v13, v212
	v_and_b32_e32 v13, s30, v13
	v_or_b32_e32 v13, 0x52, v13
	v_ashrrev_i32_e32 v212, 31, v14
	v_or_b32_e32 v212, 0x80000000, v212
	v_xor_b32_e32 v14, v14, v212
	v_and_b32_e32 v14, s30, v14
	v_or_b32_e32 v14, 0x51, v14
	v_ashrrev_i32_e32 v212, 31, v15
	v_or_b32_e32 v212, 0x80000000, v212
	v_xor_b32_e32 v15, v15, v212
	v_and_b32_e32 v15, s30, v15
	v_or_b32_e32 v15, 0x50, v15
	v_ashrrev_i32_e32 v212, 31, v16
	v_or_b32_e32 v212, 0x80000000, v212
	v_xor_b32_e32 v16, v16, v212
	v_and_b32_e32 v16, s30, v16
	v_or_b32_e32 v16, 0x4f, v16
; __device__ __forceinline__ unsigned f2key(float f) { const unsigned u = __float_as_uint(f); return (u & 0x80000000u) ? ~u : (u | 0x80000000u); }
; __device__ void ph_peer(const float* __restrict__ SC, const bf16_t* __restrict__ H  , const float* __restrict__ gffn, const unsigned char* __restrict__ U, const unsigned char* __restrict__ V, float* X, const float* __restrict__ fgain) {
;     ...
;             for (int u = 0; u < 2; ++u) { const float* sc = SC + (size_t)tok * 2048 + (h + u) * 256;
;                 const float2 a0 = ((const float2*)sc)[lane], a1 = ((const float2*)(sc + 128))[lane];
;                 k00[u] = (f2key(a0.x) & ~127u) | (unsigned)(127 - 2 * lane); k01[u] = (f2key(a0.y) & ~127u) | (unsigned)(126 - 2 * lane);
;                 k10[u] = (f2key(a1.x) & ~127u) | (unsigned)(127 - 2 * lane); k11[u] = (f2key(a1.y) & ~127u) | (unsigned)(126 - 2 * lane);
;     ...
;             for (int it = 0; it < 16; ++it) {
; #pragma unroll
;                 for (int u = 0; u < 2; ++u) {
;                     const unsigned m0 = wave_max_u32(k00[u] > k01[u] ? k00[u] : k01[u]);
;                     const unsigned m1 = wave_max_u32(k10[u] > k11[u] ? k10[u] : k11[u]);
;                     if (lane == it) { top0[u] = m0; top1[u] = m1; }
;                     if (k00[u] == m0) k00[u] = 0u; if (k01[u] == m0) k01[u] = 0u;
;                     if (k10[u] == m1) k10[u] = 0u; if (k11[u] == m1) k11[u] = 0u; }
;             }
	v_ashrrev_i32_e32 v212, 31, v17
	v_or_b32_e32 v212, 0x80000000, v212
	v_xor_b32_e32 v17, v17, v212
	v_and_b32_e32 v17, s30, v17
	v_or_b32_e32 v17, 0x4e, v17
	v_ashrrev_i32_e32 v212, 31, v18
	v_or_b32_e32 v212, 0x80000000, v212
	v_xor_b32_e32 v18, v18, v212
	v_and_b32_e32 v18, s30, v18
	v_or_b32_e32 v18, 0x4d, v18
	v_ashrrev_i32_e32 v212, 31, v19
	v_or_b32_e32 v212, 0x80000000, v212
	v_xor_b32_e32 v19, v19, v212
	v_and_b32_e32 v19, s30, v19
	v_or_b32_e32 v19, 0x4c, v19
	v_ashrrev_i32_e32 v212, 31, v20
	v_or_b32_e32 v212, 0x80000000, v212
	v_xor_b32_e32 v20, v20, v212
	v_and_b32_e32 v20, s30, v20
	v_or_b32_e32 v20, 0x4b, v20
	v_ashrrev_i32_e32 v212, 31, v21
	v_or_b32_e32 v212, 0x80000000, v212
	v_xor_b32_e32 v21, v21, v212
	v_and_b32_e32 v21, s30, v21
	v_or_b32_e32 v21, 0x4a, v21
	v_ashrrev_i32_e32 v212, 31, v22
	v_or_b32_e32 v212, 0x80000000, v212
	v_xor_b32_e32 v22, v22, v212
	v_and_b32_e32 v22, s30, v22
	v_or_b32_e32 v22, 0x49, v22
	v_ashrrev_i32_e32 v212, 31, v23
	v_or_b32_e32 v212, 0x80000000, v212
	v_xor_b32_e32 v23, v23, v212
	v_and_b32_e32 v23, s30, v23
	v_or_b32_e32 v23, 0x48, v23
	v_ashrrev_i32_e32 v212, 31, v24
	v_or_b32_e32 v212, 0x80000000, v212
	v_xor_b32_e32 v24, v24, v212
	v_and_b32_e32 v24, s30, v24
	v_or_b32_e32 v24, 0x47, v24
	v_ashrrev_i32_e32 v212, 31, v25
	v_or_b32_e32 v212, 0x80000000, v212
	v_xor_b32_e32 v25, v25, v212
	v_and_b32_e32 v25, s30, v25
	v_or_b32_e32 v25, 0x46, v25
	v_ashrrev_i32_e32 v212, 31, v26
	v_or_b32_e32 v212, 0x80000000, v212
	v_xor_b32_e32 v26, v26, v212
	v_and_b32_e32 v26, s30, v26
	v_or_b32_e32 v26, 0x45, v26
	v_ashrrev_i32_e32 v212, 31, v27
	v_or_b32_e32 v212, 0x80000000, v212
	v_xor_b32_e32 v27, v27, v212
	v_and_b32_e32 v27, s30, v27
	v_or_b32_e32 v27, 0x44, v27
	v_ashrrev_i32_e32 v212, 31, v28
	v_or_b32_e32 v212, 0x80000000, v212
	v_xor_b32_e32 v28, v28, v212
	v_and_b32_e32 v28, s30, v28
	v_or_b32_e32 v28, 0x43, v28
	v_ashrrev_i32_e32 v212, 31, v29
	v_or_b32_e32 v212, 0x80000000, v212
	v_xor_b32_e32 v29, v29, v212
	v_and_b32_e32 v29, s30, v29
	v_or_b32_e32 v29, 0x42, v29
	v_ashrrev_i32_e32 v212, 31, v30
	v_or_b32_e32 v212, 0x80000000, v212
	v_xor_b32_e32 v30, v30, v212
	v_and_b32_e32 v30, s30, v30
	v_or_b32_e32 v30, 0x41, v30
	v_ashrrev_i32_e32 v212, 31, v31
	v_or_b32_e32 v212, 0x80000000, v212
	v_xor_b32_e32 v31, v31, v212
	v_and_or_b32 v31, v31, s30, 64
	v_max_u32_e32 v215, v0, v1
	v_min_u32_e32 v1, v0, v1
	v_max_u32_e32 v214, v16, v17
	v_min_u32_e32 v17, v16, v17
	v_max_u32_e32 v213, v2, v3
	v_min_u32_e32 v3, v2, v3
	v_max_u32_e32 v0, v18, v19
	v_min_u32_e32 v19, v18, v19
	v_max_u32_e32 v16, v4, v5
	v_min_u32_e32 v5, v4, v5
	v_max_u32_e32 v2, v20, v21
	v_min_u32_e32 v21, v20, v21
	v_max_u32_e32 v18, v6, v7
	v_min_u32_e32 v7, v6, v7
	v_max_u32_e32 v4, v22, v23
	v_min_u32_e32 v23, v22, v23
	v_max_u32_e32 v20, v8, v9
	v_min_u32_e32 v9, v8, v9
	v_max_u32_e32 v6, v24, v25
	v_min_u32_e32 v25, v24, v25
	v_max_u32_e32 v22, v10, v11
	v_min_u32_e32 v11, v10, v11
	v_max_u32_e32 v8, v26, v27
	v_min_u32_e32 v27, v26, v27
	v_max_u32_e32 v24, v12, v13
	v_min_u32_e32 v13, v12, v13
	v_max_u32_e32 v10, v28, v29
	v_min_u32_e32 v29, v28, v29
	v_max_u32_e32 v26, v14, v15
	v_min_u32_e32 v15, v14, v15
	v_max_u32_e32 v12, v30, v31
	v_min_u32_e32 v31, v30, v31
	v_max_u32_e32 v28, v215, v213
	v_min_u32_e32 v213, v215, v213
	v_max_u32_e32 v14, v214, v0
	v_min_u32_e32 v0, v214, v0
	v_max_u32_e32 v30, v1, v3
	v_min_u32_e32 v3, v1, v3
	v_max_u32_e32 v215, v17, v19
	v_min_u32_e32 v19, v17, v19
	v_max_u32_e32 v214, v16, v18
	v_min_u32_e32 v18, v16, v18
	v_max_u32_e32 v1, v2, v4
	v_min_u32_e32 v4, v2, v4
	v_max_u32_e32 v17, v5, v7
	v_min_u32_e32 v7, v5, v7
	v_max_u32_e32 v16, v21, v23
	v_min_u32_e32 v23, v21, v23
	v_max_u32_e32 v2, v20, v22
	v_min_u32_e32 v22, v20, v22
	v_max_u32_e32 v5, v6, v8
	v_min_u32_e32 v8, v6, v8
	v_max_u32_e32 v21, v9, v11
	v_min_u32_e32 v11, v9, v11
	v_max_u32_e32 v20, v25, v27
	v_min_u32_e32 v27, v25, v27
	v_max_u32_e32 v6, v24, v26
	v_min_u32_e32 v26, v24, v26
	v_max_u32_e32 v9, v10, v12
	v_min_u32_e32 v12, v10, v12
	v_max_u32_e32 v25, v13, v15
	v_min_u32_e32 v15, v13, v15
	v_max_u32_e32 v24, v29, v31
	v_min_u32_e32 v31, v29, v31
	v_max_u32_e32 v10, v30, v213
	v_min_u32_e32 v213, v30, v213
	v_max_u32_e32 v13, v215, v0
	v_min_u32_e32 v0, v215, v0
	v_max_u32_e32 v29, v17, v18
	v_min_u32_e32 v18, v17, v18
	v_max_u32_e32 v30, v16, v4
	v_min_u32_e32 v4, v16, v4
	v_max_u32_e32 v215, v21, v22
	v_min_u32_e32 v22, v21, v22
	v_max_u32_e32 v17, v20, v8
	v_min_u32_e32 v8, v20, v8
	v_max_u32_e32 v16, v25, v26
	v_min_u32_e32 v26, v25, v26
	v_max_u32_e32 v21, v24, v12
	v_min_u32_e32 v12, v24, v12
	v_max_u32_e32 v20, v28, v214
	v_min_u32_e32 v214, v28, v214
	v_max_u32_e32 v25, v14, v1
	v_min_u32_e32 v1, v14, v1
	v_max_u32_e32 v24, v10, v29
	v_min_u32_e32 v29, v10, v29
	v_max_u32_e32 v28, v13, v30
	v_min_u32_e32 v30, v13, v30
	v_max_u32_e32 v14, v213, v18
	v_min_u32_e32 v18, v213, v18
	v_max_u32_e32 v10, v0, v4
	v_min_u32_e32 v4, v0, v4
	v_max_u32_e32 v13, v3, v7
	v_min_u32_e32 v7, v3, v7
	v_max_u32_e32 v213, v19, v23
	v_min_u32_e32 v23, v19, v23
	v_max_u32_e32 v0, v2, v6
	v_min_u32_e32 v6, v2, v6
	v_max_u32_e32 v3, v5, v9
	v_min_u32_e32 v9, v5, v9
	v_max_u32_e32 v19, v215, v16
	v_min_u32_e32 v16, v215, v16
	v_max_u32_e32 v2, v17, v21
	v_min_u32_e32 v21, v17, v21
	v_max_u32_e32 v5, v22, v26
	v_min_u32_e32 v26, v22, v26
	v_max_u32_e32 v215, v8, v12
	v_min_u32_e32 v12, v8, v12
	v_max_u32_e32 v17, v11, v15
	v_min_u32_e32 v15, v11, v15
	v_max_u32_e32 v22, v27, v31
	v_min_u32_e32 v31, v27, v31
	v_max_u32_e32 v8, v14, v214
	v_min_u32_e32 v214, v14, v214
	v_max_u32_e32 v11, v10, v1
	v_min_u32_e32 v1, v10, v1
; __device__ void ph_peer(const float* __restrict__ SC, const bf16_t* __restrict__ H  , const float* __restrict__ gffn, const unsigned char* __restrict__ U, const unsigned char* __restrict__ V, float* X, const float* __restrict__ fgain) {
;     ...
;             for (int it = 0; it < 16; ++it) {
; #pragma unroll
;                 for (int u = 0; u < 2; ++u) {
;                     const unsigned m0 = wave_max_u32(k00[u] > k01[u] ? k00[u] : k01[u]);
;                     const unsigned m1 = wave_max_u32(k10[u] > k11[u] ? k10[u] : k11[u]);
;                     if (lane == it) { top0[u] = m0; top1[u] = m1; }
;                     if (k00[u] == m0) k00[u] = 0u; if (k01[u] == m0) k01[u] = 0u;
;                     if (k10[u] == m1) k10[u] = 0u; if (k11[u] == m1) k11[u] = 0u; }
;             }
	v_max_u32_e32 v27, v13, v29
	v_min_u32_e32 v29, v13, v29
	v_max_u32_e32 v14, v213, v30
	v_min_u32_e32 v30, v213, v30
	v_max_u32_e32 v10, v5, v6
	v_min_u32_e32 v6, v5, v6
	v_max_u32_e32 v13, v215, v9
	v_min_u32_e32 v9, v215, v9
	v_max_u32_e32 v213, v17, v16
	v_min_u32_e32 v16, v17, v16
	v_max_u32_e32 v5, v22, v21
	v_min_u32_e32 v21, v22, v21
	v_max_u32_e32 v215, v24, v8
	v_min_u32_e32 v8, v24, v8
	v_max_u32_e32 v17, v28, v11
	v_min_u32_e32 v11, v28, v11
	v_max_u32_e32 v22, v27, v214
	v_min_u32_e32 v214, v27, v214
	v_max_u32_e32 v24, v14, v1
	v_min_u32_e32 v1, v14, v1
	v_max_u32_e32 v28, v29, v18
	v_min_u32_e32 v18, v29, v18
	v_max_u32_e32 v27, v30, v4
	v_min_u32_e32 v4, v30, v4
	v_max_u32_e32 v14, v19, v10
	v_min_u32_e32 v10, v19, v10
	v_max_u32_e32 v29, v2, v13
	v_min_u32_e32 v13, v2, v13
	v_max_u32_e32 v30, v213, v6
	v_min_u32_e32 v6, v213, v6
	v_max_u32_e32 v19, v5, v9
	v_min_u32_e32 v9, v5, v9
	v_max_u32_e32 v2, v16, v26
	v_min_u32_e32 v26, v16, v26
	v_max_u32_e32 v213, v21, v12
	v_min_u32_e32 v12, v21, v12
	v_max_u32_e32 v5, v20, v0
	v_min_u32_e32 v0, v20, v0
	v_max_u32_e32 v16, v25, v3
	v_min_u32_e32 v3, v25, v3
	v_max_u32_e32 v21, v215, v14
	v_min_u32_e32 v14, v215, v14
	v_max_u32_e32 v20, v17, v29
	v_min_u32_e32 v29, v17, v29
	v_max_u32_e32 v25, v8, v10
	v_min_u32_e32 v10, v8, v10
	v_max_u32_e32 v215, v11, v13
	v_min_u32_e32 v13, v11, v13
	v_max_u32_e32 v17, v22, v30
	v_min_u32_e32 v30, v22, v30
	v_max_u32_e32 v8, v24, v19
	v_min_u32_e32 v19, v24, v19
	v_max_u32_e32 v11, v214, v6
	v_min_u32_e32 v6, v214, v6
	v_max_u32_e32 v22, v1, v9
	v_min_u32_e32 v9, v1, v9
	v_max_u32_e32 v24, v28, v2
	v_min_u32_e32 v2, v28, v2
	v_max_u32_e32 v214, v27, v213
	v_min_u32_e32 v213, v27, v213
	v_max_u32_e32 v1, v18, v26
	v_min_u32_e32 v26, v18, v26
	v_max_u32_e32 v28, v4, v12
	v_min_u32_e32 v12, v4, v12
	v_max_u32_e32 v27, v7, v15
	v_min_u32_e32 v15, v7, v15
	v_max_u32_e32 v18, v23, v31
	v_min_u32_e32 v31, v23, v31
	v_max_u32_e32 v4, v11, v0
	v_min_u32_e32 v0, v11, v0
	v_max_u32_e32 v7, v22, v3
	v_min_u32_e32 v3, v22, v3
	v_max_u32_e32 v23, v24, v14
	v_min_u32_e32 v14, v24, v14
	v_max_u32_e32 v11, v214, v29
	v_min_u32_e32 v29, v214, v29
	v_max_u32_e32 v22, v1, v10
	v_min_u32_e32 v10, v1, v10
	v_max_u32_e32 v24, v28, v13
	v_min_u32_e32 v13, v28, v13
	v_max_u32_e32 v214, v27, v30
	v_min_u32_e32 v30, v27, v30
	v_max_u32_e32 v1, v18, v19
	v_min_u32_e32 v19, v18, v19
	v_max_u32_e32 v28, v25, v4
	v_min_u32_e32 v4, v25, v4
	v_max_u32_e32 v27, v215, v7
	v_min_u32_e32 v7, v215, v7
	v_max_u32_e32 v18, v17, v23
	v_min_u32_e32 v23, v17, v23
	v_max_u32_e32 v25, v8, v11
	v_min_u32_e32 v11, v8, v11
	v_max_u32_e32 v215, v22, v0
	v_min_u32_e32 v0, v22, v0
	v_max_u32_e32 v17, v24, v3
	v_min_u32_e32 v3, v24, v3
	v_max_u32_e32 v8, v214, v14
	v_min_u32_e32 v14, v214, v14
	v_max_u32_e32 v22, v1, v29
	v_min_u32_e32 v29, v1, v29
	v_max_u32_e32 v24, v10, v6
	v_min_u32_e32 v6, v10, v6
	v_max_u32_e32 v214, v13, v9
	v_min_u32_e32 v9, v13, v9
	v_max_u32_e32 v1, v30, v2
	v_min_u32_e32 v2, v30, v2
	v_max_u32_e32 v10, v19, v213
	v_min_u32_e32 v213, v19, v213
	v_max_u32_e32 v13, v21, v28
	v_min_u32_e32 v28, v21, v28
	v_max_u32_e32 v30, v20, v27
	v_min_u32_e32 v27, v20, v27
	v_max_u32_e32 v19, v18, v4
	v_min_u32_e32 v4, v18, v4
	v_max_u32_e32 v21, v25, v7
	v_min_u32_e32 v7, v25, v7
	v_max_u32_e32 v20, v23, v215
	v_min_u32_e32 v215, v23, v215
	v_max_u32_e32 v18, v11, v17
	v_min_u32_e32 v17, v11, v17
	v_max_u32_e32 v25, v8, v0
	v_min_u32_e32 v0, v8, v0
	v_max_u32_e32 v23, v22, v3
	v_min_u32_e32 v3, v22, v3
	v_max_u32_e32 v11, v14, v24
	v_min_u32_e32 v24, v14, v24
	v_max_u32_e32 v8, v29, v214
	v_min_u32_e32 v214, v29, v214
	v_max_u32_e32 v22, v1, v6
	v_min_u32_e32 v6, v1, v6
	v_max_u32_e32 v14, v10, v9
	v_min_u32_e32 v9, v10, v9
	v_max_u32_e32 v29, v2, v26
	v_min_u32_e32 v26, v2, v26
	v_max_u32_e32 v1, v213, v12
	v_min_u32_e32 v12, v213, v12
	v_max_u32_e32 v51, v39, v15
	v_max_u32_e32 v37, v46, v26
	v_max_u32_e32 v35, v38, v29
	v_max_u32_e32 v41, v48, v6
	v_max_u32_e32 v39, v43, v22
	v_max_u32_e32 v46, v44, v24
	v_max_u32_e32 v38, v42, v11
	v_max_u32_e32 v48, v32, v0
	v_max_u32_e32 v43, v47, v25
	v_max_u32_e32 v44, v50, v215
	v_max_u32_e32 v42, v49, v20
	v_max_u32_e32 v32, v36, v4
	v_max_u32_e32 v47, v45, v19
	v_max_u32_e32 v50, v34, v28
	v_max_u32_e32 v49, v33, v13
	v_max_u32_e32 v36, v40, v5
	v_max_u32_e32 v45, v51, v43
	v_min_u32_e32 v43, v51, v43
	v_max_u32_e32 v34, v37, v44
	v_min_u32_e32 v44, v37, v44
	v_max_u32_e32 v33, v35, v42
	v_min_u32_e32 v42, v35, v42
	v_max_u32_e32 v40, v41, v32
	v_min_u32_e32 v32, v41, v32
	v_max_u32_e32 v51, v39, v47
	v_min_u32_e32 v47, v39, v47
	v_max_u32_e32 v37, v46, v50
	v_min_u32_e32 v50, v46, v50
	v_max_u32_e32 v35, v38, v49
	v_min_u32_e32 v49, v38, v49
	v_max_u32_e32 v41, v48, v36
	v_min_u32_e32 v36, v48, v36
	v_max_u32_e32 v39, v45, v51
	v_min_u32_e32 v51, v45, v51
	v_max_u32_e32 v46, v34, v37
	v_min_u32_e32 v37, v34, v37
	v_max_u32_e32 v38, v33, v35
	v_min_u32_e32 v35, v33, v35
	v_max_u32_e32 v48, v40, v41
	v_min_u32_e32 v41, v40, v41
	v_max_u32_e32 v45, v43, v47
	v_min_u32_e32 v47, v43, v47
	v_max_u32_e32 v34, v44, v50
	v_min_u32_e32 v50, v44, v50
	v_max_u32_e32 v33, v42, v49
	v_min_u32_e32 v49, v42, v49
	v_max_u32_e32 v40, v32, v36
	v_min_u32_e32 v36, v32, v36
	v_max_u32_e32 v43, v39, v38
	v_min_u32_e32 v38, v39, v38
	v_max_u32_e32 v44, v46, v48
	v_min_u32_e32 v48, v46, v48
	v_max_u32_e32 v42, v51, v35
	v_min_u32_e32 v35, v51, v35
	v_max_u32_e32 v32, v37, v41
	v_min_u32_e32 v41, v37, v41
	v_max_u32_e32 v39, v45, v33
	v_min_u32_e32 v33, v45, v33
	v_max_u32_e32 v46, v34, v40
	v_min_u32_e32 v40, v34, v40
	v_max_u32_e32 v51, v47, v49
; __device__ void ph_peer(const float* __restrict__ SC, const bf16_t* __restrict__ H  , const float* __restrict__ gffn, const unsigned char* __restrict__ U, const unsigned char* __restrict__ V, float* X, const float* __restrict__ fgain) {
;     ...
;             for (int it = 0; it < 16; ++it) {
; #pragma unroll
;                 for (int u = 0; u < 2; ++u) {
;                     const unsigned m0 = wave_max_u32(k00[u] > k01[u] ? k00[u] : k01[u]);
;                     const unsigned m1 = wave_max_u32(k10[u] > k11[u] ? k10[u] : k11[u]);
;                     if (lane == it) { top0[u] = m0; top1[u] = m1; }
;                     if (k00[u] == m0) k00[u] = 0u; if (k01[u] == m0) k01[u] = 0u;
;                     if (k10[u] == m1) k10[u] = 0u; if (k11[u] == m1) k11[u] = 0u; }
;             }
	v_min_u32_e32 v49, v47, v49
	v_max_u32_e32 v37, v50, v36
	v_min_u32_e32 v36, v50, v36
	v_max_u32_e32 v45, v43, v44
	v_min_u32_e32 v44, v43, v44
	v_max_u32_e32 v34, v38, v48
	v_min_u32_e32 v48, v38, v48
	v_max_u32_e32 v47, v42, v32
	v_min_u32_e32 v32, v42, v32
	v_max_u32_e32 v50, v35, v41
	v_min_u32_e32 v41, v35, v41
	v_max_u32_e32 v43, v39, v46
	v_min_u32_e32 v46, v39, v46
	v_max_u32_e32 v38, v33, v40
	v_min_u32_e32 v40, v33, v40
	v_max_u32_e32 v42, v51, v37
	v_min_u32_e32 v37, v51, v37
	v_max_u32_e32 v35, v49, v36
	v_min_u32_e32 v36, v49, v36
	v_max_u32_e32 v39, v45, v31
	v_max_u32_e32 v33, v44, v12
	v_max_u32_e32 v51, v34, v1
	v_max_u32_e32 v49, v48, v9
	v_max_u32_e32 v45, v47, v14
	v_max_u32_e32 v44, v32, v214
	v_max_u32_e32 v34, v50, v8
	v_max_u32_e32 v48, v41, v3
	v_max_u32_e32 v47, v43, v23
	v_max_u32_e32 v32, v46, v17
	v_max_u32_e32 v50, v38, v18
	v_max_u32_e32 v41, v40, v7
	v_max_u32_e32 v43, v42, v21
	v_max_u32_e32 v46, v37, v27
	v_max_u32_e32 v38, v35, v30
	v_max_u32_e32 v40, v36, v16
	v_max_u32_e32 v42, v39, v47
	v_min_u32_e32 v47, v39, v47
	v_max_u32_e32 v37, v33, v32
	v_min_u32_e32 v32, v33, v32
	v_max_u32_e32 v35, v51, v50
	v_min_u32_e32 v50, v51, v50
	v_max_u32_e32 v36, v49, v41
	v_min_u32_e32 v41, v49, v41
	v_max_u32_e32 v39, v45, v43
	v_min_u32_e32 v43, v45, v43
	v_max_u32_e32 v33, v44, v46
	v_min_u32_e32 v46, v44, v46
	v_max_u32_e32 v51, v34, v38
	v_min_u32_e32 v38, v34, v38
	v_max_u32_e32 v49, v48, v40
	v_min_u32_e32 v40, v48, v40
	v_max_u32_e32 v45, v42, v39
	v_min_u32_e32 v39, v42, v39
	v_max_u32_e32 v44, v37, v33
	v_min_u32_e32 v33, v37, v33
	v_max_u32_e32 v34, v35, v51
	v_min_u32_e32 v51, v35, v51
	v_max_u32_e32 v48, v36, v49
	v_min_u32_e32 v49, v36, v49
	v_max_u32_e32 v42, v47, v43
	v_min_u32_e32 v43, v47, v43
	v_max_u32_e32 v37, v32, v46
	v_min_u32_e32 v46, v32, v46
	v_max_u32_e32 v35, v50, v38
	v_min_u32_e32 v38, v50, v38
	v_max_u32_e32 v36, v41, v40
	v_min_u32_e32 v40, v41, v40
	v_max_u32_e32 v47, v45, v34
	v_min_u32_e32 v34, v45, v34
	v_max_u32_e32 v32, v44, v48
	v_min_u32_e32 v48, v44, v48
	v_max_u32_e32 v50, v39, v51
	v_min_u32_e32 v51, v39, v51
	v_max_u32_e32 v41, v33, v49
	v_min_u32_e32 v49, v33, v49
	v_max_u32_e32 v45, v42, v35
	v_min_u32_e32 v35, v42, v35
	v_max_u32_e32 v44, v37, v36
	v_min_u32_e32 v36, v37, v36
	v_max_u32_e32 v39, v43, v38
	v_min_u32_e32 v38, v43, v38
	v_max_u32_e32 v33, v46, v40
	v_min_u32_e32 v40, v46, v40
	v_max_u32_e32 v42, v47, v32
	v_min_u32_e32 v32, v47, v32
	v_max_u32_e32 v37, v34, v48
	v_min_u32_e32 v48, v34, v48
	v_max_u32_e32 v43, v50, v41
	v_min_u32_e32 v41, v50, v41
	v_max_u32_e32 v46, v51, v49
	v_min_u32_e32 v49, v51, v49
	v_max_u32_e32 v47, v45, v44
	v_min_u32_e32 v44, v45, v44
	v_max_u32_e32 v34, v35, v36
	v_min_u32_e32 v36, v35, v36
	v_max_u32_e32 v50, v39, v33
	v_min_u32_e32 v33, v39, v33
	v_max_u32_e32 v51, v38, v40
	v_min_u32_e32 v40, v38, v40
	v_mov_b32_e32 v217, v216
	global_load_dwordx4 v[52:55], v217, s[28:29] offset:896
	v_add_u32_e32 v157, s36, v217
	global_load_dwordx4 v[56:59], v157, s[28:29] offset:896
	v_add_u32_e32 v217, s36, v157
	global_load_dwordx4 v[60:63], v217, s[28:29] offset:896
	v_add_u32_e32 v157, s36, v217
	global_load_dwordx4 v[112:115], v157, s[28:29] offset:896
	v_add_u32_e32 v217, s36, v157
	global_load_dwordx4 v[116:119], v217, s[28:29] offset:896
	v_add_u32_e32 v157, s36, v217
	global_load_dwordx4 v[120:123], v157, s[28:29] offset:896
	v_add_u32_e32 v217, s36, v157
	global_load_dwordx4 v[124:127], v217, s[28:29] offset:896
	v_add_u32_e32 v157, s36, v217
	global_load_dwordx4 v[158:161], v157, s[28:29] offset:896
	s_waitcnt vmcnt(8)
	ds_write_b128 v144, v[180:183] offset:0
	ds_write_b128 v144, v[184:187] offset:1152
	ds_write_b128 v144, v[188:191] offset:2304
	ds_write_b128 v144, v[192:195] offset:3456
	ds_write_b128 v144, v[196:199] offset:4608
	ds_write_b128 v144, v[200:203] offset:5760
	ds_write_b128 v144, v[204:207] offset:6912
	ds_write_b128 v144, v[208:211] offset:8064
	ds_read_b128 v[0:3], v145 offset:0
	ds_read_b128 v[4:7], v145 offset:16
	ds_read_b128 v[8:11], v145 offset:32
	ds_read_b128 v[12:15], v145 offset:48
	ds_read_b128 v[16:19], v145 offset:64
	ds_read_b128 v[20:23], v145 offset:80
	ds_read_b128 v[24:27], v145 offset:96
	ds_read_b128 v[28:31], v145 offset:112
	s_waitcnt lgkmcnt(0)
; __device__ __forceinline__ unsigned f2key(float f) { const unsigned u = __float_as_uint(f); return (u & 0x80000000u) ? ~u : (u | 0x80000000u); }
; __device__ void ph_peer(const float* __restrict__ SC, const bf16_t* __restrict__ H  , const float* __restrict__ gffn, const unsigned char* __restrict__ U, const unsigned char* __restrict__ V, float* X, const float* __restrict__ fgain) {
;     ...
;             for (int u = 0; u < 2; ++u) { const float* sc = SC + (size_t)tok * 2048 + (h + u) * 256;
;                 const float2 a0 = ((const float2*)sc)[lane], a1 = ((const float2*)(sc + 128))[lane];
;                 k00[u] = (f2key(a0.x) & ~127u) | (unsigned)(127 - 2 * lane); k01[u] = (f2key(a0.y) & ~127u) | (unsigned)(126 - 2 * lane);
;                 k10[u] = (f2key(a1.x) & ~127u) | (unsigned)(127 - 2 * lane); k11[u] = (f2key(a1.y) & ~127u) | (unsigned)(126 - 2 * lane);
;     ...
;             for (int it = 0; it < 16; ++it) {
; #pragma unroll
;                 for (int u = 0; u < 2; ++u) {
;                     const unsigned m0 = wave_max_u32(k00[u] > k01[u] ? k00[u] : k01[u]);
;                     const unsigned m1 = wave_max_u32(k10[u] > k11[u] ? k10[u] : k11[u]);
;                     if (lane == it) { top0[u] = m0; top1[u] = m1; }
;                     if (k00[u] == m0) k00[u] = 0u; if (k01[u] == m0) k01[u] = 0u;
;                     if (k10[u] == m1) k10[u] = 0u; if (k11[u] == m1) k11[u] = 0u; }
;             }
	v_ashrrev_i32_e32 v212, 31, v0
	v_or_b32_e32 v212, 0x80000000, v212
	v_xor_b32_e32 v0, v0, v212
	v_and_or_b32 v0, v0, s30, 63
	v_ashrrev_i32_e32 v212, 31, v1
	v_or_b32_e32 v212, 0x80000000, v212
	v_xor_b32_e32 v1, v1, v212
	v_and_or_b32 v1, v1, s30, 62
	v_ashrrev_i32_e32 v212, 31, v2
	v_or_b32_e32 v212, 0x80000000, v212
	v_xor_b32_e32 v2, v2, v212
	v_and_or_b32 v2, v2, s30, 61
	v_ashrrev_i32_e32 v212, 31, v3
	v_or_b32_e32 v212, 0x80000000, v212
	v_xor_b32_e32 v3, v3, v212
	v_and_or_b32 v3, v3, s30, 60
	v_ashrrev_i32_e32 v212, 31, v4
	v_or_b32_e32 v212, 0x80000000, v212
	v_xor_b32_e32 v4, v4, v212
	v_and_or_b32 v4, v4, s30, 59
	v_ashrrev_i32_e32 v212, 31, v5
	v_or_b32_e32 v212, 0x80000000, v212
	v_xor_b32_e32 v5, v5, v212
	v_and_or_b32 v5, v5, s30, 58
	v_ashrrev_i32_e32 v212, 31, v6
	v_or_b32_e32 v212, 0x80000000, v212
	v_xor_b32_e32 v6, v6, v212
	v_and_or_b32 v6, v6, s30, 57
	v_ashrrev_i32_e32 v212, 31, v7
	v_or_b32_e32 v212, 0x80000000, v212
	v_xor_b32_e32 v7, v7, v212
	v_and_or_b32 v7, v7, s30, 56
	v_ashrrev_i32_e32 v212, 31, v8
	v_or_b32_e32 v212, 0x80000000, v212
	v_xor_b32_e32 v8, v8, v212
	v_and_or_b32 v8, v8, s30, 55
	v_ashrrev_i32_e32 v212, 31, v9
	v_or_b32_e32 v212, 0x80000000, v212
	v_xor_b32_e32 v9, v9, v212
	v_and_or_b32 v9, v9, s30, 54
	v_ashrrev_i32_e32 v212, 31, v10
	v_or_b32_e32 v212, 0x80000000, v212
	v_xor_b32_e32 v10, v10, v212
	v_and_or_b32 v10, v10, s30, 53
	v_ashrrev_i32_e32 v212, 31, v11
	v_or_b32_e32 v212, 0x80000000, v212
	v_xor_b32_e32 v11, v11, v212
	v_and_or_b32 v11, v11, s30, 52
	v_ashrrev_i32_e32 v212, 31, v12
	v_or_b32_e32 v212, 0x80000000, v212
	v_xor_b32_e32 v12, v12, v212
	v_and_or_b32 v12, v12, s30, 51
	v_ashrrev_i32_e32 v212, 31, v13
	v_or_b32_e32 v212, 0x80000000, v212
	v_xor_b32_e32 v13, v13, v212
	v_and_or_b32 v13, v13, s30, 50
	v_ashrrev_i32_e32 v212, 31, v14
	v_or_b32_e32 v212, 0x80000000, v212
	v_xor_b32_e32 v14, v14, v212
	v_and_or_b32 v14, v14, s30, 49
	v_ashrrev_i32_e32 v212, 31, v15
	v_or_b32_e32 v212, 0x80000000, v212
	v_xor_b32_e32 v15, v15, v212
	v_and_or_b32 v15, v15, s30, 48
	v_ashrrev_i32_e32 v212, 31, v16
	v_or_b32_e32 v212, 0x80000000, v212
	v_xor_b32_e32 v16, v16, v212
	v_and_or_b32 v16, v16, s30, 47
	v_ashrrev_i32_e32 v212, 31, v17
	v_or_b32_e32 v212, 0x80000000, v212
	v_xor_b32_e32 v17, v17, v212
	v_and_or_b32 v17, v17, s30, 46
	v_ashrrev_i32_e32 v212, 31, v18
	v_or_b32_e32 v212, 0x80000000, v212
	v_xor_b32_e32 v18, v18, v212
	v_and_or_b32 v18, v18, s30, 45
	v_ashrrev_i32_e32 v212, 31, v19
	v_or_b32_e32 v212, 0x80000000, v212
	v_xor_b32_e32 v19, v19, v212
	v_and_or_b32 v19, v19, s30, 44
	v_ashrrev_i32_e32 v212, 31, v20
	v_or_b32_e32 v212, 0x80000000, v212
	v_xor_b32_e32 v20, v20, v212
	v_and_or_b32 v20, v20, s30, 43
	v_ashrrev_i32_e32 v212, 31, v21
	v_or_b32_e32 v212, 0x80000000, v212
	v_xor_b32_e32 v21, v21, v212
	v_and_or_b32 v21, v21, s30, 42
	v_ashrrev_i32_e32 v212, 31, v22
	v_or_b32_e32 v212, 0x80000000, v212
	v_xor_b32_e32 v22, v22, v212
	v_and_or_b32 v22, v22, s30, 41
	v_ashrrev_i32_e32 v212, 31, v23
	v_or_b32_e32 v212, 0x80000000, v212
	v_xor_b32_e32 v23, v23, v212
	v_and_or_b32 v23, v23, s30, 40
	v_ashrrev_i32_e32 v212, 31, v24
	v_or_b32_e32 v212, 0x80000000, v212
	v_xor_b32_e32 v24, v24, v212
	v_and_or_b32 v24, v24, s30, 39
	v_ashrrev_i32_e32 v212, 31, v25
	v_or_b32_e32 v212, 0x80000000, v212
	v_xor_b32_e32 v25, v25, v212
	v_and_or_b32 v25, v25, s30, 38
	v_ashrrev_i32_e32 v212, 31, v26
	v_or_b32_e32 v212, 0x80000000, v212
	v_xor_b32_e32 v26, v26, v212
	v_and_or_b32 v26, v26, s30, 37
	v_ashrrev_i32_e32 v212, 31, v27
	v_or_b32_e32 v212, 0x80000000, v212
	v_xor_b32_e32 v27, v27, v212
	v_and_or_b32 v27, v27, s30, 36
	v_ashrrev_i32_e32 v212, 31, v28
	v_or_b32_e32 v212, 0x80000000, v212
	v_xor_b32_e32 v28, v28, v212
	v_and_or_b32 v28, v28, s30, 35
	v_ashrrev_i32_e32 v212, 31, v29
	v_or_b32_e32 v212, 0x80000000, v212
	v_xor_b32_e32 v29, v29, v212
	v_and_or_b32 v29, v29, s30, 34
	v_ashrrev_i32_e32 v212, 31, v30
	v_or_b32_e32 v212, 0x80000000, v212
	v_xor_b32_e32 v30, v30, v212
	v_and_or_b32 v30, v30, s30, 33
	v_ashrrev_i32_e32 v212, 31, v31
	v_or_b32_e32 v212, 0x80000000, v212
	v_xor_b32_e32 v31, v31, v212
	v_and_or_b32 v31, v31, s30, 32
	v_max_u32_e32 v215, v0, v1
	v_min_u32_e32 v1, v0, v1
	v_max_u32_e32 v214, v16, v17
	v_min_u32_e32 v17, v16, v17
	v_max_u32_e32 v213, v2, v3
	v_min_u32_e32 v3, v2, v3
	v_max_u32_e32 v0, v18, v19
	v_min_u32_e32 v19, v18, v19
	v_max_u32_e32 v16, v4, v5
	v_min_u32_e32 v5, v4, v5
	v_max_u32_e32 v2, v20, v21
	v_min_u32_e32 v21, v20, v21
	v_max_u32_e32 v18, v6, v7
	v_min_u32_e32 v7, v6, v7
	v_max_u32_e32 v4, v22, v23
	v_min_u32_e32 v23, v22, v23
	v_max_u32_e32 v20, v8, v9
	v_min_u32_e32 v9, v8, v9
	v_max_u32_e32 v6, v24, v25
	v_min_u32_e32 v25, v24, v25
	v_max_u32_e32 v22, v10, v11
	v_min_u32_e32 v11, v10, v11
	v_max_u32_e32 v8, v26, v27
	v_min_u32_e32 v27, v26, v27
	v_max_u32_e32 v24, v12, v13
	v_min_u32_e32 v13, v12, v13
	v_max_u32_e32 v10, v28, v29
	v_min_u32_e32 v29, v28, v29
	v_max_u32_e32 v26, v14, v15
	v_min_u32_e32 v15, v14, v15
	v_max_u32_e32 v12, v30, v31
	v_min_u32_e32 v31, v30, v31
	v_max_u32_e32 v28, v215, v213
	v_min_u32_e32 v213, v215, v213
	v_max_u32_e32 v14, v214, v0
	v_min_u32_e32 v0, v214, v0
	v_max_u32_e32 v30, v1, v3
	v_min_u32_e32 v3, v1, v3
	v_max_u32_e32 v215, v17, v19
	v_min_u32_e32 v19, v17, v19
	v_max_u32_e32 v214, v16, v18
	v_min_u32_e32 v18, v16, v18
	v_max_u32_e32 v1, v2, v4
	v_min_u32_e32 v4, v2, v4
	v_max_u32_e32 v17, v5, v7
	v_min_u32_e32 v7, v5, v7
	v_max_u32_e32 v16, v21, v23
	v_min_u32_e32 v23, v21, v23
	v_max_u32_e32 v2, v20, v22
	v_min_u32_e32 v22, v20, v22
	v_max_u32_e32 v5, v6, v8
	v_min_u32_e32 v8, v6, v8
; __device__ void ph_peer(const float* __restrict__ SC, const bf16_t* __restrict__ H  , const float* __restrict__ gffn, const unsigned char* __restrict__ U, const unsigned char* __restrict__ V, float* X, const float* __restrict__ fgain) {
;     ...
;             for (int it = 0; it < 16; ++it) {
; #pragma unroll
;                 for (int u = 0; u < 2; ++u) {
;                     const unsigned m0 = wave_max_u32(k00[u] > k01[u] ? k00[u] : k01[u]);
;                     const unsigned m1 = wave_max_u32(k10[u] > k11[u] ? k10[u] : k11[u]);
;                     if (lane == it) { top0[u] = m0; top1[u] = m1; }
;                     if (k00[u] == m0) k00[u] = 0u; if (k01[u] == m0) k01[u] = 0u;
;                     if (k10[u] == m1) k10[u] = 0u; if (k11[u] == m1) k11[u] = 0u; }
;             }
	v_max_u32_e32 v21, v9, v11
	v_min_u32_e32 v11, v9, v11
	v_max_u32_e32 v20, v25, v27
	v_min_u32_e32 v27, v25, v27
	v_max_u32_e32 v6, v24, v26
	v_min_u32_e32 v26, v24, v26
	v_max_u32_e32 v9, v10, v12
	v_min_u32_e32 v12, v10, v12
	v_max_u32_e32 v25, v13, v15
	v_min_u32_e32 v15, v13, v15
	v_max_u32_e32 v24, v29, v31
	v_min_u32_e32 v31, v29, v31
	v_max_u32_e32 v10, v30, v213
	v_min_u32_e32 v213, v30, v213
	v_max_u32_e32 v13, v215, v0
	v_min_u32_e32 v0, v215, v0
	v_max_u32_e32 v29, v17, v18
	v_min_u32_e32 v18, v17, v18
	v_max_u32_e32 v30, v16, v4
	v_min_u32_e32 v4, v16, v4
	v_max_u32_e32 v215, v21, v22
	v_min_u32_e32 v22, v21, v22
	v_max_u32_e32 v17, v20, v8
	v_min_u32_e32 v8, v20, v8
	v_max_u32_e32 v16, v25, v26
	v_min_u32_e32 v26, v25, v26
	v_max_u32_e32 v21, v24, v12
	v_min_u32_e32 v12, v24, v12
	v_max_u32_e32 v20, v28, v214
	v_min_u32_e32 v214, v28, v214
	v_max_u32_e32 v25, v14, v1
	v_min_u32_e32 v1, v14, v1
	v_max_u32_e32 v24, v10, v29
	v_min_u32_e32 v29, v10, v29
	v_max_u32_e32 v28, v13, v30
	v_min_u32_e32 v30, v13, v30
	v_max_u32_e32 v14, v213, v18
	v_min_u32_e32 v18, v213, v18
	v_max_u32_e32 v10, v0, v4
	v_min_u32_e32 v4, v0, v4
	v_max_u32_e32 v13, v3, v7
	v_min_u32_e32 v7, v3, v7
	v_max_u32_e32 v213, v19, v23
	v_min_u32_e32 v23, v19, v23
	v_max_u32_e32 v0, v2, v6
	v_min_u32_e32 v6, v2, v6
	v_max_u32_e32 v3, v5, v9
	v_min_u32_e32 v9, v5, v9
	v_max_u32_e32 v19, v215, v16
	v_min_u32_e32 v16, v215, v16
	v_max_u32_e32 v2, v17, v21
	v_min_u32_e32 v21, v17, v21
	v_max_u32_e32 v5, v22, v26
	v_min_u32_e32 v26, v22, v26
	v_max_u32_e32 v215, v8, v12
	v_min_u32_e32 v12, v8, v12
	v_max_u32_e32 v17, v11, v15
	v_min_u32_e32 v15, v11, v15
	v_max_u32_e32 v22, v27, v31
	v_min_u32_e32 v31, v27, v31
	v_max_u32_e32 v8, v14, v214
	v_min_u32_e32 v214, v14, v214
	v_max_u32_e32 v11, v10, v1
	v_min_u32_e32 v1, v10, v1
	v_max_u32_e32 v27, v13, v29
	v_min_u32_e32 v29, v13, v29
	v_max_u32_e32 v14, v213, v30
	v_min_u32_e32 v30, v213, v30
	v_max_u32_e32 v10, v5, v6
	v_min_u32_e32 v6, v5, v6
	v_max_u32_e32 v13, v215, v9
	v_min_u32_e32 v9, v215, v9
	v_max_u32_e32 v213, v17, v16
	v_min_u32_e32 v16, v17, v16
	v_max_u32_e32 v5, v22, v21
	v_min_u32_e32 v21, v22, v21
	v_max_u32_e32 v215, v24, v8
	v_min_u32_e32 v8, v24, v8
	v_max_u32_e32 v17, v28, v11
	v_min_u32_e32 v11, v28, v11
	v_max_u32_e32 v22, v27, v214
	v_min_u32_e32 v214, v27, v214
	v_max_u32_e32 v24, v14, v1
	v_min_u32_e32 v1, v14, v1
	v_max_u32_e32 v28, v29, v18
	v_min_u32_e32 v18, v29, v18
	v_max_u32_e32 v27, v30, v4
	v_min_u32_e32 v4, v30, v4
	v_max_u32_e32 v14, v19, v10
	v_min_u32_e32 v10, v19, v10
	v_max_u32_e32 v29, v2, v13
	v_min_u32_e32 v13, v2, v13
	v_max_u32_e32 v30, v213, v6
	v_min_u32_e32 v6, v213, v6
	v_max_u32_e32 v19, v5, v9
	v_min_u32_e32 v9, v5, v9
	v_max_u32_e32 v2, v16, v26
	v_min_u32_e32 v26, v16, v26
	v_max_u32_e32 v213, v21, v12
	v_min_u32_e32 v12, v21, v12
	v_max_u32_e32 v5, v20, v0
	v_min_u32_e32 v0, v20, v0
	v_max_u32_e32 v16, v25, v3
	v_min_u32_e32 v3, v25, v3
	v_max_u32_e32 v21, v215, v14
	v_min_u32_e32 v14, v215, v14
	v_max_u32_e32 v20, v17, v29
	v_min_u32_e32 v29, v17, v29
	v_max_u32_e32 v25, v8, v10
	v_min_u32_e32 v10, v8, v10
	v_max_u32_e32 v215, v11, v13
	v_min_u32_e32 v13, v11, v13
	v_max_u32_e32 v17, v22, v30
	v_min_u32_e32 v30, v22, v30
	v_max_u32_e32 v8, v24, v19
	v_min_u32_e32 v19, v24, v19
	v_max_u32_e32 v11, v214, v6
	v_min_u32_e32 v6, v214, v6
	v_max_u32_e32 v22, v1, v9
	v_min_u32_e32 v9, v1, v9
	v_max_u32_e32 v24, v28, v2
	v_min_u32_e32 v2, v28, v2
	v_max_u32_e32 v214, v27, v213
	v_min_u32_e32 v213, v27, v213
	v_max_u32_e32 v1, v18, v26
	v_min_u32_e32 v26, v18, v26
	v_max_u32_e32 v28, v4, v12
	v_min_u32_e32 v12, v4, v12
	v_max_u32_e32 v27, v7, v15
	v_min_u32_e32 v15, v7, v15
	v_max_u32_e32 v18, v23, v31
	v_min_u32_e32 v31, v23, v31
	v_max_u32_e32 v4, v11, v0
	v_min_u32_e32 v0, v11, v0
	v_max_u32_e32 v7, v22, v3
	v_min_u32_e32 v3, v22, v3
	v_max_u32_e32 v23, v24, v14
	v_min_u32_e32 v14, v24, v14
	v_max_u32_e32 v11, v214, v29
	v_min_u32_e32 v29, v214, v29
	v_max_u32_e32 v22, v1, v10
	v_min_u32_e32 v10, v1, v10
	v_max_u32_e32 v24, v28, v13
	v_min_u32_e32 v13, v28, v13
	v_max_u32_e32 v214, v27, v30
	v_min_u32_e32 v30, v27, v30
	v_max_u32_e32 v1, v18, v19
	v_min_u32_e32 v19, v18, v19
	v_max_u32_e32 v28, v25, v4
	v_min_u32_e32 v4, v25, v4
	v_max_u32_e32 v27, v215, v7
	v_min_u32_e32 v7, v215, v7
	v_max_u32_e32 v18, v17, v23
	v_min_u32_e32 v23, v17, v23
	v_max_u32_e32 v25, v8, v11
	v_min_u32_e32 v11, v8, v11
	v_max_u32_e32 v215, v22, v0
	v_min_u32_e32 v0, v22, v0
	v_max_u32_e32 v17, v24, v3
	v_min_u32_e32 v3, v24, v3
	v_max_u32_e32 v8, v214, v14
	v_min_u32_e32 v14, v214, v14
	v_max_u32_e32 v22, v1, v29
	v_min_u32_e32 v29, v1, v29
	v_max_u32_e32 v24, v10, v6
	v_min_u32_e32 v6, v10, v6
	v_max_u32_e32 v214, v13, v9
	v_min_u32_e32 v9, v13, v9
	v_max_u32_e32 v1, v30, v2
	v_min_u32_e32 v2, v30, v2
	v_max_u32_e32 v10, v19, v213
	v_min_u32_e32 v213, v19, v213
	v_max_u32_e32 v13, v21, v28
	v_min_u32_e32 v28, v21, v28
	v_max_u32_e32 v30, v20, v27
	v_min_u32_e32 v27, v20, v27
	v_max_u32_e32 v19, v18, v4
	v_min_u32_e32 v4, v18, v4
	v_max_u32_e32 v21, v25, v7
	v_min_u32_e32 v7, v25, v7
	v_max_u32_e32 v20, v23, v215
	v_min_u32_e32 v215, v23, v215
	v_max_u32_e32 v18, v11, v17
	v_min_u32_e32 v17, v11, v17
	v_max_u32_e32 v25, v8, v0
	v_min_u32_e32 v0, v8, v0
	v_max_u32_e32 v23, v22, v3
	v_min_u32_e32 v3, v22, v3
	v_max_u32_e32 v11, v14, v24
	v_min_u32_e32 v24, v14, v24
	v_max_u32_e32 v8, v29, v214
	v_min_u32_e32 v214, v29, v214
	v_max_u32_e32 v22, v1, v6
	v_min_u32_e32 v6, v1, v6
	v_max_u32_e32 v14, v10, v9
	v_min_u32_e32 v9, v10, v9
	v_max_u32_e32 v29, v2, v26
	v_min_u32_e32 v26, v2, v26
; __device__ void ph_peer(const float* __restrict__ SC, const bf16_t* __restrict__ H  , const float* __restrict__ gffn, const unsigned char* __restrict__ U, const unsigned char* __restrict__ V, float* X, const float* __restrict__ fgain) {
;     ...
;             for (int it = 0; it < 16; ++it) {
; #pragma unroll
;                 for (int u = 0; u < 2; ++u) {
;                     const unsigned m0 = wave_max_u32(k00[u] > k01[u] ? k00[u] : k01[u]);
;                     const unsigned m1 = wave_max_u32(k10[u] > k11[u] ? k10[u] : k11[u]);
;                     if (lane == it) { top0[u] = m0; top1[u] = m1; }
;                     if (k00[u] == m0) k00[u] = 0u; if (k01[u] == m0) k01[u] = 0u;
;                     if (k10[u] == m1) k10[u] = 0u; if (k11[u] == m1) k11[u] = 0u; }
;             }
	v_max_u32_e32 v1, v213, v12
	v_min_u32_e32 v12, v213, v12
	v_max_u32_e32 v45, v42, v15
	v_max_u32_e32 v35, v32, v26
	v_max_u32_e32 v39, v37, v29
	v_max_u32_e32 v38, v48, v6
	v_max_u32_e32 v42, v43, v22
	v_max_u32_e32 v32, v41, v24
	v_max_u32_e32 v37, v46, v11
	v_max_u32_e32 v48, v49, v0
	v_max_u32_e32 v43, v47, v25
	v_max_u32_e32 v41, v44, v215
	v_max_u32_e32 v46, v34, v20
	v_max_u32_e32 v49, v36, v4
	v_max_u32_e32 v47, v50, v19
	v_max_u32_e32 v44, v33, v28
	v_max_u32_e32 v34, v51, v13
	v_max_u32_e32 v36, v40, v5
	v_max_u32_e32 v50, v45, v43
	v_min_u32_e32 v43, v45, v43
	v_max_u32_e32 v33, v35, v41
	v_min_u32_e32 v41, v35, v41
	v_max_u32_e32 v51, v39, v46
	v_min_u32_e32 v46, v39, v46
	v_max_u32_e32 v40, v38, v49
	v_min_u32_e32 v49, v38, v49
	v_max_u32_e32 v45, v42, v47
	v_min_u32_e32 v47, v42, v47
	v_max_u32_e32 v35, v32, v44
	v_min_u32_e32 v44, v32, v44
	v_max_u32_e32 v39, v37, v34
	v_min_u32_e32 v34, v37, v34
	v_max_u32_e32 v38, v48, v36
	v_min_u32_e32 v36, v48, v36
	v_max_u32_e32 v42, v50, v45
	v_min_u32_e32 v45, v50, v45
	v_max_u32_e32 v32, v33, v35
	v_min_u32_e32 v35, v33, v35
	v_max_u32_e32 v37, v51, v39
	v_min_u32_e32 v39, v51, v39
	v_max_u32_e32 v48, v40, v38
	v_min_u32_e32 v38, v40, v38
	v_max_u32_e32 v50, v43, v47
	v_min_u32_e32 v47, v43, v47
	v_max_u32_e32 v33, v41, v44
	v_min_u32_e32 v44, v41, v44
	v_max_u32_e32 v51, v46, v34
	v_min_u32_e32 v34, v46, v34
	v_max_u32_e32 v40, v49, v36
	v_min_u32_e32 v36, v49, v36
	v_max_u32_e32 v43, v42, v37
	v_min_u32_e32 v37, v42, v37
	v_max_u32_e32 v41, v32, v48
	v_min_u32_e32 v48, v32, v48
	v_max_u32_e32 v46, v45, v39
	v_min_u32_e32 v39, v45, v39
	v_max_u32_e32 v49, v35, v38
	v_min_u32_e32 v38, v35, v38
	v_max_u32_e32 v42, v50, v51
	v_min_u32_e32 v51, v50, v51
	v_max_u32_e32 v32, v33, v40
	v_min_u32_e32 v40, v33, v40
	v_max_u32_e32 v45, v47, v34
	v_min_u32_e32 v34, v47, v34
	v_max_u32_e32 v35, v44, v36
	v_min_u32_e32 v36, v44, v36
	v_max_u32_e32 v50, v43, v41
	v_min_u32_e32 v41, v43, v41
	v_max_u32_e32 v33, v37, v48
	v_min_u32_e32 v48, v37, v48
	v_max_u32_e32 v47, v46, v49
	v_min_u32_e32 v49, v46, v49
	v_max_u32_e32 v44, v39, v38
	v_min_u32_e32 v38, v39, v38
	v_max_u32_e32 v43, v42, v32
	v_min_u32_e32 v32, v42, v32
	v_max_u32_e32 v37, v51, v40
	v_min_u32_e32 v40, v51, v40
	v_max_u32_e32 v46, v45, v35
	v_min_u32_e32 v35, v45, v35
	v_max_u32_e32 v39, v34, v36
	v_min_u32_e32 v36, v34, v36
	v_max_u32_e32 v42, v50, v31
	v_max_u32_e32 v51, v41, v12
	v_max_u32_e32 v45, v33, v1
	v_max_u32_e32 v34, v48, v9
	v_max_u32_e32 v50, v47, v14
	v_max_u32_e32 v41, v49, v214
	v_max_u32_e32 v33, v44, v8
	v_max_u32_e32 v48, v38, v3
	v_max_u32_e32 v47, v43, v23
	v_max_u32_e32 v49, v32, v17
	v_max_u32_e32 v44, v37, v18
	v_max_u32_e32 v38, v40, v7
	v_max_u32_e32 v43, v46, v21
	v_max_u32_e32 v32, v35, v27
	v_max_u32_e32 v37, v39, v30
	v_max_u32_e32 v40, v36, v16
	v_max_u32_e32 v46, v42, v47
	v_min_u32_e32 v47, v42, v47
	v_max_u32_e32 v35, v51, v49
	v_min_u32_e32 v49, v51, v49
	v_max_u32_e32 v39, v45, v44
	v_min_u32_e32 v44, v45, v44
	v_max_u32_e32 v36, v34, v38
	v_min_u32_e32 v38, v34, v38
	v_max_u32_e32 v42, v50, v43
	v_min_u32_e32 v43, v50, v43
	v_max_u32_e32 v51, v41, v32
	v_min_u32_e32 v32, v41, v32
	v_max_u32_e32 v45, v33, v37
	v_min_u32_e32 v37, v33, v37
	v_max_u32_e32 v34, v48, v40
	v_min_u32_e32 v40, v48, v40
	v_max_u32_e32 v50, v46, v42
	v_min_u32_e32 v42, v46, v42
	v_max_u32_e32 v41, v35, v51
	v_min_u32_e32 v51, v35, v51
	v_max_u32_e32 v33, v39, v45
	v_min_u32_e32 v45, v39, v45
	v_max_u32_e32 v48, v36, v34
	v_min_u32_e32 v34, v36, v34
	v_max_u32_e32 v46, v47, v43
	v_min_u32_e32 v43, v47, v43
	v_max_u32_e32 v35, v49, v32
	v_min_u32_e32 v32, v49, v32
	v_max_u32_e32 v39, v44, v37
	v_min_u32_e32 v37, v44, v37
	v_max_u32_e32 v36, v38, v40
	v_min_u32_e32 v40, v38, v40
	v_max_u32_e32 v47, v50, v33
	v_min_u32_e32 v33, v50, v33
	v_max_u32_e32 v49, v41, v48
	v_min_u32_e32 v48, v41, v48
	v_max_u32_e32 v44, v42, v45
	v_min_u32_e32 v45, v42, v45
	v_max_u32_e32 v38, v51, v34
	v_min_u32_e32 v34, v51, v34
	v_max_u32_e32 v50, v46, v39
	v_min_u32_e32 v39, v46, v39
	v_max_u32_e32 v41, v35, v36
	v_min_u32_e32 v36, v35, v36
	v_max_u32_e32 v42, v43, v37
	v_min_u32_e32 v37, v43, v37
	v_max_u32_e32 v51, v32, v40
	v_min_u32_e32 v40, v32, v40
	v_max_u32_e32 v46, v47, v49
	v_min_u32_e32 v49, v47, v49
	v_max_u32_e32 v35, v33, v48
	v_min_u32_e32 v48, v33, v48
	v_max_u32_e32 v43, v44, v38
	v_min_u32_e32 v38, v44, v38
	v_max_u32_e32 v32, v45, v34
	v_min_u32_e32 v34, v45, v34
	v_max_u32_e32 v47, v50, v41
	v_min_u32_e32 v41, v50, v41
	v_max_u32_e32 v33, v39, v36
	v_min_u32_e32 v36, v39, v36
	v_max_u32_e32 v44, v42, v51
	v_min_u32_e32 v51, v42, v51
	v_max_u32_e32 v45, v37, v40
	v_min_u32_e32 v40, v37, v40
	s_waitcnt vmcnt(0)
	ds_write_b128 v144, v[52:55] offset:0
	ds_write_b128 v144, v[56:59] offset:1152
	ds_write_b128 v144, v[60:63] offset:2304
	ds_write_b128 v144, v[112:115] offset:3456
	ds_write_b128 v144, v[116:119] offset:4608
	ds_write_b128 v144, v[120:123] offset:5760
	ds_write_b128 v144, v[124:127] offset:6912
	ds_write_b128 v144, v[158:161] offset:8064
	ds_read_b128 v[0:3], v145 offset:0
	ds_read_b128 v[4:7], v145 offset:16
	ds_read_b128 v[8:11], v145 offset:32
	ds_read_b128 v[12:15], v145 offset:48
	ds_read_b128 v[16:19], v145 offset:64
	ds_read_b128 v[20:23], v145 offset:80
	ds_read_b128 v[24:27], v145 offset:96
	ds_read_b128 v[28:31], v145 offset:112
	s_waitcnt lgkmcnt(0)
; __device__ __forceinline__ unsigned f2key(float f) { const unsigned u = __float_as_uint(f); return (u & 0x80000000u) ? ~u : (u | 0x80000000u); }
; __device__ void ph_peer(const float* __restrict__ SC, const bf16_t* __restrict__ H  , const float* __restrict__ gffn, const unsigned char* __restrict__ U, const unsigned char* __restrict__ V, float* X, const float* __restrict__ fgain) {
;     ...
;             for (int u = 0; u < 2; ++u) { const float* sc = SC + (size_t)tok * 2048 + (h + u) * 256;
;                 const float2 a0 = ((const float2*)sc)[lane], a1 = ((const float2*)(sc + 128))[lane];
;                 k00[u] = (f2key(a0.x) & ~127u) | (unsigned)(127 - 2 * lane); k01[u] = (f2key(a0.y) & ~127u) | (unsigned)(126 - 2 * lane);
;                 k10[u] = (f2key(a1.x) & ~127u) | (unsigned)(127 - 2 * lane); k11[u] = (f2key(a1.y) & ~127u) | (unsigned)(126 - 2 * lane);
;     ...
;             for (int it = 0; it < 16; ++it) {
; #pragma unroll
;                 for (int u = 0; u < 2; ++u) {
;                     const unsigned m0 = wave_max_u32(k00[u] > k01[u] ? k00[u] : k01[u]);
;                     const unsigned m1 = wave_max_u32(k10[u] > k11[u] ? k10[u] : k11[u]);
;                     if (lane == it) { top0[u] = m0; top1[u] = m1; }
;                     if (k00[u] == m0) k00[u] = 0u; if (k01[u] == m0) k01[u] = 0u;
;                     if (k10[u] == m1) k10[u] = 0u; if (k11[u] == m1) k11[u] = 0u; }
;             }
	v_ashrrev_i32_e32 v212, 31, v0
	v_or_b32_e32 v212, 0x80000000, v212
	v_xor_b32_e32 v0, v0, v212
	v_and_or_b32 v0, v0, s30, 31
	v_ashrrev_i32_e32 v212, 31, v1
	v_or_b32_e32 v212, 0x80000000, v212
	v_xor_b32_e32 v1, v1, v212
	v_and_or_b32 v1, v1, s30, 30
	v_ashrrev_i32_e32 v212, 31, v2
	v_or_b32_e32 v212, 0x80000000, v212
	v_xor_b32_e32 v2, v2, v212
	v_and_or_b32 v2, v2, s30, 29
	v_ashrrev_i32_e32 v212, 31, v3
	v_or_b32_e32 v212, 0x80000000, v212
	v_xor_b32_e32 v3, v3, v212
	v_and_or_b32 v3, v3, s30, 28
	v_ashrrev_i32_e32 v212, 31, v4
	v_or_b32_e32 v212, 0x80000000, v212
	v_xor_b32_e32 v4, v4, v212
	v_and_or_b32 v4, v4, s30, 27
	v_ashrrev_i32_e32 v212, 31, v5
	v_or_b32_e32 v212, 0x80000000, v212
	v_xor_b32_e32 v5, v5, v212
	v_and_or_b32 v5, v5, s30, 26
	v_ashrrev_i32_e32 v212, 31, v6
	v_or_b32_e32 v212, 0x80000000, v212
	v_xor_b32_e32 v6, v6, v212
	v_and_or_b32 v6, v6, s30, 25
	v_ashrrev_i32_e32 v212, 31, v7
	v_or_b32_e32 v212, 0x80000000, v212
	v_xor_b32_e32 v7, v7, v212
	v_and_or_b32 v7, v7, s30, 24
	v_ashrrev_i32_e32 v212, 31, v8
	v_or_b32_e32 v212, 0x80000000, v212
	v_xor_b32_e32 v8, v8, v212
	v_and_or_b32 v8, v8, s30, 23
	v_ashrrev_i32_e32 v212, 31, v9
	v_or_b32_e32 v212, 0x80000000, v212
	v_xor_b32_e32 v9, v9, v212
	v_and_or_b32 v9, v9, s30, 22
	v_ashrrev_i32_e32 v212, 31, v10
	v_or_b32_e32 v212, 0x80000000, v212
	v_xor_b32_e32 v10, v10, v212
	v_and_or_b32 v10, v10, s30, 21
	v_ashrrev_i32_e32 v212, 31, v11
	v_or_b32_e32 v212, 0x80000000, v212
	v_xor_b32_e32 v11, v11, v212
	v_and_or_b32 v11, v11, s30, 20
	v_ashrrev_i32_e32 v212, 31, v12
	v_or_b32_e32 v212, 0x80000000, v212
	v_xor_b32_e32 v12, v12, v212
	v_and_or_b32 v12, v12, s30, 19
	v_ashrrev_i32_e32 v212, 31, v13
	v_or_b32_e32 v212, 0x80000000, v212
	v_xor_b32_e32 v13, v13, v212
	v_and_or_b32 v13, v13, s30, 18
	v_ashrrev_i32_e32 v212, 31, v14
	v_or_b32_e32 v212, 0x80000000, v212
	v_xor_b32_e32 v14, v14, v212
	v_and_or_b32 v14, v14, s30, 17
	v_ashrrev_i32_e32 v212, 31, v15
	v_or_b32_e32 v212, 0x80000000, v212
	v_xor_b32_e32 v15, v15, v212
	v_and_or_b32 v15, v15, s30, 16
	v_ashrrev_i32_e32 v212, 31, v16
	v_or_b32_e32 v212, 0x80000000, v212
	v_xor_b32_e32 v16, v16, v212
	v_and_or_b32 v16, v16, s30, 15
	v_ashrrev_i32_e32 v212, 31, v17
	v_or_b32_e32 v212, 0x80000000, v212
	v_xor_b32_e32 v17, v17, v212
	v_and_or_b32 v17, v17, s30, 14
	v_ashrrev_i32_e32 v212, 31, v18
	v_or_b32_e32 v212, 0x80000000, v212
	v_xor_b32_e32 v18, v18, v212
	v_and_or_b32 v18, v18, s30, 13
	v_ashrrev_i32_e32 v212, 31, v19
	v_or_b32_e32 v212, 0x80000000, v212
	v_xor_b32_e32 v19, v19, v212
	v_and_or_b32 v19, v19, s30, 12
	v_ashrrev_i32_e32 v212, 31, v20
	v_or_b32_e32 v212, 0x80000000, v212
	v_xor_b32_e32 v20, v20, v212
	v_and_or_b32 v20, v20, s30, 11
	v_ashrrev_i32_e32 v212, 31, v21
	v_or_b32_e32 v212, 0x80000000, v212
	v_xor_b32_e32 v21, v21, v212
	v_and_or_b32 v21, v21, s30, 10
	v_ashrrev_i32_e32 v212, 31, v22
	v_or_b32_e32 v212, 0x80000000, v212
	v_xor_b32_e32 v22, v22, v212
	v_and_or_b32 v22, v22, s30, 9
	v_ashrrev_i32_e32 v212, 31, v23
	v_or_b32_e32 v212, 0x80000000, v212
	v_xor_b32_e32 v23, v23, v212
	v_and_or_b32 v23, v23, s30, 8
	v_ashrrev_i32_e32 v212, 31, v24
	v_or_b32_e32 v212, 0x80000000, v212
	v_xor_b32_e32 v24, v24, v212
	v_and_or_b32 v24, v24, s30, 7
	v_ashrrev_i32_e32 v212, 31, v25
	v_or_b32_e32 v212, 0x80000000, v212
	v_xor_b32_e32 v25, v25, v212
	v_and_or_b32 v25, v25, s30, 6
	v_ashrrev_i32_e32 v212, 31, v26
	v_or_b32_e32 v212, 0x80000000, v212
	v_xor_b32_e32 v26, v26, v212
	v_and_or_b32 v26, v26, s30, 5
	v_ashrrev_i32_e32 v212, 31, v27
	v_or_b32_e32 v212, 0x80000000, v212
	v_xor_b32_e32 v27, v27, v212
	v_and_or_b32 v27, v27, s30, 4
	v_ashrrev_i32_e32 v212, 31, v28
	v_or_b32_e32 v212, 0x80000000, v212
	v_xor_b32_e32 v28, v28, v212
	v_and_or_b32 v28, v28, s30, 3
	v_ashrrev_i32_e32 v212, 31, v29
	v_or_b32_e32 v212, 0x80000000, v212
	v_xor_b32_e32 v29, v29, v212
	v_and_or_b32 v29, v29, s30, 2
	v_ashrrev_i32_e32 v212, 31, v30
	v_or_b32_e32 v212, 0x80000000, v212
	v_xor_b32_e32 v30, v30, v212
	v_and_or_b32 v30, v30, s30, 1
	v_ashrrev_i32_e32 v212, 31, v31
	v_or_b32_e32 v212, 0x80000000, v212
	v_xor_b32_e32 v31, v31, v212
	v_and_or_b32 v31, v31, s30, 0
	v_max_u32_e32 v215, v0, v1
	v_min_u32_e32 v1, v0, v1
	v_max_u32_e32 v214, v16, v17
	v_min_u32_e32 v17, v16, v17
	v_max_u32_e32 v213, v2, v3
	v_min_u32_e32 v3, v2, v3
	v_max_u32_e32 v0, v18, v19
	v_min_u32_e32 v19, v18, v19
	v_max_u32_e32 v16, v4, v5
	v_min_u32_e32 v5, v4, v5
	v_max_u32_e32 v2, v20, v21
	v_min_u32_e32 v21, v20, v21
	v_max_u32_e32 v18, v6, v7
	v_min_u32_e32 v7, v6, v7
	v_max_u32_e32 v4, v22, v23
	v_min_u32_e32 v23, v22, v23
	v_max_u32_e32 v20, v8, v9
	v_min_u32_e32 v9, v8, v9
	v_max_u32_e32 v6, v24, v25
	v_min_u32_e32 v25, v24, v25
	v_max_u32_e32 v22, v10, v11
	v_min_u32_e32 v11, v10, v11
	v_max_u32_e32 v8, v26, v27
	v_min_u32_e32 v27, v26, v27
	v_max_u32_e32 v24, v12, v13
	v_min_u32_e32 v13, v12, v13
	v_max_u32_e32 v10, v28, v29
	v_min_u32_e32 v29, v28, v29
	v_max_u32_e32 v26, v14, v15
	v_min_u32_e32 v15, v14, v15
	v_max_u32_e32 v12, v30, v31
	v_min_u32_e32 v31, v30, v31
	v_max_u32_e32 v28, v215, v213
	v_min_u32_e32 v213, v215, v213
	v_max_u32_e32 v14, v214, v0
	v_min_u32_e32 v0, v214, v0
	v_max_u32_e32 v30, v1, v3
	v_min_u32_e32 v3, v1, v3
	v_max_u32_e32 v215, v17, v19
	v_min_u32_e32 v19, v17, v19
	v_max_u32_e32 v214, v16, v18
	v_min_u32_e32 v18, v16, v18
	v_max_u32_e32 v1, v2, v4
	v_min_u32_e32 v4, v2, v4
	v_max_u32_e32 v17, v5, v7
	v_min_u32_e32 v7, v5, v7
	v_max_u32_e32 v16, v21, v23
	v_min_u32_e32 v23, v21, v23
	v_max_u32_e32 v2, v20, v22
	v_min_u32_e32 v22, v20, v22
	v_max_u32_e32 v5, v6, v8
	v_min_u32_e32 v8, v6, v8
; __device__ void ph_peer(const float* __restrict__ SC, const bf16_t* __restrict__ H  , const float* __restrict__ gffn, const unsigned char* __restrict__ U, const unsigned char* __restrict__ V, float* X, const float* __restrict__ fgain) {
;     ...
;             for (int it = 0; it < 16; ++it) {
; #pragma unroll
;                 for (int u = 0; u < 2; ++u) {
;                     const unsigned m0 = wave_max_u32(k00[u] > k01[u] ? k00[u] : k01[u]);
;                     const unsigned m1 = wave_max_u32(k10[u] > k11[u] ? k10[u] : k11[u]);
;                     if (lane == it) { top0[u] = m0; top1[u] = m1; }
;                     if (k00[u] == m0) k00[u] = 0u; if (k01[u] == m0) k01[u] = 0u;
;                     if (k10[u] == m1) k10[u] = 0u; if (k11[u] == m1) k11[u] = 0u; }
;             }
	v_max_u32_e32 v21, v9, v11
	v_min_u32_e32 v11, v9, v11
	v_max_u32_e32 v20, v25, v27
	v_min_u32_e32 v27, v25, v27
	v_max_u32_e32 v6, v24, v26
	v_min_u32_e32 v26, v24, v26
	v_max_u32_e32 v9, v10, v12
	v_min_u32_e32 v12, v10, v12
	v_max_u32_e32 v25, v13, v15
	v_min_u32_e32 v15, v13, v15
	v_max_u32_e32 v24, v29, v31
	v_min_u32_e32 v31, v29, v31
	v_max_u32_e32 v10, v30, v213
	v_min_u32_e32 v213, v30, v213
	v_max_u32_e32 v13, v215, v0
	v_min_u32_e32 v0, v215, v0
	v_max_u32_e32 v29, v17, v18
	v_min_u32_e32 v18, v17, v18
	v_max_u32_e32 v30, v16, v4
	v_min_u32_e32 v4, v16, v4
	v_max_u32_e32 v215, v21, v22
	v_min_u32_e32 v22, v21, v22
	v_max_u32_e32 v17, v20, v8
	v_min_u32_e32 v8, v20, v8
	v_max_u32_e32 v16, v25, v26
	v_min_u32_e32 v26, v25, v26
	v_max_u32_e32 v21, v24, v12
	v_min_u32_e32 v12, v24, v12
	v_max_u32_e32 v20, v28, v214
	v_min_u32_e32 v214, v28, v214
	v_max_u32_e32 v25, v14, v1
	v_min_u32_e32 v1, v14, v1
	v_max_u32_e32 v24, v10, v29
	v_min_u32_e32 v29, v10, v29
	v_max_u32_e32 v28, v13, v30
	v_min_u32_e32 v30, v13, v30
	v_max_u32_e32 v14, v213, v18
	v_min_u32_e32 v18, v213, v18
	v_max_u32_e32 v10, v0, v4
	v_min_u32_e32 v4, v0, v4
	v_max_u32_e32 v13, v3, v7
	v_min_u32_e32 v7, v3, v7
	v_max_u32_e32 v213, v19, v23
	v_min_u32_e32 v23, v19, v23
	v_max_u32_e32 v0, v2, v6
	v_min_u32_e32 v6, v2, v6
	v_max_u32_e32 v3, v5, v9
	v_min_u32_e32 v9, v5, v9
	v_max_u32_e32 v19, v215, v16
	v_min_u32_e32 v16, v215, v16
	v_max_u32_e32 v2, v17, v21
	v_min_u32_e32 v21, v17, v21
	v_max_u32_e32 v5, v22, v26
	v_min_u32_e32 v26, v22, v26
	v_max_u32_e32 v215, v8, v12
	v_min_u32_e32 v12, v8, v12
	v_max_u32_e32 v17, v11, v15
	v_min_u32_e32 v15, v11, v15
	v_max_u32_e32 v22, v27, v31
	v_min_u32_e32 v31, v27, v31
	v_max_u32_e32 v8, v14, v214
	v_min_u32_e32 v214, v14, v214
	v_max_u32_e32 v11, v10, v1
	v_min_u32_e32 v1, v10, v1
	v_max_u32_e32 v27, v13, v29
	v_min_u32_e32 v29, v13, v29
	v_max_u32_e32 v14, v213, v30
	v_min_u32_e32 v30, v213, v30
	v_max_u32_e32 v10, v5, v6
	v_min_u32_e32 v6, v5, v6
	v_max_u32_e32 v13, v215, v9
	v_min_u32_e32 v9, v215, v9
	v_max_u32_e32 v213, v17, v16
	v_min_u32_e32 v16, v17, v16
	v_max_u32_e32 v5, v22, v21
	v_min_u32_e32 v21, v22, v21
	v_max_u32_e32 v215, v24, v8
	v_min_u32_e32 v8, v24, v8
	v_max_u32_e32 v17, v28, v11
	v_min_u32_e32 v11, v28, v11
	v_max_u32_e32 v22, v27, v214
	v_min_u32_e32 v214, v27, v214
	v_max_u32_e32 v24, v14, v1
	v_min_u32_e32 v1, v14, v1
	v_max_u32_e32 v28, v29, v18
	v_min_u32_e32 v18, v29, v18
	v_max_u32_e32 v27, v30, v4
	v_min_u32_e32 v4, v30, v4
	v_max_u32_e32 v14, v19, v10
	v_min_u32_e32 v10, v19, v10
	v_max_u32_e32 v29, v2, v13
	v_min_u32_e32 v13, v2, v13
	v_max_u32_e32 v30, v213, v6
	v_min_u32_e32 v6, v213, v6
	v_max_u32_e32 v19, v5, v9
	v_min_u32_e32 v9, v5, v9
	v_max_u32_e32 v2, v16, v26
	v_min_u32_e32 v26, v16, v26
	v_max_u32_e32 v213, v21, v12
	v_min_u32_e32 v12, v21, v12
	v_max_u32_e32 v5, v20, v0
	v_min_u32_e32 v0, v20, v0
	v_max_u32_e32 v16, v25, v3
	v_min_u32_e32 v3, v25, v3
	v_max_u32_e32 v21, v215, v14
	v_min_u32_e32 v14, v215, v14
	v_max_u32_e32 v20, v17, v29
	v_min_u32_e32 v29, v17, v29
	v_max_u32_e32 v25, v8, v10
	v_min_u32_e32 v10, v8, v10
	v_max_u32_e32 v215, v11, v13
	v_min_u32_e32 v13, v11, v13
	v_max_u32_e32 v17, v22, v30
	v_min_u32_e32 v30, v22, v30
	v_max_u32_e32 v8, v24, v19
	v_min_u32_e32 v19, v24, v19
	v_max_u32_e32 v11, v214, v6
	v_min_u32_e32 v6, v214, v6
	v_max_u32_e32 v22, v1, v9
	v_min_u32_e32 v9, v1, v9
	v_max_u32_e32 v24, v28, v2
	v_min_u32_e32 v2, v28, v2
	v_max_u32_e32 v214, v27, v213
	v_min_u32_e32 v213, v27, v213
	v_max_u32_e32 v1, v18, v26
	v_min_u32_e32 v26, v18, v26
	v_max_u32_e32 v28, v4, v12
	v_min_u32_e32 v12, v4, v12
	v_max_u32_e32 v27, v7, v15
	v_min_u32_e32 v15, v7, v15
	v_max_u32_e32 v18, v23, v31
	v_min_u32_e32 v31, v23, v31
	v_max_u32_e32 v4, v11, v0
	v_min_u32_e32 v0, v11, v0
	v_max_u32_e32 v7, v22, v3
	v_min_u32_e32 v3, v22, v3
	v_max_u32_e32 v23, v24, v14
	v_min_u32_e32 v14, v24, v14
	v_max_u32_e32 v11, v214, v29
	v_min_u32_e32 v29, v214, v29
	v_max_u32_e32 v22, v1, v10
	v_min_u32_e32 v10, v1, v10
	v_max_u32_e32 v24, v28, v13
	v_min_u32_e32 v13, v28, v13
	v_max_u32_e32 v214, v27, v30
	v_min_u32_e32 v30, v27, v30
	v_max_u32_e32 v1, v18, v19
	v_min_u32_e32 v19, v18, v19
	v_max_u32_e32 v28, v25, v4
	v_min_u32_e32 v4, v25, v4
	v_max_u32_e32 v27, v215, v7
	v_min_u32_e32 v7, v215, v7
	v_max_u32_e32 v18, v17, v23
	v_min_u32_e32 v23, v17, v23
	v_max_u32_e32 v25, v8, v11
	v_min_u32_e32 v11, v8, v11
	v_max_u32_e32 v215, v22, v0
	v_min_u32_e32 v0, v22, v0
	v_max_u32_e32 v17, v24, v3
	v_min_u32_e32 v3, v24, v3
	v_max_u32_e32 v8, v214, v14
	v_min_u32_e32 v14, v214, v14
	v_max_u32_e32 v22, v1, v29
	v_min_u32_e32 v29, v1, v29
	v_max_u32_e32 v24, v10, v6
	v_min_u32_e32 v6, v10, v6
	v_max_u32_e32 v214, v13, v9
	v_min_u32_e32 v9, v13, v9
	v_max_u32_e32 v1, v30, v2
	v_min_u32_e32 v2, v30, v2
	v_max_u32_e32 v10, v19, v213
	v_min_u32_e32 v213, v19, v213
	v_max_u32_e32 v13, v21, v28
	v_min_u32_e32 v28, v21, v28
	v_max_u32_e32 v30, v20, v27
	v_min_u32_e32 v27, v20, v27
	v_max_u32_e32 v19, v18, v4
	v_min_u32_e32 v4, v18, v4
	v_max_u32_e32 v21, v25, v7
	v_min_u32_e32 v7, v25, v7
	v_max_u32_e32 v20, v23, v215
	v_min_u32_e32 v215, v23, v215
	v_max_u32_e32 v18, v11, v17
	v_min_u32_e32 v17, v11, v17
	v_max_u32_e32 v25, v8, v0
	v_min_u32_e32 v0, v8, v0
	v_max_u32_e32 v23, v22, v3
	v_min_u32_e32 v3, v22, v3
	v_max_u32_e32 v11, v14, v24
	v_min_u32_e32 v24, v14, v24
	v_max_u32_e32 v8, v29, v214
	v_min_u32_e32 v214, v29, v214
	v_max_u32_e32 v22, v1, v6
	v_min_u32_e32 v6, v1, v6
	v_max_u32_e32 v14, v10, v9
	v_min_u32_e32 v9, v10, v9
	v_max_u32_e32 v29, v2, v26
	v_min_u32_e32 v26, v2, v26
; __device__ __forceinline__ float key2f(unsigned k) { return __uint_as_float((k & 0x80000000u) ? (k & 0x7fffffffu) : ~k); }
; __device__ void ph_peer(const float* __restrict__ SC, const bf16_t* __restrict__ H  , const float* __restrict__ gffn, const unsigned char* __restrict__ U, const unsigned char* __restrict__ V, float* X, const float* __restrict__ fgain) {
;     ...
;             for (int it = 0; it < 16; ++it) {
; #pragma unroll
;                 for (int u = 0; u < 2; ++u) {
;                     const unsigned m0 = wave_max_u32(k00[u] > k01[u] ? k00[u] : k01[u]);
;                     const unsigned m1 = wave_max_u32(k10[u] > k11[u] ? k10[u] : k11[u]);
;                     if (lane == it) { top0[u] = m0; top1[u] = m1; }
;                     if (k00[u] == m0) k00[u] = 0u; if (k01[u] == m0) k01[u] = 0u;
;                     if (k10[u] == m1) k10[u] = 0u; if (k11[u] == m1) k11[u] = 0u; }
;             }
;     ...
;                 const float s0 = key2f(top0[u] & ~127u), s1 = key2f(top1[u] & ~127u);
;                 n0[u] = 127 - (int)(top0[u] & 127u); n1[u] = 127 - (int)(top1[u] & 127u);
	v_max_u32_e32 v1, v213, v12
	v_min_u32_e32 v12, v213, v12
	v_max_u32_e32 v50, v46, v15
	v_max_u32_e32 v39, v49, v26
	v_max_u32_e32 v42, v35, v29
	v_max_u32_e32 v37, v48, v6
	v_max_u32_e32 v46, v43, v22
	v_max_u32_e32 v49, v38, v24
	v_max_u32_e32 v35, v32, v11
	v_max_u32_e32 v48, v34, v0
	v_max_u32_e32 v43, v47, v25
	v_max_u32_e32 v38, v41, v215
	v_max_u32_e32 v32, v33, v20
	v_max_u32_e32 v34, v36, v4
	v_max_u32_e32 v47, v44, v19
	v_max_u32_e32 v41, v51, v28
	v_max_u32_e32 v33, v45, v13
	v_max_u32_e32 v36, v40, v5
	v_max_u32_e32 v44, v50, v43
	v_min_u32_e32 v43, v50, v43
	v_max_u32_e32 v51, v39, v38
	v_min_u32_e32 v38, v39, v38
	v_max_u32_e32 v45, v42, v32
	v_min_u32_e32 v32, v42, v32
	v_max_u32_e32 v40, v37, v34
	v_min_u32_e32 v34, v37, v34
	v_max_u32_e32 v50, v46, v47
	v_min_u32_e32 v47, v46, v47
	v_max_u32_e32 v39, v49, v41
	v_min_u32_e32 v41, v49, v41
	v_max_u32_e32 v42, v35, v33
	v_min_u32_e32 v33, v35, v33
	v_max_u32_e32 v37, v48, v36
	v_min_u32_e32 v36, v48, v36
	v_max_u32_e32 v46, v44, v50
	v_min_u32_e32 v50, v44, v50
	v_max_u32_e32 v49, v51, v39
	v_min_u32_e32 v39, v51, v39
	v_max_u32_e32 v35, v45, v42
	v_min_u32_e32 v42, v45, v42
	v_max_u32_e32 v48, v40, v37
	v_min_u32_e32 v37, v40, v37
	v_max_u32_e32 v44, v43, v47
	v_min_u32_e32 v47, v43, v47
	v_max_u32_e32 v51, v38, v41
	v_min_u32_e32 v41, v38, v41
	v_max_u32_e32 v45, v32, v33
	v_min_u32_e32 v33, v32, v33
	v_max_u32_e32 v40, v34, v36
	v_min_u32_e32 v36, v34, v36
	v_max_u32_e32 v43, v46, v35
	v_min_u32_e32 v35, v46, v35
	v_max_u32_e32 v38, v49, v48
	v_min_u32_e32 v48, v49, v48
	v_max_u32_e32 v32, v50, v42
	v_min_u32_e32 v42, v50, v42
	v_max_u32_e32 v34, v39, v37
	v_min_u32_e32 v37, v39, v37
	v_max_u32_e32 v46, v44, v45
	v_min_u32_e32 v45, v44, v45
	v_max_u32_e32 v49, v51, v40
	v_min_u32_e32 v40, v51, v40
	v_max_u32_e32 v50, v47, v33
	v_min_u32_e32 v33, v47, v33
	v_max_u32_e32 v39, v41, v36
	v_min_u32_e32 v36, v41, v36
	v_max_u32_e32 v44, v43, v38
	v_min_u32_e32 v38, v43, v38
	v_max_u32_e32 v51, v35, v48
	v_min_u32_e32 v48, v35, v48
	v_max_u32_e32 v47, v32, v34
	v_min_u32_e32 v34, v32, v34
	v_max_u32_e32 v41, v42, v37
	v_min_u32_e32 v37, v42, v37
	v_max_u32_e32 v43, v46, v49
	v_min_u32_e32 v49, v46, v49
	v_max_u32_e32 v35, v45, v40
	v_min_u32_e32 v40, v45, v40
	v_max_u32_e32 v32, v50, v39
	v_min_u32_e32 v39, v50, v39
	v_max_u32_e32 v42, v33, v36
	v_min_u32_e32 v36, v33, v36
	v_max_u32_e32 v46, v44, v31
	v_max_u32_e32 v45, v38, v12
	v_max_u32_e32 v50, v51, v1
	v_max_u32_e32 v33, v48, v9
	v_max_u32_e32 v44, v47, v14
	v_max_u32_e32 v38, v34, v214
	v_max_u32_e32 v51, v41, v8
	v_max_u32_e32 v48, v37, v3
	v_max_u32_e32 v47, v43, v23
	v_max_u32_e32 v34, v49, v17
	v_max_u32_e32 v41, v35, v18
	v_max_u32_e32 v37, v40, v7
	v_max_u32_e32 v43, v32, v21
	v_max_u32_e32 v49, v39, v27
	v_max_u32_e32 v35, v42, v30
	v_max_u32_e32 v40, v36, v16
	v_max_u32_e32 v32, v46, v47
	v_min_u32_e32 v47, v46, v47
	v_max_u32_e32 v39, v45, v34
	v_min_u32_e32 v34, v45, v34
	v_max_u32_e32 v42, v50, v41
	v_min_u32_e32 v41, v50, v41
	v_max_u32_e32 v36, v33, v37
	v_min_u32_e32 v37, v33, v37
	v_max_u32_e32 v46, v44, v43
	v_min_u32_e32 v43, v44, v43
	v_max_u32_e32 v45, v38, v49
	v_min_u32_e32 v49, v38, v49
	v_max_u32_e32 v50, v51, v35
	v_min_u32_e32 v35, v51, v35
	v_max_u32_e32 v33, v48, v40
	v_min_u32_e32 v40, v48, v40
	v_max_u32_e32 v44, v32, v46
	v_min_u32_e32 v46, v32, v46
	v_max_u32_e32 v38, v39, v45
	v_min_u32_e32 v45, v39, v45
	v_max_u32_e32 v51, v42, v50
	v_min_u32_e32 v50, v42, v50
	v_max_u32_e32 v48, v36, v33
	v_min_u32_e32 v33, v36, v33
	v_max_u32_e32 v32, v47, v43
	v_min_u32_e32 v43, v47, v43
	v_max_u32_e32 v39, v34, v49
	v_min_u32_e32 v49, v34, v49
	v_max_u32_e32 v42, v41, v35
	v_min_u32_e32 v35, v41, v35
	v_max_u32_e32 v36, v37, v40
	v_min_u32_e32 v40, v37, v40
	v_max_u32_e32 v47, v44, v51
	v_min_u32_e32 v51, v44, v51
	v_max_u32_e32 v34, v38, v48
	v_min_u32_e32 v48, v38, v48
	v_max_u32_e32 v41, v46, v50
	v_min_u32_e32 v50, v46, v50
	v_max_u32_e32 v37, v45, v33
	v_min_u32_e32 v33, v45, v33
	v_max_u32_e32 v44, v32, v42
	v_min_u32_e32 v42, v32, v42
	v_max_u32_e32 v38, v39, v36
	v_min_u32_e32 v36, v39, v36
	v_max_u32_e32 v46, v43, v35
	v_min_u32_e32 v35, v43, v35
	v_max_u32_e32 v45, v49, v40
	v_min_u32_e32 v40, v49, v40
	v_max_u32_e32 v32, v47, v34
	v_min_u32_e32 v34, v47, v34
	v_max_u32_e32 v39, v51, v48
	v_min_u32_e32 v48, v51, v48
	v_max_u32_e32 v43, v41, v37
	v_min_u32_e32 v37, v41, v37
	v_max_u32_e32 v49, v50, v33
	v_min_u32_e32 v33, v50, v33
	v_max_u32_e32 v47, v44, v38
	v_min_u32_e32 v38, v44, v38
	v_max_u32_e32 v51, v42, v36
	v_min_u32_e32 v36, v42, v36
	v_max_u32_e32 v41, v46, v45
	v_min_u32_e32 v45, v46, v45
	v_max_u32_e32 v50, v35, v40
	v_min_u32_e32 v40, v35, v40
	ds_write_b8 v156, v32 offset:16
	ds_write_b8 v156, v34 offset:17
	ds_write_b8 v156, v39 offset:18
	ds_write_b8 v156, v48 offset:19
	ds_write_b8 v156, v43 offset:20
	ds_write_b8 v156, v37 offset:21
	ds_write_b8 v156, v49 offset:22
	ds_write_b8 v156, v33 offset:23
	ds_write_b8 v156, v47 offset:24
	ds_write_b8 v156, v38 offset:25
	ds_write_b8 v156, v51 offset:26
	ds_write_b8 v156, v36 offset:27
	ds_write_b8 v156, v41 offset:28
	ds_write_b8 v156, v45 offset:29
	ds_write_b8 v156, v50 offset:30
	ds_write_b8 v156, v40 offset:31
	v_and_b32_e32 v112, s30, v32
	v_ashrrev_i32_e32 v212, 31, v112
	v_lshrrev_b32_e32 v212, 1, v212
	v_xnor_b32_e32 v112, v112, v212
	v_and_b32_e32 v113, s30, v34
	v_ashrrev_i32_e32 v212, 31, v113
	v_lshrrev_b32_e32 v212, 1, v212
	v_xnor_b32_e32 v113, v113, v212
	v_and_b32_e32 v114, s30, v39
	v_ashrrev_i32_e32 v212, 31, v114
	v_lshrrev_b32_e32 v212, 1, v212
	v_xnor_b32_e32 v114, v114, v212
	v_and_b32_e32 v115, s30, v48
; __device__ __forceinline__ unsigned f2key(float f) { const unsigned u = __float_as_uint(f); return (u & 0x80000000u) ? ~u : (u | 0x80000000u); }
; __device__ __forceinline__ float key2f(unsigned k) { return __uint_as_float((k & 0x80000000u) ? (k & 0x7fffffffu) : ~k); }
; __device__ void ph_peer(const float* __restrict__ SC, const bf16_t* __restrict__ H  , const float* __restrict__ gffn, const unsigned char* __restrict__ U, const unsigned char* __restrict__ V, float* X, const float* __restrict__ fgain) {
;     ...
;                 const float s0 = key2f(top0[u] & ~127u), s1 = key2f(top1[u] & ~127u);
;                 n0[u] = 127 - (int)(top0[u] & 127u); n1[u] = 127 - (int)(top1[u] & 127u);
;                 const float si = __shfl(s0, ci);
; #pragma unroll
;                 for (int jj = 0; jj < 4; ++jj) { const float sj = __shfl(s1, cj0 + jj); ck[u][jj] = (f2key(si + sj) & ~255u) | (unsigned)(255 - (ci * 16 + cj0 + jj)); }
	v_ashrrev_i32_e32 v212, 31, v115
	v_lshrrev_b32_e32 v212, 1, v212
	v_xnor_b32_e32 v115, v115, v212
	v_and_b32_e32 v116, s30, v43
	v_ashrrev_i32_e32 v212, 31, v116
	v_lshrrev_b32_e32 v212, 1, v212
	v_xnor_b32_e32 v116, v116, v212
	v_and_b32_e32 v117, s30, v37
	v_ashrrev_i32_e32 v212, 31, v117
	v_lshrrev_b32_e32 v212, 1, v212
	v_xnor_b32_e32 v117, v117, v212
	v_and_b32_e32 v118, s30, v49
	v_ashrrev_i32_e32 v212, 31, v118
	v_lshrrev_b32_e32 v212, 1, v212
	v_xnor_b32_e32 v118, v118, v212
	v_and_b32_e32 v119, s30, v33
	v_ashrrev_i32_e32 v212, 31, v119
	v_lshrrev_b32_e32 v212, 1, v212
	v_xnor_b32_e32 v119, v119, v212
	v_and_b32_e32 v120, s30, v47
	v_ashrrev_i32_e32 v212, 31, v120
	v_lshrrev_b32_e32 v212, 1, v212
	v_xnor_b32_e32 v120, v120, v212
	v_and_b32_e32 v121, s30, v38
	v_ashrrev_i32_e32 v212, 31, v121
	v_lshrrev_b32_e32 v212, 1, v212
	v_xnor_b32_e32 v121, v121, v212
	v_and_b32_e32 v122, s30, v51
	v_ashrrev_i32_e32 v212, 31, v122
	v_lshrrev_b32_e32 v212, 1, v212
	v_xnor_b32_e32 v122, v122, v212
	v_and_b32_e32 v123, s30, v36
	v_ashrrev_i32_e32 v212, 31, v123
	v_lshrrev_b32_e32 v212, 1, v212
	v_xnor_b32_e32 v123, v123, v212
	v_and_b32_e32 v124, s30, v41
	v_ashrrev_i32_e32 v212, 31, v124
	v_lshrrev_b32_e32 v212, 1, v212
	v_xnor_b32_e32 v124, v124, v212
	v_and_b32_e32 v125, s30, v45
	v_ashrrev_i32_e32 v212, 31, v125
	v_lshrrev_b32_e32 v212, 1, v212
	v_xnor_b32_e32 v125, v125, v212
	v_and_b32_e32 v126, s30, v50
	v_ashrrev_i32_e32 v212, 31, v126
	v_lshrrev_b32_e32 v212, 1, v212
	v_xnor_b32_e32 v126, v126, v212
	v_and_b32_e32 v127, s30, v40
	v_ashrrev_i32_e32 v212, 31, v127
	v_lshrrev_b32_e32 v212, 1, v212
	v_xnor_b32_e32 v127, v127, v212
	v_add_f32_e32 v0, v96, v112
	v_add_f32_e32 v1, v96, v113
	v_add_f32_e32 v2, v96, v114
	v_add_f32_e32 v3, v96, v115
	v_add_f32_e32 v4, v96, v116
	v_add_f32_e32 v5, v96, v117
	v_add_f32_e32 v6, v96, v118
	v_add_f32_e32 v7, v96, v119
	v_add_f32_e32 v8, v96, v120
	v_add_f32_e32 v9, v96, v121
	v_add_f32_e32 v10, v96, v122
	v_add_f32_e32 v11, v96, v123
	v_add_f32_e32 v12, v96, v124
	v_add_f32_e32 v13, v96, v125
	v_add_f32_e32 v14, v96, v126
	v_add_f32_e32 v15, v96, v127
	v_add_f32_e32 v16, v97, v112
	v_add_f32_e32 v17, v97, v113
	v_add_f32_e32 v18, v97, v114
	v_add_f32_e32 v19, v97, v115
	v_add_f32_e32 v20, v97, v116
	v_add_f32_e32 v21, v97, v117
	v_add_f32_e32 v22, v97, v118
	v_add_f32_e32 v23, v97, v119
	v_add_f32_e32 v24, v98, v112
	v_add_f32_e32 v25, v98, v113
	v_add_f32_e32 v26, v98, v114
	v_add_f32_e32 v27, v98, v115
	v_add_f32_e32 v28, v98, v116
	v_add_f32_e32 v29, v99, v112
	v_add_f32_e32 v30, v99, v113
	v_add_f32_e32 v31, v99, v114
	v_add_f32_e32 v180, v99, v115
	v_add_f32_e32 v181, v100, v112
	v_add_f32_e32 v182, v100, v113
	v_add_f32_e32 v183, v100, v114
	v_add_f32_e32 v184, v101, v112
	v_add_f32_e32 v185, v101, v113
	v_add_f32_e32 v186, v102, v112
	v_add_f32_e32 v187, v102, v113
	v_add_f32_e32 v188, v103, v112
	v_add_f32_e32 v189, v103, v113
	v_add_f32_e32 v190, v104, v112
	v_add_f32_e32 v191, v105, v112
	v_add_f32_e32 v192, v106, v112
	v_add_f32_e32 v193, v107, v112
	v_add_f32_e32 v194, v108, v112
	v_add_f32_e32 v195, v109, v112
	v_add_f32_e32 v196, v110, v112
	v_add_f32_e32 v197, v111, v112
	v_ashrrev_i32_e32 v212, 31, v0
	v_or_b32_e32 v212, 0x80000000, v212
	v_xor_b32_e32 v0, v0, v212
	v_and_b32_e32 v0, s31, v0
	v_or_b32_e32 v0, 0xff, v0
	v_ashrrev_i32_e32 v212, 31, v1
	v_or_b32_e32 v212, 0x80000000, v212
	v_xor_b32_e32 v1, v1, v212
	v_and_b32_e32 v1, s31, v1
	v_or_b32_e32 v1, 0xfe, v1
	v_ashrrev_i32_e32 v212, 31, v2
	v_or_b32_e32 v212, 0x80000000, v212
	v_xor_b32_e32 v2, v2, v212
	v_and_b32_e32 v2, s31, v2
	v_or_b32_e32 v2, 0xfd, v2
	v_ashrrev_i32_e32 v212, 31, v3
	v_or_b32_e32 v212, 0x80000000, v212
	v_xor_b32_e32 v3, v3, v212
	v_and_b32_e32 v3, s31, v3
	v_or_b32_e32 v3, 0xfc, v3
	v_ashrrev_i32_e32 v212, 31, v4
	v_or_b32_e32 v212, 0x80000000, v212
	v_xor_b32_e32 v4, v4, v212
	v_and_b32_e32 v4, s31, v4
	v_or_b32_e32 v4, 0xfb, v4
	v_ashrrev_i32_e32 v212, 31, v5
	v_or_b32_e32 v212, 0x80000000, v212
	v_xor_b32_e32 v5, v5, v212
	v_and_b32_e32 v5, s31, v5
	v_or_b32_e32 v5, 0xfa, v5
	v_ashrrev_i32_e32 v212, 31, v6
	v_or_b32_e32 v212, 0x80000000, v212
	v_xor_b32_e32 v6, v6, v212
	v_and_b32_e32 v6, s31, v6
	v_or_b32_e32 v6, 0xf9, v6
	v_ashrrev_i32_e32 v212, 31, v7
	v_or_b32_e32 v212, 0x80000000, v212
	v_xor_b32_e32 v7, v7, v212
	v_and_b32_e32 v7, s31, v7
	v_or_b32_e32 v7, 0xf8, v7
	v_ashrrev_i32_e32 v212, 31, v8
	v_or_b32_e32 v212, 0x80000000, v212
	v_xor_b32_e32 v8, v8, v212
	v_and_b32_e32 v8, s31, v8
	v_or_b32_e32 v8, 0xf7, v8
	v_ashrrev_i32_e32 v212, 31, v9
	v_or_b32_e32 v212, 0x80000000, v212
	v_xor_b32_e32 v9, v9, v212
	v_and_b32_e32 v9, s31, v9
	v_or_b32_e32 v9, 0xf6, v9
	v_ashrrev_i32_e32 v212, 31, v10
	v_or_b32_e32 v212, 0x80000000, v212
	v_xor_b32_e32 v10, v10, v212
	v_and_b32_e32 v10, s31, v10
	v_or_b32_e32 v10, 0xf5, v10
	v_ashrrev_i32_e32 v212, 31, v11
	v_or_b32_e32 v212, 0x80000000, v212
	v_xor_b32_e32 v11, v11, v212
	v_and_b32_e32 v11, s31, v11
	v_or_b32_e32 v11, 0xf4, v11
	v_ashrrev_i32_e32 v212, 31, v12
	v_or_b32_e32 v212, 0x80000000, v212
	v_xor_b32_e32 v12, v12, v212
	v_and_b32_e32 v12, s31, v12
	v_or_b32_e32 v12, 0xf3, v12
	v_ashrrev_i32_e32 v212, 31, v13
	v_or_b32_e32 v212, 0x80000000, v212
	v_xor_b32_e32 v13, v13, v212
	v_and_b32_e32 v13, s31, v13
	v_or_b32_e32 v13, 0xf2, v13
	v_ashrrev_i32_e32 v212, 31, v14
	v_or_b32_e32 v212, 0x80000000, v212
	v_xor_b32_e32 v14, v14, v212
	v_and_b32_e32 v14, s31, v14
	v_or_b32_e32 v14, 0xf1, v14
	v_ashrrev_i32_e32 v212, 31, v15
	v_or_b32_e32 v212, 0x80000000, v212
	v_xor_b32_e32 v15, v15, v212
	v_and_b32_e32 v15, s31, v15
	v_or_b32_e32 v15, 0xf0, v15
; __device__ __forceinline__ unsigned f2key(float f) { const unsigned u = __float_as_uint(f); return (u & 0x80000000u) ? ~u : (u | 0x80000000u); }
; __device__ __forceinline__ float key2f(unsigned k) { return __uint_as_float((k & 0x80000000u) ? (k & 0x7fffffffu) : ~k); }
; __device__ void ph_peer(const float* __restrict__ SC, const bf16_t* __restrict__ H  , const float* __restrict__ gffn, const unsigned char* __restrict__ U, const unsigned char* __restrict__ V, float* X, const float* __restrict__ fgain) {
;     ...
;                 const float s0 = key2f(top0[u] & ~127u), s1 = key2f(top1[u] & ~127u);
;                 n0[u] = 127 - (int)(top0[u] & 127u); n1[u] = 127 - (int)(top1[u] & 127u);
;                 const float si = __shfl(s0, ci);
; #pragma unroll
;                 for (int jj = 0; jj < 4; ++jj) { const float sj = __shfl(s1, cj0 + jj); ck[u][jj] = (f2key(si + sj) & ~255u) | (unsigned)(255 - (ci * 16 + cj0 + jj)); }
	v_ashrrev_i32_e32 v212, 31, v16
	v_or_b32_e32 v212, 0x80000000, v212
	v_xor_b32_e32 v16, v16, v212
	v_and_b32_e32 v16, s31, v16
	v_or_b32_e32 v16, 0xef, v16
	v_ashrrev_i32_e32 v212, 31, v17
	v_or_b32_e32 v212, 0x80000000, v212
	v_xor_b32_e32 v17, v17, v212
	v_and_b32_e32 v17, s31, v17
	v_or_b32_e32 v17, 0xee, v17
	v_ashrrev_i32_e32 v212, 31, v18
	v_or_b32_e32 v212, 0x80000000, v212
	v_xor_b32_e32 v18, v18, v212
	v_and_b32_e32 v18, s31, v18
	v_or_b32_e32 v18, 0xed, v18
	v_ashrrev_i32_e32 v212, 31, v19
	v_or_b32_e32 v212, 0x80000000, v212
	v_xor_b32_e32 v19, v19, v212
	v_and_b32_e32 v19, s31, v19
	v_or_b32_e32 v19, 0xec, v19
	v_ashrrev_i32_e32 v212, 31, v20
	v_or_b32_e32 v212, 0x80000000, v212
	v_xor_b32_e32 v20, v20, v212
	v_and_b32_e32 v20, s31, v20
	v_or_b32_e32 v20, 0xeb, v20
	v_ashrrev_i32_e32 v212, 31, v21
	v_or_b32_e32 v212, 0x80000000, v212
	v_xor_b32_e32 v21, v21, v212
	v_and_b32_e32 v21, s31, v21
	v_or_b32_e32 v21, 0xea, v21
	v_ashrrev_i32_e32 v212, 31, v22
	v_or_b32_e32 v212, 0x80000000, v212
	v_xor_b32_e32 v22, v22, v212
	v_and_b32_e32 v22, s31, v22
	v_or_b32_e32 v22, 0xe9, v22
	v_ashrrev_i32_e32 v212, 31, v23
	v_or_b32_e32 v212, 0x80000000, v212
	v_xor_b32_e32 v23, v23, v212
	v_and_b32_e32 v23, s31, v23
	v_or_b32_e32 v23, 0xe8, v23
	v_ashrrev_i32_e32 v212, 31, v24
	v_or_b32_e32 v212, 0x80000000, v212
	v_xor_b32_e32 v24, v24, v212
	v_and_b32_e32 v24, s31, v24
	v_or_b32_e32 v24, 0xdf, v24
	v_ashrrev_i32_e32 v212, 31, v25
	v_or_b32_e32 v212, 0x80000000, v212
	v_xor_b32_e32 v25, v25, v212
	v_and_b32_e32 v25, s31, v25
	v_or_b32_e32 v25, 0xde, v25
	v_ashrrev_i32_e32 v212, 31, v26
	v_or_b32_e32 v212, 0x80000000, v212
	v_xor_b32_e32 v26, v26, v212
	v_and_b32_e32 v26, s31, v26
	v_or_b32_e32 v26, 0xdd, v26
	v_ashrrev_i32_e32 v212, 31, v27
	v_or_b32_e32 v212, 0x80000000, v212
	v_xor_b32_e32 v27, v27, v212
	v_and_b32_e32 v27, s31, v27
	v_or_b32_e32 v27, 0xdc, v27
	v_ashrrev_i32_e32 v212, 31, v28
	v_or_b32_e32 v212, 0x80000000, v212
	v_xor_b32_e32 v28, v28, v212
	v_and_b32_e32 v28, s31, v28
	v_or_b32_e32 v28, 0xdb, v28
	v_ashrrev_i32_e32 v212, 31, v29
	v_or_b32_e32 v212, 0x80000000, v212
	v_xor_b32_e32 v29, v29, v212
	v_and_b32_e32 v29, s31, v29
	v_or_b32_e32 v29, 0xcf, v29
	v_ashrrev_i32_e32 v212, 31, v30
	v_or_b32_e32 v212, 0x80000000, v212
	v_xor_b32_e32 v30, v30, v212
	v_and_b32_e32 v30, s31, v30
	v_or_b32_e32 v30, 0xce, v30
	v_ashrrev_i32_e32 v212, 31, v31
	v_or_b32_e32 v212, 0x80000000, v212
	v_xor_b32_e32 v31, v31, v212
	v_and_b32_e32 v31, s31, v31
	v_or_b32_e32 v31, 0xcd, v31
	v_ashrrev_i32_e32 v212, 31, v180
	v_or_b32_e32 v212, 0x80000000, v212
	v_xor_b32_e32 v180, v180, v212
	v_and_b32_e32 v180, s31, v180
	v_or_b32_e32 v180, 0xcc, v180
	v_ashrrev_i32_e32 v212, 31, v181
	v_or_b32_e32 v212, 0x80000000, v212
	v_xor_b32_e32 v181, v181, v212
	v_and_b32_e32 v181, s31, v181
	v_or_b32_e32 v181, 0xbf, v181
	v_ashrrev_i32_e32 v212, 31, v182
	v_or_b32_e32 v212, 0x80000000, v212
	v_xor_b32_e32 v182, v182, v212
	v_and_b32_e32 v182, s31, v182
	v_or_b32_e32 v182, 0xbe, v182
	v_ashrrev_i32_e32 v212, 31, v183
	v_or_b32_e32 v212, 0x80000000, v212
	v_xor_b32_e32 v183, v183, v212
	v_and_b32_e32 v183, s31, v183
	v_or_b32_e32 v183, 0xbd, v183
	v_ashrrev_i32_e32 v212, 31, v184
	v_or_b32_e32 v212, 0x80000000, v212
	v_xor_b32_e32 v184, v184, v212
	v_and_b32_e32 v184, s31, v184
	v_or_b32_e32 v184, 0xaf, v184
	v_ashrrev_i32_e32 v212, 31, v185
	v_or_b32_e32 v212, 0x80000000, v212
	v_xor_b32_e32 v185, v185, v212
	v_and_b32_e32 v185, s31, v185
	v_or_b32_e32 v185, 0xae, v185
	v_ashrrev_i32_e32 v212, 31, v186
	v_or_b32_e32 v212, 0x80000000, v212
	v_xor_b32_e32 v186, v186, v212
	v_and_b32_e32 v186, s31, v186
	v_or_b32_e32 v186, 0x9f, v186
	v_ashrrev_i32_e32 v212, 31, v187
	v_or_b32_e32 v212, 0x80000000, v212
	v_xor_b32_e32 v187, v187, v212
	v_and_b32_e32 v187, s31, v187
	v_or_b32_e32 v187, 0x9e, v187
	v_ashrrev_i32_e32 v212, 31, v188
	v_or_b32_e32 v212, 0x80000000, v212
	v_xor_b32_e32 v188, v188, v212
	v_and_b32_e32 v188, s31, v188
	v_or_b32_e32 v188, 0x8f, v188
	v_ashrrev_i32_e32 v212, 31, v189
	v_or_b32_e32 v212, 0x80000000, v212
	v_xor_b32_e32 v189, v189, v212
	v_and_b32_e32 v189, s31, v189
	v_or_b32_e32 v189, 0x8e, v189
	v_ashrrev_i32_e32 v212, 31, v190
	v_or_b32_e32 v212, 0x80000000, v212
	v_xor_b32_e32 v190, v190, v212
	v_and_b32_e32 v190, s31, v190
	v_or_b32_e32 v190, 0x7f, v190
	v_ashrrev_i32_e32 v212, 31, v191
	v_or_b32_e32 v212, 0x80000000, v212
	v_xor_b32_e32 v191, v191, v212
	v_and_b32_e32 v191, s31, v191
	v_or_b32_e32 v191, 0x6f, v191
	v_ashrrev_i32_e32 v212, 31, v192
	v_or_b32_e32 v212, 0x80000000, v212
	v_xor_b32_e32 v192, v192, v212
	v_and_b32_e32 v192, s31, v192
	v_or_b32_e32 v192, 0x5f, v192
	v_ashrrev_i32_e32 v212, 31, v193
	v_or_b32_e32 v212, 0x80000000, v212
	v_xor_b32_e32 v193, v193, v212
	v_and_b32_e32 v193, s31, v193
	v_or_b32_e32 v193, 0x4f, v193
	v_ashrrev_i32_e32 v212, 31, v194
	v_or_b32_e32 v212, 0x80000000, v212
	v_xor_b32_e32 v194, v194, v212
	v_and_or_b32 v194, v194, s31, 63
	v_ashrrev_i32_e32 v212, 31, v195
	v_or_b32_e32 v212, 0x80000000, v212
	v_xor_b32_e32 v195, v195, v212
	v_and_or_b32 v195, v195, s31, 47
	v_ashrrev_i32_e32 v212, 31, v196
	v_or_b32_e32 v212, 0x80000000, v212
	v_xor_b32_e32 v196, v196, v212
	v_and_or_b32 v196, v196, s31, 31
	v_ashrrev_i32_e32 v212, 31, v197
	v_or_b32_e32 v212, 0x80000000, v212
	v_xor_b32_e32 v197, v197, v212
	v_and_or_b32 v197, v197, s31, 15
	v_max_u32_e32 v51, v0, v1
	v_min_u32_e32 v1, v0, v1
	v_max_u32_e32 v50, v2, v3
	v_min_u32_e32 v3, v2, v3
	v_max_u32_e32 v49, v4, v5
	v_min_u32_e32 v5, v4, v5
	v_max_u32_e32 v48, v6, v7
	v_min_u32_e32 v7, v6, v7
	v_max_u32_e32 v47, v8, v9
	v_min_u32_e32 v9, v8, v9
; __device__ void ph_peer(const float* __restrict__ SC, const bf16_t* __restrict__ H  , const float* __restrict__ gffn, const unsigned char* __restrict__ U, const unsigned char* __restrict__ V, float* X, const float* __restrict__ fgain) {
;     ...
;             for (int it = 0; it < 16; ++it) {
; #pragma unroll
;                 for (int u = 0; u < 2; ++u) {
;                     const unsigned a = ck[u][0] > ck[u][1] ? ck[u][0] : ck[u][1], b = ck[u][2] > ck[u][3] ? ck[u][2] : ck[u][3];
;                     const unsigned mx = wave_max_u32(a > b ? a : b);
;                     if (lane == it) best[u] = mx;
; #pragma unroll
;                     for (int jj = 0; jj < 4; ++jj) if (ck[u][jj] == mx) ck[u][jj] = 0u; }
;             }
	v_max_u32_e32 v46, v10, v11
	v_min_u32_e32 v11, v10, v11
	v_max_u32_e32 v45, v12, v13
	v_min_u32_e32 v13, v12, v13
	v_max_u32_e32 v44, v14, v15
	v_min_u32_e32 v15, v14, v15
	v_max_u32_e32 v43, v51, v50
	v_min_u32_e32 v50, v51, v50
	v_max_u32_e32 v42, v1, v3
	v_min_u32_e32 v3, v1, v3
	v_max_u32_e32 v41, v49, v48
	v_min_u32_e32 v48, v49, v48
	v_max_u32_e32 v40, v5, v7
	v_min_u32_e32 v7, v5, v7
	v_max_u32_e32 v39, v47, v46
	v_min_u32_e32 v46, v47, v46
	v_max_u32_e32 v38, v9, v11
	v_min_u32_e32 v11, v9, v11
	v_max_u32_e32 v37, v45, v44
	v_min_u32_e32 v44, v45, v44
	v_max_u32_e32 v36, v13, v15
	v_min_u32_e32 v15, v13, v15
	v_max_u32_e32 v35, v42, v50
	v_min_u32_e32 v50, v42, v50
	v_max_u32_e32 v34, v40, v48
	v_min_u32_e32 v48, v40, v48
	v_max_u32_e32 v33, v38, v46
	v_min_u32_e32 v46, v38, v46
	v_max_u32_e32 v32, v36, v44
	v_min_u32_e32 v44, v36, v44
	v_max_u32_e32 v0, v43, v41
	v_min_u32_e32 v41, v43, v41
	v_max_u32_e32 v2, v35, v34
	v_min_u32_e32 v34, v35, v34
	v_max_u32_e32 v4, v50, v48
	v_min_u32_e32 v48, v50, v48
	v_max_u32_e32 v6, v3, v7
	v_min_u32_e32 v7, v3, v7
	v_max_u32_e32 v8, v39, v37
	v_min_u32_e32 v37, v39, v37
	v_max_u32_e32 v10, v33, v32
	v_min_u32_e32 v32, v33, v32
	v_max_u32_e32 v12, v46, v44
	v_min_u32_e32 v44, v46, v44
	v_max_u32_e32 v14, v11, v15
	v_min_u32_e32 v15, v11, v15
	v_max_u32_e32 v51, v4, v41
	v_min_u32_e32 v41, v4, v41
	v_max_u32_e32 v1, v6, v34
	v_min_u32_e32 v34, v6, v34
	v_max_u32_e32 v49, v12, v37
	v_min_u32_e32 v37, v12, v37
	v_max_u32_e32 v5, v14, v32
	v_min_u32_e32 v32, v14, v32
	v_max_u32_e32 v47, v2, v51
	v_min_u32_e32 v51, v2, v51
	v_max_u32_e32 v9, v1, v41
	v_min_u32_e32 v41, v1, v41
	v_max_u32_e32 v45, v34, v48
	v_min_u32_e32 v48, v34, v48
	v_max_u32_e32 v13, v10, v49
	v_min_u32_e32 v49, v10, v49
	v_max_u32_e32 v42, v5, v37
	v_min_u32_e32 v37, v5, v37
	v_max_u32_e32 v40, v32, v44
	v_min_u32_e32 v44, v32, v44
	v_max_u32_e32 v38, v0, v8
	v_min_u32_e32 v8, v0, v8
	v_max_u32_e32 v36, v47, v13
	v_min_u32_e32 v13, v47, v13
	v_max_u32_e32 v43, v51, v49
	v_min_u32_e32 v49, v51, v49
	v_max_u32_e32 v35, v9, v42
	v_min_u32_e32 v42, v9, v42
	v_max_u32_e32 v50, v41, v37
	v_min_u32_e32 v37, v41, v37
	v_max_u32_e32 v3, v45, v40
	v_min_u32_e32 v40, v45, v40
	v_max_u32_e32 v39, v48, v44
	v_min_u32_e32 v44, v48, v44
	v_max_u32_e32 v33, v7, v15
	v_min_u32_e32 v15, v7, v15
	v_max_u32_e32 v46, v50, v8
	v_min_u32_e32 v8, v50, v8
	v_max_u32_e32 v11, v3, v13
	v_min_u32_e32 v13, v3, v13
	v_max_u32_e32 v4, v39, v49
	v_min_u32_e32 v49, v39, v49
	v_max_u32_e32 v6, v33, v42
	v_min_u32_e32 v42, v33, v42
	v_max_u32_e32 v12, v43, v46
	v_min_u32_e32 v46, v43, v46
	v_max_u32_e32 v14, v35, v11
	v_min_u32_e32 v11, v35, v11
	v_max_u32_e32 v2, v4, v8
	v_min_u32_e32 v8, v4, v8
	v_max_u32_e32 v1, v6, v13
	v_min_u32_e32 v13, v6, v13
	v_max_u32_e32 v34, v49, v37
	v_min_u32_e32 v37, v49, v37
	v_max_u32_e32 v10, v42, v40
	v_min_u32_e32 v40, v42, v40
	v_max_u32_e32 v5, v36, v12
	v_min_u32_e32 v12, v36, v12
	v_max_u32_e32 v32, v14, v46
	v_min_u32_e32 v46, v14, v46
	v_max_u32_e32 v0, v11, v2
	v_min_u32_e32 v2, v11, v2
	v_max_u32_e32 v47, v1, v8
	v_min_u32_e32 v8, v1, v8
	v_max_u32_e32 v51, v13, v34
	v_min_u32_e32 v34, v13, v34
	v_max_u32_e32 v9, v10, v37
	v_min_u32_e32 v37, v10, v37
	v_max_u32_e32 v41, v40, v44
	v_min_u32_e32 v44, v40, v44
	v_max_u32_e32 v45, v16, v17
	v_min_u32_e32 v17, v16, v17
	v_max_u32_e32 v48, v18, v19
	v_min_u32_e32 v19, v18, v19
	v_max_u32_e32 v7, v20, v21
	v_min_u32_e32 v21, v20, v21
	v_max_u32_e32 v50, v22, v23
	v_min_u32_e32 v23, v22, v23
	v_max_u32_e32 v3, v24, v25
	v_min_u32_e32 v25, v24, v25
	v_max_u32_e32 v39, v26, v27
	v_min_u32_e32 v27, v26, v27
	v_max_u32_e32 v33, v28, v29
	v_min_u32_e32 v29, v28, v29
	v_max_u32_e32 v43, v30, v31
	v_min_u32_e32 v31, v30, v31
	v_max_u32_e32 v35, v45, v48
	v_min_u32_e32 v48, v45, v48
	v_max_u32_e32 v4, v17, v19
	v_min_u32_e32 v19, v17, v19
	v_max_u32_e32 v6, v7, v50
	v_min_u32_e32 v50, v7, v50
	v_max_u32_e32 v49, v21, v23
	v_min_u32_e32 v23, v21, v23
	v_max_u32_e32 v42, v3, v39
	v_min_u32_e32 v39, v3, v39
	v_max_u32_e32 v36, v25, v27
	v_min_u32_e32 v27, v25, v27
	v_max_u32_e32 v14, v33, v43
	v_min_u32_e32 v43, v33, v43
	v_max_u32_e32 v11, v29, v31
	v_min_u32_e32 v31, v29, v31
	v_max_u32_e32 v1, v4, v48
	v_min_u32_e32 v48, v4, v48
	v_max_u32_e32 v13, v49, v50
	v_min_u32_e32 v50, v49, v50
	v_max_u32_e32 v10, v36, v39
	v_min_u32_e32 v39, v36, v39
	v_max_u32_e32 v40, v11, v43
	v_min_u32_e32 v43, v11, v43
	v_max_u32_e32 v16, v35, v6
	v_min_u32_e32 v6, v35, v6
	v_max_u32_e32 v18, v1, v13
	v_min_u32_e32 v13, v1, v13
	v_max_u32_e32 v20, v48, v50
	v_min_u32_e32 v50, v48, v50
	v_max_u32_e32 v22, v19, v23
	v_min_u32_e32 v23, v19, v23
	v_max_u32_e32 v24, v42, v14
	v_min_u32_e32 v14, v42, v14
	v_max_u32_e32 v26, v10, v40
	v_min_u32_e32 v40, v10, v40
	v_max_u32_e32 v28, v39, v43
	v_min_u32_e32 v43, v39, v43
	v_max_u32_e32 v30, v27, v31
	v_min_u32_e32 v31, v27, v31
	v_max_u32_e32 v45, v20, v6
	v_min_u32_e32 v6, v20, v6
	v_max_u32_e32 v17, v22, v13
	v_min_u32_e32 v13, v22, v13
	v_max_u32_e32 v7, v28, v14
	v_min_u32_e32 v14, v28, v14
	v_max_u32_e32 v21, v30, v40
	v_min_u32_e32 v40, v30, v40
	v_max_u32_e32 v3, v18, v45
	v_min_u32_e32 v45, v18, v45
	v_max_u32_e32 v25, v17, v6
	v_min_u32_e32 v6, v17, v6
	v_max_u32_e32 v33, v13, v50
	v_min_u32_e32 v50, v13, v50
	v_max_u32_e32 v29, v26, v7
	v_min_u32_e32 v7, v26, v7
	v_max_u32_e32 v4, v21, v14
	v_min_u32_e32 v14, v21, v14
	v_max_u32_e32 v49, v40, v43
	v_min_u32_e32 v43, v40, v43
	v_max_u32_e32 v36, v16, v24
	v_min_u32_e32 v24, v16, v24
	v_max_u32_e32 v11, v3, v29
	v_min_u32_e32 v29, v3, v29
	v_max_u32_e32 v35, v45, v7
	v_min_u32_e32 v7, v45, v7
; __device__ void ph_peer(const float* __restrict__ SC, const bf16_t* __restrict__ H  , const float* __restrict__ gffn, const unsigned char* __restrict__ U, const unsigned char* __restrict__ V, float* X, const float* __restrict__ fgain) {
;     ...
;             for (int it = 0; it < 16; ++it) {
; #pragma unroll
;                 for (int u = 0; u < 2; ++u) {
;                     const unsigned a = ck[u][0] > ck[u][1] ? ck[u][0] : ck[u][1], b = ck[u][2] > ck[u][3] ? ck[u][2] : ck[u][3];
;                     const unsigned mx = wave_max_u32(a > b ? a : b);
;                     if (lane == it) best[u] = mx;
; #pragma unroll
;                     for (int jj = 0; jj < 4; ++jj) if (ck[u][jj] == mx) ck[u][jj] = 0u; }
;             }
	v_max_u32_e32 v1, v25, v4
	v_min_u32_e32 v4, v25, v4
	v_max_u32_e32 v48, v6, v14
	v_min_u32_e32 v14, v6, v14
	v_max_u32_e32 v19, v33, v49
	v_min_u32_e32 v49, v33, v49
	v_max_u32_e32 v42, v50, v43
	v_min_u32_e32 v43, v50, v43
	v_max_u32_e32 v10, v23, v31
	v_min_u32_e32 v31, v23, v31
	v_max_u32_e32 v39, v48, v24
	v_min_u32_e32 v24, v48, v24
	v_max_u32_e32 v27, v19, v29
	v_min_u32_e32 v29, v19, v29
	v_max_u32_e32 v20, v42, v7
	v_min_u32_e32 v7, v42, v7
	v_max_u32_e32 v22, v10, v4
	v_min_u32_e32 v4, v10, v4
	v_max_u32_e32 v28, v35, v39
	v_min_u32_e32 v39, v35, v39
	v_max_u32_e32 v30, v1, v27
	v_min_u32_e32 v27, v1, v27
	v_max_u32_e32 v18, v20, v24
	v_min_u32_e32 v24, v20, v24
	v_max_u32_e32 v17, v22, v29
	v_min_u32_e32 v29, v22, v29
	v_max_u32_e32 v13, v7, v14
	v_min_u32_e32 v14, v7, v14
	v_max_u32_e32 v26, v4, v49
	v_min_u32_e32 v49, v4, v49
	v_max_u32_e32 v21, v11, v28
	v_min_u32_e32 v28, v11, v28
	v_max_u32_e32 v40, v30, v39
	v_min_u32_e32 v39, v30, v39
	v_max_u32_e32 v16, v27, v18
	v_min_u32_e32 v18, v27, v18
	v_max_u32_e32 v3, v17, v24
	v_min_u32_e32 v24, v17, v24
	v_max_u32_e32 v45, v29, v13
	v_min_u32_e32 v13, v29, v13
	v_max_u32_e32 v25, v26, v14
	v_min_u32_e32 v14, v26, v14
	v_max_u32_e32 v6, v49, v43
	v_min_u32_e32 v43, v49, v43
	v_max_u32_e32 v33, v180, v181
	v_min_u32_e32 v181, v180, v181
	v_max_u32_e32 v50, v182, v183
	v_min_u32_e32 v183, v182, v183
	v_max_u32_e32 v23, v184, v185
	v_min_u32_e32 v185, v184, v185
	v_max_u32_e32 v48, v186, v187
	v_min_u32_e32 v187, v186, v187
	v_max_u32_e32 v19, v188, v189
	v_min_u32_e32 v189, v188, v189
	v_max_u32_e32 v42, v190, v191
	v_min_u32_e32 v191, v190, v191
	v_max_u32_e32 v10, v192, v193
	v_min_u32_e32 v193, v192, v193
	v_max_u32_e32 v35, v194, v195
	v_min_u32_e32 v195, v194, v195
	v_max_u32_e32 v1, v33, v50
	v_min_u32_e32 v50, v33, v50
	v_max_u32_e32 v20, v181, v183
	v_min_u32_e32 v183, v181, v183
	v_max_u32_e32 v22, v23, v48
	v_min_u32_e32 v48, v23, v48
	v_max_u32_e32 v7, v185, v187
	v_min_u32_e32 v187, v185, v187
	v_max_u32_e32 v4, v19, v42
	v_min_u32_e32 v42, v19, v42
	v_max_u32_e32 v11, v189, v191
	v_min_u32_e32 v191, v189, v191
	v_max_u32_e32 v30, v10, v35
	v_min_u32_e32 v35, v10, v35
	v_max_u32_e32 v27, v193, v195
	v_min_u32_e32 v195, v193, v195
	v_max_u32_e32 v17, v20, v50
	v_min_u32_e32 v50, v20, v50
	v_max_u32_e32 v29, v7, v48
	v_min_u32_e32 v48, v7, v48
	v_max_u32_e32 v26, v11, v42
	v_min_u32_e32 v42, v11, v42
	v_max_u32_e32 v49, v27, v35
	v_min_u32_e32 v35, v27, v35
	v_max_u32_e32 v180, v1, v22
	v_min_u32_e32 v22, v1, v22
	v_max_u32_e32 v182, v17, v29
	v_min_u32_e32 v29, v17, v29
	v_max_u32_e32 v184, v50, v48
	v_min_u32_e32 v48, v50, v48
	v_max_u32_e32 v186, v183, v187
	v_min_u32_e32 v187, v183, v187
	v_max_u32_e32 v188, v4, v30
	v_min_u32_e32 v30, v4, v30
	v_max_u32_e32 v190, v26, v49
	v_min_u32_e32 v49, v26, v49
	v_max_u32_e32 v192, v42, v35
	v_min_u32_e32 v35, v42, v35
	v_max_u32_e32 v194, v191, v195
	v_min_u32_e32 v195, v191, v195
	v_max_u32_e32 v33, v184, v22
	v_min_u32_e32 v22, v184, v22
	v_max_u32_e32 v181, v186, v29
	v_min_u32_e32 v29, v186, v29
	v_max_u32_e32 v23, v192, v30
	v_min_u32_e32 v30, v192, v30
	v_max_u32_e32 v185, v194, v49
	v_min_u32_e32 v49, v194, v49
	v_max_u32_e32 v19, v182, v33
	v_min_u32_e32 v33, v182, v33
	v_max_u32_e32 v189, v181, v22
	v_min_u32_e32 v22, v181, v22
	v_max_u32_e32 v10, v29, v48
	v_min_u32_e32 v48, v29, v48
	v_max_u32_e32 v193, v190, v23
	v_min_u32_e32 v23, v190, v23
	v_max_u32_e32 v20, v185, v30
	v_min_u32_e32 v30, v185, v30
	v_max_u32_e32 v7, v49, v35
	v_min_u32_e32 v35, v49, v35
	v_max_u32_e32 v11, v180, v188
	v_min_u32_e32 v188, v180, v188
	v_max_u32_e32 v27, v19, v193
	v_min_u32_e32 v193, v19, v193
	v_max_u32_e32 v1, v33, v23
	v_min_u32_e32 v23, v33, v23
	v_max_u32_e32 v17, v189, v20
	v_min_u32_e32 v20, v189, v20
	v_max_u32_e32 v50, v22, v30
	v_min_u32_e32 v30, v22, v30
	v_max_u32_e32 v183, v10, v7
	v_min_u32_e32 v7, v10, v7
	v_max_u32_e32 v4, v48, v35
	v_min_u32_e32 v35, v48, v35
	v_max_u32_e32 v26, v187, v195
	v_min_u32_e32 v195, v187, v195
	v_max_u32_e32 v42, v50, v188
	v_min_u32_e32 v188, v50, v188
	v_max_u32_e32 v191, v183, v193
	v_min_u32_e32 v193, v183, v193
	v_max_u32_e32 v184, v4, v23
	v_min_u32_e32 v23, v4, v23
	v_max_u32_e32 v186, v26, v20
	v_min_u32_e32 v20, v26, v20
	v_max_u32_e32 v192, v1, v42
	v_min_u32_e32 v42, v1, v42
	v_max_u32_e32 v194, v17, v191
	v_min_u32_e32 v191, v17, v191
	v_max_u32_e32 v182, v184, v188
	v_min_u32_e32 v188, v184, v188
	v_max_u32_e32 v181, v186, v193
	v_min_u32_e32 v193, v186, v193
	v_max_u32_e32 v29, v23, v30
	v_min_u32_e32 v30, v23, v30
	v_max_u32_e32 v190, v20, v7
	v_min_u32_e32 v7, v20, v7
	v_max_u32_e32 v185, v27, v192
	v_min_u32_e32 v192, v27, v192
	v_max_u32_e32 v49, v194, v42
	v_min_u32_e32 v42, v194, v42
	v_max_u32_e32 v180, v191, v182
	v_min_u32_e32 v182, v191, v182
	v_max_u32_e32 v19, v181, v188
	v_min_u32_e32 v188, v181, v188
	v_max_u32_e32 v33, v193, v29
	v_min_u32_e32 v29, v193, v29
	v_max_u32_e32 v189, v190, v30
	v_min_u32_e32 v30, v190, v30
	v_max_u32_e32 v22, v7, v35
	v_min_u32_e32 v35, v7, v35
	v_max_u32_e32 v10, v196, v197
	v_min_u32_e32 v197, v196, v197
	v_max_u32_e32 v48, v38, v31
	v_max_u32_e32 v187, v5, v43
	v_max_u32_e32 v50, v12, v6
	v_max_u32_e32 v183, v32, v14
	v_max_u32_e32 v4, v46, v25
	v_max_u32_e32 v26, v0, v13
	v_max_u32_e32 v1, v2, v45
	v_max_u32_e32 v17, v47, v24
	v_max_u32_e32 v184, v8, v3
	v_max_u32_e32 v186, v51, v18
	v_max_u32_e32 v23, v34, v16
	v_max_u32_e32 v20, v9, v39
	v_max_u32_e32 v27, v37, v40
	v_max_u32_e32 v194, v41, v28
	v_max_u32_e32 v191, v44, v21
	v_max_u32_e32 v181, v15, v36
	v_max_u32_e32 v193, v48, v184
	v_min_u32_e32 v184, v48, v184
; __device__ void ph_peer(const float* __restrict__ SC, const bf16_t* __restrict__ H  , const float* __restrict__ gffn, const unsigned char* __restrict__ U, const unsigned char* __restrict__ V, float* X, const float* __restrict__ fgain) {
;     ...
;             for (int it = 0; it < 16; ++it) {
; #pragma unroll
;                 for (int u = 0; u < 2; ++u) {
;                     const unsigned a = ck[u][0] > ck[u][1] ? ck[u][0] : ck[u][1], b = ck[u][2] > ck[u][3] ? ck[u][2] : ck[u][3];
;                     const unsigned mx = wave_max_u32(a > b ? a : b);
;                     if (lane == it) best[u] = mx;
; #pragma unroll
;                     for (int jj = 0; jj < 4; ++jj) if (ck[u][jj] == mx) ck[u][jj] = 0u; }
;             }
	v_max_u32_e32 v190, v187, v186
	v_min_u32_e32 v186, v187, v186
	v_max_u32_e32 v7, v50, v23
	v_min_u32_e32 v23, v50, v23
	v_max_u32_e32 v196, v183, v20
	v_min_u32_e32 v20, v183, v20
	v_max_u32_e32 v38, v4, v27
	v_min_u32_e32 v27, v4, v27
	v_max_u32_e32 v5, v26, v194
	v_min_u32_e32 v194, v26, v194
	v_max_u32_e32 v12, v1, v191
	v_min_u32_e32 v191, v1, v191
	v_max_u32_e32 v32, v17, v181
	v_min_u32_e32 v181, v17, v181
	v_max_u32_e32 v46, v193, v38
	v_min_u32_e32 v38, v193, v38
	v_max_u32_e32 v0, v190, v5
	v_min_u32_e32 v5, v190, v5
	v_max_u32_e32 v2, v7, v12
	v_min_u32_e32 v12, v7, v12
	v_max_u32_e32 v47, v196, v32
	v_min_u32_e32 v32, v196, v32
	v_max_u32_e32 v8, v184, v27
	v_min_u32_e32 v27, v184, v27
	v_max_u32_e32 v51, v186, v194
	v_min_u32_e32 v194, v186, v194
	v_max_u32_e32 v34, v23, v191
	v_min_u32_e32 v191, v23, v191
	v_max_u32_e32 v9, v20, v181
	v_min_u32_e32 v181, v20, v181
	v_max_u32_e32 v37, v46, v2
	v_min_u32_e32 v2, v46, v2
	v_max_u32_e32 v41, v0, v47
	v_min_u32_e32 v47, v0, v47
	v_max_u32_e32 v44, v38, v12
	v_min_u32_e32 v12, v38, v12
	v_max_u32_e32 v15, v5, v32
	v_min_u32_e32 v32, v5, v32
	v_max_u32_e32 v48, v8, v34
	v_min_u32_e32 v34, v8, v34
	v_max_u32_e32 v187, v51, v9
	v_min_u32_e32 v9, v51, v9
	v_max_u32_e32 v50, v27, v191
	v_min_u32_e32 v191, v27, v191
	v_max_u32_e32 v183, v194, v181
	v_min_u32_e32 v181, v194, v181
	v_max_u32_e32 v4, v37, v41
	v_min_u32_e32 v41, v37, v41
	v_max_u32_e32 v26, v2, v47
	v_min_u32_e32 v47, v2, v47
	v_max_u32_e32 v1, v44, v15
	v_min_u32_e32 v15, v44, v15
	v_max_u32_e32 v17, v12, v32
	v_min_u32_e32 v32, v12, v32
	v_max_u32_e32 v193, v48, v187
	v_min_u32_e32 v187, v48, v187
	v_max_u32_e32 v190, v34, v9
	v_min_u32_e32 v9, v34, v9
	v_max_u32_e32 v7, v50, v183
	v_min_u32_e32 v183, v50, v183
	v_max_u32_e32 v196, v191, v181
	v_min_u32_e32 v181, v191, v181
	v_max_u32_e32 v184, v35, v197
	v_max_u32_e32 v186, v195, v10
	v_max_u32_e32 v23, v11, v188
	v_min_u32_e32 v188, v11, v188
	v_max_u32_e32 v20, v185, v33
	v_min_u32_e32 v33, v185, v33
	v_max_u32_e32 v46, v192, v29
	v_min_u32_e32 v29, v192, v29
	v_max_u32_e32 v0, v49, v189
	v_min_u32_e32 v189, v49, v189
	v_max_u32_e32 v38, v42, v30
	v_min_u32_e32 v30, v42, v30
	v_max_u32_e32 v5, v180, v22
	v_min_u32_e32 v22, v180, v22
	v_max_u32_e32 v8, v182, v184
	v_min_u32_e32 v184, v182, v184
	v_max_u32_e32 v51, v19, v186
	v_min_u32_e32 v186, v19, v186
	v_max_u32_e32 v27, v23, v38
	v_min_u32_e32 v38, v23, v38
	v_max_u32_e32 v194, v20, v5
	v_min_u32_e32 v5, v20, v5
	v_max_u32_e32 v37, v46, v8
	v_min_u32_e32 v8, v46, v8
	v_max_u32_e32 v2, v0, v51
	v_min_u32_e32 v51, v0, v51
	v_max_u32_e32 v44, v188, v30
	v_min_u32_e32 v30, v188, v30
	v_max_u32_e32 v12, v33, v22
	v_min_u32_e32 v22, v33, v22
	v_max_u32_e32 v48, v29, v184
	v_min_u32_e32 v184, v29, v184
	v_max_u32_e32 v34, v189, v186
	v_min_u32_e32 v186, v189, v186
	v_max_u32_e32 v50, v27, v37
	v_min_u32_e32 v37, v27, v37
	v_max_u32_e32 v191, v194, v2
	v_min_u32_e32 v2, v194, v2
	v_max_u32_e32 v35, v38, v8
	v_min_u32_e32 v8, v38, v8
	v_max_u32_e32 v195, v5, v51
	v_min_u32_e32 v51, v5, v51
	v_max_u32_e32 v11, v44, v48
	v_min_u32_e32 v48, v44, v48
	v_max_u32_e32 v185, v12, v34
	v_min_u32_e32 v34, v12, v34
	v_max_u32_e32 v192, v30, v184
	v_min_u32_e32 v184, v30, v184
	v_max_u32_e32 v49, v22, v186
	v_min_u32_e32 v186, v22, v186
	v_max_u32_e32 v42, v50, v191
	v_min_u32_e32 v191, v50, v191
	v_max_u32_e32 v180, v37, v2
	v_min_u32_e32 v2, v37, v2
	v_max_u32_e32 v182, v35, v195
	v_min_u32_e32 v195, v35, v195
	v_max_u32_e32 v19, v8, v51
	v_min_u32_e32 v51, v8, v51
	v_max_u32_e32 v23, v11, v185
	v_min_u32_e32 v185, v11, v185
	v_max_u32_e32 v20, v48, v34
	v_min_u32_e32 v34, v48, v34
	v_max_u32_e32 v46, v192, v49
	v_min_u32_e32 v49, v192, v49
	v_max_u32_e32 v0, v184, v186
	v_min_u32_e32 v186, v184, v186
	v_max_u32_e32 v188, v4, v186
	v_max_u32_e32 v33, v41, v0
	v_max_u32_e32 v29, v26, v49
	v_max_u32_e32 v189, v47, v46
	v_max_u32_e32 v27, v1, v34
	v_max_u32_e32 v194, v15, v20
	v_max_u32_e32 v38, v17, v185
	v_max_u32_e32 v5, v32, v23
	v_max_u32_e32 v44, v193, v51
	v_max_u32_e32 v12, v187, v19
	v_max_u32_e32 v30, v190, v195
	v_max_u32_e32 v22, v9, v182
	v_max_u32_e32 v50, v7, v2
	v_max_u32_e32 v37, v183, v180
	v_max_u32_e32 v35, v196, v191
	v_max_u32_e32 v8, v181, v42
	v_max_u32_e32 v11, v188, v44
	v_min_u32_e32 v44, v188, v44
	v_max_u32_e32 v48, v33, v12
	v_min_u32_e32 v12, v33, v12
	v_max_u32_e32 v192, v29, v30
	v_min_u32_e32 v30, v29, v30
	v_max_u32_e32 v184, v189, v22
; __device__ __forceinline__ float key2f(unsigned k) { return __uint_as_float((k & 0x80000000u) ? (k & 0x7fffffffu) : ~k); }
; __device__ void ph_peer(const float* __restrict__ SC, const bf16_t* __restrict__ H  , const float* __restrict__ gffn, const unsigned char* __restrict__ U, const unsigned char* __restrict__ V, float* X, const float* __restrict__ fgain) {
;     ...
;             for (int it = 0; it < 16; ++it) {
; #pragma unroll
;                 for (int u = 0; u < 2; ++u) {
;                     const unsigned a = ck[u][0] > ck[u][1] ? ck[u][0] : ck[u][1], b = ck[u][2] > ck[u][3] ? ck[u][2] : ck[u][3];
;                     const unsigned mx = wave_max_u32(a > b ? a : b);
;                     if (lane == it) best[u] = mx;
; #pragma unroll
;                     for (int jj = 0; jj < 4; ++jj) if (ck[u][jj] == mx) ck[u][jj] = 0u; }
;             }
; #pragma unroll
;             for (int u = 0; u < 2; ++u) {
;                 const float bs = key2f(best[u] & ~255u);
;                 const int pos = 255 - (int)(best[u] & 255u);
;                 const int e0 = __shfl(n0[u], (pos >> 4) & 15), e1 = __shfl(n1[u], pos & 15);
;                 const float mxs = __shfl(bs, 0);
	v_min_u32_e32 v22, v189, v22
	v_max_u32_e32 v4, v27, v50
	v_min_u32_e32 v50, v27, v50
	v_max_u32_e32 v41, v194, v37
	v_min_u32_e32 v37, v194, v37
	v_max_u32_e32 v26, v38, v35
	v_min_u32_e32 v35, v38, v35
	v_max_u32_e32 v47, v5, v8
	v_min_u32_e32 v8, v5, v8
	v_max_u32_e32 v1, v11, v4
	v_min_u32_e32 v4, v11, v4
	v_max_u32_e32 v15, v48, v41
	v_min_u32_e32 v41, v48, v41
	v_max_u32_e32 v17, v192, v26
	v_min_u32_e32 v26, v192, v26
	v_max_u32_e32 v32, v184, v47
	v_min_u32_e32 v47, v184, v47
	v_max_u32_e32 v193, v44, v50
	v_min_u32_e32 v50, v44, v50
	v_max_u32_e32 v187, v12, v37
	v_min_u32_e32 v37, v12, v37
	v_max_u32_e32 v190, v30, v35
	v_min_u32_e32 v35, v30, v35
	v_max_u32_e32 v9, v22, v8
	v_min_u32_e32 v8, v22, v8
	v_max_u32_e32 v7, v1, v17
	v_min_u32_e32 v17, v1, v17
	v_max_u32_e32 v183, v15, v32
	v_min_u32_e32 v32, v15, v32
	v_max_u32_e32 v196, v4, v26
	v_min_u32_e32 v26, v4, v26
	v_max_u32_e32 v181, v41, v47
	v_min_u32_e32 v47, v41, v47
	v_max_u32_e32 v188, v193, v190
	v_min_u32_e32 v190, v193, v190
	v_max_u32_e32 v33, v187, v9
	v_min_u32_e32 v9, v187, v9
	v_max_u32_e32 v29, v50, v35
	v_min_u32_e32 v35, v50, v35
	v_max_u32_e32 v189, v37, v8
	v_min_u32_e32 v8, v37, v8
	v_max_u32_e32 v27, v7, v183
	v_min_u32_e32 v183, v7, v183
	v_max_u32_e32 v194, v17, v32
	v_min_u32_e32 v32, v17, v32
	v_max_u32_e32 v38, v196, v181
	v_min_u32_e32 v181, v196, v181
	v_max_u32_e32 v5, v26, v47
	v_min_u32_e32 v47, v26, v47
	v_max_u32_e32 v11, v188, v33
	v_min_u32_e32 v33, v188, v33
	v_max_u32_e32 v48, v190, v9
	v_min_u32_e32 v9, v190, v9
	v_max_u32_e32 v192, v29, v189
	v_min_u32_e32 v189, v29, v189
	v_max_u32_e32 v184, v35, v8
	v_min_u32_e32 v8, v35, v8
	ds_write_b8 v156, v27 offset:96
	ds_write_b8 v156, v183 offset:97
	ds_write_b8 v156, v194 offset:98
	ds_write_b8 v156, v32 offset:99
	ds_write_b8 v156, v38 offset:100
	ds_write_b8 v156, v181 offset:101
	ds_write_b8 v156, v5 offset:102
	ds_write_b8 v156, v47 offset:103
	ds_write_b8 v156, v11 offset:104
	ds_write_b8 v156, v33 offset:105
	ds_write_b8 v156, v48 offset:106
	ds_write_b8 v156, v9 offset:107
	ds_write_b8 v156, v192 offset:108
	ds_write_b8 v156, v189 offset:109
	ds_write_b8 v156, v184 offset:110
	ds_write_b8 v156, v8 offset:111
	v_and_b32_e32 v96, s31, v27
	v_ashrrev_i32_e32 v212, 31, v96
	v_lshrrev_b32_e32 v212, 1, v212
	v_xnor_b32_e32 v96, v96, v212
	v_and_b32_e32 v97, s31, v183
	v_ashrrev_i32_e32 v212, 31, v97
	v_lshrrev_b32_e32 v212, 1, v212
	v_xnor_b32_e32 v97, v97, v212
	v_and_b32_e32 v98, s31, v194
	v_ashrrev_i32_e32 v212, 31, v98
	v_lshrrev_b32_e32 v212, 1, v212
	v_xnor_b32_e32 v98, v98, v212
	v_and_b32_e32 v99, s31, v32
	v_ashrrev_i32_e32 v212, 31, v99
	v_lshrrev_b32_e32 v212, 1, v212
	v_xnor_b32_e32 v99, v99, v212
	v_and_b32_e32 v100, s31, v38
	v_ashrrev_i32_e32 v212, 31, v100
	v_lshrrev_b32_e32 v212, 1, v212
	v_xnor_b32_e32 v100, v100, v212
	v_and_b32_e32 v101, s31, v181
	v_ashrrev_i32_e32 v212, 31, v101
	v_lshrrev_b32_e32 v212, 1, v212
	v_xnor_b32_e32 v101, v101, v212
	v_and_b32_e32 v102, s31, v5
	v_ashrrev_i32_e32 v212, 31, v102
	v_lshrrev_b32_e32 v212, 1, v212
	v_xnor_b32_e32 v102, v102, v212
	v_and_b32_e32 v103, s31, v47
	v_ashrrev_i32_e32 v212, 31, v103
	v_lshrrev_b32_e32 v212, 1, v212
	v_xnor_b32_e32 v103, v103, v212
	v_and_b32_e32 v104, s31, v11
	v_ashrrev_i32_e32 v212, 31, v104
	v_lshrrev_b32_e32 v212, 1, v212
	v_xnor_b32_e32 v104, v104, v212
	v_and_b32_e32 v105, s31, v33
	v_ashrrev_i32_e32 v212, 31, v105
	v_lshrrev_b32_e32 v212, 1, v212
	v_xnor_b32_e32 v105, v105, v212
	v_and_b32_e32 v106, s31, v48
	v_ashrrev_i32_e32 v212, 31, v106
	v_lshrrev_b32_e32 v212, 1, v212
	v_xnor_b32_e32 v106, v106, v212
	v_and_b32_e32 v107, s31, v9
	v_ashrrev_i32_e32 v212, 31, v107
	v_lshrrev_b32_e32 v212, 1, v212
	v_xnor_b32_e32 v107, v107, v212
	v_and_b32_e32 v108, s31, v192
	v_ashrrev_i32_e32 v212, 31, v108
	v_lshrrev_b32_e32 v212, 1, v212
	v_xnor_b32_e32 v108, v108, v212
	v_and_b32_e32 v109, s31, v189
	v_ashrrev_i32_e32 v212, 31, v109
	v_lshrrev_b32_e32 v212, 1, v212
	v_xnor_b32_e32 v109, v109, v212
	v_and_b32_e32 v110, s31, v184
	v_ashrrev_i32_e32 v212, 31, v110
	v_lshrrev_b32_e32 v212, 1, v212
	v_xnor_b32_e32 v110, v110, v212
	v_and_b32_e32 v111, s31, v8
	v_ashrrev_i32_e32 v212, 31, v111
	v_lshrrev_b32_e32 v212, 1, v212
	v_xnor_b32_e32 v111, v111, v212
	ds_write_b128 v156, v[96:99] offset:32
	ds_write_b128 v156, v[100:103] offset:48
	ds_write_b128 v156, v[104:107] offset:64
	ds_write_b128 v156, v[108:111] offset:80
	s_branch .LBB0_221

; __device__ __forceinline__ float key2f(unsigned k) { return __uint_as_float((k & 0x80000000u) ? (k & 0x7fffffffu) : ~k); }
; __device__ void ph_peer(const float* __restrict__ SC, const bf16_t* __restrict__ H  , const float* __restrict__ gffn, const unsigned char* __restrict__ U, const unsigned char* __restrict__ V, float* X, const float* __restrict__ fgain) {
;     ...
;             for (int u = 0; u < 2; ++u) {
;                 const float bs = key2f(best[u] & ~255u);
;                 const int pos = 255 - (int)(best[u] & 255u);
;                 const int e0 = __shfl(n0[u], (pos >> 4) & 15), e1 = __shfl(n1[u], pos & 15);
;                 const float mxs = __shfl(bs, 0);
;                 float e = lane < 16 ? __expf((bs - mxs) * rstd) : 0.f;
;                 const float den = row16_sum(e);
;                 const int iv = __shfl(e0 * 128 + e1, lane & 15); const float gv = __shfl(e / den, lane & 15);
;                 const int hh = h + u;
;                 if (grp == (hh & 3)) { if (hh < 4) { idx_lo = iv; g_lo = gv; } else { idx_hi = iv; g_hi = gv; } } }
.Lpeer_partB_b:
	v_lshrrev_b32_e32 v2, 11, v72
	v_lshrrev_b32_e32 v3, 6, v131
	v_lshl_add_u32 v2, v2, 3, v91
	v_mul_u32_u24_e32 v3, 0x1c00, v3
	v_mul_u32_u24_e32 v2, 0x70, v2
	v_and_b32_e32 v4, 15, v74
	v_add_u32_e32 v3, 0x12000, v3
	v_add_u32_e32 v2, v3, v2
	v_add_u32_e32 v5, v2, v4
	v_lshl_add_u32 v6, v4, 2, v2
	ds_read_u8 v7, v5 offset:96
	ds_read_u8 v8, v5 offset:544
	ds_read_b32 v9, v6 offset:32
	ds_read_b32 v10, v6 offset:480
	ds_read_b32 v11, v2 offset:32
	ds_read_b32 v13, v2 offset:480
	s_waitcnt lgkmcnt(4)
	v_not_b32_e32 v7, v7
	v_not_b32_e32 v8, v8
	v_bfe_u32 v14, v7, 4, 4
	v_and_b32_e32 v7, 15, v7
	v_bfe_u32 v15, v8, 4, 4
	v_and_b32_e32 v8, 15, v8
	v_add_u32_e32 v14, v2, v14
	v_add_u32_e32 v7, v2, v7
	v_add_u32_e32 v15, v2, v15
	v_add_u32_e32 v8, v2, v8
	ds_read_u8 v14, v14
	ds_read_u8 v7, v7 offset:16
	ds_read_u8 v15, v15 offset:448
	ds_read_u8 v8, v8 offset:464
	s_waitcnt lgkmcnt(4)
	v_sub_f32_e32 v9, v9, v11
	v_sub_f32_e32 v10, v10, v13
	v_mul_f32_e32 v9, v12, v9
	v_mul_f32_e32 v10, v12, v10
	v_mul_f32_e32 v9, 0x3fb8aa3b, v9
	v_mul_f32_e32 v10, 0x3fb8aa3b, v10
	v_exp_f32_e32 v9, v9
	v_exp_f32_e32 v10, v10
	s_nop 1
	v_add_f32_dpp v11, v9, v9 quad_perm:[1,0,3,2] row_mask:0xf bank_mask:0xf bound_ctrl:1
	v_add_f32_dpp v13, v10, v10 quad_perm:[1,0,3,2] row_mask:0xf bank_mask:0xf bound_ctrl:1
	s_nop 0
	v_add_f32_dpp v11, v11, v11 quad_perm:[2,3,0,1] row_mask:0xf bank_mask:0xf bound_ctrl:1
	v_add_f32_dpp v13, v13, v13 quad_perm:[2,3,0,1] row_mask:0xf bank_mask:0xf bound_ctrl:1
	s_nop 0
	v_add_f32_dpp v11, v11, v11 row_half_mirror row_mask:0xf bank_mask:0xf bound_ctrl:1
	v_add_f32_dpp v13, v13, v13 row_half_mirror row_mask:0xf bank_mask:0xf bound_ctrl:1
	s_nop 0
	v_add_f32_dpp v11, v11, v11 row_mirror row_mask:0xf bank_mask:0xf bound_ctrl:1
	v_add_f32_dpp v13, v13, v13 row_mirror row_mask:0xf bank_mask:0xf bound_ctrl:1
	s_nop 0
	v_div_scale_f32 v16, s[0:1], v11, v11, v9
	v_div_scale_f32 v17, s[0:1], v13, v13, v10
	v_rcp_f32_e32 v18, v16
	v_rcp_f32_e32 v19, v17
	s_nop 0
	v_fma_f32 v20, -v16, v18, 1.0
	v_fma_f32 v21, -v17, v19, 1.0
	v_fmac_f32_e32 v18, v20, v18
	v_fmac_f32_e32 v19, v21, v19
	v_div_scale_f32 v20, vcc, v9, v11, v9
	v_mul_f32_e32 v22, v20, v18
	v_fma_f32 v24, -v16, v22, v20
	v_fmac_f32_e32 v22, v24, v18
	v_fma_f32 v20, -v16, v22, v20
	v_div_fmas_f32 v20, v20, v18, v22
	v_div_fixup_f32 v73, v20, v11, v9
	v_div_scale_f32 v21, vcc, v10, v13, v10
	v_mul_f32_e32 v23, v21, v19
	v_fma_f32 v25, -v17, v23, v21
	v_fmac_f32_e32 v23, v25, v19
	v_fma_f32 v21, -v17, v23, v21
	v_div_fmas_f32 v21, v21, v19, v23
	v_div_fixup_f32 v158, v21, v13, v10
	s_waitcnt lgkmcnt(0)
	v_and_b32_e32 v14, 0x7f, v14
	v_and_b32_e32 v7, 0x7f, v7
	v_and_b32_e32 v15, 0x7f, v15
	v_and_b32_e32 v8, 0x7f, v8
	v_lshl_or_b32 v14, v14, 7, v7
	v_lshl_or_b32 v15, v15, 7, v8
	v_xor_b32_e32 v156, 0x3fff, v14
	v_xor_b32_e32 v157, 0x3fff, v15
	v_lshrrev_b32_e32 v2, 10, v156
	v_lshrrev_b32_e32 v3, 10, v157
	s_mov_b32 s2, 0
	v_mov_b32_e32 v6, 0
	v_mov_b32_e32 v7, 0
	v_cmp_eq_u32_e64 s[0:1], 0, v2
	v_cmp_eq_u32_e64 s[6:7], 0, v3
	s_nop 1
	v_mbcnt_lo_u32_b32 v4, s0, 0
	v_mbcnt_lo_u32_b32 v5, s6, 0
	v_mbcnt_hi_u32_b32 v4, s1, v4
	v_mbcnt_hi_u32_b32 v5, s7, v5
	s_bcnt1_i32_b64 s14, s[0:1]
	s_bcnt1_i32_b64 s15, s[6:7]
	v_add_u32_e32 v4, s2, v4
	s_add_i32 s14, s2, s14
	s_nop 0
	v_add_u32_e32 v5, s14, v5
	s_add_i32 s2, s14, s15
	v_cndmask_b32_e64 v6, v6, v4, s[0:1]
	v_cndmask_b32_e64 v7, v7, v5, s[6:7]
	v_cmp_eq_u32_e64 s[0:1], 1, v2
	v_cmp_eq_u32_e64 s[6:7], 1, v3
	s_nop 1
	v_mbcnt_lo_u32_b32 v4, s0, 0
	v_mbcnt_lo_u32_b32 v5, s6, 0
	v_mbcnt_hi_u32_b32 v4, s1, v4
	v_mbcnt_hi_u32_b32 v5, s7, v5
	s_bcnt1_i32_b64 s14, s[0:1]
	s_bcnt1_i32_b64 s15, s[6:7]
	v_add_u32_e32 v4, s2, v4
	s_add_i32 s14, s2, s14
	s_nop 0
	v_add_u32_e32 v5, s14, v5
	s_add_i32 s2, s14, s15
	v_cndmask_b32_e64 v6, v6, v4, s[0:1]
	v_cndmask_b32_e64 v7, v7, v5, s[6:7]
	v_cmp_eq_u32_e64 s[0:1], 2, v2
	v_cmp_eq_u32_e64 s[6:7], 2, v3
	s_nop 1
	v_mbcnt_lo_u32_b32 v4, s0, 0
	v_mbcnt_lo_u32_b32 v5, s6, 0
	v_mbcnt_hi_u32_b32 v4, s1, v4
	v_mbcnt_hi_u32_b32 v5, s7, v5
	s_bcnt1_i32_b64 s14, s[0:1]
	s_bcnt1_i32_b64 s15, s[6:7]
	v_add_u32_e32 v4, s2, v4
	s_add_i32 s14, s2, s14
	s_nop 0
	v_add_u32_e32 v5, s14, v5
	s_add_i32 s2, s14, s15
	v_cndmask_b32_e64 v6, v6, v4, s[0:1]
	v_cndmask_b32_e64 v7, v7, v5, s[6:7]
	v_cmp_eq_u32_e64 s[0:1], 3, v2
	v_cmp_eq_u32_e64 s[6:7], 3, v3
	s_nop 1
	v_mbcnt_lo_u32_b32 v4, s0, 0
	v_mbcnt_lo_u32_b32 v5, s6, 0
	v_mbcnt_hi_u32_b32 v4, s1, v4
	v_mbcnt_hi_u32_b32 v5, s7, v5
	s_bcnt1_i32_b64 s14, s[0:1]
	s_bcnt1_i32_b64 s15, s[6:7]
	v_add_u32_e32 v4, s2, v4
	s_add_i32 s14, s2, s14
	s_nop 0
	v_add_u32_e32 v5, s14, v5
	s_add_i32 s2, s14, s15
	v_cndmask_b32_e64 v6, v6, v4, s[0:1]
	v_cndmask_b32_e64 v7, v7, v5, s[6:7]
	v_cmp_eq_u32_e64 s[0:1], 4, v2
	v_cmp_eq_u32_e64 s[6:7], 4, v3
	s_nop 1
	v_mbcnt_lo_u32_b32 v4, s0, 0
	v_mbcnt_lo_u32_b32 v5, s6, 0
	v_mbcnt_hi_u32_b32 v4, s1, v4
	v_mbcnt_hi_u32_b32 v5, s7, v5
	s_bcnt1_i32_b64 s14, s[0:1]
	s_bcnt1_i32_b64 s15, s[6:7]
	v_add_u32_e32 v4, s2, v4
	s_add_i32 s14, s2, s14
	s_nop 0
	v_add_u32_e32 v5, s14, v5
	s_add_i32 s2, s14, s15
	v_cndmask_b32_e64 v6, v6, v4, s[0:1]
	v_cndmask_b32_e64 v7, v7, v5, s[6:7]
	v_cmp_eq_u32_e64 s[0:1], 5, v2
	v_cmp_eq_u32_e64 s[6:7], 5, v3
	s_nop 1
	v_mbcnt_lo_u32_b32 v4, s0, 0
	v_mbcnt_lo_u32_b32 v5, s6, 0
	v_mbcnt_hi_u32_b32 v4, s1, v4
	v_mbcnt_hi_u32_b32 v5, s7, v5
	s_bcnt1_i32_b64 s14, s[0:1]
	s_bcnt1_i32_b64 s15, s[6:7]
	v_add_u32_e32 v4, s2, v4
	s_add_i32 s14, s2, s14
	s_nop 0
	v_add_u32_e32 v5, s14, v5
	s_add_i32 s2, s14, s15
	v_cndmask_b32_e64 v6, v6, v4, s[0:1]
	v_cndmask_b32_e64 v7, v7, v5, s[6:7]
	v_cmp_eq_u32_e64 s[0:1], 6, v2
; __device__ void ph_peer(const float* __restrict__ SC, const bf16_t* __restrict__ H  , const float* __restrict__ gffn, const unsigned char* __restrict__ U, const unsigned char* __restrict__ V, float* X, const float* __restrict__ fgain) {
;     ...
;                 const int iv = __shfl(e0 * 128 + e1, lane & 15); const float gv = __shfl(e / den, lane & 15);
;                 const int hh = h + u;
;                 if (grp == (hh & 3)) { if (hh < 4) { idx_lo = iv; g_lo = gv; } else { idx_hi = iv; g_hi = gv; } } }
	v_cmp_eq_u32_e64 s[6:7], 6, v3
	s_nop 1
	v_mbcnt_lo_u32_b32 v4, s0, 0
	v_mbcnt_lo_u32_b32 v5, s6, 0
	v_mbcnt_hi_u32_b32 v4, s1, v4
	v_mbcnt_hi_u32_b32 v5, s7, v5
	s_bcnt1_i32_b64 s14, s[0:1]
	s_bcnt1_i32_b64 s15, s[6:7]
	v_add_u32_e32 v4, s2, v4
	s_add_i32 s14, s2, s14
	s_nop 0
	v_add_u32_e32 v5, s14, v5
	s_add_i32 s2, s14, s15
	v_cndmask_b32_e64 v6, v6, v4, s[0:1]
	v_cndmask_b32_e64 v7, v7, v5, s[6:7]
	v_cmp_eq_u32_e64 s[0:1], 7, v2
	v_cmp_eq_u32_e64 s[6:7], 7, v3
	s_nop 1
	v_mbcnt_lo_u32_b32 v4, s0, 0
	v_mbcnt_lo_u32_b32 v5, s6, 0
	v_mbcnt_hi_u32_b32 v4, s1, v4
	v_mbcnt_hi_u32_b32 v5, s7, v5
	s_bcnt1_i32_b64 s14, s[0:1]
	s_bcnt1_i32_b64 s15, s[6:7]
	v_add_u32_e32 v4, s2, v4
	s_add_i32 s14, s2, s14
	s_nop 0
	v_add_u32_e32 v5, s14, v5
	s_add_i32 s2, s14, s15
	v_cndmask_b32_e64 v6, v6, v4, s[0:1]
	v_cndmask_b32_e64 v7, v7, v5, s[6:7]
	v_cmp_eq_u32_e64 s[0:1], 8, v2
	v_cmp_eq_u32_e64 s[6:7], 8, v3
	s_nop 1
	v_mbcnt_lo_u32_b32 v4, s0, 0
	v_mbcnt_lo_u32_b32 v5, s6, 0
	v_mbcnt_hi_u32_b32 v4, s1, v4
	v_mbcnt_hi_u32_b32 v5, s7, v5
	s_bcnt1_i32_b64 s14, s[0:1]
	s_bcnt1_i32_b64 s15, s[6:7]
	v_add_u32_e32 v4, s2, v4
	s_add_i32 s14, s2, s14
	s_nop 0
	v_add_u32_e32 v5, s14, v5
	s_add_i32 s2, s14, s15
	v_cndmask_b32_e64 v6, v6, v4, s[0:1]
	v_cndmask_b32_e64 v7, v7, v5, s[6:7]
	v_cmp_eq_u32_e64 s[0:1], 9, v2
	v_cmp_eq_u32_e64 s[6:7], 9, v3
	s_nop 1
	v_mbcnt_lo_u32_b32 v4, s0, 0
	v_mbcnt_lo_u32_b32 v5, s6, 0
	v_mbcnt_hi_u32_b32 v4, s1, v4
	v_mbcnt_hi_u32_b32 v5, s7, v5
	s_bcnt1_i32_b64 s14, s[0:1]
	s_bcnt1_i32_b64 s15, s[6:7]
	v_add_u32_e32 v4, s2, v4
	s_add_i32 s14, s2, s14
	s_nop 0
	v_add_u32_e32 v5, s14, v5
	s_add_i32 s2, s14, s15
	v_cndmask_b32_e64 v6, v6, v4, s[0:1]
	v_cndmask_b32_e64 v7, v7, v5, s[6:7]
	v_cmp_eq_u32_e64 s[0:1], 10, v2
	v_cmp_eq_u32_e64 s[6:7], 10, v3
	s_nop 1
	v_mbcnt_lo_u32_b32 v4, s0, 0
	v_mbcnt_lo_u32_b32 v5, s6, 0
	v_mbcnt_hi_u32_b32 v4, s1, v4
	v_mbcnt_hi_u32_b32 v5, s7, v5
	s_bcnt1_i32_b64 s14, s[0:1]
	s_bcnt1_i32_b64 s15, s[6:7]
	v_add_u32_e32 v4, s2, v4
	s_add_i32 s14, s2, s14
	s_nop 0
	v_add_u32_e32 v5, s14, v5
	s_add_i32 s2, s14, s15
	v_cndmask_b32_e64 v6, v6, v4, s[0:1]
	v_cndmask_b32_e64 v7, v7, v5, s[6:7]
	v_cmp_eq_u32_e64 s[0:1], 11, v2
	v_cmp_eq_u32_e64 s[6:7], 11, v3
	s_nop 1
	v_mbcnt_lo_u32_b32 v4, s0, 0
	v_mbcnt_lo_u32_b32 v5, s6, 0
	v_mbcnt_hi_u32_b32 v4, s1, v4
	v_mbcnt_hi_u32_b32 v5, s7, v5
	s_bcnt1_i32_b64 s14, s[0:1]
	s_bcnt1_i32_b64 s15, s[6:7]
	v_add_u32_e32 v4, s2, v4
	s_add_i32 s14, s2, s14
	s_nop 0
	v_add_u32_e32 v5, s14, v5
	s_add_i32 s2, s14, s15
	v_cndmask_b32_e64 v6, v6, v4, s[0:1]
	v_cndmask_b32_e64 v7, v7, v5, s[6:7]
	v_cmp_eq_u32_e64 s[0:1], 12, v2
	v_cmp_eq_u32_e64 s[6:7], 12, v3
	s_nop 1
	v_mbcnt_lo_u32_b32 v4, s0, 0
	v_mbcnt_lo_u32_b32 v5, s6, 0
	v_mbcnt_hi_u32_b32 v4, s1, v4
	v_mbcnt_hi_u32_b32 v5, s7, v5
	s_bcnt1_i32_b64 s14, s[0:1]
	s_bcnt1_i32_b64 s15, s[6:7]
	v_add_u32_e32 v4, s2, v4
	s_add_i32 s14, s2, s14
	s_nop 0
	v_add_u32_e32 v5, s14, v5
	s_add_i32 s2, s14, s15
	v_cndmask_b32_e64 v6, v6, v4, s[0:1]
	v_cndmask_b32_e64 v7, v7, v5, s[6:7]
	v_cmp_eq_u32_e64 s[0:1], 13, v2
	v_cmp_eq_u32_e64 s[6:7], 13, v3
	s_nop 1
	v_mbcnt_lo_u32_b32 v4, s0, 0
	v_mbcnt_lo_u32_b32 v5, s6, 0
	v_mbcnt_hi_u32_b32 v4, s1, v4
	v_mbcnt_hi_u32_b32 v5, s7, v5
	s_bcnt1_i32_b64 s14, s[0:1]
	s_bcnt1_i32_b64 s15, s[6:7]
	v_add_u32_e32 v4, s2, v4
	s_add_i32 s14, s2, s14
	s_nop 0
	v_add_u32_e32 v5, s14, v5
	s_add_i32 s2, s14, s15
	v_cndmask_b32_e64 v6, v6, v4, s[0:1]
	v_cndmask_b32_e64 v7, v7, v5, s[6:7]
	v_cmp_eq_u32_e64 s[0:1], 14, v2
	v_cmp_eq_u32_e64 s[6:7], 14, v3
	s_nop 1
	v_mbcnt_lo_u32_b32 v4, s0, 0
	v_mbcnt_lo_u32_b32 v5, s6, 0
	v_mbcnt_hi_u32_b32 v4, s1, v4
	v_mbcnt_hi_u32_b32 v5, s7, v5
	s_bcnt1_i32_b64 s14, s[0:1]
	s_bcnt1_i32_b64 s15, s[6:7]
	v_add_u32_e32 v4, s2, v4
	s_add_i32 s14, s2, s14
	s_nop 0
	v_add_u32_e32 v5, s14, v5
	s_add_i32 s2, s14, s15
	v_cndmask_b32_e64 v6, v6, v4, s[0:1]
	v_cndmask_b32_e64 v7, v7, v5, s[6:7]
	v_cmp_eq_u32_e64 s[0:1], 15, v2
	v_cmp_eq_u32_e64 s[6:7], 15, v3
	s_nop 1
	v_mbcnt_lo_u32_b32 v4, s0, 0
	v_mbcnt_lo_u32_b32 v5, s6, 0
	v_mbcnt_hi_u32_b32 v4, s1, v4
	v_mbcnt_hi_u32_b32 v5, s7, v5
	s_bcnt1_i32_b64 s14, s[0:1]
	s_bcnt1_i32_b64 s15, s[6:7]
	v_add_u32_e32 v4, s2, v4
	s_add_i32 s14, s2, s14
	s_nop 0
	v_add_u32_e32 v5, s14, v5
	s_add_i32 s2, s14, s15
	v_cndmask_b32_e64 v6, v6, v4, s[0:1]
	v_cndmask_b32_e64 v7, v7, v5, s[6:7]
	v_lshrrev_b32_e32 v8, 6, v131
	v_mul_u32_u24_e32 v8, 0x2400, v8
	v_lshl_add_u32 v9, v6, 2, v8
	v_lshl_add_u32 v10, v7, 2, v8
	ds_write_b32 v9, v156 offset:1536
	ds_write_b32 v10, v157 offset:1536
	ds_write_b32 v9, v73 offset:2048
	ds_write_b32 v10, v158 offset:2048
	s_waitcnt vmcnt(0) lgkmcnt(0)
; __device__ __forceinline__ unsigned cvt_pk_bf16(float lo, float hi) { unsigned r; asm volatile("v_cvt_pk_bf16_f32 %0, %1, %2" : "=v"(r) : "v"(lo), "v"(hi)); return r; }
; __device__ __forceinline__ float bflo(unsigned w) { return __uint_as_float(w << 16); }
; __device__ __forceinline__ float bfhi(unsigned w) { return __uint_as_float(w & 0xffff0000u); }
; __device__ void ph_peer(const float* __restrict__ SC, const bf16_t* __restrict__ H  , const float* __restrict__ gffn, const unsigned char* __restrict__ U, const unsigned char* __restrict__ V, float* X, const float* __restrict__ fgain) {
;     ...
;         {   const u32x4* hp = (const u32x4*)(H + (size_t)tok * 1024 + 64 * sub);
; #pragma unroll
;             for (int q = 0; q < 8; ++q) { const u32x4 w = hp[q];
;                 const float4 ga = *(const float4*)(gffn + 64 * sub + q * 8), gb = *(const float4*)(gffn + 64 * sub + q * 8 + 4);
;                 hf2[q * 4 + 0] = cvt_pk_bf16(bflo(w.x) * rstd * ga.x, bfhi(w.x) * rstd * ga.y);
;                 hf2[q * 4 + 1] = cvt_pk_bf16(bflo(w.y) * rstd * ga.z, bfhi(w.y) * rstd * ga.w);
;                 hf2[q * 4 + 2] = cvt_pk_bf16(bflo(w.z) * rstd * gb.x, bfhi(w.z) * rstd * gb.y);
;                 hf2[q * 4 + 3] = cvt_pk_bf16(bflo(w.w) * rstd * gb.z, bfhi(w.w) * rstd * gb.w); } }
	v_lshlrev_b32_e32 v2, 16, v218
	v_and_b32_e32 v3, 0xffff0000, v218
	v_mul_f32_e32 v2, v12, v2
	v_mul_f32_e32 v3, v12, v3
	v_mul_f32_e32 v2, v64, v2
	v_mul_f32_e32 v3, v65, v3
	v_cvt_pk_bf16_f32 v212, v2, v3
	v_lshlrev_b32_e32 v2, 16, v219
	v_and_b32_e32 v3, 0xffff0000, v219
	v_mul_f32_e32 v2, v12, v2
	v_mul_f32_e32 v3, v12, v3
	v_mul_f32_e32 v2, v66, v2
	v_mul_f32_e32 v3, v67, v3
	v_cvt_pk_bf16_f32 v213, v2, v3
	v_lshlrev_b32_e32 v2, 16, v220
	v_and_b32_e32 v3, 0xffff0000, v220
	v_mul_f32_e32 v2, v12, v2
	v_mul_f32_e32 v3, v12, v3
	v_mul_f32_e32 v2, v68, v2
	v_mul_f32_e32 v3, v69, v3
	v_cvt_pk_bf16_f32 v214, v2, v3
	v_lshlrev_b32_e32 v2, 16, v221
	v_and_b32_e32 v3, 0xffff0000, v221
	v_mul_f32_e32 v2, v12, v2
	v_mul_f32_e32 v3, v12, v3
	v_mul_f32_e32 v2, v70, v2
	v_mul_f32_e32 v3, v71, v3
	v_cvt_pk_bf16_f32 v215, v2, v3
	v_lshlrev_b32_e32 v2, 16, v222
	v_and_b32_e32 v3, 0xffff0000, v222
	v_mul_f32_e32 v2, v12, v2
	v_mul_f32_e32 v3, v12, v3
	v_mul_f32_e32 v2, v32, v2
	v_mul_f32_e32 v3, v33, v3
	v_cvt_pk_bf16_f32 v218, v2, v3
	v_lshlrev_b32_e32 v2, 16, v223
	v_and_b32_e32 v3, 0xffff0000, v223
	v_mul_f32_e32 v2, v12, v2
	v_mul_f32_e32 v3, v12, v3
	v_mul_f32_e32 v2, v34, v2
	v_mul_f32_e32 v3, v35, v3
	v_cvt_pk_bf16_f32 v219, v2, v3
	v_lshlrev_b32_e32 v2, 16, v224
	v_and_b32_e32 v3, 0xffff0000, v224
	v_mul_f32_e32 v2, v12, v2
	v_mul_f32_e32 v3, v12, v3
	v_mul_f32_e32 v2, v36, v2
	v_mul_f32_e32 v3, v37, v3
	v_cvt_pk_bf16_f32 v220, v2, v3
	v_lshlrev_b32_e32 v2, 16, v225
	v_and_b32_e32 v3, 0xffff0000, v225
	v_mul_f32_e32 v2, v12, v2
	v_mul_f32_e32 v3, v12, v3
	v_mul_f32_e32 v2, v38, v2
	v_mul_f32_e32 v3, v39, v3
	v_cvt_pk_bf16_f32 v221, v2, v3
	v_lshlrev_b32_e32 v2, 16, v226
	v_and_b32_e32 v3, 0xffff0000, v226
	v_mul_f32_e32 v2, v12, v2
	v_mul_f32_e32 v3, v12, v3
	v_mul_f32_e32 v2, v40, v2
	v_mul_f32_e32 v3, v41, v3
	v_cvt_pk_bf16_f32 v222, v2, v3
	v_lshlrev_b32_e32 v2, 16, v227
	v_and_b32_e32 v3, 0xffff0000, v227
	v_mul_f32_e32 v2, v12, v2
	v_mul_f32_e32 v3, v12, v3
	v_mul_f32_e32 v2, v42, v2
	v_mul_f32_e32 v3, v43, v3
	v_cvt_pk_bf16_f32 v223, v2, v3
	v_lshlrev_b32_e32 v2, 16, v228
	v_and_b32_e32 v3, 0xffff0000, v228
	v_mul_f32_e32 v2, v12, v2
	v_mul_f32_e32 v3, v12, v3
	v_mul_f32_e32 v2, v44, v2
	v_mul_f32_e32 v3, v45, v3
	v_cvt_pk_bf16_f32 v224, v2, v3
	v_lshlrev_b32_e32 v2, 16, v229
	v_and_b32_e32 v3, 0xffff0000, v229
	v_mul_f32_e32 v2, v12, v2
	v_mul_f32_e32 v3, v12, v3
	v_mul_f32_e32 v2, v46, v2
	v_mul_f32_e32 v3, v47, v3
	v_cvt_pk_bf16_f32 v225, v2, v3
	v_lshlrev_b32_e32 v2, 16, v230
	v_and_b32_e32 v3, 0xffff0000, v230
	v_mul_f32_e32 v2, v12, v2
	v_mul_f32_e32 v3, v12, v3
	v_mul_f32_e32 v2, v48, v2
	v_mul_f32_e32 v3, v49, v3
	v_cvt_pk_bf16_f32 v226, v2, v3
	v_lshlrev_b32_e32 v2, 16, v231
	v_and_b32_e32 v3, 0xffff0000, v231
	v_mul_f32_e32 v2, v12, v2
	v_mul_f32_e32 v3, v12, v3
	v_mul_f32_e32 v2, v50, v2
	v_mul_f32_e32 v3, v51, v3
	v_cvt_pk_bf16_f32 v227, v2, v3
	v_lshlrev_b32_e32 v2, 16, v232
	v_and_b32_e32 v3, 0xffff0000, v232
	v_mul_f32_e32 v2, v12, v2
	v_mul_f32_e32 v3, v12, v3
	v_mul_f32_e32 v2, v52, v2
	v_mul_f32_e32 v3, v53, v3
	v_cvt_pk_bf16_f32 v228, v2, v3
	v_lshlrev_b32_e32 v2, 16, v233
	v_and_b32_e32 v3, 0xffff0000, v233
	v_mul_f32_e32 v2, v12, v2
	v_mul_f32_e32 v3, v12, v3
	v_mul_f32_e32 v2, v54, v2
	v_mul_f32_e32 v3, v55, v3
	v_cvt_pk_bf16_f32 v229, v2, v3
	v_lshlrev_b32_e32 v2, 16, v234
	v_and_b32_e32 v3, 0xffff0000, v234
	v_mul_f32_e32 v2, v12, v2
	v_mul_f32_e32 v3, v12, v3
	v_mul_f32_e32 v2, v56, v2
	v_mul_f32_e32 v3, v57, v3
	v_cvt_pk_bf16_f32 v230, v2, v3
	v_lshlrev_b32_e32 v2, 16, v235
	v_and_b32_e32 v3, 0xffff0000, v235
	v_mul_f32_e32 v2, v12, v2
	v_mul_f32_e32 v3, v12, v3
	v_mul_f32_e32 v2, v58, v2
	v_mul_f32_e32 v3, v59, v3
	v_cvt_pk_bf16_f32 v231, v2, v3
	v_lshlrev_b32_e32 v2, 16, v236
	v_and_b32_e32 v3, 0xffff0000, v236
	v_mul_f32_e32 v2, v12, v2
	v_mul_f32_e32 v3, v12, v3
	v_mul_f32_e32 v2, v60, v2
	v_mul_f32_e32 v3, v61, v3
	v_cvt_pk_bf16_f32 v232, v2, v3
	v_lshlrev_b32_e32 v2, 16, v237
	v_and_b32_e32 v3, 0xffff0000, v237
	v_mul_f32_e32 v2, v12, v2
	v_mul_f32_e32 v3, v12, v3
	v_mul_f32_e32 v2, v62, v2
	v_mul_f32_e32 v3, v63, v3
	v_cvt_pk_bf16_f32 v233, v2, v3
	v_lshlrev_b32_e32 v2, 16, v238
	v_and_b32_e32 v3, 0xffff0000, v238
	v_mul_f32_e32 v2, v12, v2
	v_mul_f32_e32 v3, v12, v3
	v_mul_f32_e32 v2, v98, v2
	v_mul_f32_e32 v3, v99, v3
	v_cvt_pk_bf16_f32 v234, v2, v3
	v_lshlrev_b32_e32 v2, 16, v239
	v_and_b32_e32 v3, 0xffff0000, v239
	v_mul_f32_e32 v2, v12, v2
	v_mul_f32_e32 v3, v12, v3
	v_mul_f32_e32 v2, v100, v2
	v_mul_f32_e32 v3, v101, v3
	v_cvt_pk_bf16_f32 v235, v2, v3
	v_lshlrev_b32_e32 v2, 16, v240
	v_and_b32_e32 v3, 0xffff0000, v240
	v_mul_f32_e32 v2, v12, v2
	v_mul_f32_e32 v3, v12, v3
	v_mul_f32_e32 v2, v102, v2
	v_mul_f32_e32 v3, v103, v3
	v_cvt_pk_bf16_f32 v236, v2, v3
	v_lshlrev_b32_e32 v2, 16, v241
	v_and_b32_e32 v3, 0xffff0000, v241
	v_mul_f32_e32 v2, v12, v2
	v_mul_f32_e32 v3, v12, v3
	v_mul_f32_e32 v2, v104, v2
	v_mul_f32_e32 v3, v105, v3
	v_cvt_pk_bf16_f32 v237, v2, v3
	v_lshlrev_b32_e32 v2, 16, v242
	v_and_b32_e32 v3, 0xffff0000, v242
	v_mul_f32_e32 v2, v12, v2
	v_mul_f32_e32 v3, v12, v3
	v_mul_f32_e32 v2, v106, v2
	v_mul_f32_e32 v3, v107, v3
	v_cvt_pk_bf16_f32 v238, v2, v3
	v_lshlrev_b32_e32 v2, 16, v243
	v_and_b32_e32 v3, 0xffff0000, v243
	v_mul_f32_e32 v2, v12, v2
	v_mul_f32_e32 v3, v12, v3
	v_mul_f32_e32 v2, v108, v2
	v_mul_f32_e32 v3, v109, v3
	v_cvt_pk_bf16_f32 v239, v2, v3
	v_lshlrev_b32_e32 v2, 16, v244
	v_and_b32_e32 v3, 0xffff0000, v244
	v_mul_f32_e32 v2, v12, v2
	v_mul_f32_e32 v3, v12, v3
	v_mul_f32_e32 v2, v110, v2
	v_mul_f32_e32 v3, v111, v3
	v_cvt_pk_bf16_f32 v240, v2, v3
; __device__ void ph_peer(const float* __restrict__ SC, const bf16_t* __restrict__ H  , const float* __restrict__ gffn, const unsigned char* __restrict__ U, const unsigned char* __restrict__ V, float* X, const float* __restrict__ fgain) {
;     ...
;             for (int q = 0; q < 8; ++q) { const u32x4 w = hp[q];
;                 const float4 ga = *(const float4*)(gffn + 64 * sub + q * 8), gb = *(const float4*)(gffn + 64 * sub + q * 8 + 4);
;                 hf2[q * 4 + 0] = cvt_pk_bf16(bflo(w.x) * rstd * ga.x, bfhi(w.x) * rstd * ga.y);
;                 hf2[q * 4 + 1] = cvt_pk_bf16(bflo(w.y) * rstd * ga.z, bfhi(w.y) * rstd * ga.w);
;                 hf2[q * 4 + 2] = cvt_pk_bf16(bflo(w.z) * rstd * gb.x, bfhi(w.z) * rstd * gb.y);
;                 hf2[q * 4 + 3] = cvt_pk_bf16(bflo(w.w) * rstd * gb.z, bfhi(w.w) * rstd * gb.w); } }
;     ...
;         __builtin_amdgcn_s_setprio(1);
; #pragma unroll 1
;         for (int it = 0; it < 32; ++it) {
;             const int src = (it * 4 + grp) & 63;
;             const int e = __shfl(it < 16 ? idx_lo : idx_hi, src);
;             const float gt = __shfl(it < 16 ? g_lo : g_hi, src);
;             const u32x4* up = (const u32x4*)(U + (size_t)e * 768 + 48 * sub);
;             const u32x4 u0 = up[0], u1 = up[1], u2 = up[2];
;             u32x2 vw[2][3];
; #pragma unroll
;             for (int r = 0; r < 2; ++r) { const int ea = __builtin_amdgcn_readlane(e, 32 * r), eb = __builtin_amdgcn_readlane(e, 32 * r + 16);
;                 const u32x2* vp = (const u32x2*)(V + (size_t)(half ? eb : ea) * 768 + 24 * c32); vw[r][0] = vp[0]; vw[r][1] = vp[1]; vw[r][2] = vp[2]; }
;             float d0 = 0.f, d1 = 0.f, d2 = 0.f, d3 = 0.f;
;             {   const v6u_t p0 = (v6u_t){u0.x, u0.y, u0.z, u0.w, u1.x, u1.y};
;                 const v32bf_t r0 = __builtin_amdgcn_cvt_scalef32_pk32_bf16_fp6(p0, 1.0f);
; #pragma unroll
;                 for (int k = 0; k < 16; k += 4) { d0 = dot2pb(r0[2 * k], r0[2 * k + 1], hf2[k], d0); d1 = dot2pb(r0[2 * k + 2], r0[2 * k + 3], hf2[k + 1], d1);
;                     d2 = dot2pb(r0[2 * k + 4], r0[2 * k + 5], hf2[k + 2], d2); d3 = dot2pb(r0[2 * k + 6], r0[2 * k + 7], hf2[k + 3], d3); } }
;             {   const v6u_t p1 = (v6u_t){u1.z, u1.w, u2.x, u2.y, u2.z, u2.w};
;                 const v32bf_t r1 = __builtin_amdgcn_cvt_scalef32_pk32_bf16_fp6(p1, 1.0f);
; #pragma unroll
	v_lshlrev_b32_e32 v2, 16, v245
	v_and_b32_e32 v3, 0xffff0000, v245
	v_mul_f32_e32 v2, v12, v2
	v_mul_f32_e32 v3, v12, v3
	v_mul_f32_e32 v2, v112, v2
	v_mul_f32_e32 v3, v113, v3
	v_cvt_pk_bf16_f32 v241, v2, v3
	v_lshlrev_b32_e32 v2, 16, v246
	v_and_b32_e32 v3, 0xffff0000, v246
	v_mul_f32_e32 v2, v12, v2
	v_mul_f32_e32 v3, v12, v3
	v_mul_f32_e32 v2, v114, v2
	v_mul_f32_e32 v3, v115, v3
	v_cvt_pk_bf16_f32 v242, v2, v3
	v_lshlrev_b32_e32 v2, 16, v247
	v_and_b32_e32 v3, 0xffff0000, v247
	v_mul_f32_e32 v2, v12, v2
	v_mul_f32_e32 v3, v12, v3
	v_mul_f32_e32 v2, v116, v2
	v_mul_f32_e32 v3, v117, v3
	v_cvt_pk_bf16_f32 v243, v2, v3
	v_lshlrev_b32_e32 v2, 16, v248
	v_and_b32_e32 v3, 0xffff0000, v248
	v_mul_f32_e32 v2, v12, v2
	v_mul_f32_e32 v3, v12, v3
	v_mul_f32_e32 v2, v118, v2
	v_mul_f32_e32 v3, v119, v3
	v_cvt_pk_bf16_f32 v244, v2, v3
	v_lshlrev_b32_e32 v2, 16, v249
	v_and_b32_e32 v3, 0xffff0000, v249
	v_mul_f32_e32 v2, v12, v2
	v_mul_f32_e32 v3, v12, v3
	v_mul_f32_e32 v2, v120, v2
	v_mul_f32_e32 v3, v121, v3
	v_cvt_pk_bf16_f32 v245, v2, v3
	s_setprio 1
	v_mov_b32_e32 v126, 0
	s_mov_b32 s0, 0
	s_mov_b32 s1, 0
	v_mov_b32_e32 v127, v126
	v_mov_b32_e32 v144, v126
	v_mov_b32_e32 v145, v126
	v_mov_b32_e32 v122, v126
	v_mov_b32_e32 v123, v126
	v_mov_b32_e32 v124, v126
	v_mov_b32_e32 v125, v126
	v_mov_b32_e32 v114, v126
	v_mov_b32_e32 v115, v126
	v_mov_b32_e32 v118, v126
	v_mov_b32_e32 v119, v126
	v_mov_b32_e32 v116, v126
	v_mov_b32_e32 v117, v126
	v_mov_b32_e32 v120, v126
	v_mov_b32_e32 v121, v126
	v_mov_b32_e32 v106, v126
	v_mov_b32_e32 v107, v126
	v_mov_b32_e32 v110, v126
	v_mov_b32_e32 v111, v126
	v_mov_b32_e32 v108, v126
	v_mov_b32_e32 v109, v126
	v_mov_b32_e32 v112, v126
	v_mov_b32_e32 v113, v126
	v_mov_b32_e32 v98, v126
	v_mov_b32_e32 v99, v126
	v_mov_b32_e32 v102, v126
	v_mov_b32_e32 v103, v126
	v_mov_b32_e32 v100, v126
	v_mov_b32_e32 v101, v126
	v_mov_b32_e32 v104, v126
	v_mov_b32_e32 v105, v126
	s_movk_i32 s14, 0x300
	s_mov_b32 s16, 0x3e6d3388
	s_mov_b32 s24, 0x3f07dc22
	s_mov_b32 s28, 0x3f35f0e3
	s_mov_b32 s30, 0xbe11a98e
	s_mov_b32 s36, 0x3e027906
	s_barrier
	v_lshrrev_b32_e32 v61, 6, v131
	v_mul_u32_u24_e32 v61, 0x2400, v61
	v_lshl_add_u32 v61, v91, 2, v61
	s_mov_b32 s1, 0
	ds_read_b32 v56, v61
	ds_read_b32 v57, v61 offset:512
	v_add_u32_e32 v61, 16, v61
	s_add_i32 s1, s1, 1
	s_waitcnt lgkmcnt(1)
	v_mad_u32_u24 v0, v56, s14, v92
	global_load_dwordx4 v[32:35], v0, s[46:47]
	global_load_dwordx4 v[36:39], v0, s[46:47] offset:16
	global_load_dwordx4 v[40:43], v0, s[46:47] offset:32
.Lpeer_uloop:
	ds_read_b32 v58, v61 offset:1520
	ds_read_b32 v59, v61 offset:2032
	s_waitcnt lgkmcnt(1)
	v_mad_u32_u24 v0, v58, s14, v92
	global_load_dwordx4 v[44:47], v0, s[46:47]
	global_load_dwordx4 v[48:51], v0, s[46:47] offset:16
	global_load_dwordx4 v[52:55], v0, s[46:47] offset:32
	s_waitcnt vmcnt(4)
	v_cvt_scalef32_pk32_bf16_fp6 v[0:15], v[32:37], 1.0
	v_mov_b32_e32 v23, 0
	v_mov_b32_e32 v25, 0
	v_mov_b32_e32 v22, 0
	v_mov_b32_e32 v24, 0
	v_dot2c_f32_bf16_e32 v23, v0, v95
	v_dot2c_f32_bf16_e32 v25, v1, v159
	v_dot2c_f32_bf16_e32 v22, v2, v160
	v_dot2c_f32_bf16_e32 v24, v3, v161
	v_dot2c_f32_bf16_e32 v23, v4, v180
	v_dot2c_f32_bf16_e32 v25, v5, v181
	v_dot2c_f32_bf16_e32 v22, v6, v182
	v_dot2c_f32_bf16_e32 v24, v7, v183
	v_dot2c_f32_bf16_e32 v23, v8, v184
	v_dot2c_f32_bf16_e32 v25, v9, v185
	v_dot2c_f32_bf16_e32 v22, v10, v186
	v_dot2c_f32_bf16_e32 v24, v11, v187
	v_dot2c_f32_bf16_e32 v23, v12, v188
	v_dot2c_f32_bf16_e32 v25, v13, v189
	v_dot2c_f32_bf16_e32 v22, v14, v190
	v_dot2c_f32_bf16_e32 v24, v15, v191
	s_waitcnt vmcnt(3)
	v_cvt_scalef32_pk32_bf16_fp6 v[0:15], v[38:43], 1.0
	v_dot2c_f32_bf16_e32 v23, v0, v192
	v_dot2c_f32_bf16_e32 v25, v1, v193
	v_dot2c_f32_bf16_e32 v22, v2, v194
	v_dot2c_f32_bf16_e32 v24, v3, v195
	v_dot2c_f32_bf16_e32 v23, v4, v196
	v_dot2c_f32_bf16_e32 v25, v5, v197
	v_dot2c_f32_bf16_e32 v22, v6, v198
	v_dot2c_f32_bf16_e32 v24, v7, v199
	v_dot2c_f32_bf16_e32 v23, v8, v200
	v_dot2c_f32_bf16_e32 v25, v9, v201
	v_dot2c_f32_bf16_e32 v22, v10, v202
	v_dot2c_f32_bf16_e32 v24, v11, v203
	v_dot2c_f32_bf16_e32 v23, v12, v204
	v_dot2c_f32_bf16_e32 v25, v13, v205
	v_dot2c_f32_bf16_e32 v22, v14, v206
	v_dot2c_f32_bf16_e32 v24, v15, v207
	s_nop 2
	v_pk_add_f32 v[0:1], v[24:25], v[22:23]
	s_nop 0
	v_add_f32_e32 v0, v0, v1
	s_nop 1
	v_add_f32_dpp v0, v0, v0 quad_perm:[1,0,3,2] row_mask:0xf bank_mask:0xf bound_ctrl:1
	s_nop 1
	v_add_f32_dpp v0, v0, v0 quad_perm:[2,3,0,1] row_mask:0xf bank_mask:0xf bound_ctrl:1
	s_nop 1
	v_add_f32_dpp v0, v0, v0 row_half_mirror row_mask:0xf bank_mask:0xf bound_ctrl:1
	s_nop 1
	v_add_f32_dpp v0, v0, v0 row_mirror row_mask:0xf bank_mask:0xf bound_ctrl:1
	s_waitcnt lgkmcnt(0)
	v_cndmask_b32_e64 v208, v208, v0, s[50:51]
	v_cndmask_b32_e64 v209, v209, v57, s[50:51]
	ds_read_b32 v56, v61
	ds_read_b32 v57, v61 offset:512
	v_add_u32_e32 v61, 16, v61
	s_add_i32 s1, s1, 1
	s_waitcnt lgkmcnt(1)
	v_mad_u32_u24 v0, v56, s14, v92
	global_load_dwordx4 v[32:35], v0, s[46:47]
	global_load_dwordx4 v[36:39], v0, s[46:47] offset:16
	global_load_dwordx4 v[40:43], v0, s[46:47] offset:32
	s_waitcnt vmcnt(4)
	v_cvt_scalef32_pk32_bf16_fp6 v[0:15], v[44:49], 1.0
	v_mov_b32_e32 v23, 0
	v_mov_b32_e32 v25, 0
	v_mov_b32_e32 v22, 0
	v_mov_b32_e32 v24, 0
	v_dot2c_f32_bf16_e32 v23, v0, v212
	v_dot2c_f32_bf16_e32 v25, v1, v213
	v_dot2c_f32_bf16_e32 v22, v2, v214
	v_dot2c_f32_bf16_e32 v24, v3, v215
	v_dot2c_f32_bf16_e32 v23, v4, v218
	v_dot2c_f32_bf16_e32 v25, v5, v219
	v_dot2c_f32_bf16_e32 v22, v6, v220
	v_dot2c_f32_bf16_e32 v24, v7, v221
	v_dot2c_f32_bf16_e32 v23, v8, v222
	v_dot2c_f32_bf16_e32 v25, v9, v223
	v_dot2c_f32_bf16_e32 v22, v10, v224
	v_dot2c_f32_bf16_e32 v24, v11, v225
	v_dot2c_f32_bf16_e32 v23, v12, v226
	v_dot2c_f32_bf16_e32 v25, v13, v227
	v_dot2c_f32_bf16_e32 v22, v14, v228
	v_dot2c_f32_bf16_e32 v24, v15, v229
	s_waitcnt vmcnt(3)
; __device__ __forceinline__ float gelu1(float v) { const f32x2 r = gelu_pk((f32x2){v, v}); return r.x; }
; __device__ void ph_peer(const float* __restrict__ SC, const bf16_t* __restrict__ H  , const float* __restrict__ gffn, const unsigned char* __restrict__ U, const unsigned char* __restrict__ V, float* X, const float* __restrict__ fgain) {
;     ...
;         for (int it = 0; it < 32; ++it) {
;             const int src = (it * 4 + grp) & 63;
;             const int e = __shfl(it < 16 ? idx_lo : idx_hi, src);
;             const float gt = __shfl(it < 16 ? g_lo : g_hi, src);
;             const u32x4* up = (const u32x4*)(U + (size_t)e * 768 + 48 * sub);
;             const u32x4 u0 = up[0], u1 = up[1], u2 = up[2];
;             u32x2 vw[2][3];
; #pragma unroll
;             for (int r = 0; r < 2; ++r) { const int ea = __builtin_amdgcn_readlane(e, 32 * r), eb = __builtin_amdgcn_readlane(e, 32 * r + 16);
;                 const u32x2* vp = (const u32x2*)(V + (size_t)(half ? eb : ea) * 768 + 24 * c32); vw[r][0] = vp[0]; vw[r][1] = vp[1]; vw[r][2] = vp[2]; }
;             float d0 = 0.f, d1 = 0.f, d2 = 0.f, d3 = 0.f;
;             {   const v6u_t p0 = (v6u_t){u0.x, u0.y, u0.z, u0.w, u1.x, u1.y};
;                 const v32bf_t r0 = __builtin_amdgcn_cvt_scalef32_pk32_bf16_fp6(p0, 1.0f);
; #pragma unroll
;                 for (int k = 0; k < 16; k += 4) { d0 = dot2pb(r0[2 * k], r0[2 * k + 1], hf2[k], d0); d1 = dot2pb(r0[2 * k + 2], r0[2 * k + 3], hf2[k + 1], d1);
;                     d2 = dot2pb(r0[2 * k + 4], r0[2 * k + 5], hf2[k + 2], d2); d3 = dot2pb(r0[2 * k + 6], r0[2 * k + 7], hf2[k + 3], d3); } }
;             {   const v6u_t p1 = (v6u_t){u1.z, u1.w, u2.x, u2.y, u2.z, u2.w};
;                 const v32bf_t r1 = __builtin_amdgcn_cvt_scalef32_pk32_bf16_fp6(p1, 1.0f);
; #pragma unroll
;                 for (int k = 0; k < 16; k += 4) { d0 = dot2pb(r1[2 * k], r1[2 * k + 1], hf2[16 + k], d0); d1 = dot2pb(r1[2 * k + 2], r1[2 * k + 3], hf2[16 + k + 1], d1);
;                     d2 = dot2pb(r1[2 * k + 4], r1[2 * k + 5], hf2[16 + k + 2], d2); d3 = dot2pb(r1[2 * k + 6], r1[2 * k + 7], hf2[16 + k + 3], d3); } }
;             const float d = row16_sum((d0 + d1) + (d2 + d3)) * FP6_INV;
;             const float a = gt * gelu1(d) * FP6_INV;
	v_cvt_scalef32_pk32_bf16_fp6 v[0:15], v[50:55], 1.0
	v_dot2c_f32_bf16_e32 v23, v0, v230
	v_dot2c_f32_bf16_e32 v25, v1, v231
	v_dot2c_f32_bf16_e32 v22, v2, v232
	v_dot2c_f32_bf16_e32 v24, v3, v233
	v_dot2c_f32_bf16_e32 v23, v4, v234
	v_dot2c_f32_bf16_e32 v25, v5, v235
	v_dot2c_f32_bf16_e32 v22, v6, v236
	v_dot2c_f32_bf16_e32 v24, v7, v237
	v_dot2c_f32_bf16_e32 v23, v8, v238
	v_dot2c_f32_bf16_e32 v25, v9, v239
	v_dot2c_f32_bf16_e32 v22, v10, v240
	v_dot2c_f32_bf16_e32 v24, v11, v241
	v_dot2c_f32_bf16_e32 v23, v12, v242
	v_dot2c_f32_bf16_e32 v25, v13, v243
	v_dot2c_f32_bf16_e32 v22, v14, v244
	v_dot2c_f32_bf16_e32 v24, v15, v245
	s_nop 2
	v_pk_add_f32 v[0:1], v[24:25], v[22:23]
	s_nop 0
	v_add_f32_e32 v0, v0, v1
	s_nop 1
	v_add_f32_dpp v0, v0, v0 quad_perm:[1,0,3,2] row_mask:0xf bank_mask:0xf bound_ctrl:1
	s_nop 1
	v_add_f32_dpp v0, v0, v0 quad_perm:[2,3,0,1] row_mask:0xf bank_mask:0xf bound_ctrl:1
	s_nop 1
	v_add_f32_dpp v0, v0, v0 row_half_mirror row_mask:0xf bank_mask:0xf bound_ctrl:1
	s_nop 1
	v_add_f32_dpp v0, v0, v0 row_mirror row_mask:0xf bank_mask:0xf bound_ctrl:1
	s_waitcnt lgkmcnt(0)
	v_cndmask_b32_e64 v210, v210, v0, s[50:51]
	v_cndmask_b32_e64 v211, v211, v59, s[50:51]
	ds_read_b32 v58, v61 offset:1520
	ds_read_b32 v59, v61 offset:2032
	s_waitcnt lgkmcnt(1)
	v_mad_u32_u24 v0, v58, s14, v92
	global_load_dwordx4 v[44:47], v0, s[46:47]
	global_load_dwordx4 v[48:51], v0, s[46:47] offset:16
	global_load_dwordx4 v[52:55], v0, s[46:47] offset:32
	s_waitcnt vmcnt(4)
	v_cvt_scalef32_pk32_bf16_fp6 v[0:15], v[32:37], 1.0
	v_mov_b32_e32 v23, 0
	v_mov_b32_e32 v25, 0
	v_mov_b32_e32 v22, 0
	v_mov_b32_e32 v24, 0
	v_dot2c_f32_bf16_e32 v23, v0, v95
	v_dot2c_f32_bf16_e32 v25, v1, v159
	v_dot2c_f32_bf16_e32 v22, v2, v160
	v_dot2c_f32_bf16_e32 v24, v3, v161
	v_dot2c_f32_bf16_e32 v23, v4, v180
	v_dot2c_f32_bf16_e32 v25, v5, v181
	v_dot2c_f32_bf16_e32 v22, v6, v182
	v_dot2c_f32_bf16_e32 v24, v7, v183
	v_dot2c_f32_bf16_e32 v23, v8, v184
	v_dot2c_f32_bf16_e32 v25, v9, v185
	v_dot2c_f32_bf16_e32 v22, v10, v186
	v_dot2c_f32_bf16_e32 v24, v11, v187
	v_dot2c_f32_bf16_e32 v23, v12, v188
	v_dot2c_f32_bf16_e32 v25, v13, v189
	v_dot2c_f32_bf16_e32 v22, v14, v190
	v_dot2c_f32_bf16_e32 v24, v15, v191
	s_waitcnt vmcnt(3)
	v_cvt_scalef32_pk32_bf16_fp6 v[0:15], v[38:43], 1.0
	v_dot2c_f32_bf16_e32 v23, v0, v192
	v_dot2c_f32_bf16_e32 v25, v1, v193
	v_dot2c_f32_bf16_e32 v22, v2, v194
	v_dot2c_f32_bf16_e32 v24, v3, v195
	v_dot2c_f32_bf16_e32 v23, v4, v196
	v_dot2c_f32_bf16_e32 v25, v5, v197
	v_dot2c_f32_bf16_e32 v22, v6, v198
	v_dot2c_f32_bf16_e32 v24, v7, v199
	v_dot2c_f32_bf16_e32 v23, v8, v200
	v_dot2c_f32_bf16_e32 v25, v9, v201
	v_dot2c_f32_bf16_e32 v22, v10, v202
	v_dot2c_f32_bf16_e32 v24, v11, v203
	v_dot2c_f32_bf16_e32 v23, v12, v204
	v_dot2c_f32_bf16_e32 v25, v13, v205
	v_dot2c_f32_bf16_e32 v22, v14, v206
	v_dot2c_f32_bf16_e32 v24, v15, v207
	s_nop 2
	v_pk_add_f32 v[0:1], v[24:25], v[22:23]
	s_nop 0
	v_add_f32_e32 v0, v0, v1
	s_nop 1
	v_add_f32_dpp v0, v0, v0 quad_perm:[1,0,3,2] row_mask:0xf bank_mask:0xf bound_ctrl:1
	s_nop 1
	v_add_f32_dpp v0, v0, v0 quad_perm:[2,3,0,1] row_mask:0xf bank_mask:0xf bound_ctrl:1
	s_nop 1
	v_add_f32_dpp v0, v0, v0 row_half_mirror row_mask:0xf bank_mask:0xf bound_ctrl:1
	s_nop 1
	v_add_f32_dpp v0, v0, v0 row_mirror row_mask:0xf bank_mask:0xf bound_ctrl:1
	s_waitcnt lgkmcnt(0)
	v_cndmask_b32_e64 v208, v208, v0, s[52:53]
	v_cndmask_b32_e64 v209, v209, v57, s[52:53]
	ds_read_b32 v56, v61
	ds_read_b32 v57, v61 offset:512
	v_add_u32_e32 v61, 16, v61
	s_add_i32 s1, s1, 1
	s_waitcnt lgkmcnt(1)
	v_mad_u32_u24 v0, v56, s14, v92
	global_load_dwordx4 v[32:35], v0, s[46:47]
	global_load_dwordx4 v[36:39], v0, s[46:47] offset:16
	global_load_dwordx4 v[40:43], v0, s[46:47] offset:32
	s_waitcnt vmcnt(4)
	v_cvt_scalef32_pk32_bf16_fp6 v[0:15], v[44:49], 1.0
	v_mov_b32_e32 v23, 0
	v_mov_b32_e32 v25, 0
	v_mov_b32_e32 v22, 0
	v_mov_b32_e32 v24, 0
	v_dot2c_f32_bf16_e32 v23, v0, v212
	v_dot2c_f32_bf16_e32 v25, v1, v213
	v_dot2c_f32_bf16_e32 v22, v2, v214
	v_dot2c_f32_bf16_e32 v24, v3, v215
	v_dot2c_f32_bf16_e32 v23, v4, v218
	v_dot2c_f32_bf16_e32 v25, v5, v219
	v_dot2c_f32_bf16_e32 v22, v6, v220
	v_dot2c_f32_bf16_e32 v24, v7, v221
	v_dot2c_f32_bf16_e32 v23, v8, v222
	v_dot2c_f32_bf16_e32 v25, v9, v223
	v_dot2c_f32_bf16_e32 v22, v10, v224
	v_dot2c_f32_bf16_e32 v24, v11, v225
	v_dot2c_f32_bf16_e32 v23, v12, v226
	v_dot2c_f32_bf16_e32 v25, v13, v227
	v_dot2c_f32_bf16_e32 v22, v14, v228
	v_dot2c_f32_bf16_e32 v24, v15, v229
	s_waitcnt vmcnt(3)
	v_cvt_scalef32_pk32_bf16_fp6 v[0:15], v[50:55], 1.0
	v_dot2c_f32_bf16_e32 v23, v0, v230
	v_dot2c_f32_bf16_e32 v25, v1, v231
	v_dot2c_f32_bf16_e32 v22, v2, v232
	v_dot2c_f32_bf16_e32 v24, v3, v233
	v_dot2c_f32_bf16_e32 v23, v4, v234
	v_dot2c_f32_bf16_e32 v25, v5, v235
	v_dot2c_f32_bf16_e32 v22, v6, v236
	v_dot2c_f32_bf16_e32 v24, v7, v237
	v_dot2c_f32_bf16_e32 v23, v8, v238
	v_dot2c_f32_bf16_e32 v25, v9, v239
	v_dot2c_f32_bf16_e32 v22, v10, v240
	v_dot2c_f32_bf16_e32 v24, v11, v241
	v_dot2c_f32_bf16_e32 v23, v12, v242
	v_dot2c_f32_bf16_e32 v25, v13, v243
	v_dot2c_f32_bf16_e32 v22, v14, v244
	v_dot2c_f32_bf16_e32 v24, v15, v245
	s_nop 2
	v_pk_add_f32 v[0:1], v[24:25], v[22:23]
	s_nop 0
	v_add_f32_e32 v0, v0, v1
	s_nop 1
	v_add_f32_dpp v0, v0, v0 quad_perm:[1,0,3,2] row_mask:0xf bank_mask:0xf bound_ctrl:1
	s_nop 1
	v_add_f32_dpp v0, v0, v0 quad_perm:[2,3,0,1] row_mask:0xf bank_mask:0xf bound_ctrl:1
	s_nop 1
	v_add_f32_dpp v0, v0, v0 row_half_mirror row_mask:0xf bank_mask:0xf bound_ctrl:1
	s_nop 1
	v_add_f32_dpp v0, v0, v0 row_mirror row_mask:0xf bank_mask:0xf bound_ctrl:1
	s_waitcnt lgkmcnt(0)
; __device__ __forceinline__ float gelu1(float v) { const f32x2 r = gelu_pk((f32x2){v, v}); return r.x; }
; __device__ void ph_peer(const float* __restrict__ SC, const bf16_t* __restrict__ H  , const float* __restrict__ gffn, const unsigned char* __restrict__ U, const unsigned char* __restrict__ V, float* X, const float* __restrict__ fgain) {
;     ...
;         for (int it = 0; it < 32; ++it) {
;             const int src = (it * 4 + grp) & 63;
;             const int e = __shfl(it < 16 ? idx_lo : idx_hi, src);
;             const float gt = __shfl(it < 16 ? g_lo : g_hi, src);
;             const u32x4* up = (const u32x4*)(U + (size_t)e * 768 + 48 * sub);
;             const u32x4 u0 = up[0], u1 = up[1], u2 = up[2];
;             u32x2 vw[2][3];
; #pragma unroll
;             for (int r = 0; r < 2; ++r) { const int ea = __builtin_amdgcn_readlane(e, 32 * r), eb = __builtin_amdgcn_readlane(e, 32 * r + 16);
;                 const u32x2* vp = (const u32x2*)(V + (size_t)(half ? eb : ea) * 768 + 24 * c32); vw[r][0] = vp[0]; vw[r][1] = vp[1]; vw[r][2] = vp[2]; }
;             float d0 = 0.f, d1 = 0.f, d2 = 0.f, d3 = 0.f;
;             {   const v6u_t p0 = (v6u_t){u0.x, u0.y, u0.z, u0.w, u1.x, u1.y};
;                 const v32bf_t r0 = __builtin_amdgcn_cvt_scalef32_pk32_bf16_fp6(p0, 1.0f);
; #pragma unroll
;                 for (int k = 0; k < 16; k += 4) { d0 = dot2pb(r0[2 * k], r0[2 * k + 1], hf2[k], d0); d1 = dot2pb(r0[2 * k + 2], r0[2 * k + 3], hf2[k + 1], d1);
;                     d2 = dot2pb(r0[2 * k + 4], r0[2 * k + 5], hf2[k + 2], d2); d3 = dot2pb(r0[2 * k + 6], r0[2 * k + 7], hf2[k + 3], d3); } }
;             {   const v6u_t p1 = (v6u_t){u1.z, u1.w, u2.x, u2.y, u2.z, u2.w};
;                 const v32bf_t r1 = __builtin_amdgcn_cvt_scalef32_pk32_bf16_fp6(p1, 1.0f);
; #pragma unroll
;                 for (int k = 0; k < 16; k += 4) { d0 = dot2pb(r1[2 * k], r1[2 * k + 1], hf2[16 + k], d0); d1 = dot2pb(r1[2 * k + 2], r1[2 * k + 3], hf2[16 + k + 1], d1);
;                     d2 = dot2pb(r1[2 * k + 4], r1[2 * k + 5], hf2[16 + k + 2], d2); d3 = dot2pb(r1[2 * k + 6], r1[2 * k + 7], hf2[16 + k + 3], d3); } }
;             const float d = row16_sum((d0 + d1) + (d2 + d3)) * FP6_INV;
;             const float a = gt * gelu1(d) * FP6_INV;
	v_cndmask_b32_e64 v210, v210, v0, s[52:53]
	v_cndmask_b32_e64 v211, v211, v59, s[52:53]
	ds_read_b32 v58, v61 offset:1520
	ds_read_b32 v59, v61 offset:2032
	s_waitcnt lgkmcnt(1)
	v_mad_u32_u24 v0, v58, s14, v92
	global_load_dwordx4 v[44:47], v0, s[46:47]
	global_load_dwordx4 v[48:51], v0, s[46:47] offset:16
	global_load_dwordx4 v[52:55], v0, s[46:47] offset:32
	s_waitcnt vmcnt(4)
	v_cvt_scalef32_pk32_bf16_fp6 v[0:15], v[32:37], 1.0
	v_mov_b32_e32 v23, 0
	v_mov_b32_e32 v25, 0
	v_mov_b32_e32 v22, 0
	v_mov_b32_e32 v24, 0
	v_dot2c_f32_bf16_e32 v23, v0, v95
	v_dot2c_f32_bf16_e32 v25, v1, v159
	v_dot2c_f32_bf16_e32 v22, v2, v160
	v_dot2c_f32_bf16_e32 v24, v3, v161
	v_dot2c_f32_bf16_e32 v23, v4, v180
	v_dot2c_f32_bf16_e32 v25, v5, v181
	v_dot2c_f32_bf16_e32 v22, v6, v182
	v_dot2c_f32_bf16_e32 v24, v7, v183
	v_dot2c_f32_bf16_e32 v23, v8, v184
	v_dot2c_f32_bf16_e32 v25, v9, v185
	v_dot2c_f32_bf16_e32 v22, v10, v186
	v_dot2c_f32_bf16_e32 v24, v11, v187
	v_dot2c_f32_bf16_e32 v23, v12, v188
	v_dot2c_f32_bf16_e32 v25, v13, v189
	v_dot2c_f32_bf16_e32 v22, v14, v190
	v_dot2c_f32_bf16_e32 v24, v15, v191
	s_waitcnt vmcnt(3)
	v_cvt_scalef32_pk32_bf16_fp6 v[0:15], v[38:43], 1.0
	v_dot2c_f32_bf16_e32 v23, v0, v192
	v_dot2c_f32_bf16_e32 v25, v1, v193
	v_dot2c_f32_bf16_e32 v22, v2, v194
	v_dot2c_f32_bf16_e32 v24, v3, v195
	v_dot2c_f32_bf16_e32 v23, v4, v196
	v_dot2c_f32_bf16_e32 v25, v5, v197
	v_dot2c_f32_bf16_e32 v22, v6, v198
	v_dot2c_f32_bf16_e32 v24, v7, v199
	v_dot2c_f32_bf16_e32 v23, v8, v200
	v_dot2c_f32_bf16_e32 v25, v9, v201
	v_dot2c_f32_bf16_e32 v22, v10, v202
	v_dot2c_f32_bf16_e32 v24, v11, v203
	v_dot2c_f32_bf16_e32 v23, v12, v204
	v_dot2c_f32_bf16_e32 v25, v13, v205
	v_dot2c_f32_bf16_e32 v22, v14, v206
	v_dot2c_f32_bf16_e32 v24, v15, v207
	s_nop 2
	v_pk_add_f32 v[0:1], v[24:25], v[22:23]
	s_nop 0
	v_add_f32_e32 v0, v0, v1
	s_nop 1
	v_add_f32_dpp v0, v0, v0 quad_perm:[1,0,3,2] row_mask:0xf bank_mask:0xf bound_ctrl:1
	s_nop 1
	v_add_f32_dpp v0, v0, v0 quad_perm:[2,3,0,1] row_mask:0xf bank_mask:0xf bound_ctrl:1
	s_nop 1
	v_add_f32_dpp v0, v0, v0 row_half_mirror row_mask:0xf bank_mask:0xf bound_ctrl:1
	s_nop 1
	v_add_f32_dpp v0, v0, v0 row_mirror row_mask:0xf bank_mask:0xf bound_ctrl:1
	s_waitcnt lgkmcnt(0)
	v_cndmask_b32_e64 v208, v208, v0, s[54:55]
	v_cndmask_b32_e64 v209, v209, v57, s[54:55]
	ds_read_b32 v56, v61
	ds_read_b32 v57, v61 offset:512
	v_add_u32_e32 v61, 16, v61
	s_add_i32 s1, s1, 1
	s_waitcnt lgkmcnt(1)
	v_mad_u32_u24 v0, v56, s14, v92
	global_load_dwordx4 v[32:35], v0, s[46:47]
	global_load_dwordx4 v[36:39], v0, s[46:47] offset:16
	global_load_dwordx4 v[40:43], v0, s[46:47] offset:32
	s_waitcnt vmcnt(4)
	v_cvt_scalef32_pk32_bf16_fp6 v[0:15], v[44:49], 1.0
	v_mov_b32_e32 v23, 0
	v_mov_b32_e32 v25, 0
	v_mov_b32_e32 v22, 0
	v_mov_b32_e32 v24, 0
	v_dot2c_f32_bf16_e32 v23, v0, v212
	v_dot2c_f32_bf16_e32 v25, v1, v213
	v_dot2c_f32_bf16_e32 v22, v2, v214
	v_dot2c_f32_bf16_e32 v24, v3, v215
	v_dot2c_f32_bf16_e32 v23, v4, v218
	v_dot2c_f32_bf16_e32 v25, v5, v219
	v_dot2c_f32_bf16_e32 v22, v6, v220
	v_dot2c_f32_bf16_e32 v24, v7, v221
	v_dot2c_f32_bf16_e32 v23, v8, v222
	v_dot2c_f32_bf16_e32 v25, v9, v223
	v_dot2c_f32_bf16_e32 v22, v10, v224
	v_dot2c_f32_bf16_e32 v24, v11, v225
	v_dot2c_f32_bf16_e32 v23, v12, v226
	v_dot2c_f32_bf16_e32 v25, v13, v227
	v_dot2c_f32_bf16_e32 v22, v14, v228
	v_dot2c_f32_bf16_e32 v24, v15, v229
	s_waitcnt vmcnt(3)
	v_cvt_scalef32_pk32_bf16_fp6 v[0:15], v[50:55], 1.0
	v_dot2c_f32_bf16_e32 v23, v0, v230
	v_dot2c_f32_bf16_e32 v25, v1, v231
	v_dot2c_f32_bf16_e32 v22, v2, v232
	v_dot2c_f32_bf16_e32 v24, v3, v233
	v_dot2c_f32_bf16_e32 v23, v4, v234
	v_dot2c_f32_bf16_e32 v25, v5, v235
	v_dot2c_f32_bf16_e32 v22, v6, v236
	v_dot2c_f32_bf16_e32 v24, v7, v237
	v_dot2c_f32_bf16_e32 v23, v8, v238
	v_dot2c_f32_bf16_e32 v25, v9, v239
	v_dot2c_f32_bf16_e32 v22, v10, v240
	v_dot2c_f32_bf16_e32 v24, v11, v241
	v_dot2c_f32_bf16_e32 v23, v12, v242
	v_dot2c_f32_bf16_e32 v25, v13, v243
	v_dot2c_f32_bf16_e32 v22, v14, v244
	v_dot2c_f32_bf16_e32 v24, v15, v245
	s_nop 2
	v_pk_add_f32 v[0:1], v[24:25], v[22:23]
	s_nop 0
	v_add_f32_e32 v0, v0, v1
	s_nop 1
	v_add_f32_dpp v0, v0, v0 quad_perm:[1,0,3,2] row_mask:0xf bank_mask:0xf bound_ctrl:1
	s_nop 1
	v_add_f32_dpp v0, v0, v0 quad_perm:[2,3,0,1] row_mask:0xf bank_mask:0xf bound_ctrl:1
	s_nop 1
	v_add_f32_dpp v0, v0, v0 row_half_mirror row_mask:0xf bank_mask:0xf bound_ctrl:1
	s_nop 1
	v_add_f32_dpp v0, v0, v0 row_mirror row_mask:0xf bank_mask:0xf bound_ctrl:1
	s_waitcnt lgkmcnt(0)
	v_cndmask_b32_e64 v210, v210, v0, s[54:55]
	v_cndmask_b32_e64 v211, v211, v59, s[54:55]
	ds_read_b32 v58, v61 offset:1520
	ds_read_b32 v59, v61 offset:2032
	s_waitcnt lgkmcnt(1)
	v_mad_u32_u24 v0, v58, s14, v92
	global_load_dwordx4 v[44:47], v0, s[46:47]
	global_load_dwordx4 v[48:51], v0, s[46:47] offset:16
	global_load_dwordx4 v[52:55], v0, s[46:47] offset:32
	s_waitcnt vmcnt(4)
	v_cvt_scalef32_pk32_bf16_fp6 v[0:15], v[32:37], 1.0
	v_mov_b32_e32 v23, 0
	v_mov_b32_e32 v25, 0
	v_mov_b32_e32 v22, 0
	v_mov_b32_e32 v24, 0
	v_dot2c_f32_bf16_e32 v23, v0, v95
	v_dot2c_f32_bf16_e32 v25, v1, v159
	v_dot2c_f32_bf16_e32 v22, v2, v160
	v_dot2c_f32_bf16_e32 v24, v3, v161
	v_dot2c_f32_bf16_e32 v23, v4, v180
	v_dot2c_f32_bf16_e32 v25, v5, v181
	v_dot2c_f32_bf16_e32 v22, v6, v182
	v_dot2c_f32_bf16_e32 v24, v7, v183
	v_dot2c_f32_bf16_e32 v23, v8, v184
	v_dot2c_f32_bf16_e32 v25, v9, v185
	v_dot2c_f32_bf16_e32 v22, v10, v186
	v_dot2c_f32_bf16_e32 v24, v11, v187
	v_dot2c_f32_bf16_e32 v23, v12, v188
	v_dot2c_f32_bf16_e32 v25, v13, v189
	v_dot2c_f32_bf16_e32 v22, v14, v190
	v_dot2c_f32_bf16_e32 v24, v15, v191
	s_waitcnt vmcnt(3)
; __device__ void ph_peer(const float* __restrict__ SC, const bf16_t* __restrict__ H  , const float* __restrict__ gffn, const unsigned char* __restrict__ U, const unsigned char* __restrict__ V, float* X, const float* __restrict__ fgain) {
;     ...
;         for (int it = 0; it < 32; ++it) {
;             const int src = (it * 4 + grp) & 63;
;             const int e = __shfl(it < 16 ? idx_lo : idx_hi, src);
;             const float gt = __shfl(it < 16 ? g_lo : g_hi, src);
;             const u32x4* up = (const u32x4*)(U + (size_t)e * 768 + 48 * sub);
;             const u32x4 u0 = up[0], u1 = up[1], u2 = up[2];
;             u32x2 vw[2][3];
; #pragma unroll
;             for (int r = 0; r < 2; ++r) { const int ea = __builtin_amdgcn_readlane(e, 32 * r), eb = __builtin_amdgcn_readlane(e, 32 * r + 16);
;                 const u32x2* vp = (const u32x2*)(V + (size_t)(half ? eb : ea) * 768 + 24 * c32); vw[r][0] = vp[0]; vw[r][1] = vp[1]; vw[r][2] = vp[2]; }
;             float d0 = 0.f, d1 = 0.f, d2 = 0.f, d3 = 0.f;
;             {   const v6u_t p0 = (v6u_t){u0.x, u0.y, u0.z, u0.w, u1.x, u1.y};
;                 const v32bf_t r0 = __builtin_amdgcn_cvt_scalef32_pk32_bf16_fp6(p0, 1.0f);
; #pragma unroll
;                 for (int k = 0; k < 16; k += 4) { d0 = dot2pb(r0[2 * k], r0[2 * k + 1], hf2[k], d0); d1 = dot2pb(r0[2 * k + 2], r0[2 * k + 3], hf2[k + 1], d1);
;                     d2 = dot2pb(r0[2 * k + 4], r0[2 * k + 5], hf2[k + 2], d2); d3 = dot2pb(r0[2 * k + 6], r0[2 * k + 7], hf2[k + 3], d3); } }
;             {   const v6u_t p1 = (v6u_t){u1.z, u1.w, u2.x, u2.y, u2.z, u2.w};
;                 const v32bf_t r1 = __builtin_amdgcn_cvt_scalef32_pk32_bf16_fp6(p1, 1.0f);
; #pragma unroll
;                 for (int k = 0; k < 16; k += 4) { d0 = dot2pb(r1[2 * k], r1[2 * k + 1], hf2[16 + k], d0); d1 = dot2pb(r1[2 * k + 2], r1[2 * k + 3], hf2[16 + k + 1], d1);
;                     d2 = dot2pb(r1[2 * k + 4], r1[2 * k + 5], hf2[16 + k + 2], d2); d3 = dot2pb(r1[2 * k + 6], r1[2 * k + 7], hf2[16 + k + 3], d3); } }
;             const float d = row16_sum((d0 + d1) + (d2 + d3)) * FP6_INV;
;             const float a = gt * gelu1(d) * FP6_INV;
; #pragma unroll
;             for (int r = 0; r < 2; ++r) { const float aa = __int_as_float(__builtin_amdgcn_readlane(__float_as_int(a), 32 * r)), ab = __int_as_float(__builtin_amdgcn_readlane(__float_as_int(a), 32 * r + 16));
	v_cvt_scalef32_pk32_bf16_fp6 v[0:15], v[38:43], 1.0
	v_dot2c_f32_bf16_e32 v23, v0, v192
	v_dot2c_f32_bf16_e32 v25, v1, v193
	v_dot2c_f32_bf16_e32 v22, v2, v194
	v_dot2c_f32_bf16_e32 v24, v3, v195
	v_dot2c_f32_bf16_e32 v23, v4, v196
	v_dot2c_f32_bf16_e32 v25, v5, v197
	v_dot2c_f32_bf16_e32 v22, v6, v198
	v_dot2c_f32_bf16_e32 v24, v7, v199
	v_dot2c_f32_bf16_e32 v23, v8, v200
	v_dot2c_f32_bf16_e32 v25, v9, v201
	v_dot2c_f32_bf16_e32 v22, v10, v202
	v_dot2c_f32_bf16_e32 v24, v11, v203
	v_dot2c_f32_bf16_e32 v23, v12, v204
	v_dot2c_f32_bf16_e32 v25, v13, v205
	v_dot2c_f32_bf16_e32 v22, v14, v206
	v_dot2c_f32_bf16_e32 v24, v15, v207
	s_nop 2
	v_pk_add_f32 v[0:1], v[24:25], v[22:23]
	s_nop 0
	v_add_f32_e32 v0, v0, v1
	s_nop 1
	v_add_f32_dpp v0, v0, v0 quad_perm:[1,0,3,2] row_mask:0xf bank_mask:0xf bound_ctrl:1
	s_nop 1
	v_add_f32_dpp v0, v0, v0 quad_perm:[2,3,0,1] row_mask:0xf bank_mask:0xf bound_ctrl:1
	s_nop 1
	v_add_f32_dpp v0, v0, v0 row_half_mirror row_mask:0xf bank_mask:0xf bound_ctrl:1
	s_nop 1
	v_add_f32_dpp v0, v0, v0 row_mirror row_mask:0xf bank_mask:0xf bound_ctrl:1
	s_waitcnt lgkmcnt(0)
	v_cndmask_b32_e64 v0, v208, v0, s[56:57]
	v_cndmask_b32_e64 v209, v209, v57, s[56:57]
	v_mul_f32_e32 v0, 0x3caaaaab, v0
	v_and_b32_e32 v2, 0x7fffffff, v0
	v_pk_fma_f32 v[2:3], v[2:3], s[16:17], 1.0 op_sel_hi:[0,0,0]
	v_rcp_f32_e32 v2, v2
	v_rcp_f32_e32 v3, v3
	v_mul_f32_e32 v1, v0, v0
	v_mul_f32_e32 v1, 0xbf38aa3b, v1
	v_cmp_gt_f32_e32 vcc, 0, v0
	v_pk_fma_f32 v[4:5], v[2:3], s[24:25], v[130:131] op_sel_hi:[1,0,0]
	s_nop 0
	v_pk_fma_f32 v[4:5], v[2:3], v[4:5], s[28:29] op_sel_hi:[1,1,0]
	s_nop 0
	v_pk_fma_f32 v[4:5], v[2:3], v[4:5], s[30:31] op_sel_hi:[1,1,0]
	s_nop 0
	v_pk_fma_f32 v[4:5], v[2:3], v[4:5], s[36:37] op_sel_hi:[1,1,0]
	s_nop 0
	v_pk_mul_f32 v[2:3], v[2:3], v[4:5]
	v_exp_f32_e32 v4, v1
	s_nop 0
	v_pk_mul_f32 v[2:3], v[4:5], v[2:3] op_sel_hi:[0,1]
	v_pk_fma_f32 v[4:5], v[0:1], v[2:3], v[0:1] op_sel_hi:[0,1,1] neg_lo:[1,0,0] neg_hi:[1,0,0]
	v_mul_f32_e32 v0, v0, v2
	v_cndmask_b32_e32 v0, v4, v0, vcc
	v_mul_f32_e32 v0, v0, v209
	v_mul_f32_e32 v60, 0x3caaaaab, v0
	v_add_u32_e32 v62, v61, v155
	ds_write_b32 v62, v60 offset:960
	ds_read_b32 v56, v61
	ds_read_b32 v57, v61 offset:512
	v_add_u32_e32 v61, 16, v61
	s_add_i32 s1, s1, 1
	s_waitcnt lgkmcnt(1)
	v_mad_u32_u24 v0, v56, s14, v92
	global_load_dwordx4 v[32:35], v0, s[46:47]
	global_load_dwordx4 v[36:39], v0, s[46:47] offset:16
	global_load_dwordx4 v[40:43], v0, s[46:47] offset:32
	s_waitcnt vmcnt(4)
	v_cvt_scalef32_pk32_bf16_fp6 v[0:15], v[44:49], 1.0
	v_mov_b32_e32 v23, 0
	v_mov_b32_e32 v25, 0
	v_mov_b32_e32 v22, 0
	v_mov_b32_e32 v24, 0
	v_dot2c_f32_bf16_e32 v23, v0, v212
	v_dot2c_f32_bf16_e32 v25, v1, v213
	v_dot2c_f32_bf16_e32 v22, v2, v214
	v_dot2c_f32_bf16_e32 v24, v3, v215
	v_dot2c_f32_bf16_e32 v23, v4, v218
	v_dot2c_f32_bf16_e32 v25, v5, v219
	v_dot2c_f32_bf16_e32 v22, v6, v220
	v_dot2c_f32_bf16_e32 v24, v7, v221
	v_dot2c_f32_bf16_e32 v23, v8, v222
	v_dot2c_f32_bf16_e32 v25, v9, v223
	v_dot2c_f32_bf16_e32 v22, v10, v224
	v_dot2c_f32_bf16_e32 v24, v11, v225
	v_dot2c_f32_bf16_e32 v23, v12, v226
	v_dot2c_f32_bf16_e32 v25, v13, v227
	v_dot2c_f32_bf16_e32 v22, v14, v228
	v_dot2c_f32_bf16_e32 v24, v15, v229
	s_waitcnt vmcnt(3)
	v_cvt_scalef32_pk32_bf16_fp6 v[0:15], v[50:55], 1.0
	v_dot2c_f32_bf16_e32 v23, v0, v230
	v_dot2c_f32_bf16_e32 v25, v1, v231
	v_dot2c_f32_bf16_e32 v22, v2, v232
	v_dot2c_f32_bf16_e32 v24, v3, v233
	v_dot2c_f32_bf16_e32 v23, v4, v234
	v_dot2c_f32_bf16_e32 v25, v5, v235
	v_dot2c_f32_bf16_e32 v22, v6, v236
	v_dot2c_f32_bf16_e32 v24, v7, v237
	v_dot2c_f32_bf16_e32 v23, v8, v238
	v_dot2c_f32_bf16_e32 v25, v9, v239
	v_dot2c_f32_bf16_e32 v22, v10, v240
	v_dot2c_f32_bf16_e32 v24, v11, v241
	v_dot2c_f32_bf16_e32 v23, v12, v242
	v_dot2c_f32_bf16_e32 v25, v13, v243
	v_dot2c_f32_bf16_e32 v22, v14, v244
	v_dot2c_f32_bf16_e32 v24, v15, v245
	s_nop 2
	v_pk_add_f32 v[0:1], v[24:25], v[22:23]
	s_nop 0
	v_add_f32_e32 v0, v0, v1
	s_nop 1
	v_add_f32_dpp v0, v0, v0 quad_perm:[1,0,3,2] row_mask:0xf bank_mask:0xf bound_ctrl:1
	s_nop 1
	v_add_f32_dpp v0, v0, v0 quad_perm:[2,3,0,1] row_mask:0xf bank_mask:0xf bound_ctrl:1
	s_nop 1
	v_add_f32_dpp v0, v0, v0 row_half_mirror row_mask:0xf bank_mask:0xf bound_ctrl:1
	s_nop 1
	v_add_f32_dpp v0, v0, v0 row_mirror row_mask:0xf bank_mask:0xf bound_ctrl:1
	s_waitcnt lgkmcnt(0)
	v_cndmask_b32_e64 v0, v210, v0, s[56:57]
	v_cndmask_b32_e64 v211, v211, v59, s[56:57]
	v_mul_f32_e32 v0, 0x3caaaaab, v0
	v_and_b32_e32 v2, 0x7fffffff, v0
	v_pk_fma_f32 v[2:3], v[2:3], s[16:17], 1.0 op_sel_hi:[0,0,0]
	v_rcp_f32_e32 v2, v2
	v_rcp_f32_e32 v3, v3
	v_mul_f32_e32 v1, v0, v0
	v_mul_f32_e32 v1, 0xbf38aa3b, v1
	v_cmp_gt_f32_e32 vcc, 0, v0
	v_pk_fma_f32 v[4:5], v[2:3], s[24:25], v[130:131] op_sel_hi:[1,0,0]
	s_nop 0
	v_pk_fma_f32 v[4:5], v[2:3], v[4:5], s[28:29] op_sel_hi:[1,1,0]
	s_nop 0
	v_pk_fma_f32 v[4:5], v[2:3], v[4:5], s[30:31] op_sel_hi:[1,1,0]
	s_nop 0
	v_pk_fma_f32 v[4:5], v[2:3], v[4:5], s[36:37] op_sel_hi:[1,1,0]
	s_nop 0
	v_pk_mul_f32 v[2:3], v[2:3], v[4:5]
	v_exp_f32_e32 v4, v1
	s_nop 0
	v_pk_mul_f32 v[2:3], v[4:5], v[2:3] op_sel_hi:[0,1]
	v_pk_fma_f32 v[4:5], v[0:1], v[2:3], v[0:1] op_sel_hi:[0,1,1] neg_lo:[1,0,0] neg_hi:[1,0,0]
	v_mul_f32_e32 v0, v0, v2
	v_cndmask_b32_e32 v0, v4, v0, vcc
	v_mul_f32_e32 v0, v0, v211
	v_mul_f32_e32 v60, 0x3caaaaab, v0
	v_add_u32_e32 v62, v61, v155
	ds_write_b32 v62, v60 offset:2480
	s_cmp_lt_u32 s1, 29
	s_cbranch_scc1 .Lpeer_uloop
; __device__ __forceinline__ float gelu1(float v) { const f32x2 r = gelu_pk((f32x2){v, v}); return r.x; }
; __device__ void ph_peer(const float* __restrict__ SC, const bf16_t* __restrict__ H  , const float* __restrict__ gffn, const unsigned char* __restrict__ U, const unsigned char* __restrict__ V, float* X, const float* __restrict__ fgain) {
;     ...
;         for (int it = 0; it < 32; ++it) {
;             const int src = (it * 4 + grp) & 63;
;             const int e = __shfl(it < 16 ? idx_lo : idx_hi, src);
;             const float gt = __shfl(it < 16 ? g_lo : g_hi, src);
;             const u32x4* up = (const u32x4*)(U + (size_t)e * 768 + 48 * sub);
;             const u32x4 u0 = up[0], u1 = up[1], u2 = up[2];
;             u32x2 vw[2][3];
; #pragma unroll
;             for (int r = 0; r < 2; ++r) { const int ea = __builtin_amdgcn_readlane(e, 32 * r), eb = __builtin_amdgcn_readlane(e, 32 * r + 16);
;                 const u32x2* vp = (const u32x2*)(V + (size_t)(half ? eb : ea) * 768 + 24 * c32); vw[r][0] = vp[0]; vw[r][1] = vp[1]; vw[r][2] = vp[2]; }
;             float d0 = 0.f, d1 = 0.f, d2 = 0.f, d3 = 0.f;
;             {   const v6u_t p0 = (v6u_t){u0.x, u0.y, u0.z, u0.w, u1.x, u1.y};
;                 const v32bf_t r0 = __builtin_amdgcn_cvt_scalef32_pk32_bf16_fp6(p0, 1.0f);
; #pragma unroll
;                 for (int k = 0; k < 16; k += 4) { d0 = dot2pb(r0[2 * k], r0[2 * k + 1], hf2[k], d0); d1 = dot2pb(r0[2 * k + 2], r0[2 * k + 3], hf2[k + 1], d1);
;                     d2 = dot2pb(r0[2 * k + 4], r0[2 * k + 5], hf2[k + 2], d2); d3 = dot2pb(r0[2 * k + 6], r0[2 * k + 7], hf2[k + 3], d3); } }
;             {   const v6u_t p1 = (v6u_t){u1.z, u1.w, u2.x, u2.y, u2.z, u2.w};
;                 const v32bf_t r1 = __builtin_amdgcn_cvt_scalef32_pk32_bf16_fp6(p1, 1.0f);
; #pragma unroll
;                 for (int k = 0; k < 16; k += 4) { d0 = dot2pb(r1[2 * k], r1[2 * k + 1], hf2[16 + k], d0); d1 = dot2pb(r1[2 * k + 2], r1[2 * k + 3], hf2[16 + k + 1], d1);
;                     d2 = dot2pb(r1[2 * k + 4], r1[2 * k + 5], hf2[16 + k + 2], d2); d3 = dot2pb(r1[2 * k + 6], r1[2 * k + 7], hf2[16 + k + 3], d3); } }
;             const float d = row16_sum((d0 + d1) + (d2 + d3)) * FP6_INV;
;             const float a = gt * gelu1(d) * FP6_INV;
	ds_read_b32 v58, v61 offset:1520
	ds_read_b32 v59, v61 offset:2032
	s_waitcnt lgkmcnt(1)
	v_mad_u32_u24 v0, v58, s14, v92
	global_load_dwordx4 v[44:47], v0, s[46:47]
	global_load_dwordx4 v[48:51], v0, s[46:47] offset:16
	global_load_dwordx4 v[52:55], v0, s[46:47] offset:32
	s_waitcnt vmcnt(4)
	v_cvt_scalef32_pk32_bf16_fp6 v[0:15], v[32:37], 1.0
	v_mov_b32_e32 v23, 0
	v_mov_b32_e32 v25, 0
	v_mov_b32_e32 v22, 0
	v_mov_b32_e32 v24, 0
	v_dot2c_f32_bf16_e32 v23, v0, v95
	v_dot2c_f32_bf16_e32 v25, v1, v159
	v_dot2c_f32_bf16_e32 v22, v2, v160
	v_dot2c_f32_bf16_e32 v24, v3, v161
	v_dot2c_f32_bf16_e32 v23, v4, v180
	v_dot2c_f32_bf16_e32 v25, v5, v181
	v_dot2c_f32_bf16_e32 v22, v6, v182
	v_dot2c_f32_bf16_e32 v24, v7, v183
	v_dot2c_f32_bf16_e32 v23, v8, v184
	v_dot2c_f32_bf16_e32 v25, v9, v185
	v_dot2c_f32_bf16_e32 v22, v10, v186
	v_dot2c_f32_bf16_e32 v24, v11, v187
	v_dot2c_f32_bf16_e32 v23, v12, v188
	v_dot2c_f32_bf16_e32 v25, v13, v189
	v_dot2c_f32_bf16_e32 v22, v14, v190
	v_dot2c_f32_bf16_e32 v24, v15, v191
	s_waitcnt vmcnt(3)
	v_cvt_scalef32_pk32_bf16_fp6 v[0:15], v[38:43], 1.0
	v_dot2c_f32_bf16_e32 v23, v0, v192
	v_dot2c_f32_bf16_e32 v25, v1, v193
	v_dot2c_f32_bf16_e32 v22, v2, v194
	v_dot2c_f32_bf16_e32 v24, v3, v195
	v_dot2c_f32_bf16_e32 v23, v4, v196
	v_dot2c_f32_bf16_e32 v25, v5, v197
	v_dot2c_f32_bf16_e32 v22, v6, v198
	v_dot2c_f32_bf16_e32 v24, v7, v199
	v_dot2c_f32_bf16_e32 v23, v8, v200
	v_dot2c_f32_bf16_e32 v25, v9, v201
	v_dot2c_f32_bf16_e32 v22, v10, v202
	v_dot2c_f32_bf16_e32 v24, v11, v203
	v_dot2c_f32_bf16_e32 v23, v12, v204
	v_dot2c_f32_bf16_e32 v25, v13, v205
	v_dot2c_f32_bf16_e32 v22, v14, v206
	v_dot2c_f32_bf16_e32 v24, v15, v207
	s_nop 2
	v_pk_add_f32 v[0:1], v[24:25], v[22:23]
	s_nop 0
	v_add_f32_e32 v0, v0, v1
	s_nop 1
	v_add_f32_dpp v0, v0, v0 quad_perm:[1,0,3,2] row_mask:0xf bank_mask:0xf bound_ctrl:1
	s_nop 1
	v_add_f32_dpp v0, v0, v0 quad_perm:[2,3,0,1] row_mask:0xf bank_mask:0xf bound_ctrl:1
	s_nop 1
	v_add_f32_dpp v0, v0, v0 row_half_mirror row_mask:0xf bank_mask:0xf bound_ctrl:1
	s_nop 1
	v_add_f32_dpp v0, v0, v0 row_mirror row_mask:0xf bank_mask:0xf bound_ctrl:1
	s_waitcnt lgkmcnt(0)
	v_cndmask_b32_e64 v208, v208, v0, s[50:51]
	v_cndmask_b32_e64 v209, v209, v57, s[50:51]
	ds_read_b32 v56, v61
	ds_read_b32 v57, v61 offset:512
	v_add_u32_e32 v61, 16, v61
	s_add_i32 s1, s1, 1
	s_waitcnt lgkmcnt(1)
	v_mad_u32_u24 v0, v56, s14, v92
	global_load_dwordx4 v[32:35], v0, s[46:47]
	global_load_dwordx4 v[36:39], v0, s[46:47] offset:16
	global_load_dwordx4 v[40:43], v0, s[46:47] offset:32
	s_waitcnt vmcnt(4)
	v_cvt_scalef32_pk32_bf16_fp6 v[0:15], v[44:49], 1.0
	v_mov_b32_e32 v23, 0
	v_mov_b32_e32 v25, 0
	v_mov_b32_e32 v22, 0
	v_mov_b32_e32 v24, 0
	v_dot2c_f32_bf16_e32 v23, v0, v212
	v_dot2c_f32_bf16_e32 v25, v1, v213
	v_dot2c_f32_bf16_e32 v22, v2, v214
	v_dot2c_f32_bf16_e32 v24, v3, v215
	v_dot2c_f32_bf16_e32 v23, v4, v218
	v_dot2c_f32_bf16_e32 v25, v5, v219
	v_dot2c_f32_bf16_e32 v22, v6, v220
	v_dot2c_f32_bf16_e32 v24, v7, v221
	v_dot2c_f32_bf16_e32 v23, v8, v222
	v_dot2c_f32_bf16_e32 v25, v9, v223
	v_dot2c_f32_bf16_e32 v22, v10, v224
	v_dot2c_f32_bf16_e32 v24, v11, v225
	v_dot2c_f32_bf16_e32 v23, v12, v226
	v_dot2c_f32_bf16_e32 v25, v13, v227
	v_dot2c_f32_bf16_e32 v22, v14, v228
	v_dot2c_f32_bf16_e32 v24, v15, v229
	s_waitcnt vmcnt(3)
	v_cvt_scalef32_pk32_bf16_fp6 v[0:15], v[50:55], 1.0
	v_dot2c_f32_bf16_e32 v23, v0, v230
	v_dot2c_f32_bf16_e32 v25, v1, v231
	v_dot2c_f32_bf16_e32 v22, v2, v232
	v_dot2c_f32_bf16_e32 v24, v3, v233
	v_dot2c_f32_bf16_e32 v23, v4, v234
	v_dot2c_f32_bf16_e32 v25, v5, v235
	v_dot2c_f32_bf16_e32 v22, v6, v236
	v_dot2c_f32_bf16_e32 v24, v7, v237
	v_dot2c_f32_bf16_e32 v23, v8, v238
	v_dot2c_f32_bf16_e32 v25, v9, v239
	v_dot2c_f32_bf16_e32 v22, v10, v240
	v_dot2c_f32_bf16_e32 v24, v11, v241
	v_dot2c_f32_bf16_e32 v23, v12, v242
	v_dot2c_f32_bf16_e32 v25, v13, v243
	v_dot2c_f32_bf16_e32 v22, v14, v244
	v_dot2c_f32_bf16_e32 v24, v15, v245
	s_nop 2
	v_pk_add_f32 v[0:1], v[24:25], v[22:23]
	s_nop 0
	v_add_f32_e32 v0, v0, v1
	s_nop 1
	v_add_f32_dpp v0, v0, v0 quad_perm:[1,0,3,2] row_mask:0xf bank_mask:0xf bound_ctrl:1
	s_nop 1
	v_add_f32_dpp v0, v0, v0 quad_perm:[2,3,0,1] row_mask:0xf bank_mask:0xf bound_ctrl:1
	s_nop 1
	v_add_f32_dpp v0, v0, v0 row_half_mirror row_mask:0xf bank_mask:0xf bound_ctrl:1
	s_nop 1
	v_add_f32_dpp v0, v0, v0 row_mirror row_mask:0xf bank_mask:0xf bound_ctrl:1
	s_waitcnt lgkmcnt(0)
	v_cndmask_b32_e64 v210, v210, v0, s[50:51]
	v_cndmask_b32_e64 v211, v211, v59, s[50:51]
	ds_read_b32 v58, v61 offset:1520
	ds_read_b32 v59, v61 offset:2032
	s_waitcnt lgkmcnt(1)
	v_mad_u32_u24 v0, v58, s14, v92
	global_load_dwordx4 v[44:47], v0, s[46:47]
	global_load_dwordx4 v[48:51], v0, s[46:47] offset:16
	global_load_dwordx4 v[52:55], v0, s[46:47] offset:32
	s_waitcnt vmcnt(4)
	v_cvt_scalef32_pk32_bf16_fp6 v[0:15], v[32:37], 1.0
	v_mov_b32_e32 v23, 0
	v_mov_b32_e32 v25, 0
	v_mov_b32_e32 v22, 0
	v_mov_b32_e32 v24, 0
	v_dot2c_f32_bf16_e32 v23, v0, v95
	v_dot2c_f32_bf16_e32 v25, v1, v159
	v_dot2c_f32_bf16_e32 v22, v2, v160
	v_dot2c_f32_bf16_e32 v24, v3, v161
	v_dot2c_f32_bf16_e32 v23, v4, v180
	v_dot2c_f32_bf16_e32 v25, v5, v181
	v_dot2c_f32_bf16_e32 v22, v6, v182
	v_dot2c_f32_bf16_e32 v24, v7, v183
	v_dot2c_f32_bf16_e32 v23, v8, v184
	v_dot2c_f32_bf16_e32 v25, v9, v185
	v_dot2c_f32_bf16_e32 v22, v10, v186
	v_dot2c_f32_bf16_e32 v24, v11, v187
	v_dot2c_f32_bf16_e32 v23, v12, v188
	v_dot2c_f32_bf16_e32 v25, v13, v189
	v_dot2c_f32_bf16_e32 v22, v14, v190
	v_dot2c_f32_bf16_e32 v24, v15, v191
	s_waitcnt vmcnt(3)
; __device__ __forceinline__ float gelu1(float v) { const f32x2 r = gelu_pk((f32x2){v, v}); return r.x; }
; __device__ void ph_peer(const float* __restrict__ SC, const bf16_t* __restrict__ H  , const float* __restrict__ gffn, const unsigned char* __restrict__ U, const unsigned char* __restrict__ V, float* X, const float* __restrict__ fgain) {
;     ...
;         for (int it = 0; it < 32; ++it) {
;             const int src = (it * 4 + grp) & 63;
;             const int e = __shfl(it < 16 ? idx_lo : idx_hi, src);
;             const float gt = __shfl(it < 16 ? g_lo : g_hi, src);
;             const u32x4* up = (const u32x4*)(U + (size_t)e * 768 + 48 * sub);
;             const u32x4 u0 = up[0], u1 = up[1], u2 = up[2];
;             u32x2 vw[2][3];
; #pragma unroll
;             for (int r = 0; r < 2; ++r) { const int ea = __builtin_amdgcn_readlane(e, 32 * r), eb = __builtin_amdgcn_readlane(e, 32 * r + 16);
;                 const u32x2* vp = (const u32x2*)(V + (size_t)(half ? eb : ea) * 768 + 24 * c32); vw[r][0] = vp[0]; vw[r][1] = vp[1]; vw[r][2] = vp[2]; }
;             float d0 = 0.f, d1 = 0.f, d2 = 0.f, d3 = 0.f;
;             {   const v6u_t p0 = (v6u_t){u0.x, u0.y, u0.z, u0.w, u1.x, u1.y};
;                 const v32bf_t r0 = __builtin_amdgcn_cvt_scalef32_pk32_bf16_fp6(p0, 1.0f);
; #pragma unroll
;                 for (int k = 0; k < 16; k += 4) { d0 = dot2pb(r0[2 * k], r0[2 * k + 1], hf2[k], d0); d1 = dot2pb(r0[2 * k + 2], r0[2 * k + 3], hf2[k + 1], d1);
;                     d2 = dot2pb(r0[2 * k + 4], r0[2 * k + 5], hf2[k + 2], d2); d3 = dot2pb(r0[2 * k + 6], r0[2 * k + 7], hf2[k + 3], d3); } }
;             {   const v6u_t p1 = (v6u_t){u1.z, u1.w, u2.x, u2.y, u2.z, u2.w};
;                 const v32bf_t r1 = __builtin_amdgcn_cvt_scalef32_pk32_bf16_fp6(p1, 1.0f);
; #pragma unroll
;                 for (int k = 0; k < 16; k += 4) { d0 = dot2pb(r1[2 * k], r1[2 * k + 1], hf2[16 + k], d0); d1 = dot2pb(r1[2 * k + 2], r1[2 * k + 3], hf2[16 + k + 1], d1);
;                     d2 = dot2pb(r1[2 * k + 4], r1[2 * k + 5], hf2[16 + k + 2], d2); d3 = dot2pb(r1[2 * k + 6], r1[2 * k + 7], hf2[16 + k + 3], d3); } }
;             const float d = row16_sum((d0 + d1) + (d2 + d3)) * FP6_INV;
;             const float a = gt * gelu1(d) * FP6_INV;
	v_cvt_scalef32_pk32_bf16_fp6 v[0:15], v[38:43], 1.0
	v_dot2c_f32_bf16_e32 v23, v0, v192
	v_dot2c_f32_bf16_e32 v25, v1, v193
	v_dot2c_f32_bf16_e32 v22, v2, v194
	v_dot2c_f32_bf16_e32 v24, v3, v195
	v_dot2c_f32_bf16_e32 v23, v4, v196
	v_dot2c_f32_bf16_e32 v25, v5, v197
	v_dot2c_f32_bf16_e32 v22, v6, v198
	v_dot2c_f32_bf16_e32 v24, v7, v199
	v_dot2c_f32_bf16_e32 v23, v8, v200
	v_dot2c_f32_bf16_e32 v25, v9, v201
	v_dot2c_f32_bf16_e32 v22, v10, v202
	v_dot2c_f32_bf16_e32 v24, v11, v203
	v_dot2c_f32_bf16_e32 v23, v12, v204
	v_dot2c_f32_bf16_e32 v25, v13, v205
	v_dot2c_f32_bf16_e32 v22, v14, v206
	v_dot2c_f32_bf16_e32 v24, v15, v207
	s_nop 2
	v_pk_add_f32 v[0:1], v[24:25], v[22:23]
	s_nop 0
	v_add_f32_e32 v0, v0, v1
	s_nop 1
	v_add_f32_dpp v0, v0, v0 quad_perm:[1,0,3,2] row_mask:0xf bank_mask:0xf bound_ctrl:1
	s_nop 1
	v_add_f32_dpp v0, v0, v0 quad_perm:[2,3,0,1] row_mask:0xf bank_mask:0xf bound_ctrl:1
	s_nop 1
	v_add_f32_dpp v0, v0, v0 row_half_mirror row_mask:0xf bank_mask:0xf bound_ctrl:1
	s_nop 1
	v_add_f32_dpp v0, v0, v0 row_mirror row_mask:0xf bank_mask:0xf bound_ctrl:1
	s_waitcnt lgkmcnt(0)
	v_cndmask_b32_e64 v208, v208, v0, s[52:53]
	v_cndmask_b32_e64 v209, v209, v57, s[52:53]
	ds_read_b32 v56, v61
	ds_read_b32 v57, v61 offset:512
	v_add_u32_e32 v61, 16, v61
	s_add_i32 s1, s1, 1
	s_waitcnt lgkmcnt(1)
	v_mad_u32_u24 v0, v56, s14, v92
	global_load_dwordx4 v[32:35], v0, s[46:47]
	global_load_dwordx4 v[36:39], v0, s[46:47] offset:16
	global_load_dwordx4 v[40:43], v0, s[46:47] offset:32
	s_waitcnt vmcnt(4)
	v_cvt_scalef32_pk32_bf16_fp6 v[0:15], v[44:49], 1.0
	v_mov_b32_e32 v23, 0
	v_mov_b32_e32 v25, 0
	v_mov_b32_e32 v22, 0
	v_mov_b32_e32 v24, 0
	v_dot2c_f32_bf16_e32 v23, v0, v212
	v_dot2c_f32_bf16_e32 v25, v1, v213
	v_dot2c_f32_bf16_e32 v22, v2, v214
	v_dot2c_f32_bf16_e32 v24, v3, v215
	v_dot2c_f32_bf16_e32 v23, v4, v218
	v_dot2c_f32_bf16_e32 v25, v5, v219
	v_dot2c_f32_bf16_e32 v22, v6, v220
	v_dot2c_f32_bf16_e32 v24, v7, v221
	v_dot2c_f32_bf16_e32 v23, v8, v222
	v_dot2c_f32_bf16_e32 v25, v9, v223
	v_dot2c_f32_bf16_e32 v22, v10, v224
	v_dot2c_f32_bf16_e32 v24, v11, v225
	v_dot2c_f32_bf16_e32 v23, v12, v226
	v_dot2c_f32_bf16_e32 v25, v13, v227
	v_dot2c_f32_bf16_e32 v22, v14, v228
	v_dot2c_f32_bf16_e32 v24, v15, v229
	s_waitcnt vmcnt(3)
	v_cvt_scalef32_pk32_bf16_fp6 v[0:15], v[50:55], 1.0
	v_dot2c_f32_bf16_e32 v23, v0, v230
	v_dot2c_f32_bf16_e32 v25, v1, v231
	v_dot2c_f32_bf16_e32 v22, v2, v232
	v_dot2c_f32_bf16_e32 v24, v3, v233
	v_dot2c_f32_bf16_e32 v23, v4, v234
	v_dot2c_f32_bf16_e32 v25, v5, v235
	v_dot2c_f32_bf16_e32 v22, v6, v236
	v_dot2c_f32_bf16_e32 v24, v7, v237
	v_dot2c_f32_bf16_e32 v23, v8, v238
	v_dot2c_f32_bf16_e32 v25, v9, v239
	v_dot2c_f32_bf16_e32 v22, v10, v240
	v_dot2c_f32_bf16_e32 v24, v11, v241
	v_dot2c_f32_bf16_e32 v23, v12, v242
	v_dot2c_f32_bf16_e32 v25, v13, v243
	v_dot2c_f32_bf16_e32 v22, v14, v244
	v_dot2c_f32_bf16_e32 v24, v15, v245
	s_nop 2
	v_pk_add_f32 v[0:1], v[24:25], v[22:23]
	s_nop 0
	v_add_f32_e32 v0, v0, v1
	s_nop 1
	v_add_f32_dpp v0, v0, v0 quad_perm:[1,0,3,2] row_mask:0xf bank_mask:0xf bound_ctrl:1
	s_nop 1
	v_add_f32_dpp v0, v0, v0 quad_perm:[2,3,0,1] row_mask:0xf bank_mask:0xf bound_ctrl:1
	s_nop 1
	v_add_f32_dpp v0, v0, v0 row_half_mirror row_mask:0xf bank_mask:0xf bound_ctrl:1
	s_nop 1
	v_add_f32_dpp v0, v0, v0 row_mirror row_mask:0xf bank_mask:0xf bound_ctrl:1
	s_waitcnt lgkmcnt(0)
	v_cndmask_b32_e64 v210, v210, v0, s[52:53]
	v_cndmask_b32_e64 v211, v211, v59, s[52:53]
	ds_read_b32 v58, v61 offset:1520
	ds_read_b32 v59, v61 offset:2032
	s_waitcnt lgkmcnt(1)
	v_mad_u32_u24 v0, v58, s14, v92
	global_load_dwordx4 v[44:47], v0, s[46:47]
	global_load_dwordx4 v[48:51], v0, s[46:47] offset:16
	global_load_dwordx4 v[52:55], v0, s[46:47] offset:32
	s_waitcnt vmcnt(4)
	v_cvt_scalef32_pk32_bf16_fp6 v[0:15], v[32:37], 1.0
	v_mov_b32_e32 v23, 0
	v_mov_b32_e32 v25, 0
	v_mov_b32_e32 v22, 0
	v_mov_b32_e32 v24, 0
	v_dot2c_f32_bf16_e32 v23, v0, v95
	v_dot2c_f32_bf16_e32 v25, v1, v159
	v_dot2c_f32_bf16_e32 v22, v2, v160
	v_dot2c_f32_bf16_e32 v24, v3, v161
	v_dot2c_f32_bf16_e32 v23, v4, v180
	v_dot2c_f32_bf16_e32 v25, v5, v181
	v_dot2c_f32_bf16_e32 v22, v6, v182
	v_dot2c_f32_bf16_e32 v24, v7, v183
	v_dot2c_f32_bf16_e32 v23, v8, v184
	v_dot2c_f32_bf16_e32 v25, v9, v185
	v_dot2c_f32_bf16_e32 v22, v10, v186
	v_dot2c_f32_bf16_e32 v24, v11, v187
	v_dot2c_f32_bf16_e32 v23, v12, v188
	v_dot2c_f32_bf16_e32 v25, v13, v189
	v_dot2c_f32_bf16_e32 v22, v14, v190
	v_dot2c_f32_bf16_e32 v24, v15, v191
	s_waitcnt vmcnt(3)
	v_cvt_scalef32_pk32_bf16_fp6 v[0:15], v[38:43], 1.0
	v_dot2c_f32_bf16_e32 v23, v0, v192
	v_dot2c_f32_bf16_e32 v25, v1, v193
	v_dot2c_f32_bf16_e32 v22, v2, v194
	v_dot2c_f32_bf16_e32 v24, v3, v195
	v_dot2c_f32_bf16_e32 v23, v4, v196
	v_dot2c_f32_bf16_e32 v25, v5, v197
	v_dot2c_f32_bf16_e32 v22, v6, v198
	v_dot2c_f32_bf16_e32 v24, v7, v199
	v_dot2c_f32_bf16_e32 v23, v8, v200
	v_dot2c_f32_bf16_e32 v25, v9, v201
	v_dot2c_f32_bf16_e32 v22, v10, v202
	v_dot2c_f32_bf16_e32 v24, v11, v203
	v_dot2c_f32_bf16_e32 v23, v12, v204
	v_dot2c_f32_bf16_e32 v25, v13, v205
	v_dot2c_f32_bf16_e32 v22, v14, v206
	v_dot2c_f32_bf16_e32 v24, v15, v207
	s_nop 2
	v_pk_add_f32 v[0:1], v[24:25], v[22:23]
	s_nop 0
	v_add_f32_e32 v0, v0, v1
	s_nop 1
	v_add_f32_dpp v0, v0, v0 quad_perm:[1,0,3,2] row_mask:0xf bank_mask:0xf bound_ctrl:1
	s_nop 1
	v_add_f32_dpp v0, v0, v0 quad_perm:[2,3,0,1] row_mask:0xf bank_mask:0xf bound_ctrl:1
	s_nop 1
	v_add_f32_dpp v0, v0, v0 row_half_mirror row_mask:0xf bank_mask:0xf bound_ctrl:1
	s_nop 1
	v_add_f32_dpp v0, v0, v0 row_mirror row_mask:0xf bank_mask:0xf bound_ctrl:1
	s_waitcnt lgkmcnt(0)
; __device__ void ph_peer(const float* __restrict__ SC, const bf16_t* __restrict__ H  , const float* __restrict__ gffn, const unsigned char* __restrict__ U, const unsigned char* __restrict__ V, float* X, const float* __restrict__ fgain) {
;     ...
;         for (int it = 0; it < 32; ++it) {
;             const int src = (it * 4 + grp) & 63;
;             const int e = __shfl(it < 16 ? idx_lo : idx_hi, src);
;             const float gt = __shfl(it < 16 ? g_lo : g_hi, src);
;             const u32x4* up = (const u32x4*)(U + (size_t)e * 768 + 48 * sub);
;             const u32x4 u0 = up[0], u1 = up[1], u2 = up[2];
;             u32x2 vw[2][3];
; #pragma unroll
;             for (int r = 0; r < 2; ++r) { const int ea = __builtin_amdgcn_readlane(e, 32 * r), eb = __builtin_amdgcn_readlane(e, 32 * r + 16);
;                 const u32x2* vp = (const u32x2*)(V + (size_t)(half ? eb : ea) * 768 + 24 * c32); vw[r][0] = vp[0]; vw[r][1] = vp[1]; vw[r][2] = vp[2]; }
;             float d0 = 0.f, d1 = 0.f, d2 = 0.f, d3 = 0.f;
;             {   const v6u_t p0 = (v6u_t){u0.x, u0.y, u0.z, u0.w, u1.x, u1.y};
;                 const v32bf_t r0 = __builtin_amdgcn_cvt_scalef32_pk32_bf16_fp6(p0, 1.0f);
; #pragma unroll
;                 for (int k = 0; k < 16; k += 4) { d0 = dot2pb(r0[2 * k], r0[2 * k + 1], hf2[k], d0); d1 = dot2pb(r0[2 * k + 2], r0[2 * k + 3], hf2[k + 1], d1);
;                     d2 = dot2pb(r0[2 * k + 4], r0[2 * k + 5], hf2[k + 2], d2); d3 = dot2pb(r0[2 * k + 6], r0[2 * k + 7], hf2[k + 3], d3); } }
;             {   const v6u_t p1 = (v6u_t){u1.z, u1.w, u2.x, u2.y, u2.z, u2.w};
;                 const v32bf_t r1 = __builtin_amdgcn_cvt_scalef32_pk32_bf16_fp6(p1, 1.0f);
; #pragma unroll
;                 for (int k = 0; k < 16; k += 4) { d0 = dot2pb(r1[2 * k], r1[2 * k + 1], hf2[16 + k], d0); d1 = dot2pb(r1[2 * k + 2], r1[2 * k + 3], hf2[16 + k + 1], d1);
;                     d2 = dot2pb(r1[2 * k + 4], r1[2 * k + 5], hf2[16 + k + 2], d2); d3 = dot2pb(r1[2 * k + 6], r1[2 * k + 7], hf2[16 + k + 3], d3); } }
;             const float d = row16_sum((d0 + d1) + (d2 + d3)) * FP6_INV;
;             const float a = gt * gelu1(d) * FP6_INV;
; #pragma unroll
;             for (int r = 0; r < 2; ++r) { const float aa = __int_as_float(__builtin_amdgcn_readlane(__float_as_int(a), 32 * r)), ab = __int_as_float(__builtin_amdgcn_readlane(__float_as_int(a), 32 * r + 16));
	v_cndmask_b32_e64 v208, v208, v0, s[54:55]
	v_cndmask_b32_e64 v209, v209, v57, s[54:55]
	ds_read_b32 v56, v61
	ds_read_b32 v57, v61 offset:512
	v_add_u32_e32 v61, 16, v61
	s_add_i32 s1, s1, 1
	s_waitcnt lgkmcnt(1)
	v_mad_u32_u24 v0, v56, s14, v92
	global_load_dwordx4 v[32:35], v0, s[46:47]
	global_load_dwordx4 v[36:39], v0, s[46:47] offset:16
	global_load_dwordx4 v[40:43], v0, s[46:47] offset:32
	s_waitcnt vmcnt(4)
	v_cvt_scalef32_pk32_bf16_fp6 v[0:15], v[44:49], 1.0
	v_mov_b32_e32 v23, 0
	v_mov_b32_e32 v25, 0
	v_mov_b32_e32 v22, 0
	v_mov_b32_e32 v24, 0
	v_dot2c_f32_bf16_e32 v23, v0, v212
	v_dot2c_f32_bf16_e32 v25, v1, v213
	v_dot2c_f32_bf16_e32 v22, v2, v214
	v_dot2c_f32_bf16_e32 v24, v3, v215
	v_dot2c_f32_bf16_e32 v23, v4, v218
	v_dot2c_f32_bf16_e32 v25, v5, v219
	v_dot2c_f32_bf16_e32 v22, v6, v220
	v_dot2c_f32_bf16_e32 v24, v7, v221
	v_dot2c_f32_bf16_e32 v23, v8, v222
	v_dot2c_f32_bf16_e32 v25, v9, v223
	v_dot2c_f32_bf16_e32 v22, v10, v224
	v_dot2c_f32_bf16_e32 v24, v11, v225
	v_dot2c_f32_bf16_e32 v23, v12, v226
	v_dot2c_f32_bf16_e32 v25, v13, v227
	v_dot2c_f32_bf16_e32 v22, v14, v228
	v_dot2c_f32_bf16_e32 v24, v15, v229
	s_waitcnt vmcnt(3)
	v_cvt_scalef32_pk32_bf16_fp6 v[0:15], v[50:55], 1.0
	v_dot2c_f32_bf16_e32 v23, v0, v230
	v_dot2c_f32_bf16_e32 v25, v1, v231
	v_dot2c_f32_bf16_e32 v22, v2, v232
	v_dot2c_f32_bf16_e32 v24, v3, v233
	v_dot2c_f32_bf16_e32 v23, v4, v234
	v_dot2c_f32_bf16_e32 v25, v5, v235
	v_dot2c_f32_bf16_e32 v22, v6, v236
	v_dot2c_f32_bf16_e32 v24, v7, v237
	v_dot2c_f32_bf16_e32 v23, v8, v238
	v_dot2c_f32_bf16_e32 v25, v9, v239
	v_dot2c_f32_bf16_e32 v22, v10, v240
	v_dot2c_f32_bf16_e32 v24, v11, v241
	v_dot2c_f32_bf16_e32 v23, v12, v242
	v_dot2c_f32_bf16_e32 v25, v13, v243
	v_dot2c_f32_bf16_e32 v22, v14, v244
	v_dot2c_f32_bf16_e32 v24, v15, v245
	s_nop 2
	v_pk_add_f32 v[0:1], v[24:25], v[22:23]
	s_nop 0
	v_add_f32_e32 v0, v0, v1
	s_nop 1
	v_add_f32_dpp v0, v0, v0 quad_perm:[1,0,3,2] row_mask:0xf bank_mask:0xf bound_ctrl:1
	s_nop 1
	v_add_f32_dpp v0, v0, v0 quad_perm:[2,3,0,1] row_mask:0xf bank_mask:0xf bound_ctrl:1
	s_nop 1
	v_add_f32_dpp v0, v0, v0 row_half_mirror row_mask:0xf bank_mask:0xf bound_ctrl:1
	s_nop 1
	v_add_f32_dpp v0, v0, v0 row_mirror row_mask:0xf bank_mask:0xf bound_ctrl:1
	s_waitcnt lgkmcnt(0)
	v_cndmask_b32_e64 v210, v210, v0, s[54:55]
	v_cndmask_b32_e64 v211, v211, v59, s[54:55]
	ds_read_b32 v58, v61 offset:1520
	ds_read_b32 v59, v61 offset:2032
	s_waitcnt lgkmcnt(1)
	v_mad_u32_u24 v0, v58, s14, v92
	global_load_dwordx4 v[44:47], v0, s[46:47]
	global_load_dwordx4 v[48:51], v0, s[46:47] offset:16
	global_load_dwordx4 v[52:55], v0, s[46:47] offset:32
	s_waitcnt vmcnt(4)
	v_cvt_scalef32_pk32_bf16_fp6 v[0:15], v[32:37], 1.0
	v_mov_b32_e32 v23, 0
	v_mov_b32_e32 v25, 0
	v_mov_b32_e32 v22, 0
	v_mov_b32_e32 v24, 0
	v_dot2c_f32_bf16_e32 v23, v0, v95
	v_dot2c_f32_bf16_e32 v25, v1, v159
	v_dot2c_f32_bf16_e32 v22, v2, v160
	v_dot2c_f32_bf16_e32 v24, v3, v161
	v_dot2c_f32_bf16_e32 v23, v4, v180
	v_dot2c_f32_bf16_e32 v25, v5, v181
	v_dot2c_f32_bf16_e32 v22, v6, v182
	v_dot2c_f32_bf16_e32 v24, v7, v183
	v_dot2c_f32_bf16_e32 v23, v8, v184
	v_dot2c_f32_bf16_e32 v25, v9, v185
	v_dot2c_f32_bf16_e32 v22, v10, v186
	v_dot2c_f32_bf16_e32 v24, v11, v187
	v_dot2c_f32_bf16_e32 v23, v12, v188
	v_dot2c_f32_bf16_e32 v25, v13, v189
	v_dot2c_f32_bf16_e32 v22, v14, v190
	v_dot2c_f32_bf16_e32 v24, v15, v191
	s_waitcnt vmcnt(3)
	v_cvt_scalef32_pk32_bf16_fp6 v[0:15], v[38:43], 1.0
	v_dot2c_f32_bf16_e32 v23, v0, v192
	v_dot2c_f32_bf16_e32 v25, v1, v193
	v_dot2c_f32_bf16_e32 v22, v2, v194
	v_dot2c_f32_bf16_e32 v24, v3, v195
	v_dot2c_f32_bf16_e32 v23, v4, v196
	v_dot2c_f32_bf16_e32 v25, v5, v197
	v_dot2c_f32_bf16_e32 v22, v6, v198
	v_dot2c_f32_bf16_e32 v24, v7, v199
	v_dot2c_f32_bf16_e32 v23, v8, v200
	v_dot2c_f32_bf16_e32 v25, v9, v201
	v_dot2c_f32_bf16_e32 v22, v10, v202
	v_dot2c_f32_bf16_e32 v24, v11, v203
	v_dot2c_f32_bf16_e32 v23, v12, v204
	v_dot2c_f32_bf16_e32 v25, v13, v205
	v_dot2c_f32_bf16_e32 v22, v14, v206
	v_dot2c_f32_bf16_e32 v24, v15, v207
	s_nop 2
	v_pk_add_f32 v[0:1], v[24:25], v[22:23]
	s_nop 0
	v_add_f32_e32 v0, v0, v1
	s_nop 1
	v_add_f32_dpp v0, v0, v0 quad_perm:[1,0,3,2] row_mask:0xf bank_mask:0xf bound_ctrl:1
	s_nop 1
	v_add_f32_dpp v0, v0, v0 quad_perm:[2,3,0,1] row_mask:0xf bank_mask:0xf bound_ctrl:1
	s_nop 1
	v_add_f32_dpp v0, v0, v0 row_half_mirror row_mask:0xf bank_mask:0xf bound_ctrl:1
	s_nop 1
	v_add_f32_dpp v0, v0, v0 row_mirror row_mask:0xf bank_mask:0xf bound_ctrl:1
	s_waitcnt lgkmcnt(0)
	v_cndmask_b32_e64 v0, v208, v0, s[56:57]
	v_cndmask_b32_e64 v209, v209, v57, s[56:57]
	v_mul_f32_e32 v0, 0x3caaaaab, v0
	v_and_b32_e32 v2, 0x7fffffff, v0
	v_pk_fma_f32 v[2:3], v[2:3], s[16:17], 1.0 op_sel_hi:[0,0,0]
	v_rcp_f32_e32 v2, v2
	v_rcp_f32_e32 v3, v3
	v_mul_f32_e32 v1, v0, v0
	v_mul_f32_e32 v1, 0xbf38aa3b, v1
	v_cmp_gt_f32_e32 vcc, 0, v0
	v_pk_fma_f32 v[4:5], v[2:3], s[24:25], v[130:131] op_sel_hi:[1,0,0]
	s_nop 0
	v_pk_fma_f32 v[4:5], v[2:3], v[4:5], s[28:29] op_sel_hi:[1,1,0]
	s_nop 0
	v_pk_fma_f32 v[4:5], v[2:3], v[4:5], s[30:31] op_sel_hi:[1,1,0]
	s_nop 0
	v_pk_fma_f32 v[4:5], v[2:3], v[4:5], s[36:37] op_sel_hi:[1,1,0]
	s_nop 0
	v_pk_mul_f32 v[2:3], v[2:3], v[4:5]
	v_exp_f32_e32 v4, v1
	s_nop 0
	v_pk_mul_f32 v[2:3], v[4:5], v[2:3] op_sel_hi:[0,1]
	v_pk_fma_f32 v[4:5], v[0:1], v[2:3], v[0:1] op_sel_hi:[0,1,1] neg_lo:[1,0,0] neg_hi:[1,0,0]
	v_mul_f32_e32 v0, v0, v2
	v_cndmask_b32_e32 v0, v4, v0, vcc
	v_mul_f32_e32 v0, v0, v209
	v_mul_f32_e32 v60, 0x3caaaaab, v0
	v_add_u32_e32 v62, v61, v155
	ds_write_b32 v62, v60 offset:960
	s_waitcnt vmcnt(1)
; __device__ void ph_peer(const float* __restrict__ SC, const bf16_t* __restrict__ H  , const float* __restrict__ gffn, const unsigned char* __restrict__ U, const unsigned char* __restrict__ V, float* X, const float* __restrict__ fgain) {
;     ...
;         for (int it = 0; it < 32; ++it) {
;             const int src = (it * 4 + grp) & 63;
;             const int e = __shfl(it < 16 ? idx_lo : idx_hi, src);
;             const float gt = __shfl(it < 16 ? g_lo : g_hi, src);
;             const u32x4* up = (const u32x4*)(U + (size_t)e * 768 + 48 * sub);
;             const u32x4 u0 = up[0], u1 = up[1], u2 = up[2];
;             u32x2 vw[2][3];
; #pragma unroll
;             for (int r = 0; r < 2; ++r) { const int ea = __builtin_amdgcn_readlane(e, 32 * r), eb = __builtin_amdgcn_readlane(e, 32 * r + 16);
;                 const u32x2* vp = (const u32x2*)(V + (size_t)(half ? eb : ea) * 768 + 24 * c32); vw[r][0] = vp[0]; vw[r][1] = vp[1]; vw[r][2] = vp[2]; }
;             float d0 = 0.f, d1 = 0.f, d2 = 0.f, d3 = 0.f;
;             {   const v6u_t p0 = (v6u_t){u0.x, u0.y, u0.z, u0.w, u1.x, u1.y};
;                 const v32bf_t r0 = __builtin_amdgcn_cvt_scalef32_pk32_bf16_fp6(p0, 1.0f);
; #pragma unroll
;                 for (int k = 0; k < 16; k += 4) { d0 = dot2pb(r0[2 * k], r0[2 * k + 1], hf2[k], d0); d1 = dot2pb(r0[2 * k + 2], r0[2 * k + 3], hf2[k + 1], d1);
;                     d2 = dot2pb(r0[2 * k + 4], r0[2 * k + 5], hf2[k + 2], d2); d3 = dot2pb(r0[2 * k + 6], r0[2 * k + 7], hf2[k + 3], d3); } }
;             {   const v6u_t p1 = (v6u_t){u1.z, u1.w, u2.x, u2.y, u2.z, u2.w};
;                 const v32bf_t r1 = __builtin_amdgcn_cvt_scalef32_pk32_bf16_fp6(p1, 1.0f);
; #pragma unroll
;                 for (int k = 0; k < 16; k += 4) { d0 = dot2pb(r1[2 * k], r1[2 * k + 1], hf2[16 + k], d0); d1 = dot2pb(r1[2 * k + 2], r1[2 * k + 3], hf2[16 + k + 1], d1);
;                     d2 = dot2pb(r1[2 * k + 4], r1[2 * k + 5], hf2[16 + k + 2], d2); d3 = dot2pb(r1[2 * k + 6], r1[2 * k + 7], hf2[16 + k + 3], d3); } }
;             const float d = row16_sum((d0 + d1) + (d2 + d3)) * FP6_INV;
;             const float a = gt * gelu1(d) * FP6_INV;
; #pragma unroll
;             for (int r = 0; r < 2; ++r) { const float aa = __int_as_float(__builtin_amdgcn_readlane(__float_as_int(a), 32 * r)), ab = __int_as_float(__builtin_amdgcn_readlane(__float_as_int(a), 32 * r + 16));
	v_cvt_scalef32_pk32_bf16_fp6 v[0:15], v[44:49], 1.0
	v_mov_b32_e32 v23, 0
	v_mov_b32_e32 v25, 0
	v_mov_b32_e32 v22, 0
	v_mov_b32_e32 v24, 0
	v_dot2c_f32_bf16_e32 v23, v0, v212
	v_dot2c_f32_bf16_e32 v25, v1, v213
	v_dot2c_f32_bf16_e32 v22, v2, v214
	v_dot2c_f32_bf16_e32 v24, v3, v215
	v_dot2c_f32_bf16_e32 v23, v4, v218
	v_dot2c_f32_bf16_e32 v25, v5, v219
	v_dot2c_f32_bf16_e32 v22, v6, v220
	v_dot2c_f32_bf16_e32 v24, v7, v221
	v_dot2c_f32_bf16_e32 v23, v8, v222
	v_dot2c_f32_bf16_e32 v25, v9, v223
	v_dot2c_f32_bf16_e32 v22, v10, v224
	v_dot2c_f32_bf16_e32 v24, v11, v225
	v_dot2c_f32_bf16_e32 v23, v12, v226
	v_dot2c_f32_bf16_e32 v25, v13, v227
	v_dot2c_f32_bf16_e32 v22, v14, v228
	v_dot2c_f32_bf16_e32 v24, v15, v229
	s_waitcnt vmcnt(0)
	v_cvt_scalef32_pk32_bf16_fp6 v[0:15], v[50:55], 1.0
	v_dot2c_f32_bf16_e32 v23, v0, v230
	v_dot2c_f32_bf16_e32 v25, v1, v231
	v_dot2c_f32_bf16_e32 v22, v2, v232
	v_dot2c_f32_bf16_e32 v24, v3, v233
	v_dot2c_f32_bf16_e32 v23, v4, v234
	v_dot2c_f32_bf16_e32 v25, v5, v235
	v_dot2c_f32_bf16_e32 v22, v6, v236
	v_dot2c_f32_bf16_e32 v24, v7, v237
	v_dot2c_f32_bf16_e32 v23, v8, v238
	v_dot2c_f32_bf16_e32 v25, v9, v239
	v_dot2c_f32_bf16_e32 v22, v10, v240
	v_dot2c_f32_bf16_e32 v24, v11, v241
	v_dot2c_f32_bf16_e32 v23, v12, v242
	v_dot2c_f32_bf16_e32 v25, v13, v243
	v_dot2c_f32_bf16_e32 v22, v14, v244
	v_dot2c_f32_bf16_e32 v24, v15, v245
	s_nop 2
	v_pk_add_f32 v[0:1], v[24:25], v[22:23]
	s_nop 0
	v_add_f32_e32 v0, v0, v1
	s_nop 1
	v_add_f32_dpp v0, v0, v0 quad_perm:[1,0,3,2] row_mask:0xf bank_mask:0xf bound_ctrl:1
	s_nop 1
	v_add_f32_dpp v0, v0, v0 quad_perm:[2,3,0,1] row_mask:0xf bank_mask:0xf bound_ctrl:1
	s_nop 1
	v_add_f32_dpp v0, v0, v0 row_half_mirror row_mask:0xf bank_mask:0xf bound_ctrl:1
	s_nop 1
	v_add_f32_dpp v0, v0, v0 row_mirror row_mask:0xf bank_mask:0xf bound_ctrl:1
	s_waitcnt lgkmcnt(0)
	v_cndmask_b32_e64 v0, v210, v0, s[56:57]
	v_cndmask_b32_e64 v211, v211, v59, s[56:57]
	v_mul_f32_e32 v0, 0x3caaaaab, v0
	v_and_b32_e32 v2, 0x7fffffff, v0
	v_pk_fma_f32 v[2:3], v[2:3], s[16:17], 1.0 op_sel_hi:[0,0,0]
	v_rcp_f32_e32 v2, v2
	v_rcp_f32_e32 v3, v3
	v_mul_f32_e32 v1, v0, v0
	v_mul_f32_e32 v1, 0xbf38aa3b, v1
	v_cmp_gt_f32_e32 vcc, 0, v0
	v_pk_fma_f32 v[4:5], v[2:3], s[24:25], v[130:131] op_sel_hi:[1,0,0]
	s_nop 0
	v_pk_fma_f32 v[4:5], v[2:3], v[4:5], s[28:29] op_sel_hi:[1,1,0]
	s_nop 0
	v_pk_fma_f32 v[4:5], v[2:3], v[4:5], s[30:31] op_sel_hi:[1,1,0]
	s_nop 0
	v_pk_fma_f32 v[4:5], v[2:3], v[4:5], s[36:37] op_sel_hi:[1,1,0]
	s_nop 0
	v_pk_mul_f32 v[2:3], v[2:3], v[4:5]
	v_exp_f32_e32 v4, v1
	s_nop 0
	v_pk_mul_f32 v[2:3], v[4:5], v[2:3] op_sel_hi:[0,1]
	v_pk_fma_f32 v[4:5], v[0:1], v[2:3], v[0:1] op_sel_hi:[0,1,1] neg_lo:[1,0,0] neg_hi:[1,0,0]
	v_mul_f32_e32 v0, v0, v2
	v_cndmask_b32_e32 v0, v4, v0, vcc
	v_mul_f32_e32 v0, v0, v211
	v_mul_f32_e32 v60, 0x3caaaaab, v0
	v_add_u32_e32 v62, v61, v155
	ds_write_b32 v62, v60 offset:2496
	v_mov_b32_e32 v180, 0
	v_mov_b32_e32 v181, 0
	v_mov_b32_e32 v182, 0
	v_mov_b32_e32 v183, 0
	v_mov_b32_e32 v184, 0
	v_mov_b32_e32 v185, 0
	v_mov_b32_e32 v186, 0
	v_mov_b32_e32 v187, 0
	v_mov_b32_e32 v188, 0
	v_mov_b32_e32 v189, 0
	v_mov_b32_e32 v190, 0
	v_mov_b32_e32 v191, 0
	v_mov_b32_e32 v192, 0
	v_mov_b32_e32 v193, 0
	v_mov_b32_e32 v194, 0
	v_mov_b32_e32 v195, 0
	v_mov_b32_e32 v196, 0
	v_mov_b32_e32 v197, 0
	v_mov_b32_e32 v198, 0
	v_mov_b32_e32 v199, 0
	v_mov_b32_e32 v200, 0
	v_mov_b32_e32 v201, 0
	v_mov_b32_e32 v202, 0
	v_mov_b32_e32 v203, 0
	v_mov_b32_e32 v204, 0
	v_mov_b32_e32 v205, 0
	v_mov_b32_e32 v206, 0
	v_mov_b32_e32 v207, 0
	v_mov_b32_e32 v208, 0
	v_mov_b32_e32 v209, 0
	v_mov_b32_e32 v210, 0
	v_mov_b32_e32 v211, 0
	s_barrier
	v_lshrrev_b32_e32 v61, 6, v131
	v_lshrrev_b32_e32 v0, 5, v74
	v_mul_u32_u24_e32 v61, 0x2400, v61
	v_lshl_add_u32 v61, v0, 2, v61
	s_mov_b32 s1, 0
	ds_read_b32 v32, v61 offset:0
	ds_read_b32 v33, v61 offset:8
	ds_read_b32 v56, v61 offset:1024
	ds_read_b32 v58, v61 offset:1032
	v_add_u32_e32 v61, 16, v61
	s_add_i32 s1, s1, 1
	s_waitcnt lgkmcnt(2)
	v_mad_u32_u24 v0, v32, s14, v93
	v_mad_u32_u24 v1, v33, s14, v93
	global_load_dwordx4 v[44:47], v0, s[48:49]
	global_load_dwordx2 v[48:49], v0, s[48:49] offset:16
	global_load_dwordx4 v[50:53], v1, s[48:49]
	global_load_dwordx2 v[54:55], v1, s[48:49] offset:16
; __device__ void ph_peer(const float* __restrict__ SC, const bf16_t* __restrict__ H  , const float* __restrict__ gffn, const unsigned char* __restrict__ U, const unsigned char* __restrict__ V, float* X, const float* __restrict__ fgain) {
;     ...
;             u32x2 vw[2][3];
; #pragma unroll
;             for (int r = 0; r < 2; ++r) { const int ea = __builtin_amdgcn_readlane(e, 32 * r), eb = __builtin_amdgcn_readlane(e, 32 * r + 16);
;                 const u32x2* vp = (const u32x2*)(V + (size_t)(half ? eb : ea) * 768 + 24 * c32); vw[r][0] = vp[0]; vw[r][1] = vp[1]; vw[r][2] = vp[2]; }
;             float d0 = 0.f, d1 = 0.f, d2 = 0.f, d3 = 0.f;
;             {   const v6u_t p0 = (v6u_t){u0.x, u0.y, u0.z, u0.w, u1.x, u1.y};
;                 const v32bf_t r0 = __builtin_amdgcn_cvt_scalef32_pk32_bf16_fp6(p0, 1.0f);
; #pragma unroll
;                 for (int k = 0; k < 16; k += 4) { d0 = dot2pb(r0[2 * k], r0[2 * k + 1], hf2[k], d0); d1 = dot2pb(r0[2 * k + 2], r0[2 * k + 3], hf2[k + 1], d1);
;                     d2 = dot2pb(r0[2 * k + 4], r0[2 * k + 5], hf2[k + 2], d2); d3 = dot2pb(r0[2 * k + 6], r0[2 * k + 7], hf2[k + 3], d3); } }
;             {   const v6u_t p1 = (v6u_t){u1.z, u1.w, u2.x, u2.y, u2.z, u2.w};
;                 const v32bf_t r1 = __builtin_amdgcn_cvt_scalef32_pk32_bf16_fp6(p1, 1.0f);
; #pragma unroll
;                 for (int k = 0; k < 16; k += 4) { d0 = dot2pb(r1[2 * k], r1[2 * k + 1], hf2[16 + k], d0); d1 = dot2pb(r1[2 * k + 2], r1[2 * k + 3], hf2[16 + k + 1], d1);
;                     d2 = dot2pb(r1[2 * k + 4], r1[2 * k + 5], hf2[16 + k + 2], d2); d3 = dot2pb(r1[2 * k + 6], r1[2 * k + 7], hf2[16 + k + 3], d3); } }
;             const float d = row16_sum((d0 + d1) + (d2 + d3)) * FP6_INV;
;             const float a = gt * gelu1(d) * FP6_INV;
; #pragma unroll
;             for (int r = 0; r < 2; ++r) { const float aa = __int_as_float(__builtin_amdgcn_readlane(__float_as_int(a), 32 * r)), ab = __int_as_float(__builtin_amdgcn_readlane(__float_as_int(a), 32 * r + 16));
;                 const float ak = half ? ab : aa;
;                 const v6u_t pv = (v6u_t){vw[r][0].x, vw[r][0].y, vw[r][1].x, vw[r][1].y, vw[r][2].x, vw[r][2].y};
;                 const v32f_t rv = __builtin_amdgcn_cvt_scalef32_pk32_f32_fp6(pv, 1.0f);
; #pragma unroll
;                 for (int i = 0; i < 32; ++i) acc[i] += ak * rv[i]; }
.Lpeer_vloop:
	ds_read_b32 v218, v61 offset:1520
	ds_read_b32 v219, v61 offset:1528
	ds_read_b32 v220, v61 offset:2544
	ds_read_b32 v222, v61 offset:2552
	s_waitcnt lgkmcnt(2)
	v_mad_u32_u24 v0, v218, s14, v93
	v_mad_u32_u24 v1, v219, s14, v93
	global_load_dwordx4 v[230:233], v0, s[48:49]
	global_load_dwordx2 v[234:235], v0, s[48:49] offset:16
	global_load_dwordx4 v[236:239], v1, s[48:49]
	global_load_dwordx2 v[240:241], v1, s[48:49] offset:16
	s_waitcnt vmcnt(6)
	v_cvt_scalef32_pk32_f32_fp6 v[0:31], v[44:49], 1.0
	s_nop 1
	v_pk_fma_f32 v[126:127], v[0:1], v[56:57], v[126:127] op_sel_hi:[1,0,1]
	v_pk_fma_f32 v[122:123], v[2:3], v[56:57], v[122:123] op_sel_hi:[1,0,1]
	v_pk_fma_f32 v[114:115], v[4:5], v[56:57], v[114:115] op_sel_hi:[1,0,1]
	v_pk_fma_f32 v[116:117], v[6:7], v[56:57], v[116:117] op_sel_hi:[1,0,1]
	v_pk_fma_f32 v[106:107], v[8:9], v[56:57], v[106:107] op_sel_hi:[1,0,1]
	v_pk_fma_f32 v[108:109], v[10:11], v[56:57], v[108:109] op_sel_hi:[1,0,1]
	v_pk_fma_f32 v[98:99], v[12:13], v[56:57], v[98:99] op_sel_hi:[1,0,1]
	v_pk_fma_f32 v[100:101], v[14:15], v[56:57], v[100:101] op_sel_hi:[1,0,1]
	v_pk_fma_f32 v[144:145], v[16:17], v[56:57], v[144:145] op_sel_hi:[1,0,1]
	v_pk_fma_f32 v[124:125], v[18:19], v[56:57], v[124:125] op_sel_hi:[1,0,1]
	v_pk_fma_f32 v[118:119], v[20:21], v[56:57], v[118:119] op_sel_hi:[1,0,1]
	v_pk_fma_f32 v[120:121], v[22:23], v[56:57], v[120:121] op_sel_hi:[1,0,1]
	v_pk_fma_f32 v[110:111], v[24:25], v[56:57], v[110:111] op_sel_hi:[1,0,1]
	v_pk_fma_f32 v[112:113], v[26:27], v[56:57], v[112:113] op_sel_hi:[1,0,1]
	v_pk_fma_f32 v[102:103], v[28:29], v[56:57], v[102:103] op_sel_hi:[1,0,1]
	v_pk_fma_f32 v[104:105], v[30:31], v[56:57], v[104:105] op_sel_hi:[1,0,1]
	s_waitcnt vmcnt(4)
	v_cvt_scalef32_pk32_f32_fp6 v[0:31], v[50:55], 1.0
	s_nop 1
	v_pk_fma_f32 v[126:127], v[0:1], v[58:59], v[126:127] op_sel_hi:[1,0,1]
	v_pk_fma_f32 v[122:123], v[2:3], v[58:59], v[122:123] op_sel_hi:[1,0,1]
	v_pk_fma_f32 v[114:115], v[4:5], v[58:59], v[114:115] op_sel_hi:[1,0,1]
	v_pk_fma_f32 v[116:117], v[6:7], v[58:59], v[116:117] op_sel_hi:[1,0,1]
	v_pk_fma_f32 v[106:107], v[8:9], v[58:59], v[106:107] op_sel_hi:[1,0,1]
	v_pk_fma_f32 v[108:109], v[10:11], v[58:59], v[108:109] op_sel_hi:[1,0,1]
	v_pk_fma_f32 v[98:99], v[12:13], v[58:59], v[98:99] op_sel_hi:[1,0,1]
	v_pk_fma_f32 v[100:101], v[14:15], v[58:59], v[100:101] op_sel_hi:[1,0,1]
	v_pk_fma_f32 v[144:145], v[16:17], v[58:59], v[144:145] op_sel_hi:[1,0,1]
	v_pk_fma_f32 v[124:125], v[18:19], v[58:59], v[124:125] op_sel_hi:[1,0,1]
	v_pk_fma_f32 v[118:119], v[20:21], v[58:59], v[118:119] op_sel_hi:[1,0,1]
	v_pk_fma_f32 v[120:121], v[22:23], v[58:59], v[120:121] op_sel_hi:[1,0,1]
	v_pk_fma_f32 v[110:111], v[24:25], v[58:59], v[110:111] op_sel_hi:[1,0,1]
	v_pk_fma_f32 v[112:113], v[26:27], v[58:59], v[112:113] op_sel_hi:[1,0,1]
	v_pk_fma_f32 v[102:103], v[28:29], v[58:59], v[102:103] op_sel_hi:[1,0,1]
	v_pk_fma_f32 v[104:105], v[30:31], v[58:59], v[104:105] op_sel_hi:[1,0,1]
	ds_read_b32 v32, v61 offset:0
	ds_read_b32 v33, v61 offset:8
	ds_read_b32 v56, v61 offset:1024
	ds_read_b32 v58, v61 offset:1032
	v_add_u32_e32 v61, 16, v61
	s_add_i32 s1, s1, 1
	s_waitcnt lgkmcnt(2)
	v_mad_u32_u24 v0, v32, s14, v93
	v_mad_u32_u24 v1, v33, s14, v93
	global_load_dwordx4 v[44:47], v0, s[48:49]
	global_load_dwordx2 v[48:49], v0, s[48:49] offset:16
	global_load_dwordx4 v[50:53], v1, s[48:49]
	global_load_dwordx2 v[54:55], v1, s[48:49] offset:16
	s_waitcnt vmcnt(6)
	v_cvt_scalef32_pk32_f32_fp6 v[0:31], v[230:235], 1.0
	s_nop 1
	v_pk_fma_f32 v[180:181], v[0:1], v[220:221], v[180:181] op_sel_hi:[1,0,1]
	v_pk_fma_f32 v[182:183], v[2:3], v[220:221], v[182:183] op_sel_hi:[1,0,1]
	v_pk_fma_f32 v[184:185], v[4:5], v[220:221], v[184:185] op_sel_hi:[1,0,1]
	v_pk_fma_f32 v[186:187], v[6:7], v[220:221], v[186:187] op_sel_hi:[1,0,1]
	v_pk_fma_f32 v[188:189], v[8:9], v[220:221], v[188:189] op_sel_hi:[1,0,1]
	v_pk_fma_f32 v[190:191], v[10:11], v[220:221], v[190:191] op_sel_hi:[1,0,1]
	v_pk_fma_f32 v[192:193], v[12:13], v[220:221], v[192:193] op_sel_hi:[1,0,1]
	v_pk_fma_f32 v[194:195], v[14:15], v[220:221], v[194:195] op_sel_hi:[1,0,1]
	v_pk_fma_f32 v[196:197], v[16:17], v[220:221], v[196:197] op_sel_hi:[1,0,1]
	v_pk_fma_f32 v[198:199], v[18:19], v[220:221], v[198:199] op_sel_hi:[1,0,1]
	v_pk_fma_f32 v[200:201], v[20:21], v[220:221], v[200:201] op_sel_hi:[1,0,1]
	v_pk_fma_f32 v[202:203], v[22:23], v[220:221], v[202:203] op_sel_hi:[1,0,1]
	v_pk_fma_f32 v[204:205], v[24:25], v[220:221], v[204:205] op_sel_hi:[1,0,1]
	v_pk_fma_f32 v[206:207], v[26:27], v[220:221], v[206:207] op_sel_hi:[1,0,1]
	v_pk_fma_f32 v[208:209], v[28:29], v[220:221], v[208:209] op_sel_hi:[1,0,1]
	v_pk_fma_f32 v[210:211], v[30:31], v[220:221], v[210:211] op_sel_hi:[1,0,1]
	s_waitcnt vmcnt(4)
	v_cvt_scalef32_pk32_f32_fp6 v[0:31], v[236:241], 1.0
	s_nop 1
	v_pk_fma_f32 v[180:181], v[0:1], v[222:223], v[180:181] op_sel_hi:[1,0,1]
	v_pk_fma_f32 v[182:183], v[2:3], v[222:223], v[182:183] op_sel_hi:[1,0,1]
	v_pk_fma_f32 v[184:185], v[4:5], v[222:223], v[184:185] op_sel_hi:[1,0,1]
	v_pk_fma_f32 v[186:187], v[6:7], v[222:223], v[186:187] op_sel_hi:[1,0,1]
	v_pk_fma_f32 v[188:189], v[8:9], v[222:223], v[188:189] op_sel_hi:[1,0,1]
	v_pk_fma_f32 v[190:191], v[10:11], v[222:223], v[190:191] op_sel_hi:[1,0,1]
	v_pk_fma_f32 v[192:193], v[12:13], v[222:223], v[192:193] op_sel_hi:[1,0,1]
	v_pk_fma_f32 v[194:195], v[14:15], v[222:223], v[194:195] op_sel_hi:[1,0,1]
	v_pk_fma_f32 v[196:197], v[16:17], v[222:223], v[196:197] op_sel_hi:[1,0,1]
	v_pk_fma_f32 v[198:199], v[18:19], v[222:223], v[198:199] op_sel_hi:[1,0,1]
	v_pk_fma_f32 v[200:201], v[20:21], v[222:223], v[200:201] op_sel_hi:[1,0,1]
	v_pk_fma_f32 v[202:203], v[22:23], v[222:223], v[202:203] op_sel_hi:[1,0,1]
	v_pk_fma_f32 v[204:205], v[24:25], v[222:223], v[204:205] op_sel_hi:[1,0,1]
	v_pk_fma_f32 v[206:207], v[26:27], v[222:223], v[206:207] op_sel_hi:[1,0,1]
	v_pk_fma_f32 v[208:209], v[28:29], v[222:223], v[208:209] op_sel_hi:[1,0,1]
	v_pk_fma_f32 v[210:211], v[30:31], v[222:223], v[210:211] op_sel_hi:[1,0,1]
	s_cmp_lt_u32 s1, 32
	s_cbranch_scc1 .Lpeer_vloop
; __device__ void ph_peer(const float* __restrict__ SC, const bf16_t* __restrict__ H  , const float* __restrict__ gffn, const unsigned char* __restrict__ U, const unsigned char* __restrict__ V, float* X, const float* __restrict__ fgain) {
;     ...
;             u32x2 vw[2][3];
; #pragma unroll
;             for (int r = 0; r < 2; ++r) { const int ea = __builtin_amdgcn_readlane(e, 32 * r), eb = __builtin_amdgcn_readlane(e, 32 * r + 16);
;                 const u32x2* vp = (const u32x2*)(V + (size_t)(half ? eb : ea) * 768 + 24 * c32); vw[r][0] = vp[0]; vw[r][1] = vp[1]; vw[r][2] = vp[2]; }
;             float d0 = 0.f, d1 = 0.f, d2 = 0.f, d3 = 0.f;
;             {   const v6u_t p0 = (v6u_t){u0.x, u0.y, u0.z, u0.w, u1.x, u1.y};
;                 const v32bf_t r0 = __builtin_amdgcn_cvt_scalef32_pk32_bf16_fp6(p0, 1.0f);
; #pragma unroll
;                 for (int k = 0; k < 16; k += 4) { d0 = dot2pb(r0[2 * k], r0[2 * k + 1], hf2[k], d0); d1 = dot2pb(r0[2 * k + 2], r0[2 * k + 3], hf2[k + 1], d1);
;                     d2 = dot2pb(r0[2 * k + 4], r0[2 * k + 5], hf2[k + 2], d2); d3 = dot2pb(r0[2 * k + 6], r0[2 * k + 7], hf2[k + 3], d3); } }
;             {   const v6u_t p1 = (v6u_t){u1.z, u1.w, u2.x, u2.y, u2.z, u2.w};
;                 const v32bf_t r1 = __builtin_amdgcn_cvt_scalef32_pk32_bf16_fp6(p1, 1.0f);
; #pragma unroll
;                 for (int k = 0; k < 16; k += 4) { d0 = dot2pb(r1[2 * k], r1[2 * k + 1], hf2[16 + k], d0); d1 = dot2pb(r1[2 * k + 2], r1[2 * k + 3], hf2[16 + k + 1], d1);
;                     d2 = dot2pb(r1[2 * k + 4], r1[2 * k + 5], hf2[16 + k + 2], d2); d3 = dot2pb(r1[2 * k + 6], r1[2 * k + 7], hf2[16 + k + 3], d3); } }
;             const float d = row16_sum((d0 + d1) + (d2 + d3)) * FP6_INV;
;             const float a = gt * gelu1(d) * FP6_INV;
; #pragma unroll
;             for (int r = 0; r < 2; ++r) { const float aa = __int_as_float(__builtin_amdgcn_readlane(__float_as_int(a), 32 * r)), ab = __int_as_float(__builtin_amdgcn_readlane(__float_as_int(a), 32 * r + 16));
;                 const float ak = half ? ab : aa;
;                 const v6u_t pv = (v6u_t){vw[r][0].x, vw[r][0].y, vw[r][1].x, vw[r][1].y, vw[r][2].x, vw[r][2].y};
;                 const v32f_t rv = __builtin_amdgcn_cvt_scalef32_pk32_f32_fp6(pv, 1.0f);
; #pragma unroll
;                 for (int i = 0; i < 32; ++i) acc[i] += ak * rv[i]; }
;         }
	ds_read_b32 v218, v61 offset:1520
	ds_read_b32 v219, v61 offset:1528
	ds_read_b32 v220, v61 offset:2544
	ds_read_b32 v222, v61 offset:2552
	s_waitcnt lgkmcnt(2)
	v_mad_u32_u24 v0, v218, s14, v93
	v_mad_u32_u24 v1, v219, s14, v93
	global_load_dwordx4 v[230:233], v0, s[48:49]
	global_load_dwordx2 v[234:235], v0, s[48:49] offset:16
	global_load_dwordx4 v[236:239], v1, s[48:49]
	global_load_dwordx2 v[240:241], v1, s[48:49] offset:16
	s_waitcnt vmcnt(6)
	v_cvt_scalef32_pk32_f32_fp6 v[0:31], v[44:49], 1.0
	s_nop 1
	v_pk_fma_f32 v[126:127], v[0:1], v[56:57], v[126:127] op_sel_hi:[1,0,1]
	v_pk_fma_f32 v[122:123], v[2:3], v[56:57], v[122:123] op_sel_hi:[1,0,1]
	v_pk_fma_f32 v[114:115], v[4:5], v[56:57], v[114:115] op_sel_hi:[1,0,1]
	v_pk_fma_f32 v[116:117], v[6:7], v[56:57], v[116:117] op_sel_hi:[1,0,1]
	v_pk_fma_f32 v[106:107], v[8:9], v[56:57], v[106:107] op_sel_hi:[1,0,1]
	v_pk_fma_f32 v[108:109], v[10:11], v[56:57], v[108:109] op_sel_hi:[1,0,1]
	v_pk_fma_f32 v[98:99], v[12:13], v[56:57], v[98:99] op_sel_hi:[1,0,1]
	v_pk_fma_f32 v[100:101], v[14:15], v[56:57], v[100:101] op_sel_hi:[1,0,1]
	v_pk_fma_f32 v[144:145], v[16:17], v[56:57], v[144:145] op_sel_hi:[1,0,1]
	v_pk_fma_f32 v[124:125], v[18:19], v[56:57], v[124:125] op_sel_hi:[1,0,1]
	v_pk_fma_f32 v[118:119], v[20:21], v[56:57], v[118:119] op_sel_hi:[1,0,1]
	v_pk_fma_f32 v[120:121], v[22:23], v[56:57], v[120:121] op_sel_hi:[1,0,1]
	v_pk_fma_f32 v[110:111], v[24:25], v[56:57], v[110:111] op_sel_hi:[1,0,1]
	v_pk_fma_f32 v[112:113], v[26:27], v[56:57], v[112:113] op_sel_hi:[1,0,1]
	v_pk_fma_f32 v[102:103], v[28:29], v[56:57], v[102:103] op_sel_hi:[1,0,1]
	v_pk_fma_f32 v[104:105], v[30:31], v[56:57], v[104:105] op_sel_hi:[1,0,1]
	s_waitcnt vmcnt(4)
	v_cvt_scalef32_pk32_f32_fp6 v[0:31], v[50:55], 1.0
	s_nop 1
	v_pk_fma_f32 v[126:127], v[0:1], v[58:59], v[126:127] op_sel_hi:[1,0,1]
	v_pk_fma_f32 v[122:123], v[2:3], v[58:59], v[122:123] op_sel_hi:[1,0,1]
	v_pk_fma_f32 v[114:115], v[4:5], v[58:59], v[114:115] op_sel_hi:[1,0,1]
	v_pk_fma_f32 v[116:117], v[6:7], v[58:59], v[116:117] op_sel_hi:[1,0,1]
	v_pk_fma_f32 v[106:107], v[8:9], v[58:59], v[106:107] op_sel_hi:[1,0,1]
	v_pk_fma_f32 v[108:109], v[10:11], v[58:59], v[108:109] op_sel_hi:[1,0,1]
	v_pk_fma_f32 v[98:99], v[12:13], v[58:59], v[98:99] op_sel_hi:[1,0,1]
	v_pk_fma_f32 v[100:101], v[14:15], v[58:59], v[100:101] op_sel_hi:[1,0,1]
	v_pk_fma_f32 v[144:145], v[16:17], v[58:59], v[144:145] op_sel_hi:[1,0,1]
	v_pk_fma_f32 v[124:125], v[18:19], v[58:59], v[124:125] op_sel_hi:[1,0,1]
	v_pk_fma_f32 v[118:119], v[20:21], v[58:59], v[118:119] op_sel_hi:[1,0,1]
	v_pk_fma_f32 v[120:121], v[22:23], v[58:59], v[120:121] op_sel_hi:[1,0,1]
	v_pk_fma_f32 v[110:111], v[24:25], v[58:59], v[110:111] op_sel_hi:[1,0,1]
	v_pk_fma_f32 v[112:113], v[26:27], v[58:59], v[112:113] op_sel_hi:[1,0,1]
	v_pk_fma_f32 v[102:103], v[28:29], v[58:59], v[102:103] op_sel_hi:[1,0,1]
	v_pk_fma_f32 v[104:105], v[30:31], v[58:59], v[104:105] op_sel_hi:[1,0,1]
	s_waitcnt vmcnt(2) lgkmcnt(0)
	v_cvt_scalef32_pk32_f32_fp6 v[0:31], v[230:235], 1.0
	s_nop 1
	v_pk_fma_f32 v[180:181], v[0:1], v[220:221], v[180:181] op_sel_hi:[1,0,1]
	v_pk_fma_f32 v[182:183], v[2:3], v[220:221], v[182:183] op_sel_hi:[1,0,1]
	v_pk_fma_f32 v[184:185], v[4:5], v[220:221], v[184:185] op_sel_hi:[1,0,1]
	v_pk_fma_f32 v[186:187], v[6:7], v[220:221], v[186:187] op_sel_hi:[1,0,1]
	v_pk_fma_f32 v[188:189], v[8:9], v[220:221], v[188:189] op_sel_hi:[1,0,1]
	v_pk_fma_f32 v[190:191], v[10:11], v[220:221], v[190:191] op_sel_hi:[1,0,1]
	v_pk_fma_f32 v[192:193], v[12:13], v[220:221], v[192:193] op_sel_hi:[1,0,1]
	v_pk_fma_f32 v[194:195], v[14:15], v[220:221], v[194:195] op_sel_hi:[1,0,1]
	v_pk_fma_f32 v[196:197], v[16:17], v[220:221], v[196:197] op_sel_hi:[1,0,1]
	v_pk_fma_f32 v[198:199], v[18:19], v[220:221], v[198:199] op_sel_hi:[1,0,1]
	v_pk_fma_f32 v[200:201], v[20:21], v[220:221], v[200:201] op_sel_hi:[1,0,1]
	v_pk_fma_f32 v[202:203], v[22:23], v[220:221], v[202:203] op_sel_hi:[1,0,1]
	v_pk_fma_f32 v[204:205], v[24:25], v[220:221], v[204:205] op_sel_hi:[1,0,1]
	v_pk_fma_f32 v[206:207], v[26:27], v[220:221], v[206:207] op_sel_hi:[1,0,1]
	v_pk_fma_f32 v[208:209], v[28:29], v[220:221], v[208:209] op_sel_hi:[1,0,1]
	v_pk_fma_f32 v[210:211], v[30:31], v[220:221], v[210:211] op_sel_hi:[1,0,1]
	s_waitcnt vmcnt(0)
	v_cvt_scalef32_pk32_f32_fp6 v[0:31], v[236:241], 1.0
	s_nop 1
	v_pk_fma_f32 v[180:181], v[0:1], v[222:223], v[180:181] op_sel_hi:[1,0,1]
	v_pk_fma_f32 v[182:183], v[2:3], v[222:223], v[182:183] op_sel_hi:[1,0,1]
	v_pk_fma_f32 v[184:185], v[4:5], v[222:223], v[184:185] op_sel_hi:[1,0,1]
	v_pk_fma_f32 v[186:187], v[6:7], v[222:223], v[186:187] op_sel_hi:[1,0,1]
	v_pk_fma_f32 v[188:189], v[8:9], v[222:223], v[188:189] op_sel_hi:[1,0,1]
	v_pk_fma_f32 v[190:191], v[10:11], v[222:223], v[190:191] op_sel_hi:[1,0,1]
	v_pk_fma_f32 v[192:193], v[12:13], v[222:223], v[192:193] op_sel_hi:[1,0,1]
	v_pk_fma_f32 v[194:195], v[14:15], v[222:223], v[194:195] op_sel_hi:[1,0,1]
	v_pk_fma_f32 v[196:197], v[16:17], v[222:223], v[196:197] op_sel_hi:[1,0,1]
	v_pk_fma_f32 v[198:199], v[18:19], v[222:223], v[198:199] op_sel_hi:[1,0,1]
	v_pk_fma_f32 v[200:201], v[20:21], v[222:223], v[200:201] op_sel_hi:[1,0,1]
	v_pk_fma_f32 v[202:203], v[22:23], v[222:223], v[202:203] op_sel_hi:[1,0,1]
	v_pk_fma_f32 v[204:205], v[24:25], v[222:223], v[204:205] op_sel_hi:[1,0,1]
	v_pk_fma_f32 v[206:207], v[26:27], v[222:223], v[206:207] op_sel_hi:[1,0,1]
	v_pk_fma_f32 v[208:209], v[28:29], v[222:223], v[208:209] op_sel_hi:[1,0,1]
	v_pk_fma_f32 v[210:211], v[30:31], v[222:223], v[210:211] op_sel_hi:[1,0,1]
	s_setprio 0
	ds_bpermute_b32 v0, v154, v126
	ds_bpermute_b32 v2, v154, v144
	ds_bpermute_b32 v1, v154, v127
	ds_bpermute_b32 v3, v154, v145
	v_lshl_add_u64 v[28:29], v[96:97], 2, v[84:85]
	ds_bpermute_b32 v16, v154, v122
	ds_bpermute_b32 v18, v154, v124
	s_waitcnt lgkmcnt(3)
; __device__ void ph_peer(const float* __restrict__ SC, const bf16_t* __restrict__ H  , const float* __restrict__ gffn, const unsigned char* __restrict__ U, const unsigned char* __restrict__ V, float* X, const float* __restrict__ fgain) {
;     ...
;         for (int i = 0; i < 16; ++i) { const float lo = acc[i] + __shfl_xor(acc[i], 32), hi = acc[16 + i] + __shfl_xor(acc[16 + i], 32); o16[i] = half ? hi : lo; }
;         float4* xp = (float4*)(X + (size_t)tok * 1024 + 32 * c32 + 16 * half);
;         float4 xo[4]; float ss = 0.f;
; #pragma unroll
;         for (int j = 0; j < 4; ++j) { float4 a = xp[j]; a.x += o16[j * 4 + 0]; a.y += o16[j * 4 + 1]; a.z += o16[j * 4 + 2]; a.w += o16[j * 4 + 3]; xo[j] = a; ss += a.x * a.x + a.y * a.y + a.z * a.z + a.w * a.w; }
;         if (fgain) { ss = wave_sum(ss); const float rs = rsqrtf(ss * (1.0f / 1024.0f) + 1e-6f);
; #pragma unroll
;             for (int j = 0; j < 4; ++j) { const float4 g = *(const float4*)(fgain + 32 * c32 + 16 * half + j * 4); xo[j].x *= rs * g.x; xo[j].y *= rs * g.y; xo[j].z *= rs * g.z; xo[j].w *= rs * g.w; } }
; #pragma unroll
;         for (int j = 0; j < 4; ++j) xp[j] = xo[j];
	v_pk_add_f32 v[0:1], v[126:127], v[0:1]
	s_waitcnt lgkmcnt(2)
	v_pk_add_f32 v[2:3], v[144:145], v[2:3]
	ds_bpermute_b32 v17, v154, v123
	v_cndmask_b32_e64 v47, v3, v1, s[44:45]
	v_cndmask_b32_e64 v46, v2, v0, s[44:45]
	global_load_dwordx4 v[8:11], v[28:29], off offset:48
	global_load_dwordx4 v[12:15], v[28:29], off offset:32
	global_load_dwordx4 v[4:7], v[28:29], off offset:16
	global_load_dwordx4 v[0:3], v[28:29], off
	ds_bpermute_b32 v19, v154, v125
	ds_bpermute_b32 v20, v154, v114
	ds_bpermute_b32 v22, v154, v118
	ds_bpermute_b32 v21, v154, v115
	ds_bpermute_b32 v23, v154, v119
	ds_bpermute_b32 v24, v154, v116
	ds_bpermute_b32 v26, v154, v120
	ds_bpermute_b32 v25, v154, v117
	ds_bpermute_b32 v27, v154, v121
	ds_bpermute_b32 v30, v154, v106
	ds_bpermute_b32 v32, v154, v110
	ds_bpermute_b32 v31, v154, v107
	ds_bpermute_b32 v33, v154, v111
	s_waitcnt lgkmcnt(13)
	v_pk_add_f32 v[16:17], v[122:123], v[16:17]
	s_waitcnt lgkmcnt(12)
	v_pk_add_f32 v[18:19], v[124:125], v[18:19]
	ds_bpermute_b32 v34, v154, v108
	ds_bpermute_b32 v36, v154, v112
	ds_bpermute_b32 v35, v154, v109
	ds_bpermute_b32 v37, v154, v113
	v_cndmask_b32_e64 v17, v19, v17, s[44:45]
	v_cndmask_b32_e64 v16, v18, v16, s[44:45]
	s_waitcnt lgkmcnt(12)
	v_pk_add_f32 v[18:19], v[118:119], v[22:23]
	ds_bpermute_b32 v38, v154, v98
	ds_bpermute_b32 v40, v154, v102
	ds_bpermute_b32 v39, v154, v99
	ds_bpermute_b32 v41, v154, v103
	ds_bpermute_b32 v42, v154, v100
	ds_bpermute_b32 v44, v154, v104
	ds_bpermute_b32 v43, v154, v101
	ds_bpermute_b32 v45, v154, v105
	s_and_b64 vcc, exec, s[92:93]
	s_waitcnt vmcnt(0)
	v_pk_add_f32 v[2:3], v[16:17], v[2:3]
	v_pk_add_f32 v[16:17], v[114:115], v[20:21]
	s_waitcnt lgkmcnt(14)
	v_pk_add_f32 v[20:21], v[120:121], v[26:27]
	v_cndmask_b32_e64 v17, v19, v17, s[44:45]
	v_cndmask_b32_e64 v16, v18, v16, s[44:45]
	v_pk_add_f32 v[18:19], v[116:117], v[24:25]
	v_pk_add_f32 v[4:5], v[16:17], v[4:5]
	v_cndmask_b32_e64 v19, v21, v19, s[44:45]
	v_cndmask_b32_e64 v18, v20, v18, s[44:45]
	v_pk_add_f32 v[6:7], v[18:19], v[6:7]
	s_waitcnt lgkmcnt(13)
	v_pk_add_f32 v[16:17], v[106:107], v[30:31]
	s_waitcnt lgkmcnt(12)
	v_pk_add_f32 v[18:19], v[110:111], v[32:33]
	s_waitcnt lgkmcnt(8)
	v_pk_add_f32 v[20:21], v[112:113], v[36:37]
	v_cndmask_b32_e64 v17, v19, v17, s[44:45]
	v_cndmask_b32_e64 v16, v18, v16, s[44:45]
	v_pk_add_f32 v[18:19], v[108:109], v[34:35]
	v_pk_add_f32 v[12:13], v[16:17], v[12:13]
	v_cndmask_b32_e64 v19, v21, v19, s[44:45]
	v_cndmask_b32_e64 v18, v20, v18, s[44:45]
	v_pk_add_f32 v[14:15], v[18:19], v[14:15]
	s_waitcnt lgkmcnt(5)
	v_pk_add_f32 v[16:17], v[98:99], v[38:39]
	s_waitcnt lgkmcnt(4)
	v_pk_add_f32 v[18:19], v[102:103], v[40:41]
	s_waitcnt lgkmcnt(0)
	v_pk_add_f32 v[20:21], v[104:105], v[44:45]
	v_cndmask_b32_e64 v17, v19, v17, s[44:45]
	v_cndmask_b32_e64 v16, v18, v16, s[44:45]
	v_pk_add_f32 v[18:19], v[100:101], v[42:43]
	v_pk_add_f32 v[0:1], v[46:47], v[0:1]
	v_cndmask_b32_e64 v19, v21, v19, s[44:45]
	v_cndmask_b32_e64 v18, v20, v18, s[44:45]
	v_pk_add_f32 v[8:9], v[16:17], v[8:9]
	v_pk_add_f32 v[10:11], v[18:19], v[10:11]
	s_cbranch_vccz .Lpeer_st_a
	v_mov_b32_e32 v18, v1
	v_mov_b32_e32 v19, v5
	v_mov_b32_e32 v16, v0
	v_mov_b32_e32 v17, v4
	v_pk_mul_f32 v[18:19], v[18:19], v[18:19]
	v_mov_b32_e32 v20, v13
	v_pk_fma_f32 v[16:17], v[16:17], v[16:17], v[18:19]
	v_mov_b32_e32 v18, v2
	v_mov_b32_e32 v19, v6
	v_pk_fma_f32 v[16:17], v[18:19], v[18:19], v[16:17]
	v_mov_b32_e32 v18, v3
	v_mov_b32_e32 v19, v7
	v_mov_b32_e32 v21, v9
	v_pk_fma_f32 v[16:17], v[18:19], v[18:19], v[16:17]
	v_mov_b32_e32 v18, v12
	v_mov_b32_e32 v19, v8
	v_pk_mul_f32 v[20:21], v[20:21], v[20:21]
	v_add_f32_e32 v16, v16, v17
	v_pk_fma_f32 v[18:19], v[18:19], v[18:19], v[20:21]
	v_mov_b32_e32 v20, v14
	v_mov_b32_e32 v21, v10
	v_pk_fma_f32 v[18:19], v[20:21], v[20:21], v[18:19]
	v_mov_b32_e32 v20, v15
	v_mov_b32_e32 v21, v11
	v_pk_fma_f32 v[18:19], v[20:21], v[20:21], v[18:19]
	s_nop 0
	v_add_f32_e32 v16, v16, v18
	v_add_f32_e32 v16, v16, v19
	s_nop 1
	v_add_f32_dpp v16, v16, v16 quad_perm:[1,0,3,2] row_mask:0xf bank_mask:0xf bound_ctrl:1
	s_nop 1
	v_add_f32_dpp v16, v16, v16 quad_perm:[2,3,0,1] row_mask:0xf bank_mask:0xf bound_ctrl:1
	s_nop 1
	v_add_f32_dpp v16, v16, v16 row_half_mirror row_mask:0xf bank_mask:0xf bound_ctrl:1
	s_nop 1
	v_add_f32_dpp v16, v16, v16 row_mirror row_mask:0xf bank_mask:0xf bound_ctrl:1
	s_nop 0
	v_readlane_b32 s2, v16, 16
	v_readlane_b32 s6, v16, 48
	v_readlane_b32 s0, v16, 0
	v_readlane_b32 s1, v16, 32
	v_mov_b32_e32 v16, s2
	v_mov_b32_e32 v17, s6
	v_pk_add_f32 v[16:17], s[0:1], v[16:17]
	s_mov_b32 s0, 0x800000
	v_add_f32_e32 v16, v16, v17
	v_fmamk_f32 v16, v16, 0x3a800000, v170
	v_cmp_gt_f32_e32 vcc, s0, v16
	v_mul_f32_e32 v17, 0x4b800000, v16
	s_nop 0
	v_cndmask_b32_e32 v16, v16, v17, vcc
	v_rsq_f32_e32 v16, v16
	s_nop 0
	v_mul_f32_e32 v17, 0x45800000, v16
	v_cndmask_b32_e32 v30, v16, v17, vcc
	global_load_dwordx4 v[16:19], v[86:87], off offset:48
	global_load_dwordx4 v[20:23], v[86:87], off offset:32
	global_load_dwordx4 v[24:27], v[86:87], off offset:16
	global_load_dwordx4 v[32:35], v[86:87], off
	s_waitcnt vmcnt(3)
	v_pk_mul_f32 v[16:17], v[30:31], v[16:17] op_sel_hi:[0,1]
	s_waitcnt vmcnt(2)
	v_pk_mul_f32 v[20:21], v[20:21], v[30:31] op_sel_hi:[1,0]
	s_waitcnt vmcnt(1)
	v_pk_mul_f32 v[24:25], v[24:25], v[30:31] op_sel_hi:[1,0]
	s_waitcnt vmcnt(0)
	v_pk_mul_f32 v[32:33], v[32:33], v[30:31] op_sel_hi:[1,0]
	v_pk_mul_f32 v[4:5], v[4:5], v[24:25]
	v_pk_mul_f32 v[0:1], v[0:1], v[32:33]
	v_pk_mul_f32 v[32:33], v[34:35], v[30:31] op_sel_hi:[1,0]
	v_pk_mul_f32 v[24:25], v[26:27], v[30:31] op_sel_hi:[1,0]
	v_pk_mul_f32 v[12:13], v[12:13], v[20:21]
	v_pk_mul_f32 v[20:21], v[30:31], v[22:23] op_sel_hi:[0,1]
	v_pk_mul_f32 v[8:9], v[8:9], v[16:17]
	v_pk_mul_f32 v[16:17], v[30:31], v[18:19] op_sel_hi:[0,1]
	v_pk_mul_f32 v[2:3], v[2:3], v[32:33]
	v_pk_mul_f32 v[6:7], v[6:7], v[24:25]
	v_pk_mul_f32 v[14:15], v[14:15], v[20:21]
	v_pk_mul_f32 v[10:11], v[10:11], v[16:17]
